# second saddr pass: the +0x80 LDS-DMA loads read a spare SGPR base (base+0x80, 2 SALU/iter) - GEMM K-loops now contain no VALU address math
# baseline (speedup 1.0000x reference)
;     __device__ bool next(int i, Unit& u) const { if (r0 + i >= r1) return false; return base.next(r0 + i, u); }
;     __device__ bool next(int i, Unit& u) const { const int L = i * G + c; if (L >= 256) return false; u.pm = L; u.pn = L >> 3; return true; }
; #define PG8_STAGE(bufoff, gbase, voff) do { _Pragma("unroll") for (int _i = 0; _i < 2; ++_i) \
;         __builtin_amdgcn_global_load_lds((const unsigned*)((const char*)(gbase) + (voff)[_i]), (LAS unsigned*)(lds + (bufoff) + ldsw + _i * 8192), 16, 0, 0); } while (0)
; #define PG8_LDA(dst, b, h) do { _Pragma("unroll") for (int m = 0; m < 4; ++m) _Pragma("unroll") for (int k = 0; k < 2; ++k) dst[m][k] = *(const LAS bf16x8*)(lds + PG8_SA(b, h) + aoff + m * 2048 + k * 1024); } while (0)
; #define PG8_WAIT_V(n) asm volatile("s_waitcnt vmcnt(" #n ")" ::: "memory")
; template <class Epi, class Sched>
; __device__ __forceinline__ void gemm_phase(LAS unsigned char* lds, const Gemm g, const Sched& S, const Epi& E, int wave_id) {
;     ...
;         const bool has_next = S.next(ui + 1, nxt);
;         const char* nA = has_next ? (const char*)g.A + (size_t)nxt.pm * tstepA : cA; const char* nB = has_next ? (const char*)g.Bt + (size_t)nxt.pn * tstepB : cB;
;         for (int t = 0; t < nt; t += 2) {
;             const bool last = (t == nt - 2);
;             const char* a1 = cA + (size_t)(t + 1) * kstep;
;             const char* a2 = last ? nA : cA + (size_t)(t + 2) * kstep; const char* b2 = last ? nB : cB + (size_t)(t + 2) * kstep;
;             const char* a3 = a2 + kstep; const char* b3 = b2 + kstep;
;             PG8_LDB(B0, 0, 0); PG8_LDB(B1, 0, 1); PG8_SCHED; PG8_LDA(At, 0, 0); PG8_STAGE(PG8_SA(1, 1), a1 + hstepA, voffA);
;             PG8_WAIT_V(8); PG8_WAIT_L(0); PG8_BAR; PG8_MMA(0, 0, At, B0); PG8_MMA(0, 1, At, B1); PG8_BAR; PG8_SCHED;
;             PG8_LDA(At, 0, 1); PG8_STAGE(PG8_SB(0, 0), b2, voffB); PG8_STAGE(PG8_SB(0, 1), b2 + hstepB, voffB); PG8_STAGE(PG8_SA(0, 0), a2, voffA);
;             PG8_WAIT_V(8); PG8_WAIT_L(0); PG8_BAR; PG8_MMA(1, 0, At, B0); PG8_MMA(1, 1, At, B1); PG8_BAR; PG8_SCHED;
;     __device__ __forceinline__ void load(Pre& p, const pg8::Unit& u, int ai, int m, int wr, int wc, int fr, int fq) const {
;         const int row = u.pm * 256 + ai * 128 + wr * 64 + m * 16 + fr;
;         if (MODE == EM_PROJ || MODE == EM_GATES) p.rs = ((const float*)(ws + WS_RINV0))[row];
.LBB0_251:
	s_ashr_i32 s45, s44, 31
	s_lshl_b64 s[14:15], s[44:45], 19
	s_add_u32 s46, s52, s14
	s_addc_u32 s47, s53, s15
	s_and_b64 s[14:15], s[4:5], exec
	s_cselect_b32 s2, s47, s11
	s_cselect_b32 s7, s46, s10
	s_ashr_i32 s39, s38, 31
	s_lshl_b64 s[14:15], s[38:39], 19
	s_add_u32 s48, s92, s14
	s_addc_u32 s49, s93, s15
	s_and_b64 s[14:15], s[4:5], exec
	s_cselect_b32 s9, s49, s13
	s_cselect_b32 s18, s48, s12
	s_add_u32 s10, s10, 0x40080
	s_addc_u32 s11, s11, 0
	s_add_u32 s33, s12, 0x100
	s_addc_u32 s39, s13, 0
	s_mov_b32 s45, -2
	s_lshl_b32 s14, s8, 8
	s_add_i32 s14, s14, s61
	v_or_b32_e32 v252, s14, v167
	v_ashrrev_i32_e32 v253, 31, v252
	v_lshl_add_u64 v[252:253], v[252:253], 2, s[26:27]
	global_load_dword v244, v[252:253], off
	global_load_dword v245, v[252:253], off offset:64
	global_load_dword v246, v[252:253], off offset:128
	global_load_dword v247, v[252:253], off offset:192
	global_load_dword v248, v[252:253], off offset:512
	global_load_dword v249, v[252:253], off offset:576
	global_load_dword v250, v[252:253], off offset:640
	global_load_dword v251, v[252:253], off offset:704
	ds_read_b128 v[16:19], v183
	ds_read_b128 v[20:23], v183 offset:1024
	ds_read_b128 v[32:35], v183 offset:2048
	ds_read_b128 v[36:39], v183 offset:3072
	ds_read_b128 v[184:187], v190
	ds_read_b128 v[194:197], v190 offset:1024
	ds_read_b128 v[198:201], v190 offset:2048
	ds_read_b128 v[202:205], v190 offset:3072
	s_add_u32 s12, s10, 0xfffc0080
	s_addc_u32 s13, s11, -1
	s_cmp_eq_u32 s45, 12
	s_cselect_b32 s15, s2, s13
	s_cselect_b32 s14, s7, s12
	s_cselect_b32 s13, s9, s39
	s_cselect_b32 s12, s18, s33
	s_add_u32 s98, s14, 0x80
	s_addc_u32 s99, s15, 0
	s_add_u32 s74, s12, 0x80
	s_addc_u32 s75, s13, 0
	s_add_i32 m0, s55, 0xc000
	ds_read_b128 v[206:209], v191
	ds_read_b128 v[210:213], v191 offset:1024
	ds_read_b128 v[214:217], v191 offset:2048
	ds_read_b128 v[218:221], v191 offset:3072
	ds_read_b128 v[222:225], v191 offset:4096
	ds_read_b128 v[226:229], v191 offset:5120
	ds_read_b128 v[230:233], v191 offset:6144
	ds_read_b128 v[234:237], v191 offset:7168
	global_load_lds_dwordx4 v158, s[10:11]
	s_add_i32 m0, s55, 0xe000
	s_nop 0
	global_load_lds_dwordx4 v160, s[10:11]
	s_waitcnt vmcnt(16)
	s_waitcnt lgkmcnt(0)
	s_barrier
	s_setprio 1
	s_waitcnt lgkmcnt(0)
	v_mfma_f32_16x16x32_bf16 v[140:143], v[16:19], v[206:209], 0
	v_mfma_f32_16x16x32_bf16 v[136:139], v[32:35], v[206:209], 0
	v_mfma_f32_16x16x32_bf16 v[124:127], v[16:19], v[214:217], 0
	v_mfma_f32_16x16x32_bf16 v[120:123], v[32:35], v[214:217], 0
	v_mfma_f32_16x16x32_bf16 v[108:111], v[16:19], v[222:225], 0
	v_mfma_f32_16x16x32_bf16 v[104:107], v[32:35], v[222:225], 0
	v_mfma_f32_16x16x32_bf16 v[92:95], v[16:19], v[230:233], 0
	v_mfma_f32_16x16x32_bf16 v[88:91], v[32:35], v[230:233], 0
	v_mfma_f32_16x16x32_bf16 v[140:143], v[20:23], v[210:213], v[140:143]
	v_mfma_f32_16x16x32_bf16 v[136:139], v[36:39], v[210:213], v[136:139]
	v_mfma_f32_16x16x32_bf16 v[124:127], v[20:23], v[218:221], v[124:127]
	v_mfma_f32_16x16x32_bf16 v[120:123], v[36:39], v[218:221], v[120:123]
	v_mfma_f32_16x16x32_bf16 v[108:111], v[20:23], v[226:229], v[108:111]
	v_mfma_f32_16x16x32_bf16 v[104:107], v[36:39], v[226:229], v[104:107]
	v_mfma_f32_16x16x32_bf16 v[92:95], v[20:23], v[234:237], v[92:95]
	v_mfma_f32_16x16x32_bf16 v[88:91], v[36:39], v[234:237], v[88:91]
	s_setprio 0
	s_setprio 1
	v_mfma_f32_16x16x32_bf16 v[132:135], v[184:187], v[206:209], 0
	v_mfma_f32_16x16x32_bf16 v[128:131], v[198:201], v[206:209], 0
	v_mfma_f32_16x16x32_bf16 v[116:119], v[184:187], v[214:217], 0
	v_mfma_f32_16x16x32_bf16 v[112:115], v[198:201], v[214:217], 0
	v_mfma_f32_16x16x32_bf16 v[100:103], v[184:187], v[222:225], 0
	v_mfma_f32_16x16x32_bf16 v[96:99], v[198:201], v[222:225], 0
	v_mfma_f32_16x16x32_bf16 v[84:87], v[184:187], v[230:233], 0
	v_mfma_f32_16x16x32_bf16 v[80:83], v[198:201], v[230:233], 0
	v_mfma_f32_16x16x32_bf16 v[132:135], v[194:197], v[210:213], v[132:135]
	v_mfma_f32_16x16x32_bf16 v[128:131], v[202:205], v[210:213], v[128:131]
	v_mfma_f32_16x16x32_bf16 v[116:119], v[194:197], v[218:221], v[116:119]
	v_mfma_f32_16x16x32_bf16 v[112:115], v[202:205], v[218:221], v[112:115]
	v_mfma_f32_16x16x32_bf16 v[100:103], v[194:197], v[226:229], v[100:103]
	v_mfma_f32_16x16x32_bf16 v[96:99], v[202:205], v[226:229], v[96:99]
	v_mfma_f32_16x16x32_bf16 v[84:87], v[194:197], v[234:237], v[84:87]
	v_mfma_f32_16x16x32_bf16 v[80:83], v[202:205], v[234:237], v[80:83]
	s_setprio 0
	s_barrier
	s_add_i32 s50, s67, s54
	s_mov_b32 m0, s50
	ds_read_b128 v[206:209], v191 offset:16384
	ds_read_b128 v[210:213], v191 offset:17408
	ds_read_b128 v[214:217], v191 offset:18432
	ds_read_b128 v[218:221], v191 offset:19456
	ds_read_b128 v[222:225], v191 offset:20480
	ds_read_b128 v[226:229], v191 offset:21504
	ds_read_b128 v[230:233], v191 offset:22528
	ds_read_b128 v[234:237], v191 offset:23552
	global_load_lds_dwordx4 v146, s[12:13]
	s_add_i32 m0, s50, 0x2000
	s_add_u32 s50, s12, 0x40000
	s_addc_u32 s51, s13, 0
	s_add_i32 s78, s72, s54
	global_load_lds_dwordx4 v150, s[12:13]
	s_mov_b32 m0, s78
	s_nop 0
	global_load_lds_dwordx4 v146, s[50:51]
	s_add_i32 m0, s78, 0x2000
	s_nop 0
	global_load_lds_dwordx4 v150, s[50:51]
	s_mov_b32 m0, s55
	s_nop 0
	global_load_lds_dwordx4 v144, s[14:15]
	s_mov_b32 m0, s58
	s_nop 0
	global_load_lds_dwordx4 v148, s[14:15]
	s_waitcnt vmcnt(16)
	s_waitcnt lgkmcnt(0)
	s_barrier
; #define PG8_STAGE(bufoff, gbase, voff) do { _Pragma("unroll") for (int _i = 0; _i < 2; ++_i) \
;         __builtin_amdgcn_global_load_lds((const unsigned*)((const char*)(gbase) + (voff)[_i]), (LAS unsigned*)(lds + (bufoff) + ldsw + _i * 8192), 16, 0, 0); } while (0)
; #define PG8_LDA(dst, b, h) do { _Pragma("unroll") for (int m = 0; m < 4; ++m) _Pragma("unroll") for (int k = 0; k < 2; ++k) dst[m][k] = *(const LAS bf16x8*)(lds + PG8_SA(b, h) + aoff + m * 2048 + k * 1024); } while (0)
; #define PG8_LDB(dst, b, h) do { _Pragma("unroll") for (int n = 0; n < 2; ++n) _Pragma("unroll") for (int k = 0; k < 2; ++k) dst[n][k] = *(const LAS bf16x8*)(lds + PG8_SB(b, h) + boff + n * 2048 + k * 1024); } while (0)
; #define PG8_MMA(ai, bj, At, Bt) do { __builtin_amdgcn_s_setprio(1); _Pragma("unroll") for (int m = 0; m < 4; ++m) _Pragma("unroll") for (int n = 0; n < 2; ++n) _Pragma("unroll") for (int k = 0; k < 2; ++k) \
;         acc[ai][bj][m][n] = __builtin_amdgcn_mfma_f32_16x16x32_bf16(Bt[n][k], At[m][k], acc[ai][bj][m][n], 0, 0, 0); __builtin_amdgcn_s_setprio(0); } while (0)
; #define PG8_WAIT_V(n) asm volatile("s_waitcnt vmcnt(" #n ")" ::: "memory")
; #define PG8_WAIT_L(n) asm volatile("s_waitcnt lgkmcnt(" #n ")" ::: "memory")
; #define PG8_BAR __builtin_amdgcn_s_barrier()
; #define PG8_SCHED __builtin_amdgcn_sched_barrier(0)
; template <class Epi, class Sched>
; __device__ __forceinline__ void gemm_phase(LAS unsigned char* lds, const Gemm g, const Sched& S, const Epi& E, int wave_id) {
;     ...
;             PG8_LDB(B0, 1, 0); PG8_LDB(B1, 1, 1); PG8_SCHED; PG8_LDA(At, 1, 0); PG8_STAGE(PG8_SA(0, 1), a2 + hstepA, voffA);
;             PG8_WAIT_V(8); PG8_WAIT_L(0); PG8_BAR; PG8_MMA(0, 0, At, B0); PG8_MMA(0, 1, At, B1); PG8_BAR; PG8_SCHED;
	s_setprio 1
	s_waitcnt lgkmcnt(0)
	v_mfma_f32_16x16x32_bf16 v[76:79], v[16:19], v[206:209], 0
	v_mfma_f32_16x16x32_bf16 v[72:75], v[32:35], v[206:209], 0
	v_mfma_f32_16x16x32_bf16 v[60:63], v[16:19], v[214:217], 0
	v_mfma_f32_16x16x32_bf16 v[56:59], v[32:35], v[214:217], 0
	v_mfma_f32_16x16x32_bf16 v[44:47], v[16:19], v[222:225], 0
	v_mfma_f32_16x16x32_bf16 v[40:43], v[32:35], v[222:225], 0
	v_mfma_f32_16x16x32_bf16 v[12:15], v[16:19], v[230:233], 0
	v_mfma_f32_16x16x32_bf16 v[8:11], v[32:35], v[230:233], 0
	v_mfma_f32_16x16x32_bf16 v[76:79], v[20:23], v[210:213], v[76:79]
	v_mfma_f32_16x16x32_bf16 v[72:75], v[36:39], v[210:213], v[72:75]
	v_mfma_f32_16x16x32_bf16 v[60:63], v[20:23], v[218:221], v[60:63]
	v_mfma_f32_16x16x32_bf16 v[56:59], v[36:39], v[218:221], v[56:59]
	v_mfma_f32_16x16x32_bf16 v[44:47], v[20:23], v[226:229], v[44:47]
	v_mfma_f32_16x16x32_bf16 v[40:43], v[36:39], v[226:229], v[40:43]
	v_mfma_f32_16x16x32_bf16 v[12:15], v[20:23], v[234:237], v[12:15]
	v_mfma_f32_16x16x32_bf16 v[8:11], v[36:39], v[234:237], v[8:11]
	s_setprio 0
	s_setprio 1
	v_mfma_f32_16x16x32_bf16 v[28:31], v[184:187], v[222:225], 0
	v_mfma_f32_16x16x32_bf16 v[24:27], v[198:201], v[222:225], 0
	v_mfma_f32_16x16x32_bf16 v[4:7], v[184:187], v[230:233], 0
	v_mfma_f32_16x16x32_bf16 v[0:3], v[198:201], v[230:233], 0
	v_mfma_f32_16x16x32_bf16 v[16:19], v[184:187], v[206:209], 0
	v_mfma_f32_16x16x32_bf16 v[20:23], v[198:201], v[206:209], 0
	v_mfma_f32_16x16x32_bf16 v[32:35], v[184:187], v[214:217], 0
	v_mfma_f32_16x16x32_bf16 v[36:39], v[198:201], v[214:217], 0
	v_mfma_f32_16x16x32_bf16 v[28:31], v[194:197], v[226:229], v[28:31]
	v_mfma_f32_16x16x32_bf16 v[24:27], v[202:205], v[226:229], v[24:27]
	v_mfma_f32_16x16x32_bf16 v[4:7], v[194:197], v[234:237], v[4:7]
	v_mfma_f32_16x16x32_bf16 v[0:3], v[202:205], v[234:237], v[0:3]
	v_mfma_f32_16x16x32_bf16 v[16:19], v[194:197], v[210:213], v[16:19]
	v_mfma_f32_16x16x32_bf16 v[20:23], v[202:205], v[210:213], v[20:23]
	v_mfma_f32_16x16x32_bf16 v[32:35], v[194:197], v[218:221], v[32:35]
	v_mfma_f32_16x16x32_bf16 v[36:39], v[202:205], v[218:221], v[36:39]
	s_setprio 0
	s_barrier
	s_add_i32 s50, 0, 0x18000
	s_add_i32 s51, 0, 0x1c000
	v_add_u32_e32 v68, s50, v171
	v_add_u32_e32 v152, s51, v171
	ds_read_b128 v[48:51], v68
	ds_read_b128 v[52:55], v68 offset:1024
	ds_read_b128 v[64:67], v68 offset:2048
	ds_read_b128 v[68:71], v68 offset:3072
	ds_read_b128 v[184:187], v152
	ds_read_b128 v[194:197], v152 offset:1024
	ds_read_b128 v[198:201], v152 offset:2048
	ds_read_b128 v[202:205], v152 offset:3072
	s_add_u32 s14, s14, 0x40000
	s_addc_u32 s15, s15, 0
	s_mov_b32 m0, s59
	ds_read_b128 v[206:209], v191 offset:32768
	ds_read_b128 v[210:213], v191 offset:33792
	ds_read_b128 v[214:217], v191 offset:34816
	ds_read_b128 v[218:221], v191 offset:35840
	ds_read_b128 v[222:225], v191 offset:36864
	ds_read_b128 v[226:229], v191 offset:37888
	ds_read_b128 v[230:233], v191 offset:38912
	ds_read_b128 v[234:237], v191 offset:39936
	global_load_lds_dwordx4 v144, s[14:15]
	s_mov_b32 m0, s60
	s_nop 0
	global_load_lds_dwordx4 v148, s[14:15]
	s_waitcnt vmcnt(8)
	s_waitcnt lgkmcnt(0)
	s_barrier
	s_setprio 1
	s_waitcnt lgkmcnt(0)
	v_mfma_f32_16x16x32_bf16 v[140:143], v[48:51], v[206:209], v[140:143]
	v_mfma_f32_16x16x32_bf16 v[136:139], v[64:67], v[206:209], v[136:139]
	v_mfma_f32_16x16x32_bf16 v[124:127], v[48:51], v[214:217], v[124:127]
	v_mfma_f32_16x16x32_bf16 v[120:123], v[64:67], v[214:217], v[120:123]
	v_mfma_f32_16x16x32_bf16 v[108:111], v[48:51], v[222:225], v[108:111]
	v_mfma_f32_16x16x32_bf16 v[104:107], v[64:67], v[222:225], v[104:107]
	v_mfma_f32_16x16x32_bf16 v[92:95], v[48:51], v[230:233], v[92:95]
	v_mfma_f32_16x16x32_bf16 v[88:91], v[64:67], v[230:233], v[88:91]
	v_mfma_f32_16x16x32_bf16 v[140:143], v[52:55], v[210:213], v[140:143]
	v_mfma_f32_16x16x32_bf16 v[136:139], v[68:71], v[210:213], v[136:139]
	v_mfma_f32_16x16x32_bf16 v[124:127], v[52:55], v[218:221], v[124:127]
	v_mfma_f32_16x16x32_bf16 v[120:123], v[68:71], v[218:221], v[120:123]
	v_mfma_f32_16x16x32_bf16 v[108:111], v[52:55], v[226:229], v[108:111]
	v_mfma_f32_16x16x32_bf16 v[104:107], v[68:71], v[226:229], v[104:107]
	v_mfma_f32_16x16x32_bf16 v[92:95], v[52:55], v[234:237], v[92:95]
	v_mfma_f32_16x16x32_bf16 v[88:91], v[68:71], v[234:237], v[88:91]
	s_setprio 0
	s_setprio 1
	v_mfma_f32_16x16x32_bf16 v[132:135], v[184:187], v[206:209], v[132:135]
	v_mfma_f32_16x16x32_bf16 v[128:131], v[198:201], v[206:209], v[128:131]
	v_mfma_f32_16x16x32_bf16 v[116:119], v[184:187], v[214:217], v[116:119]
	v_mfma_f32_16x16x32_bf16 v[112:115], v[198:201], v[214:217], v[112:115]
	v_mfma_f32_16x16x32_bf16 v[100:103], v[184:187], v[222:225], v[100:103]
	v_mfma_f32_16x16x32_bf16 v[96:99], v[198:201], v[222:225], v[96:99]
	v_mfma_f32_16x16x32_bf16 v[84:87], v[184:187], v[230:233], v[84:87]
	v_mfma_f32_16x16x32_bf16 v[80:83], v[198:201], v[230:233], v[80:83]
	v_mfma_f32_16x16x32_bf16 v[132:135], v[194:197], v[210:213], v[132:135]
	v_mfma_f32_16x16x32_bf16 v[128:131], v[202:205], v[210:213], v[128:131]
	v_mfma_f32_16x16x32_bf16 v[116:119], v[194:197], v[218:221], v[116:119]
	v_mfma_f32_16x16x32_bf16 v[112:115], v[202:205], v[218:221], v[112:115]
	v_mfma_f32_16x16x32_bf16 v[100:103], v[194:197], v[226:229], v[100:103]
	v_mfma_f32_16x16x32_bf16 v[96:99], v[202:205], v[226:229], v[96:99]
	v_mfma_f32_16x16x32_bf16 v[84:87], v[194:197], v[234:237], v[84:87]
	v_mfma_f32_16x16x32_bf16 v[80:83], v[202:205], v[234:237], v[80:83]
	s_setprio 0
	s_barrier
; #define PG8_STAGE(bufoff, gbase, voff) do { _Pragma("unroll") for (int _i = 0; _i < 2; ++_i) \
;         __builtin_amdgcn_global_load_lds((const unsigned*)((const char*)(gbase) + (voff)[_i]), (LAS unsigned*)(lds + (bufoff) + ldsw + _i * 8192), 16, 0, 0); } while (0)
; #define PG8_LDA(dst, b, h) do { _Pragma("unroll") for (int m = 0; m < 4; ++m) _Pragma("unroll") for (int k = 0; k < 2; ++k) dst[m][k] = *(const LAS bf16x8*)(lds + PG8_SA(b, h) + aoff + m * 2048 + k * 1024); } while (0)
; #define PG8_LDB(dst, b, h) do { _Pragma("unroll") for (int n = 0; n < 2; ++n) _Pragma("unroll") for (int k = 0; k < 2; ++k) dst[n][k] = *(const LAS bf16x8*)(lds + PG8_SB(b, h) + boff + n * 2048 + k * 1024); } while (0)
; #define PG8_MMA(ai, bj, At, Bt) do { __builtin_amdgcn_s_setprio(1); _Pragma("unroll") for (int m = 0; m < 4; ++m) _Pragma("unroll") for (int n = 0; n < 2; ++n) _Pragma("unroll") for (int k = 0; k < 2; ++k) \
;         acc[ai][bj][m][n] = __builtin_amdgcn_mfma_f32_16x16x32_bf16(Bt[n][k], At[m][k], acc[ai][bj][m][n], 0, 0, 0); __builtin_amdgcn_s_setprio(0); } while (0)
; #define PG8_WAIT_V(n) asm volatile("s_waitcnt vmcnt(" #n ")" ::: "memory")
; #define PG8_WAIT_L(n) asm volatile("s_waitcnt lgkmcnt(" #n ")" ::: "memory")
; #define PG8_BAR __builtin_amdgcn_s_barrier()
; #define PG8_SCHED __builtin_amdgcn_sched_barrier(0)
; template <class Epi, class Sched>
; __device__ __forceinline__ void gemm_phase(LAS unsigned char* lds, const Gemm g, const Sched& S, const Epi& E, int wave_id) {
;     ...
;             PG8_LDB(B0, 0, 0); PG8_LDB(B1, 0, 1); PG8_SCHED; PG8_LDA(At, 0, 0); PG8_STAGE(PG8_SA(1, 1), a1 + hstepA, voffA);
;             PG8_WAIT_V(8); PG8_WAIT_L(0); PG8_BAR; PG8_MMA(0, 0, At, B0); PG8_MMA(0, 1, At, B1); PG8_BAR; PG8_SCHED;
;     ...
;             PG8_LDA(At, 1, 1); PG8_STAGE(PG8_SB(1, 0), b3, voffB); PG8_STAGE(PG8_SB(1, 1), b3 + hstepB, voffB); PG8_STAGE(PG8_SA(1, 0), a3, voffA);
;             PG8_WAIT_V(8); PG8_WAIT_L(0); PG8_BAR; PG8_MMA(1, 0, At, B0); PG8_MMA(1, 1, At, B1); PG8_BAR; PG8_SCHED;
	s_add_i32 s14, s50, s54
	s_mov_b32 m0, s14
	ds_read_b128 v[206:209], v191 offset:49152
	ds_read_b128 v[210:213], v191 offset:50176
	ds_read_b128 v[214:217], v191 offset:51200
	ds_read_b128 v[218:221], v191 offset:52224
	ds_read_b128 v[222:225], v191 offset:53248
	ds_read_b128 v[226:229], v191 offset:54272
	ds_read_b128 v[230:233], v191 offset:55296
	ds_read_b128 v[234:237], v191 offset:56320
	global_load_lds_dwordx4 v146, s[74:75]
	s_add_i32 m0, s14, 0x2000
	s_add_u32 s12, s12, 0x40080
	s_addc_u32 s13, s13, 0
	s_add_i32 s14, s51, s54
	global_load_lds_dwordx4 v150, s[74:75]
	s_mov_b32 m0, s14
	s_nop 0
	global_load_lds_dwordx4 v146, s[12:13]
	s_add_i32 m0, s14, 0x2000
	s_nop 0
	global_load_lds_dwordx4 v150, s[12:13]
	s_mov_b32 m0, s62
	s_nop 0
	global_load_lds_dwordx4 v144, s[98:99]
	s_mov_b32 m0, s63
	s_nop 0
	global_load_lds_dwordx4 v148, s[98:99]
	s_waitcnt vmcnt(8)
	s_waitcnt lgkmcnt(0)
	s_barrier
	s_setprio 1
	s_waitcnt lgkmcnt(0)
	v_mfma_f32_16x16x32_bf16 v[76:79], v[48:51], v[206:209], v[76:79]
	v_mfma_f32_16x16x32_bf16 v[72:75], v[64:67], v[206:209], v[72:75]
	v_mfma_f32_16x16x32_bf16 v[60:63], v[48:51], v[214:217], v[60:63]
	v_mfma_f32_16x16x32_bf16 v[56:59], v[64:67], v[214:217], v[56:59]
	v_mfma_f32_16x16x32_bf16 v[44:47], v[48:51], v[222:225], v[44:47]
	v_mfma_f32_16x16x32_bf16 v[40:43], v[64:67], v[222:225], v[40:43]
	v_mfma_f32_16x16x32_bf16 v[12:15], v[48:51], v[230:233], v[12:15]
	v_mfma_f32_16x16x32_bf16 v[8:11], v[64:67], v[230:233], v[8:11]
	v_mfma_f32_16x16x32_bf16 v[76:79], v[52:55], v[210:213], v[76:79]
	v_mfma_f32_16x16x32_bf16 v[72:75], v[68:71], v[210:213], v[72:75]
	v_mfma_f32_16x16x32_bf16 v[60:63], v[52:55], v[218:221], v[60:63]
	v_mfma_f32_16x16x32_bf16 v[56:59], v[68:71], v[218:221], v[56:59]
	v_mfma_f32_16x16x32_bf16 v[44:47], v[52:55], v[226:229], v[44:47]
	v_mfma_f32_16x16x32_bf16 v[40:43], v[68:71], v[226:229], v[40:43]
	v_mfma_f32_16x16x32_bf16 v[12:15], v[52:55], v[234:237], v[12:15]
	v_mfma_f32_16x16x32_bf16 v[8:11], v[68:71], v[234:237], v[8:11]
	s_setprio 0
	s_setprio 1
	v_mfma_f32_16x16x32_bf16 v[16:19], v[184:187], v[206:209], v[16:19]
	v_mfma_f32_16x16x32_bf16 v[68:71], v[194:197], v[210:213], v[16:19]
	v_mfma_f32_16x16x32_bf16 v[16:19], v[198:201], v[206:209], v[20:23]
	v_mfma_f32_16x16x32_bf16 v[64:67], v[202:205], v[210:213], v[16:19]
	v_mfma_f32_16x16x32_bf16 v[16:19], v[184:187], v[214:217], v[32:35]
	v_mfma_f32_16x16x32_bf16 v[52:55], v[194:197], v[218:221], v[16:19]
	v_mfma_f32_16x16x32_bf16 v[16:19], v[198:201], v[214:217], v[36:39]
	v_mfma_f32_16x16x32_bf16 v[48:51], v[202:205], v[218:221], v[16:19]
	v_mfma_f32_16x16x32_bf16 v[16:19], v[184:187], v[222:225], v[28:31]
	v_mfma_f32_16x16x32_bf16 v[28:31], v[194:197], v[226:229], v[16:19]
	v_mfma_f32_16x16x32_bf16 v[16:19], v[198:201], v[222:225], v[24:27]
	v_mfma_f32_16x16x32_bf16 v[4:7], v[184:187], v[230:233], v[4:7]
	v_mfma_f32_16x16x32_bf16 v[0:3], v[198:201], v[230:233], v[0:3]
	v_mfma_f32_16x16x32_bf16 v[24:27], v[202:205], v[226:229], v[16:19]
	v_mfma_f32_16x16x32_bf16 v[4:7], v[194:197], v[234:237], v[4:7]
	v_mfma_f32_16x16x32_bf16 v[0:3], v[202:205], v[234:237], v[0:3]
	s_setprio 0
	s_barrier
	s_add_i32 s45, s45, 2
	s_add_u32 s10, s10, 0x100
	s_addc_u32 s11, s11, 0
	s_add_u32 s33, s33, 0x100
	s_addc_u32 s39, s39, 0
	s_cmp_gt_u32 s45, 13
.LBB0_252:
	ds_read_b128 v[16:19], v183
	ds_read_b128 v[20:23], v183 offset:1024
	ds_read_b128 v[32:35], v183 offset:2048
	ds_read_b128 v[36:39], v183 offset:3072
	ds_read_b128 v[184:187], v190
	ds_read_b128 v[194:197], v190 offset:1024
	ds_read_b128 v[198:201], v190 offset:2048
	ds_read_b128 v[202:205], v190 offset:3072
	s_add_u32 s12, s10, 0xfffc0080
	s_addc_u32 s13, s11, -1
	s_cmp_eq_u32 s45, 12
	s_cselect_b32 s15, s2, s13
	s_cselect_b32 s14, s7, s12
	s_cselect_b32 s13, s9, s39
	s_cselect_b32 s12, s18, s33
	s_add_u32 s98, s14, 0x80
	s_addc_u32 s99, s15, 0
	s_add_u32 s74, s12, 0x80
	s_addc_u32 s75, s13, 0
	s_add_i32 m0, s55, 0xc000
	ds_read_b128 v[206:209], v191
	ds_read_b128 v[210:213], v191 offset:1024
	ds_read_b128 v[214:217], v191 offset:2048
	ds_read_b128 v[218:221], v191 offset:3072
	ds_read_b128 v[222:225], v191 offset:4096
	ds_read_b128 v[226:229], v191 offset:5120
	ds_read_b128 v[230:233], v191 offset:6144
	ds_read_b128 v[234:237], v191 offset:7168
	global_load_lds_dwordx4 v158, s[10:11]
	s_add_i32 m0, s55, 0xe000
	s_nop 0
	global_load_lds_dwordx4 v160, s[10:11]
	s_waitcnt vmcnt(8)
	s_waitcnt lgkmcnt(0)
	s_barrier
	s_setprio 1
	s_waitcnt lgkmcnt(0)
	v_mfma_f32_16x16x32_bf16 v[140:143], v[16:19], v[206:209], v[140:143]
	v_mfma_f32_16x16x32_bf16 v[136:139], v[32:35], v[206:209], v[136:139]
	v_mfma_f32_16x16x32_bf16 v[124:127], v[16:19], v[214:217], v[124:127]
	v_mfma_f32_16x16x32_bf16 v[120:123], v[32:35], v[214:217], v[120:123]
	v_mfma_f32_16x16x32_bf16 v[108:111], v[16:19], v[222:225], v[108:111]
	v_mfma_f32_16x16x32_bf16 v[104:107], v[32:35], v[222:225], v[104:107]
	v_mfma_f32_16x16x32_bf16 v[92:95], v[16:19], v[230:233], v[92:95]
	v_mfma_f32_16x16x32_bf16 v[88:91], v[32:35], v[230:233], v[88:91]
	v_mfma_f32_16x16x32_bf16 v[140:143], v[20:23], v[210:213], v[140:143]
	v_mfma_f32_16x16x32_bf16 v[136:139], v[36:39], v[210:213], v[136:139]
	v_mfma_f32_16x16x32_bf16 v[124:127], v[20:23], v[218:221], v[124:127]
	v_mfma_f32_16x16x32_bf16 v[120:123], v[36:39], v[218:221], v[120:123]
	v_mfma_f32_16x16x32_bf16 v[108:111], v[20:23], v[226:229], v[108:111]
	v_mfma_f32_16x16x32_bf16 v[104:107], v[36:39], v[226:229], v[104:107]
	v_mfma_f32_16x16x32_bf16 v[92:95], v[20:23], v[234:237], v[92:95]
	v_mfma_f32_16x16x32_bf16 v[88:91], v[36:39], v[234:237], v[88:91]
	s_setprio 0
	s_setprio 1
	v_mfma_f32_16x16x32_bf16 v[132:135], v[184:187], v[206:209], v[132:135]
	v_mfma_f32_16x16x32_bf16 v[128:131], v[198:201], v[206:209], v[128:131]
	v_mfma_f32_16x16x32_bf16 v[116:119], v[184:187], v[214:217], v[116:119]
	v_mfma_f32_16x16x32_bf16 v[112:115], v[198:201], v[214:217], v[112:115]
	v_mfma_f32_16x16x32_bf16 v[100:103], v[184:187], v[222:225], v[100:103]
	v_mfma_f32_16x16x32_bf16 v[96:99], v[198:201], v[222:225], v[96:99]
	v_mfma_f32_16x16x32_bf16 v[84:87], v[184:187], v[230:233], v[84:87]
	v_mfma_f32_16x16x32_bf16 v[80:83], v[198:201], v[230:233], v[80:83]
	v_mfma_f32_16x16x32_bf16 v[132:135], v[194:197], v[210:213], v[132:135]
	v_mfma_f32_16x16x32_bf16 v[128:131], v[202:205], v[210:213], v[128:131]
	v_mfma_f32_16x16x32_bf16 v[116:119], v[194:197], v[218:221], v[116:119]
	v_mfma_f32_16x16x32_bf16 v[112:115], v[202:205], v[218:221], v[112:115]
	v_mfma_f32_16x16x32_bf16 v[100:103], v[194:197], v[226:229], v[100:103]
	v_mfma_f32_16x16x32_bf16 v[96:99], v[202:205], v[226:229], v[96:99]
	v_mfma_f32_16x16x32_bf16 v[84:87], v[194:197], v[234:237], v[84:87]
	v_mfma_f32_16x16x32_bf16 v[80:83], v[202:205], v[234:237], v[80:83]
	s_setprio 0
	s_barrier
; #define PG8_STAGE(bufoff, gbase, voff) do { _Pragma("unroll") for (int _i = 0; _i < 2; ++_i) \
;         __builtin_amdgcn_global_load_lds((const unsigned*)((const char*)(gbase) + (voff)[_i]), (LAS unsigned*)(lds + (bufoff) + ldsw + _i * 8192), 16, 0, 0); } while (0)
; #define PG8_LDA(dst, b, h) do { _Pragma("unroll") for (int m = 0; m < 4; ++m) _Pragma("unroll") for (int k = 0; k < 2; ++k) dst[m][k] = *(const LAS bf16x8*)(lds + PG8_SA(b, h) + aoff + m * 2048 + k * 1024); } while (0)
; #define PG8_LDB(dst, b, h) do { _Pragma("unroll") for (int n = 0; n < 2; ++n) _Pragma("unroll") for (int k = 0; k < 2; ++k) dst[n][k] = *(const LAS bf16x8*)(lds + PG8_SB(b, h) + boff + n * 2048 + k * 1024); } while (0)
; #define PG8_MMA(ai, bj, At, Bt) do { __builtin_amdgcn_s_setprio(1); _Pragma("unroll") for (int m = 0; m < 4; ++m) _Pragma("unroll") for (int n = 0; n < 2; ++n) _Pragma("unroll") for (int k = 0; k < 2; ++k) \
;         acc[ai][bj][m][n] = __builtin_amdgcn_mfma_f32_16x16x32_bf16(Bt[n][k], At[m][k], acc[ai][bj][m][n], 0, 0, 0); __builtin_amdgcn_s_setprio(0); } while (0)
; #define PG8_WAIT_V(n) asm volatile("s_waitcnt vmcnt(" #n ")" ::: "memory")
; #define PG8_WAIT_L(n) asm volatile("s_waitcnt lgkmcnt(" #n ")" ::: "memory")
; #define PG8_BAR __builtin_amdgcn_s_barrier()
; #define PG8_SCHED __builtin_amdgcn_sched_barrier(0)
; template <class Epi, class Sched>
; __device__ __forceinline__ void gemm_phase(LAS unsigned char* lds, const Gemm g, const Sched& S, const Epi& E, int wave_id) {
;     ...
;             PG8_LDB(B0, 0, 0); PG8_LDB(B1, 0, 1); PG8_SCHED; PG8_LDA(At, 0, 0); PG8_STAGE(PG8_SA(1, 1), a1 + hstepA, voffA);
;             PG8_WAIT_V(8); PG8_WAIT_L(0); PG8_BAR; PG8_MMA(0, 0, At, B0); PG8_MMA(0, 1, At, B1); PG8_BAR; PG8_SCHED;
;             PG8_LDA(At, 0, 1); PG8_STAGE(PG8_SB(0, 0), b2, voffB); PG8_STAGE(PG8_SB(0, 1), b2 + hstepB, voffB); PG8_STAGE(PG8_SA(0, 0), a2, voffA);
;             PG8_WAIT_V(8); PG8_WAIT_L(0); PG8_BAR; PG8_MMA(1, 0, At, B0); PG8_MMA(1, 1, At, B1); PG8_BAR; PG8_SCHED;
;             PG8_LDB(B0, 1, 0); PG8_LDB(B1, 1, 1); PG8_SCHED; PG8_LDA(At, 1, 0); PG8_STAGE(PG8_SA(0, 1), a2 + hstepA, voffA);
;             PG8_WAIT_V(8); PG8_WAIT_L(0); PG8_BAR; PG8_MMA(0, 0, At, B0); PG8_MMA(0, 1, At, B1); PG8_BAR; PG8_SCHED;
	s_add_i32 s50, s67, s54
	s_mov_b32 m0, s50
	ds_read_b128 v[206:209], v191 offset:16384
	ds_read_b128 v[210:213], v191 offset:17408
	ds_read_b128 v[214:217], v191 offset:18432
	ds_read_b128 v[218:221], v191 offset:19456
	ds_read_b128 v[222:225], v191 offset:20480
	ds_read_b128 v[226:229], v191 offset:21504
	ds_read_b128 v[230:233], v191 offset:22528
	ds_read_b128 v[234:237], v191 offset:23552
	global_load_lds_dwordx4 v146, s[12:13]
	s_add_i32 m0, s50, 0x2000
	s_add_u32 s50, s12, 0x40000
	s_addc_u32 s51, s13, 0
	s_add_i32 s78, s72, s54
	global_load_lds_dwordx4 v150, s[12:13]
	s_mov_b32 m0, s78
	s_nop 0
	global_load_lds_dwordx4 v146, s[50:51]
	s_add_i32 m0, s78, 0x2000
	s_nop 0
	global_load_lds_dwordx4 v150, s[50:51]
	s_mov_b32 m0, s55
	s_nop 0
	global_load_lds_dwordx4 v144, s[14:15]
	s_mov_b32 m0, s58
	s_nop 0
	global_load_lds_dwordx4 v148, s[14:15]
	s_waitcnt vmcnt(8)
	s_waitcnt lgkmcnt(0)
	s_barrier
	s_setprio 1
	s_waitcnt lgkmcnt(0)
	v_mfma_f32_16x16x32_bf16 v[76:79], v[16:19], v[206:209], v[76:79]
	v_mfma_f32_16x16x32_bf16 v[72:75], v[32:35], v[206:209], v[72:75]
	v_mfma_f32_16x16x32_bf16 v[60:63], v[16:19], v[214:217], v[60:63]
	v_mfma_f32_16x16x32_bf16 v[56:59], v[32:35], v[214:217], v[56:59]
	v_mfma_f32_16x16x32_bf16 v[44:47], v[16:19], v[222:225], v[44:47]
	v_mfma_f32_16x16x32_bf16 v[40:43], v[32:35], v[222:225], v[40:43]
	v_mfma_f32_16x16x32_bf16 v[12:15], v[16:19], v[230:233], v[12:15]
	v_mfma_f32_16x16x32_bf16 v[8:11], v[32:35], v[230:233], v[8:11]
	v_mfma_f32_16x16x32_bf16 v[76:79], v[20:23], v[210:213], v[76:79]
	v_mfma_f32_16x16x32_bf16 v[72:75], v[36:39], v[210:213], v[72:75]
	v_mfma_f32_16x16x32_bf16 v[60:63], v[20:23], v[218:221], v[60:63]
	v_mfma_f32_16x16x32_bf16 v[56:59], v[36:39], v[218:221], v[56:59]
	v_mfma_f32_16x16x32_bf16 v[44:47], v[20:23], v[226:229], v[44:47]
	v_mfma_f32_16x16x32_bf16 v[40:43], v[36:39], v[226:229], v[40:43]
	v_mfma_f32_16x16x32_bf16 v[12:15], v[20:23], v[234:237], v[12:15]
	v_mfma_f32_16x16x32_bf16 v[8:11], v[36:39], v[234:237], v[8:11]
	s_setprio 0
	s_setprio 1
	v_mfma_f32_16x16x32_bf16 v[28:31], v[184:187], v[222:225], v[28:31]
	v_mfma_f32_16x16x32_bf16 v[24:27], v[198:201], v[222:225], v[24:27]
	v_mfma_f32_16x16x32_bf16 v[4:7], v[184:187], v[230:233], v[4:7]
	v_mfma_f32_16x16x32_bf16 v[0:3], v[198:201], v[230:233], v[0:3]
	v_mfma_f32_16x16x32_bf16 v[16:19], v[184:187], v[206:209], v[68:71]
	v_mfma_f32_16x16x32_bf16 v[20:23], v[198:201], v[206:209], v[64:67]
	v_mfma_f32_16x16x32_bf16 v[32:35], v[184:187], v[214:217], v[52:55]
	v_mfma_f32_16x16x32_bf16 v[36:39], v[198:201], v[214:217], v[48:51]
	v_mfma_f32_16x16x32_bf16 v[28:31], v[194:197], v[226:229], v[28:31]
	v_mfma_f32_16x16x32_bf16 v[24:27], v[202:205], v[226:229], v[24:27]
	v_mfma_f32_16x16x32_bf16 v[4:7], v[194:197], v[234:237], v[4:7]
	v_mfma_f32_16x16x32_bf16 v[0:3], v[202:205], v[234:237], v[0:3]
	v_mfma_f32_16x16x32_bf16 v[16:19], v[194:197], v[210:213], v[16:19]
	v_mfma_f32_16x16x32_bf16 v[20:23], v[202:205], v[210:213], v[20:23]
	v_mfma_f32_16x16x32_bf16 v[32:35], v[194:197], v[218:221], v[32:35]
	v_mfma_f32_16x16x32_bf16 v[36:39], v[202:205], v[218:221], v[36:39]
	s_setprio 0
	s_barrier
	s_add_i32 s50, 0, 0x18000
	s_add_i32 s51, 0, 0x1c000
	v_add_u32_e32 v68, s50, v171
	v_add_u32_e32 v152, s51, v171
	ds_read_b128 v[48:51], v68
	ds_read_b128 v[52:55], v68 offset:1024
	ds_read_b128 v[64:67], v68 offset:2048
	ds_read_b128 v[68:71], v68 offset:3072
	ds_read_b128 v[184:187], v152
	ds_read_b128 v[194:197], v152 offset:1024
	ds_read_b128 v[198:201], v152 offset:2048
	ds_read_b128 v[202:205], v152 offset:3072
	s_add_u32 s14, s14, 0x40000
	s_addc_u32 s15, s15, 0
	s_mov_b32 m0, s59
	ds_read_b128 v[206:209], v191 offset:32768
	ds_read_b128 v[210:213], v191 offset:33792
	ds_read_b128 v[214:217], v191 offset:34816
	ds_read_b128 v[218:221], v191 offset:35840
	ds_read_b128 v[222:225], v191 offset:36864
	ds_read_b128 v[226:229], v191 offset:37888
	ds_read_b128 v[230:233], v191 offset:38912
	ds_read_b128 v[234:237], v191 offset:39936
	global_load_lds_dwordx4 v144, s[14:15]
	s_mov_b32 m0, s60
	s_nop 0
	global_load_lds_dwordx4 v148, s[14:15]
	s_waitcnt vmcnt(8)
	s_waitcnt lgkmcnt(0)
	s_barrier
; #define PG8_STAGE(bufoff, gbase, voff) do { _Pragma("unroll") for (int _i = 0; _i < 2; ++_i) \
;         __builtin_amdgcn_global_load_lds((const unsigned*)((const char*)(gbase) + (voff)[_i]), (LAS unsigned*)(lds + (bufoff) + ldsw + _i * 8192), 16, 0, 0); } while (0)
; #define PG8_LDA(dst, b, h) do { _Pragma("unroll") for (int m = 0; m < 4; ++m) _Pragma("unroll") for (int k = 0; k < 2; ++k) dst[m][k] = *(const LAS bf16x8*)(lds + PG8_SA(b, h) + aoff + m * 2048 + k * 1024); } while (0)
; #define PG8_MMA(ai, bj, At, Bt) do { __builtin_amdgcn_s_setprio(1); _Pragma("unroll") for (int m = 0; m < 4; ++m) _Pragma("unroll") for (int n = 0; n < 2; ++n) _Pragma("unroll") for (int k = 0; k < 2; ++k) \
;         acc[ai][bj][m][n] = __builtin_amdgcn_mfma_f32_16x16x32_bf16(Bt[n][k], At[m][k], acc[ai][bj][m][n], 0, 0, 0); __builtin_amdgcn_s_setprio(0); } while (0)
; #define PG8_WAIT_V(n) asm volatile("s_waitcnt vmcnt(" #n ")" ::: "memory")
; #define PG8_WAIT_L(n) asm volatile("s_waitcnt lgkmcnt(" #n ")" ::: "memory")
; #define PG8_BAR __builtin_amdgcn_s_barrier()
; #define PG8_SCHED __builtin_amdgcn_sched_barrier(0)
; template <class Epi, class Sched>
; __device__ __forceinline__ void gemm_phase(LAS unsigned char* lds, const Gemm g, const Sched& S, const Epi& E, int wave_id) {
;     ...
;             PG8_LDA(At, 1, 1); PG8_STAGE(PG8_SB(1, 0), b3, voffB); PG8_STAGE(PG8_SB(1, 1), b3 + hstepB, voffB); PG8_STAGE(PG8_SA(1, 0), a3, voffA);
;             PG8_WAIT_V(8); PG8_WAIT_L(0); PG8_BAR; PG8_MMA(1, 0, At, B0); PG8_MMA(1, 1, At, B1); PG8_BAR; PG8_SCHED;
;         }
;         if (wr == 0) PG8_BAR;
	s_setprio 1
	s_waitcnt lgkmcnt(0)
	v_mfma_f32_16x16x32_bf16 v[140:143], v[48:51], v[206:209], v[140:143]
	v_mfma_f32_16x16x32_bf16 v[136:139], v[64:67], v[206:209], v[136:139]
	v_mfma_f32_16x16x32_bf16 v[124:127], v[48:51], v[214:217], v[124:127]
	v_mfma_f32_16x16x32_bf16 v[120:123], v[64:67], v[214:217], v[120:123]
	v_mfma_f32_16x16x32_bf16 v[108:111], v[48:51], v[222:225], v[108:111]
	v_mfma_f32_16x16x32_bf16 v[104:107], v[64:67], v[222:225], v[104:107]
	v_mfma_f32_16x16x32_bf16 v[92:95], v[48:51], v[230:233], v[92:95]
	v_mfma_f32_16x16x32_bf16 v[88:91], v[64:67], v[230:233], v[88:91]
	v_mfma_f32_16x16x32_bf16 v[140:143], v[52:55], v[210:213], v[140:143]
	v_mfma_f32_16x16x32_bf16 v[136:139], v[68:71], v[210:213], v[136:139]
	v_mfma_f32_16x16x32_bf16 v[124:127], v[52:55], v[218:221], v[124:127]
	v_mfma_f32_16x16x32_bf16 v[120:123], v[68:71], v[218:221], v[120:123]
	v_mfma_f32_16x16x32_bf16 v[108:111], v[52:55], v[226:229], v[108:111]
	v_mfma_f32_16x16x32_bf16 v[104:107], v[68:71], v[226:229], v[104:107]
	v_mfma_f32_16x16x32_bf16 v[92:95], v[52:55], v[234:237], v[92:95]
	v_mfma_f32_16x16x32_bf16 v[88:91], v[68:71], v[234:237], v[88:91]
	s_setprio 0
	s_setprio 1
	v_mfma_f32_16x16x32_bf16 v[132:135], v[184:187], v[206:209], v[132:135]
	v_mfma_f32_16x16x32_bf16 v[128:131], v[198:201], v[206:209], v[128:131]
	v_mfma_f32_16x16x32_bf16 v[116:119], v[184:187], v[214:217], v[116:119]
	v_mfma_f32_16x16x32_bf16 v[112:115], v[198:201], v[214:217], v[112:115]
	v_mfma_f32_16x16x32_bf16 v[100:103], v[184:187], v[222:225], v[100:103]
	v_mfma_f32_16x16x32_bf16 v[96:99], v[198:201], v[222:225], v[96:99]
	v_mfma_f32_16x16x32_bf16 v[84:87], v[184:187], v[230:233], v[84:87]
	v_mfma_f32_16x16x32_bf16 v[80:83], v[198:201], v[230:233], v[80:83]
	v_mfma_f32_16x16x32_bf16 v[132:135], v[194:197], v[210:213], v[132:135]
	v_mfma_f32_16x16x32_bf16 v[128:131], v[202:205], v[210:213], v[128:131]
	v_mfma_f32_16x16x32_bf16 v[116:119], v[194:197], v[218:221], v[116:119]
	v_mfma_f32_16x16x32_bf16 v[112:115], v[202:205], v[218:221], v[112:115]
	v_mfma_f32_16x16x32_bf16 v[100:103], v[194:197], v[226:229], v[100:103]
	v_mfma_f32_16x16x32_bf16 v[96:99], v[202:205], v[226:229], v[96:99]
	v_mfma_f32_16x16x32_bf16 v[84:87], v[194:197], v[234:237], v[84:87]
	v_mfma_f32_16x16x32_bf16 v[80:83], v[202:205], v[234:237], v[80:83]
	s_setprio 0
	s_barrier
	s_add_i32 s14, s50, s54
	s_mov_b32 m0, s14
	ds_read_b128 v[206:209], v191 offset:49152
	ds_read_b128 v[210:213], v191 offset:50176
	ds_read_b128 v[214:217], v191 offset:51200
	ds_read_b128 v[218:221], v191 offset:52224
	ds_read_b128 v[222:225], v191 offset:53248
	ds_read_b128 v[226:229], v191 offset:54272
	ds_read_b128 v[230:233], v191 offset:55296
	ds_read_b128 v[234:237], v191 offset:56320
	global_load_lds_dwordx4 v146, s[74:75]
	s_add_i32 m0, s14, 0x2000
	s_add_u32 s12, s12, 0x40080
	s_addc_u32 s13, s13, 0
	s_add_i32 s14, s51, s54
	global_load_lds_dwordx4 v150, s[74:75]
	s_mov_b32 m0, s14
	s_nop 0
	global_load_lds_dwordx4 v146, s[12:13]
	s_add_i32 m0, s14, 0x2000
	s_nop 0
	global_load_lds_dwordx4 v150, s[12:13]
	s_mov_b32 m0, s62
	s_nop 0
	global_load_lds_dwordx4 v144, s[98:99]
	s_mov_b32 m0, s63
	s_nop 0
	global_load_lds_dwordx4 v148, s[98:99]
	s_waitcnt vmcnt(8)
	s_waitcnt lgkmcnt(0)
	s_barrier
	s_setprio 1
	s_waitcnt lgkmcnt(0)
	v_mfma_f32_16x16x32_bf16 v[76:79], v[48:51], v[206:209], v[76:79]
	v_mfma_f32_16x16x32_bf16 v[72:75], v[64:67], v[206:209], v[72:75]
	v_mfma_f32_16x16x32_bf16 v[60:63], v[48:51], v[214:217], v[60:63]
	v_mfma_f32_16x16x32_bf16 v[56:59], v[64:67], v[214:217], v[56:59]
	v_mfma_f32_16x16x32_bf16 v[44:47], v[48:51], v[222:225], v[44:47]
	v_mfma_f32_16x16x32_bf16 v[40:43], v[64:67], v[222:225], v[40:43]
	v_mfma_f32_16x16x32_bf16 v[12:15], v[48:51], v[230:233], v[12:15]
	v_mfma_f32_16x16x32_bf16 v[8:11], v[64:67], v[230:233], v[8:11]
	v_mfma_f32_16x16x32_bf16 v[76:79], v[52:55], v[210:213], v[76:79]
	v_mfma_f32_16x16x32_bf16 v[72:75], v[68:71], v[210:213], v[72:75]
	v_mfma_f32_16x16x32_bf16 v[60:63], v[52:55], v[218:221], v[60:63]
	v_mfma_f32_16x16x32_bf16 v[56:59], v[68:71], v[218:221], v[56:59]
	v_mfma_f32_16x16x32_bf16 v[44:47], v[52:55], v[226:229], v[44:47]
	v_mfma_f32_16x16x32_bf16 v[40:43], v[68:71], v[226:229], v[40:43]
	v_mfma_f32_16x16x32_bf16 v[12:15], v[52:55], v[234:237], v[12:15]
	v_mfma_f32_16x16x32_bf16 v[8:11], v[68:71], v[234:237], v[8:11]
	s_setprio 0
	s_setprio 1
	v_mfma_f32_16x16x32_bf16 v[16:19], v[184:187], v[206:209], v[16:19]
	v_mfma_f32_16x16x32_bf16 v[68:71], v[194:197], v[210:213], v[16:19]
	v_mfma_f32_16x16x32_bf16 v[16:19], v[198:201], v[206:209], v[20:23]
	v_mfma_f32_16x16x32_bf16 v[64:67], v[202:205], v[210:213], v[16:19]
	v_mfma_f32_16x16x32_bf16 v[16:19], v[184:187], v[214:217], v[32:35]
	v_mfma_f32_16x16x32_bf16 v[52:55], v[194:197], v[218:221], v[16:19]
	v_mfma_f32_16x16x32_bf16 v[16:19], v[198:201], v[214:217], v[36:39]
	v_mfma_f32_16x16x32_bf16 v[48:51], v[202:205], v[218:221], v[16:19]
	v_mfma_f32_16x16x32_bf16 v[16:19], v[184:187], v[222:225], v[28:31]
	v_mfma_f32_16x16x32_bf16 v[28:31], v[194:197], v[226:229], v[16:19]
	v_mfma_f32_16x16x32_bf16 v[16:19], v[198:201], v[222:225], v[24:27]
	v_mfma_f32_16x16x32_bf16 v[4:7], v[184:187], v[230:233], v[4:7]
	v_mfma_f32_16x16x32_bf16 v[0:3], v[198:201], v[230:233], v[0:3]
	v_mfma_f32_16x16x32_bf16 v[24:27], v[202:205], v[226:229], v[16:19]
	v_mfma_f32_16x16x32_bf16 v[4:7], v[194:197], v[234:237], v[4:7]
	v_mfma_f32_16x16x32_bf16 v[0:3], v[202:205], v[234:237], v[0:3]
	s_setprio 0
	s_barrier
	s_add_i32 s45, s45, 2
	s_add_u32 s10, s10, 0x100
	s_addc_u32 s11, s11, 0
	s_add_u32 s33, s33, 0x100
	s_addc_u32 s39, s39, 0
	s_cmp_gt_u32 s45, 13
	s_cbranch_scc0 .LBB0_252
	s_and_b64 vcc, exec, s[24:25]
	s_cbranch_vccz .LBB0_255
	s_barrier

;     __device__ bool next(int i, Unit& u) const { if (r0 + i >= r1) return false; return base.next(r0 + i, u); }
;     __device__ bool next(int i, Unit& u) const { const int L = i * G + c; if (L >= 256) return false; u.pm = L; u.pn = L >> 3; return true; }
; #define PG8_STAGE(bufoff, gbase, voff) do { _Pragma("unroll") for (int _i = 0; _i < 2; ++_i) \
;         __builtin_amdgcn_global_load_lds((const unsigned*)((const char*)(gbase) + (voff)[_i]), (LAS unsigned*)(lds + (bufoff) + ldsw + _i * 8192), 16, 0, 0); } while (0)
; #define PG8_LDA(dst, b, h) do { _Pragma("unroll") for (int m = 0; m < 4; ++m) _Pragma("unroll") for (int k = 0; k < 2; ++k) dst[m][k] = *(const LAS bf16x8*)(lds + PG8_SA(b, h) + aoff + m * 2048 + k * 1024); } while (0)
; #define PG8_LDB(dst, b, h) do { _Pragma("unroll") for (int n = 0; n < 2; ++n) _Pragma("unroll") for (int k = 0; k < 2; ++k) dst[n][k] = *(const LAS bf16x8*)(lds + PG8_SB(b, h) + boff + n * 2048 + k * 1024); } while (0)
; #define PG8_WAIT_V(n) asm volatile("s_waitcnt vmcnt(" #n ")" ::: "memory")
; #define PG8_WAIT_L(n) asm volatile("s_waitcnt lgkmcnt(" #n ")" ::: "memory")
; template <class Epi, class Sched>
; __device__ __forceinline__ void gemm_phase(LAS unsigned char* lds, const Gemm g, const Sched& S, const Epi& E, int wave_id) {
;     ...
;         const bool has_next = S.next(ui + 1, nxt);
;         const char* nA = has_next ? (const char*)g.A + (size_t)nxt.pm * tstepA : cA; const char* nB = has_next ? (const char*)g.Bt + (size_t)nxt.pn * tstepB : cB;
;         for (int t = 0; t < nt; t += 2) {
;             const bool last = (t == nt - 2);
;             const char* a1 = cA + (size_t)(t + 1) * kstep;
;             const char* a2 = last ? nA : cA + (size_t)(t + 2) * kstep; const char* b2 = last ? nB : cB + (size_t)(t + 2) * kstep;
;             const char* a3 = a2 + kstep; const char* b3 = b2 + kstep;
;             PG8_LDB(B0, 0, 0); PG8_LDB(B1, 0, 1); PG8_SCHED; PG8_LDA(At, 0, 0); PG8_STAGE(PG8_SA(1, 1), a1 + hstepA, voffA);
;             PG8_WAIT_V(8); PG8_WAIT_L(0); PG8_BAR; PG8_MMA(0, 0, At, B0); PG8_MMA(0, 1, At, B1); PG8_BAR; PG8_SCHED;
;             PG8_LDA(At, 0, 1); PG8_STAGE(PG8_SB(0, 0), b2, voffB); PG8_STAGE(PG8_SB(0, 1), b2 + hstepB, voffB); PG8_STAGE(PG8_SA(0, 0), a2, voffA);
;             PG8_WAIT_V(8); PG8_WAIT_L(0); PG8_BAR; PG8_MMA(1, 0, At, B0); PG8_MMA(1, 1, At, B1); PG8_BAR; PG8_SCHED;
.LBB0_672:
	s_ashr_i32 s23, s22, 31
	s_lshl_b64 s[26:27], s[22:23], 19
	s_add_u32 s26, s15, s26
	s_addc_u32 s27, s33, s27
	s_and_b64 s[28:29], s[24:25], exec
	s_cselect_b32 s23, s27, s35
	s_cselect_b32 s61, s26, s34
	s_ashr_i32 s17, s16, 31
	s_lshl_b64 s[28:29], s[16:17], 19
	s_add_u32 s28, s44, s28
	s_addc_u32 s29, s45, s29
	s_and_b64 s[38:39], s[24:25], exec
	s_cselect_b32 s17, s29, s37
	s_cselect_b32 s62, s28, s36
	s_add_u32 s34, s34, 0x40080
	s_addc_u32 s35, s35, 0
	s_add_u32 s63, s36, 0x100
	s_addc_u32 s64, s37, 0
	s_mov_b32 s65, -2
	ds_read_b128 v[142:145], v161
	ds_read_b128 v[146:149], v161 offset:1024
	ds_read_b128 v[150:153], v161 offset:2048
	ds_read_b128 v[154:157], v161 offset:3072
	ds_read_b128 v[164:167], v162
	ds_read_b128 v[168:171], v162 offset:1024
	ds_read_b128 v[172:175], v162 offset:2048
	ds_read_b128 v[176:179], v162 offset:3072
	s_add_u32 s36, s34, 0xfffc0080
	s_addc_u32 s37, s35, -1
	s_cmp_eq_u32 s65, 12
	s_cselect_b32 s39, s23, s37
	s_cselect_b32 s38, s61, s36
	s_cselect_b32 s37, s17, s64
	s_cselect_b32 s36, s62, s63
	s_add_u32 s78, s38, 0x80
	s_addc_u32 s79, s39, 0
	s_add_u32 s74, s36, 0x80
	s_addc_u32 s75, s37, 0
	s_add_i32 m0, s31, 0xc000
	ds_read_b128 v[180:183], v163
	ds_read_b128 v[184:187], v163 offset:1024
	ds_read_b128 v[188:191], v163 offset:2048
	ds_read_b128 v[192:195], v163 offset:3072
	ds_read_b128 v[196:199], v163 offset:4096
	ds_read_b128 v[200:203], v163 offset:5120
	ds_read_b128 v[204:207], v163 offset:6144
	ds_read_b128 v[208:211], v163 offset:7168
	global_load_lds_dwordx4 v136, s[34:35]
	s_add_i32 m0, s31, 0xe000
	s_nop 0
	global_load_lds_dwordx4 v138, s[34:35]
	s_waitcnt vmcnt(8)
	s_waitcnt lgkmcnt(0)
	s_barrier
	s_setprio 1
	s_waitcnt lgkmcnt(0)
	v_mfma_f32_16x16x32_bf16 v[124:127], v[142:145], v[180:183], 0
	v_mfma_f32_16x16x32_bf16 v[120:123], v[150:153], v[180:183], 0
	v_mfma_f32_16x16x32_bf16 v[108:111], v[142:145], v[188:191], 0
	v_mfma_f32_16x16x32_bf16 v[104:107], v[150:153], v[188:191], 0
	v_mfma_f32_16x16x32_bf16 v[92:95], v[142:145], v[196:199], 0
	v_mfma_f32_16x16x32_bf16 v[88:91], v[150:153], v[196:199], 0
	v_mfma_f32_16x16x32_bf16 v[76:79], v[142:145], v[204:207], 0
	v_mfma_f32_16x16x32_bf16 v[72:75], v[150:153], v[204:207], 0
	v_mfma_f32_16x16x32_bf16 v[124:127], v[146:149], v[184:187], v[124:127]
	v_mfma_f32_16x16x32_bf16 v[120:123], v[154:157], v[184:187], v[120:123]
	v_mfma_f32_16x16x32_bf16 v[108:111], v[146:149], v[192:195], v[108:111]
	v_mfma_f32_16x16x32_bf16 v[104:107], v[154:157], v[192:195], v[104:107]
	v_mfma_f32_16x16x32_bf16 v[92:95], v[146:149], v[200:203], v[92:95]
	v_mfma_f32_16x16x32_bf16 v[88:91], v[154:157], v[200:203], v[88:91]
	v_mfma_f32_16x16x32_bf16 v[76:79], v[146:149], v[208:211], v[76:79]
	v_mfma_f32_16x16x32_bf16 v[72:75], v[154:157], v[208:211], v[72:75]
	s_setprio 0
	s_setprio 1
	v_mfma_f32_16x16x32_bf16 v[116:119], v[164:167], v[180:183], 0
	v_mfma_f32_16x16x32_bf16 v[112:115], v[172:175], v[180:183], 0
	v_mfma_f32_16x16x32_bf16 v[100:103], v[164:167], v[188:191], 0
	v_mfma_f32_16x16x32_bf16 v[96:99], v[172:175], v[188:191], 0
	v_mfma_f32_16x16x32_bf16 v[84:87], v[164:167], v[196:199], 0
	v_mfma_f32_16x16x32_bf16 v[80:83], v[172:175], v[196:199], 0
	v_mfma_f32_16x16x32_bf16 v[68:71], v[164:167], v[204:207], 0
	v_mfma_f32_16x16x32_bf16 v[64:67], v[172:175], v[204:207], 0
	v_mfma_f32_16x16x32_bf16 v[116:119], v[168:171], v[184:187], v[116:119]
	v_mfma_f32_16x16x32_bf16 v[112:115], v[176:179], v[184:187], v[112:115]
	v_mfma_f32_16x16x32_bf16 v[100:103], v[168:171], v[192:195], v[100:103]
	v_mfma_f32_16x16x32_bf16 v[96:99], v[176:179], v[192:195], v[96:99]
	v_mfma_f32_16x16x32_bf16 v[84:87], v[168:171], v[200:203], v[84:87]
	v_mfma_f32_16x16x32_bf16 v[80:83], v[176:179], v[200:203], v[80:83]
	v_mfma_f32_16x16x32_bf16 v[68:71], v[168:171], v[208:211], v[68:71]
	v_mfma_f32_16x16x32_bf16 v[64:67], v[176:179], v[208:211], v[64:67]
	s_setprio 0
	s_barrier
	s_add_i32 s66, s55, s46
	s_mov_b32 m0, s66
	ds_read_b128 v[180:183], v163 offset:16384
	ds_read_b128 v[184:187], v163 offset:17408
	ds_read_b128 v[188:191], v163 offset:18432
	ds_read_b128 v[192:195], v163 offset:19456
	ds_read_b128 v[196:199], v163 offset:20480
	ds_read_b128 v[200:203], v163 offset:21504
	ds_read_b128 v[204:207], v163 offset:22528
	ds_read_b128 v[208:211], v163 offset:23552
	global_load_lds_dwordx4 v130, s[36:37]
	s_add_i32 m0, s66, 0x2000
	s_add_u32 s66, s36, 0x40000
	s_addc_u32 s67, s37, 0
	s_add_i32 s72, s58, s46
	global_load_lds_dwordx4 v134, s[36:37]
	s_mov_b32 m0, s72
	s_nop 0
	global_load_lds_dwordx4 v130, s[66:67]
	s_add_i32 m0, s72, 0x2000
	s_nop 0
	global_load_lds_dwordx4 v134, s[66:67]
	s_mov_b32 m0, s31
	s_nop 0
	global_load_lds_dwordx4 v128, s[38:39]
	s_mov_b32 m0, s47
	s_nop 0
	global_load_lds_dwordx4 v132, s[38:39]
	s_waitcnt vmcnt(8)
	s_waitcnt lgkmcnt(0)
	s_barrier
; #define PG8_STAGE(bufoff, gbase, voff) do { _Pragma("unroll") for (int _i = 0; _i < 2; ++_i) \
;         __builtin_amdgcn_global_load_lds((const unsigned*)((const char*)(gbase) + (voff)[_i]), (LAS unsigned*)(lds + (bufoff) + ldsw + _i * 8192), 16, 0, 0); } while (0)
; #define PG8_LDA(dst, b, h) do { _Pragma("unroll") for (int m = 0; m < 4; ++m) _Pragma("unroll") for (int k = 0; k < 2; ++k) dst[m][k] = *(const LAS bf16x8*)(lds + PG8_SA(b, h) + aoff + m * 2048 + k * 1024); } while (0)
; #define PG8_LDB(dst, b, h) do { _Pragma("unroll") for (int n = 0; n < 2; ++n) _Pragma("unroll") for (int k = 0; k < 2; ++k) dst[n][k] = *(const LAS bf16x8*)(lds + PG8_SB(b, h) + boff + n * 2048 + k * 1024); } while (0)
; #define PG8_MMA(ai, bj, At, Bt) do { __builtin_amdgcn_s_setprio(1); _Pragma("unroll") for (int m = 0; m < 4; ++m) _Pragma("unroll") for (int n = 0; n < 2; ++n) _Pragma("unroll") for (int k = 0; k < 2; ++k) \
;         acc[ai][bj][m][n] = __builtin_amdgcn_mfma_f32_16x16x32_bf16(Bt[n][k], At[m][k], acc[ai][bj][m][n], 0, 0, 0); __builtin_amdgcn_s_setprio(0); } while (0)
; #define PG8_WAIT_V(n) asm volatile("s_waitcnt vmcnt(" #n ")" ::: "memory")
; #define PG8_WAIT_L(n) asm volatile("s_waitcnt lgkmcnt(" #n ")" ::: "memory")
; #define PG8_BAR __builtin_amdgcn_s_barrier()
; #define PG8_SCHED __builtin_amdgcn_sched_barrier(0)
; template <class Epi, class Sched>
; __device__ __forceinline__ void gemm_phase(LAS unsigned char* lds, const Gemm g, const Sched& S, const Epi& E, int wave_id) {
;     ...
;             PG8_LDB(B0, 1, 0); PG8_LDB(B1, 1, 1); PG8_SCHED; PG8_LDA(At, 1, 0); PG8_STAGE(PG8_SA(0, 1), a2 + hstepA, voffA);
;             PG8_WAIT_V(8); PG8_WAIT_L(0); PG8_BAR; PG8_MMA(0, 0, At, B0); PG8_MMA(0, 1, At, B1); PG8_BAR; PG8_SCHED;
	s_setprio 1
	s_waitcnt lgkmcnt(0)
	v_mfma_f32_16x16x32_bf16 v[60:63], v[142:145], v[180:183], 0
	v_mfma_f32_16x16x32_bf16 v[56:59], v[150:153], v[180:183], 0
	v_mfma_f32_16x16x32_bf16 v[44:47], v[142:145], v[188:191], 0
	v_mfma_f32_16x16x32_bf16 v[40:43], v[150:153], v[188:191], 0
	v_mfma_f32_16x16x32_bf16 v[28:31], v[142:145], v[196:199], 0
	v_mfma_f32_16x16x32_bf16 v[24:27], v[150:153], v[196:199], 0
	v_mfma_f32_16x16x32_bf16 v[12:15], v[142:145], v[204:207], 0
	v_mfma_f32_16x16x32_bf16 v[8:11], v[150:153], v[204:207], 0
	v_mfma_f32_16x16x32_bf16 v[60:63], v[146:149], v[184:187], v[60:63]
	v_mfma_f32_16x16x32_bf16 v[56:59], v[154:157], v[184:187], v[56:59]
	v_mfma_f32_16x16x32_bf16 v[44:47], v[146:149], v[192:195], v[44:47]
	v_mfma_f32_16x16x32_bf16 v[40:43], v[154:157], v[192:195], v[40:43]
	v_mfma_f32_16x16x32_bf16 v[28:31], v[146:149], v[200:203], v[28:31]
	v_mfma_f32_16x16x32_bf16 v[24:27], v[154:157], v[200:203], v[24:27]
	v_mfma_f32_16x16x32_bf16 v[12:15], v[146:149], v[208:211], v[12:15]
	v_mfma_f32_16x16x32_bf16 v[8:11], v[154:157], v[208:211], v[8:11]
	s_setprio 0
	s_setprio 1
	v_mfma_f32_16x16x32_bf16 v[52:55], v[164:167], v[180:183], 0
	v_mfma_f32_16x16x32_bf16 v[48:51], v[172:175], v[180:183], 0
	v_mfma_f32_16x16x32_bf16 v[36:39], v[164:167], v[188:191], 0
	v_mfma_f32_16x16x32_bf16 v[32:35], v[172:175], v[188:191], 0
	v_mfma_f32_16x16x32_bf16 v[20:23], v[164:167], v[196:199], 0
	v_mfma_f32_16x16x32_bf16 v[16:19], v[172:175], v[196:199], 0
	v_mfma_f32_16x16x32_bf16 v[4:7], v[164:167], v[204:207], 0
	v_mfma_f32_16x16x32_bf16 v[0:3], v[172:175], v[204:207], 0
	v_mfma_f32_16x16x32_bf16 v[52:55], v[168:171], v[184:187], v[52:55]
	v_mfma_f32_16x16x32_bf16 v[48:51], v[176:179], v[184:187], v[48:51]
	v_mfma_f32_16x16x32_bf16 v[36:39], v[168:171], v[192:195], v[36:39]
	v_mfma_f32_16x16x32_bf16 v[32:35], v[176:179], v[192:195], v[32:35]
	v_mfma_f32_16x16x32_bf16 v[20:23], v[168:171], v[200:203], v[20:23]
	v_mfma_f32_16x16x32_bf16 v[16:19], v[176:179], v[200:203], v[16:19]
	v_mfma_f32_16x16x32_bf16 v[4:7], v[168:171], v[208:211], v[4:7]
	v_mfma_f32_16x16x32_bf16 v[0:3], v[176:179], v[208:211], v[0:3]
	s_setprio 0
	s_barrier
	s_add_i32 s66, 0, 0x18000
	s_add_i32 s67, 0, 0x1c000
	v_add_u32_e32 v154, s66, v159
	v_add_u32_e32 v176, s67, v159
	ds_read_b128 v[142:145], v154
	ds_read_b128 v[146:149], v154 offset:1024
	ds_read_b128 v[150:153], v154 offset:2048
	ds_read_b128 v[154:157], v154 offset:3072
	ds_read_b128 v[164:167], v176
	ds_read_b128 v[168:171], v176 offset:1024
	ds_read_b128 v[172:175], v176 offset:2048
	ds_read_b128 v[176:179], v176 offset:3072
	s_add_u32 s38, s38, 0x40000
	s_addc_u32 s39, s39, 0
	s_mov_b32 m0, s48
	ds_read_b128 v[180:183], v163 offset:32768
	ds_read_b128 v[184:187], v163 offset:33792
	ds_read_b128 v[188:191], v163 offset:34816
	ds_read_b128 v[192:195], v163 offset:35840
	ds_read_b128 v[196:199], v163 offset:36864
	ds_read_b128 v[200:203], v163 offset:37888
	ds_read_b128 v[204:207], v163 offset:38912
	ds_read_b128 v[208:211], v163 offset:39936
	global_load_lds_dwordx4 v128, s[38:39]
	s_mov_b32 m0, s49
	s_nop 0
	global_load_lds_dwordx4 v132, s[38:39]
	s_waitcnt vmcnt(8)
	s_waitcnt lgkmcnt(0)
	s_barrier
	s_setprio 1
	s_waitcnt lgkmcnt(0)
	v_mfma_f32_16x16x32_bf16 v[124:127], v[142:145], v[180:183], v[124:127]
	v_mfma_f32_16x16x32_bf16 v[120:123], v[150:153], v[180:183], v[120:123]
	v_mfma_f32_16x16x32_bf16 v[108:111], v[142:145], v[188:191], v[108:111]
	v_mfma_f32_16x16x32_bf16 v[104:107], v[150:153], v[188:191], v[104:107]
	v_mfma_f32_16x16x32_bf16 v[92:95], v[142:145], v[196:199], v[92:95]
	v_mfma_f32_16x16x32_bf16 v[88:91], v[150:153], v[196:199], v[88:91]
	v_mfma_f32_16x16x32_bf16 v[76:79], v[142:145], v[204:207], v[76:79]
	v_mfma_f32_16x16x32_bf16 v[72:75], v[150:153], v[204:207], v[72:75]
	v_mfma_f32_16x16x32_bf16 v[124:127], v[146:149], v[184:187], v[124:127]
	v_mfma_f32_16x16x32_bf16 v[120:123], v[154:157], v[184:187], v[120:123]
	v_mfma_f32_16x16x32_bf16 v[108:111], v[146:149], v[192:195], v[108:111]
	v_mfma_f32_16x16x32_bf16 v[104:107], v[154:157], v[192:195], v[104:107]
	v_mfma_f32_16x16x32_bf16 v[92:95], v[146:149], v[200:203], v[92:95]
	v_mfma_f32_16x16x32_bf16 v[88:91], v[154:157], v[200:203], v[88:91]
	v_mfma_f32_16x16x32_bf16 v[76:79], v[146:149], v[208:211], v[76:79]
	v_mfma_f32_16x16x32_bf16 v[72:75], v[154:157], v[208:211], v[72:75]
	s_setprio 0
	s_setprio 1
	v_mfma_f32_16x16x32_bf16 v[116:119], v[164:167], v[180:183], v[116:119]
	v_mfma_f32_16x16x32_bf16 v[112:115], v[172:175], v[180:183], v[112:115]
	v_mfma_f32_16x16x32_bf16 v[100:103], v[164:167], v[188:191], v[100:103]
	v_mfma_f32_16x16x32_bf16 v[96:99], v[172:175], v[188:191], v[96:99]
	v_mfma_f32_16x16x32_bf16 v[84:87], v[164:167], v[196:199], v[84:87]
	v_mfma_f32_16x16x32_bf16 v[80:83], v[172:175], v[196:199], v[80:83]
	v_mfma_f32_16x16x32_bf16 v[68:71], v[164:167], v[204:207], v[68:71]
	v_mfma_f32_16x16x32_bf16 v[64:67], v[172:175], v[204:207], v[64:67]
	v_mfma_f32_16x16x32_bf16 v[116:119], v[168:171], v[184:187], v[116:119]
	v_mfma_f32_16x16x32_bf16 v[112:115], v[176:179], v[184:187], v[112:115]
	v_mfma_f32_16x16x32_bf16 v[100:103], v[168:171], v[192:195], v[100:103]
	v_mfma_f32_16x16x32_bf16 v[96:99], v[176:179], v[192:195], v[96:99]
	v_mfma_f32_16x16x32_bf16 v[84:87], v[168:171], v[200:203], v[84:87]
	v_mfma_f32_16x16x32_bf16 v[80:83], v[176:179], v[200:203], v[80:83]
	v_mfma_f32_16x16x32_bf16 v[68:71], v[168:171], v[208:211], v[68:71]
	v_mfma_f32_16x16x32_bf16 v[64:67], v[176:179], v[208:211], v[64:67]
	s_setprio 0
	s_barrier
; #define PG8_STAGE(bufoff, gbase, voff) do { _Pragma("unroll") for (int _i = 0; _i < 2; ++_i) \
;         __builtin_amdgcn_global_load_lds((const unsigned*)((const char*)(gbase) + (voff)[_i]), (LAS unsigned*)(lds + (bufoff) + ldsw + _i * 8192), 16, 0, 0); } while (0)
; #define PG8_LDA(dst, b, h) do { _Pragma("unroll") for (int m = 0; m < 4; ++m) _Pragma("unroll") for (int k = 0; k < 2; ++k) dst[m][k] = *(const LAS bf16x8*)(lds + PG8_SA(b, h) + aoff + m * 2048 + k * 1024); } while (0)
; #define PG8_LDB(dst, b, h) do { _Pragma("unroll") for (int n = 0; n < 2; ++n) _Pragma("unroll") for (int k = 0; k < 2; ++k) dst[n][k] = *(const LAS bf16x8*)(lds + PG8_SB(b, h) + boff + n * 2048 + k * 1024); } while (0)
; #define PG8_WAIT_V(n) asm volatile("s_waitcnt vmcnt(" #n ")" ::: "memory")
; #define PG8_BAR __builtin_amdgcn_s_barrier()
; template <class Epi, class Sched>
; __device__ __forceinline__ void gemm_phase(LAS unsigned char* lds, const Gemm g, const Sched& S, const Epi& E, int wave_id) {
;     ...
;         for (int t = 0; t < nt; t += 2) {
;             const bool last = (t == nt - 2);
;             const char* a1 = cA + (size_t)(t + 1) * kstep;
;             const char* a2 = last ? nA : cA + (size_t)(t + 2) * kstep; const char* b2 = last ? nB : cB + (size_t)(t + 2) * kstep;
;             const char* a3 = a2 + kstep; const char* b3 = b2 + kstep;
;             PG8_LDB(B0, 0, 0); PG8_LDB(B1, 0, 1); PG8_SCHED; PG8_LDA(At, 0, 0); PG8_STAGE(PG8_SA(1, 1), a1 + hstepA, voffA);
;             PG8_WAIT_V(8); PG8_WAIT_L(0); PG8_BAR; PG8_MMA(0, 0, At, B0); PG8_MMA(0, 1, At, B1); PG8_BAR; PG8_SCHED;
;             PG8_LDA(At, 0, 1); PG8_STAGE(PG8_SB(0, 0), b2, voffB); PG8_STAGE(PG8_SB(0, 1), b2 + hstepB, voffB); PG8_STAGE(PG8_SA(0, 0), a2, voffA);
;             PG8_WAIT_V(8); PG8_WAIT_L(0); PG8_BAR; PG8_MMA(1, 0, At, B0); PG8_MMA(1, 1, At, B1); PG8_BAR; PG8_SCHED;
;             PG8_LDB(B0, 1, 0); PG8_LDB(B1, 1, 1); PG8_SCHED; PG8_LDA(At, 1, 0); PG8_STAGE(PG8_SA(0, 1), a2 + hstepA, voffA);
;             PG8_WAIT_V(8); PG8_WAIT_L(0); PG8_BAR; PG8_MMA(0, 0, At, B0); PG8_MMA(0, 1, At, B1); PG8_BAR; PG8_SCHED;
;             PG8_LDA(At, 1, 1); PG8_STAGE(PG8_SB(1, 0), b3, voffB); PG8_STAGE(PG8_SB(1, 1), b3 + hstepB, voffB); PG8_STAGE(PG8_SA(1, 0), a3, voffA);
;             PG8_WAIT_V(8); PG8_WAIT_L(0); PG8_BAR; PG8_MMA(1, 0, At, B0); PG8_MMA(1, 1, At, B1); PG8_BAR; PG8_SCHED;
	s_add_i32 s38, s66, s46
	s_mov_b32 m0, s38
	ds_read_b128 v[180:183], v163 offset:49152
	ds_read_b128 v[184:187], v163 offset:50176
	ds_read_b128 v[188:191], v163 offset:51200
	ds_read_b128 v[192:195], v163 offset:52224
	ds_read_b128 v[196:199], v163 offset:53248
	ds_read_b128 v[200:203], v163 offset:54272
	ds_read_b128 v[204:207], v163 offset:55296
	ds_read_b128 v[208:211], v163 offset:56320
	global_load_lds_dwordx4 v130, s[74:75]
	s_add_i32 m0, s38, 0x2000
	s_add_u32 s36, s36, 0x40080
	s_addc_u32 s37, s37, 0
	s_add_i32 s38, s67, s46
	global_load_lds_dwordx4 v134, s[74:75]
	s_mov_b32 m0, s38
	s_nop 0
	global_load_lds_dwordx4 v130, s[36:37]
	s_add_i32 m0, s38, 0x2000
	s_nop 0
	global_load_lds_dwordx4 v134, s[36:37]
	s_mov_b32 m0, s52
	s_nop 0
	global_load_lds_dwordx4 v128, s[78:79]
	s_mov_b32 m0, s53
	s_nop 0
	global_load_lds_dwordx4 v132, s[78:79]
	s_waitcnt vmcnt(8)
	s_waitcnt lgkmcnt(0)
	s_barrier
	s_setprio 1
	s_waitcnt lgkmcnt(0)
	v_mfma_f32_16x16x32_bf16 v[60:63], v[142:145], v[180:183], v[60:63]
	v_mfma_f32_16x16x32_bf16 v[56:59], v[150:153], v[180:183], v[56:59]
	v_mfma_f32_16x16x32_bf16 v[44:47], v[142:145], v[188:191], v[44:47]
	v_mfma_f32_16x16x32_bf16 v[40:43], v[150:153], v[188:191], v[40:43]
	v_mfma_f32_16x16x32_bf16 v[28:31], v[142:145], v[196:199], v[28:31]
	v_mfma_f32_16x16x32_bf16 v[24:27], v[150:153], v[196:199], v[24:27]
	v_mfma_f32_16x16x32_bf16 v[12:15], v[142:145], v[204:207], v[12:15]
	v_mfma_f32_16x16x32_bf16 v[8:11], v[150:153], v[204:207], v[8:11]
	v_mfma_f32_16x16x32_bf16 v[60:63], v[146:149], v[184:187], v[60:63]
	v_mfma_f32_16x16x32_bf16 v[56:59], v[154:157], v[184:187], v[56:59]
	v_mfma_f32_16x16x32_bf16 v[44:47], v[146:149], v[192:195], v[44:47]
	v_mfma_f32_16x16x32_bf16 v[40:43], v[154:157], v[192:195], v[40:43]
	v_mfma_f32_16x16x32_bf16 v[28:31], v[146:149], v[200:203], v[28:31]
	v_mfma_f32_16x16x32_bf16 v[24:27], v[154:157], v[200:203], v[24:27]
	v_mfma_f32_16x16x32_bf16 v[12:15], v[146:149], v[208:211], v[12:15]
	v_mfma_f32_16x16x32_bf16 v[8:11], v[154:157], v[208:211], v[8:11]
	s_setprio 0
	s_setprio 1
	v_mfma_f32_16x16x32_bf16 v[52:55], v[164:167], v[180:183], v[52:55]
	v_mfma_f32_16x16x32_bf16 v[48:51], v[172:175], v[180:183], v[48:51]
	v_mfma_f32_16x16x32_bf16 v[36:39], v[164:167], v[188:191], v[36:39]
	v_mfma_f32_16x16x32_bf16 v[32:35], v[172:175], v[188:191], v[32:35]
	v_mfma_f32_16x16x32_bf16 v[20:23], v[164:167], v[196:199], v[20:23]
	v_mfma_f32_16x16x32_bf16 v[16:19], v[172:175], v[196:199], v[16:19]
	v_mfma_f32_16x16x32_bf16 v[4:7], v[164:167], v[204:207], v[4:7]
	v_mfma_f32_16x16x32_bf16 v[0:3], v[172:175], v[204:207], v[0:3]
	v_mfma_f32_16x16x32_bf16 v[52:55], v[168:171], v[184:187], v[52:55]
	v_mfma_f32_16x16x32_bf16 v[48:51], v[176:179], v[184:187], v[48:51]
	v_mfma_f32_16x16x32_bf16 v[36:39], v[168:171], v[192:195], v[36:39]
	v_mfma_f32_16x16x32_bf16 v[32:35], v[176:179], v[192:195], v[32:35]
	v_mfma_f32_16x16x32_bf16 v[20:23], v[168:171], v[200:203], v[20:23]
	v_mfma_f32_16x16x32_bf16 v[16:19], v[176:179], v[200:203], v[16:19]
	v_mfma_f32_16x16x32_bf16 v[4:7], v[168:171], v[208:211], v[4:7]
	v_mfma_f32_16x16x32_bf16 v[0:3], v[176:179], v[208:211], v[0:3]
	s_setprio 0
	s_barrier
	s_add_i32 s65, s65, 2
	s_add_u32 s34, s34, 0x100
	s_addc_u32 s35, s35, 0
	s_add_u32 s63, s63, 0x100
	s_addc_u32 s64, s64, 0
	s_cmp_gt_u32 s65, 13
.LBB0_673:
	ds_read_b128 v[142:145], v161
	ds_read_b128 v[146:149], v161 offset:1024
	ds_read_b128 v[150:153], v161 offset:2048
	ds_read_b128 v[154:157], v161 offset:3072
	ds_read_b128 v[164:167], v162
	ds_read_b128 v[168:171], v162 offset:1024
	ds_read_b128 v[172:175], v162 offset:2048
	ds_read_b128 v[176:179], v162 offset:3072
	s_add_u32 s36, s34, 0xfffc0080
	s_addc_u32 s37, s35, -1
	s_cmp_eq_u32 s65, 12
	s_cselect_b32 s39, s23, s37
	s_cselect_b32 s38, s61, s36
	s_cselect_b32 s37, s17, s64
	s_cselect_b32 s36, s62, s63
	s_add_u32 s78, s38, 0x80
	s_addc_u32 s79, s39, 0
	s_add_u32 s74, s36, 0x80
	s_addc_u32 s75, s37, 0
	s_add_i32 m0, s31, 0xc000
	ds_read_b128 v[180:183], v163
	ds_read_b128 v[184:187], v163 offset:1024
	ds_read_b128 v[188:191], v163 offset:2048
	ds_read_b128 v[192:195], v163 offset:3072
	ds_read_b128 v[196:199], v163 offset:4096
	ds_read_b128 v[200:203], v163 offset:5120
	ds_read_b128 v[204:207], v163 offset:6144
	ds_read_b128 v[208:211], v163 offset:7168
	global_load_lds_dwordx4 v136, s[34:35]
	s_add_i32 m0, s31, 0xe000
	s_nop 0
	global_load_lds_dwordx4 v138, s[34:35]
	s_waitcnt vmcnt(8)
	s_waitcnt lgkmcnt(0)
	s_barrier
; #define PG8_STAGE(bufoff, gbase, voff) do { _Pragma("unroll") for (int _i = 0; _i < 2; ++_i) \
;         __builtin_amdgcn_global_load_lds((const unsigned*)((const char*)(gbase) + (voff)[_i]), (LAS unsigned*)(lds + (bufoff) + ldsw + _i * 8192), 16, 0, 0); } while (0)
; #define PG8_LDA(dst, b, h) do { _Pragma("unroll") for (int m = 0; m < 4; ++m) _Pragma("unroll") for (int k = 0; k < 2; ++k) dst[m][k] = *(const LAS bf16x8*)(lds + PG8_SA(b, h) + aoff + m * 2048 + k * 1024); } while (0)
; #define PG8_LDB(dst, b, h) do { _Pragma("unroll") for (int n = 0; n < 2; ++n) _Pragma("unroll") for (int k = 0; k < 2; ++k) dst[n][k] = *(const LAS bf16x8*)(lds + PG8_SB(b, h) + boff + n * 2048 + k * 1024); } while (0)
; #define PG8_MMA(ai, bj, At, Bt) do { __builtin_amdgcn_s_setprio(1); _Pragma("unroll") for (int m = 0; m < 4; ++m) _Pragma("unroll") for (int n = 0; n < 2; ++n) _Pragma("unroll") for (int k = 0; k < 2; ++k) \
;         acc[ai][bj][m][n] = __builtin_amdgcn_mfma_f32_16x16x32_bf16(Bt[n][k], At[m][k], acc[ai][bj][m][n], 0, 0, 0); __builtin_amdgcn_s_setprio(0); } while (0)
; #define PG8_WAIT_V(n) asm volatile("s_waitcnt vmcnt(" #n ")" ::: "memory")
; #define PG8_WAIT_L(n) asm volatile("s_waitcnt lgkmcnt(" #n ")" ::: "memory")
; #define PG8_BAR __builtin_amdgcn_s_barrier()
; #define PG8_SCHED __builtin_amdgcn_sched_barrier(0)
; template <class Epi, class Sched>
; __device__ __forceinline__ void gemm_phase(LAS unsigned char* lds, const Gemm g, const Sched& S, const Epi& E, int wave_id) {
;     ...
;             PG8_WAIT_V(8); PG8_WAIT_L(0); PG8_BAR; PG8_MMA(0, 0, At, B0); PG8_MMA(0, 1, At, B1); PG8_BAR; PG8_SCHED;
;             PG8_LDA(At, 0, 1); PG8_STAGE(PG8_SB(0, 0), b2, voffB); PG8_STAGE(PG8_SB(0, 1), b2 + hstepB, voffB); PG8_STAGE(PG8_SA(0, 0), a2, voffA);
;             PG8_WAIT_V(8); PG8_WAIT_L(0); PG8_BAR; PG8_MMA(1, 0, At, B0); PG8_MMA(1, 1, At, B1); PG8_BAR; PG8_SCHED;
;             PG8_LDB(B0, 1, 0); PG8_LDB(B1, 1, 1); PG8_SCHED; PG8_LDA(At, 1, 0); PG8_STAGE(PG8_SA(0, 1), a2 + hstepA, voffA);
;             PG8_WAIT_V(8); PG8_WAIT_L(0); PG8_BAR; PG8_MMA(0, 0, At, B0); PG8_MMA(0, 1, At, B1); PG8_BAR; PG8_SCHED;
	s_setprio 1
	s_waitcnt lgkmcnt(0)
	v_mfma_f32_16x16x32_bf16 v[124:127], v[142:145], v[180:183], v[124:127]
	v_mfma_f32_16x16x32_bf16 v[120:123], v[150:153], v[180:183], v[120:123]
	v_mfma_f32_16x16x32_bf16 v[108:111], v[142:145], v[188:191], v[108:111]
	v_mfma_f32_16x16x32_bf16 v[104:107], v[150:153], v[188:191], v[104:107]
	v_mfma_f32_16x16x32_bf16 v[92:95], v[142:145], v[196:199], v[92:95]
	v_mfma_f32_16x16x32_bf16 v[88:91], v[150:153], v[196:199], v[88:91]
	v_mfma_f32_16x16x32_bf16 v[76:79], v[142:145], v[204:207], v[76:79]
	v_mfma_f32_16x16x32_bf16 v[72:75], v[150:153], v[204:207], v[72:75]
	v_mfma_f32_16x16x32_bf16 v[124:127], v[146:149], v[184:187], v[124:127]
	v_mfma_f32_16x16x32_bf16 v[120:123], v[154:157], v[184:187], v[120:123]
	v_mfma_f32_16x16x32_bf16 v[108:111], v[146:149], v[192:195], v[108:111]
	v_mfma_f32_16x16x32_bf16 v[104:107], v[154:157], v[192:195], v[104:107]
	v_mfma_f32_16x16x32_bf16 v[92:95], v[146:149], v[200:203], v[92:95]
	v_mfma_f32_16x16x32_bf16 v[88:91], v[154:157], v[200:203], v[88:91]
	v_mfma_f32_16x16x32_bf16 v[76:79], v[146:149], v[208:211], v[76:79]
	v_mfma_f32_16x16x32_bf16 v[72:75], v[154:157], v[208:211], v[72:75]
	s_setprio 0
	s_setprio 1
	v_mfma_f32_16x16x32_bf16 v[116:119], v[164:167], v[180:183], v[116:119]
	v_mfma_f32_16x16x32_bf16 v[112:115], v[172:175], v[180:183], v[112:115]
	v_mfma_f32_16x16x32_bf16 v[100:103], v[164:167], v[188:191], v[100:103]
	v_mfma_f32_16x16x32_bf16 v[96:99], v[172:175], v[188:191], v[96:99]
	v_mfma_f32_16x16x32_bf16 v[84:87], v[164:167], v[196:199], v[84:87]
	v_mfma_f32_16x16x32_bf16 v[80:83], v[172:175], v[196:199], v[80:83]
	v_mfma_f32_16x16x32_bf16 v[68:71], v[164:167], v[204:207], v[68:71]
	v_mfma_f32_16x16x32_bf16 v[64:67], v[172:175], v[204:207], v[64:67]
	v_mfma_f32_16x16x32_bf16 v[116:119], v[168:171], v[184:187], v[116:119]
	v_mfma_f32_16x16x32_bf16 v[112:115], v[176:179], v[184:187], v[112:115]
	v_mfma_f32_16x16x32_bf16 v[100:103], v[168:171], v[192:195], v[100:103]
	v_mfma_f32_16x16x32_bf16 v[96:99], v[176:179], v[192:195], v[96:99]
	v_mfma_f32_16x16x32_bf16 v[84:87], v[168:171], v[200:203], v[84:87]
	v_mfma_f32_16x16x32_bf16 v[80:83], v[176:179], v[200:203], v[80:83]
	v_mfma_f32_16x16x32_bf16 v[68:71], v[168:171], v[208:211], v[68:71]
	v_mfma_f32_16x16x32_bf16 v[64:67], v[176:179], v[208:211], v[64:67]
	s_setprio 0
	s_barrier
	s_add_i32 s66, s55, s46
	s_mov_b32 m0, s66
	ds_read_b128 v[180:183], v163 offset:16384
	ds_read_b128 v[184:187], v163 offset:17408
	ds_read_b128 v[188:191], v163 offset:18432
	ds_read_b128 v[192:195], v163 offset:19456
	ds_read_b128 v[196:199], v163 offset:20480
	ds_read_b128 v[200:203], v163 offset:21504
	ds_read_b128 v[204:207], v163 offset:22528
	ds_read_b128 v[208:211], v163 offset:23552
	global_load_lds_dwordx4 v130, s[36:37]
	s_add_i32 m0, s66, 0x2000
	s_add_u32 s66, s36, 0x40000
	s_addc_u32 s67, s37, 0
	s_add_i32 s72, s58, s46
	global_load_lds_dwordx4 v134, s[36:37]
	s_mov_b32 m0, s72
	s_nop 0
	global_load_lds_dwordx4 v130, s[66:67]
	s_add_i32 m0, s72, 0x2000
	s_nop 0
	global_load_lds_dwordx4 v134, s[66:67]
	s_mov_b32 m0, s31
	s_nop 0
	global_load_lds_dwordx4 v128, s[38:39]
	s_mov_b32 m0, s47
	s_nop 0
	global_load_lds_dwordx4 v132, s[38:39]
	s_waitcnt vmcnt(8)
	s_waitcnt lgkmcnt(0)
	s_barrier
	s_setprio 1
	s_waitcnt lgkmcnt(0)
	v_mfma_f32_16x16x32_bf16 v[60:63], v[142:145], v[180:183], v[60:63]
	v_mfma_f32_16x16x32_bf16 v[56:59], v[150:153], v[180:183], v[56:59]
	v_mfma_f32_16x16x32_bf16 v[44:47], v[142:145], v[188:191], v[44:47]
	v_mfma_f32_16x16x32_bf16 v[40:43], v[150:153], v[188:191], v[40:43]
	v_mfma_f32_16x16x32_bf16 v[28:31], v[142:145], v[196:199], v[28:31]
	v_mfma_f32_16x16x32_bf16 v[24:27], v[150:153], v[196:199], v[24:27]
	v_mfma_f32_16x16x32_bf16 v[12:15], v[142:145], v[204:207], v[12:15]
	v_mfma_f32_16x16x32_bf16 v[8:11], v[150:153], v[204:207], v[8:11]
	v_mfma_f32_16x16x32_bf16 v[60:63], v[146:149], v[184:187], v[60:63]
	v_mfma_f32_16x16x32_bf16 v[56:59], v[154:157], v[184:187], v[56:59]
	v_mfma_f32_16x16x32_bf16 v[44:47], v[146:149], v[192:195], v[44:47]
	v_mfma_f32_16x16x32_bf16 v[40:43], v[154:157], v[192:195], v[40:43]
	v_mfma_f32_16x16x32_bf16 v[28:31], v[146:149], v[200:203], v[28:31]
	v_mfma_f32_16x16x32_bf16 v[24:27], v[154:157], v[200:203], v[24:27]
	v_mfma_f32_16x16x32_bf16 v[12:15], v[146:149], v[208:211], v[12:15]
	v_mfma_f32_16x16x32_bf16 v[8:11], v[154:157], v[208:211], v[8:11]
	s_setprio 0
	s_setprio 1
	v_mfma_f32_16x16x32_bf16 v[52:55], v[164:167], v[180:183], v[52:55]
	v_mfma_f32_16x16x32_bf16 v[48:51], v[172:175], v[180:183], v[48:51]
	v_mfma_f32_16x16x32_bf16 v[36:39], v[164:167], v[188:191], v[36:39]
	v_mfma_f32_16x16x32_bf16 v[32:35], v[172:175], v[188:191], v[32:35]
	v_mfma_f32_16x16x32_bf16 v[20:23], v[164:167], v[196:199], v[20:23]
	v_mfma_f32_16x16x32_bf16 v[16:19], v[172:175], v[196:199], v[16:19]
	v_mfma_f32_16x16x32_bf16 v[4:7], v[164:167], v[204:207], v[4:7]
	v_mfma_f32_16x16x32_bf16 v[0:3], v[172:175], v[204:207], v[0:3]
	v_mfma_f32_16x16x32_bf16 v[52:55], v[168:171], v[184:187], v[52:55]
	v_mfma_f32_16x16x32_bf16 v[48:51], v[176:179], v[184:187], v[48:51]
	v_mfma_f32_16x16x32_bf16 v[36:39], v[168:171], v[192:195], v[36:39]
	v_mfma_f32_16x16x32_bf16 v[32:35], v[176:179], v[192:195], v[32:35]
	v_mfma_f32_16x16x32_bf16 v[20:23], v[168:171], v[200:203], v[20:23]
	v_mfma_f32_16x16x32_bf16 v[16:19], v[176:179], v[200:203], v[16:19]
	v_mfma_f32_16x16x32_bf16 v[4:7], v[168:171], v[208:211], v[4:7]
	v_mfma_f32_16x16x32_bf16 v[0:3], v[176:179], v[208:211], v[0:3]
	s_setprio 0
	s_barrier
; #define PG8_STAGE(bufoff, gbase, voff) do { _Pragma("unroll") for (int _i = 0; _i < 2; ++_i) \
;         __builtin_amdgcn_global_load_lds((const unsigned*)((const char*)(gbase) + (voff)[_i]), (LAS unsigned*)(lds + (bufoff) + ldsw + _i * 8192), 16, 0, 0); } while (0)
; #define PG8_LDA(dst, b, h) do { _Pragma("unroll") for (int m = 0; m < 4; ++m) _Pragma("unroll") for (int k = 0; k < 2; ++k) dst[m][k] = *(const LAS bf16x8*)(lds + PG8_SA(b, h) + aoff + m * 2048 + k * 1024); } while (0)
; #define PG8_LDB(dst, b, h) do { _Pragma("unroll") for (int n = 0; n < 2; ++n) _Pragma("unroll") for (int k = 0; k < 2; ++k) dst[n][k] = *(const LAS bf16x8*)(lds + PG8_SB(b, h) + boff + n * 2048 + k * 1024); } while (0)
; #define PG8_MMA(ai, bj, At, Bt) do { __builtin_amdgcn_s_setprio(1); _Pragma("unroll") for (int m = 0; m < 4; ++m) _Pragma("unroll") for (int n = 0; n < 2; ++n) _Pragma("unroll") for (int k = 0; k < 2; ++k) \
;         acc[ai][bj][m][n] = __builtin_amdgcn_mfma_f32_16x16x32_bf16(Bt[n][k], At[m][k], acc[ai][bj][m][n], 0, 0, 0); __builtin_amdgcn_s_setprio(0); } while (0)
; #define PG8_WAIT_V(n) asm volatile("s_waitcnt vmcnt(" #n ")" ::: "memory")
; #define PG8_WAIT_L(n) asm volatile("s_waitcnt lgkmcnt(" #n ")" ::: "memory")
; #define PG8_BAR __builtin_amdgcn_s_barrier()
; #define PG8_SCHED __builtin_amdgcn_sched_barrier(0)
; template <class Epi, class Sched>
; __device__ __forceinline__ void gemm_phase(LAS unsigned char* lds, const Gemm g, const Sched& S, const Epi& E, int wave_id) {
;     ...
;             PG8_LDB(B0, 1, 0); PG8_LDB(B1, 1, 1); PG8_SCHED; PG8_LDA(At, 1, 0); PG8_STAGE(PG8_SA(0, 1), a2 + hstepA, voffA);
;             PG8_WAIT_V(8); PG8_WAIT_L(0); PG8_BAR; PG8_MMA(0, 0, At, B0); PG8_MMA(0, 1, At, B1); PG8_BAR; PG8_SCHED;
;             PG8_LDA(At, 1, 1); PG8_STAGE(PG8_SB(1, 0), b3, voffB); PG8_STAGE(PG8_SB(1, 1), b3 + hstepB, voffB); PG8_STAGE(PG8_SA(1, 0), a3, voffA);
;             PG8_WAIT_V(8); PG8_WAIT_L(0); PG8_BAR; PG8_MMA(1, 0, At, B0); PG8_MMA(1, 1, At, B1); PG8_BAR; PG8_SCHED;
;         }
;         if (wr == 0) PG8_BAR;
	s_add_i32 s66, 0, 0x18000
	s_add_i32 s67, 0, 0x1c000
	v_add_u32_e32 v154, s66, v159
	v_add_u32_e32 v176, s67, v159
	ds_read_b128 v[142:145], v154
	ds_read_b128 v[146:149], v154 offset:1024
	ds_read_b128 v[150:153], v154 offset:2048
	ds_read_b128 v[154:157], v154 offset:3072
	ds_read_b128 v[164:167], v176
	ds_read_b128 v[168:171], v176 offset:1024
	ds_read_b128 v[172:175], v176 offset:2048
	ds_read_b128 v[176:179], v176 offset:3072
	s_add_u32 s38, s38, 0x40000
	s_addc_u32 s39, s39, 0
	s_mov_b32 m0, s48
	ds_read_b128 v[180:183], v163 offset:32768
	ds_read_b128 v[184:187], v163 offset:33792
	ds_read_b128 v[188:191], v163 offset:34816
	ds_read_b128 v[192:195], v163 offset:35840
	ds_read_b128 v[196:199], v163 offset:36864
	ds_read_b128 v[200:203], v163 offset:37888
	ds_read_b128 v[204:207], v163 offset:38912
	ds_read_b128 v[208:211], v163 offset:39936
	global_load_lds_dwordx4 v128, s[38:39]
	s_mov_b32 m0, s49
	s_nop 0
	global_load_lds_dwordx4 v132, s[38:39]
	s_waitcnt vmcnt(8)
	s_waitcnt lgkmcnt(0)
	s_barrier
	s_setprio 1
	s_waitcnt lgkmcnt(0)
	v_mfma_f32_16x16x32_bf16 v[124:127], v[142:145], v[180:183], v[124:127]
	v_mfma_f32_16x16x32_bf16 v[120:123], v[150:153], v[180:183], v[120:123]
	v_mfma_f32_16x16x32_bf16 v[108:111], v[142:145], v[188:191], v[108:111]
	v_mfma_f32_16x16x32_bf16 v[104:107], v[150:153], v[188:191], v[104:107]
	v_mfma_f32_16x16x32_bf16 v[92:95], v[142:145], v[196:199], v[92:95]
	v_mfma_f32_16x16x32_bf16 v[88:91], v[150:153], v[196:199], v[88:91]
	v_mfma_f32_16x16x32_bf16 v[76:79], v[142:145], v[204:207], v[76:79]
	v_mfma_f32_16x16x32_bf16 v[72:75], v[150:153], v[204:207], v[72:75]
	v_mfma_f32_16x16x32_bf16 v[124:127], v[146:149], v[184:187], v[124:127]
	v_mfma_f32_16x16x32_bf16 v[120:123], v[154:157], v[184:187], v[120:123]
	v_mfma_f32_16x16x32_bf16 v[108:111], v[146:149], v[192:195], v[108:111]
	v_mfma_f32_16x16x32_bf16 v[104:107], v[154:157], v[192:195], v[104:107]
	v_mfma_f32_16x16x32_bf16 v[92:95], v[146:149], v[200:203], v[92:95]
	v_mfma_f32_16x16x32_bf16 v[88:91], v[154:157], v[200:203], v[88:91]
	v_mfma_f32_16x16x32_bf16 v[76:79], v[146:149], v[208:211], v[76:79]
	v_mfma_f32_16x16x32_bf16 v[72:75], v[154:157], v[208:211], v[72:75]
	s_setprio 0
	s_setprio 1
	v_mfma_f32_16x16x32_bf16 v[116:119], v[164:167], v[180:183], v[116:119]
	v_mfma_f32_16x16x32_bf16 v[112:115], v[172:175], v[180:183], v[112:115]
	v_mfma_f32_16x16x32_bf16 v[100:103], v[164:167], v[188:191], v[100:103]
	v_mfma_f32_16x16x32_bf16 v[96:99], v[172:175], v[188:191], v[96:99]
	v_mfma_f32_16x16x32_bf16 v[84:87], v[164:167], v[196:199], v[84:87]
	v_mfma_f32_16x16x32_bf16 v[80:83], v[172:175], v[196:199], v[80:83]
	v_mfma_f32_16x16x32_bf16 v[68:71], v[164:167], v[204:207], v[68:71]
	v_mfma_f32_16x16x32_bf16 v[64:67], v[172:175], v[204:207], v[64:67]
	v_mfma_f32_16x16x32_bf16 v[116:119], v[168:171], v[184:187], v[116:119]
	v_mfma_f32_16x16x32_bf16 v[112:115], v[176:179], v[184:187], v[112:115]
	v_mfma_f32_16x16x32_bf16 v[100:103], v[168:171], v[192:195], v[100:103]
	v_mfma_f32_16x16x32_bf16 v[96:99], v[176:179], v[192:195], v[96:99]
	v_mfma_f32_16x16x32_bf16 v[84:87], v[168:171], v[200:203], v[84:87]
	v_mfma_f32_16x16x32_bf16 v[80:83], v[176:179], v[200:203], v[80:83]
	v_mfma_f32_16x16x32_bf16 v[68:71], v[168:171], v[208:211], v[68:71]
	v_mfma_f32_16x16x32_bf16 v[64:67], v[176:179], v[208:211], v[64:67]
	s_setprio 0
	s_barrier
	s_add_i32 s38, s66, s46
	s_mov_b32 m0, s38
	ds_read_b128 v[180:183], v163 offset:49152
	ds_read_b128 v[184:187], v163 offset:50176
	ds_read_b128 v[188:191], v163 offset:51200
	ds_read_b128 v[192:195], v163 offset:52224
	ds_read_b128 v[196:199], v163 offset:53248
	ds_read_b128 v[200:203], v163 offset:54272
	ds_read_b128 v[204:207], v163 offset:55296
	ds_read_b128 v[208:211], v163 offset:56320
	global_load_lds_dwordx4 v130, s[74:75]
	s_add_i32 m0, s38, 0x2000
	s_add_u32 s36, s36, 0x40080
	s_addc_u32 s37, s37, 0
	s_add_i32 s38, s67, s46
	global_load_lds_dwordx4 v134, s[74:75]
	s_mov_b32 m0, s38
	s_nop 0
	global_load_lds_dwordx4 v130, s[36:37]
	s_add_i32 m0, s38, 0x2000
	s_nop 0
	global_load_lds_dwordx4 v134, s[36:37]
	s_mov_b32 m0, s52
	s_nop 0
	global_load_lds_dwordx4 v128, s[78:79]
	s_mov_b32 m0, s53
	s_nop 0
	global_load_lds_dwordx4 v132, s[78:79]
	s_waitcnt vmcnt(8)
	s_waitcnt lgkmcnt(0)
	s_barrier
	s_setprio 1
	s_waitcnt lgkmcnt(0)
	v_mfma_f32_16x16x32_bf16 v[60:63], v[142:145], v[180:183], v[60:63]
	v_mfma_f32_16x16x32_bf16 v[56:59], v[150:153], v[180:183], v[56:59]
	v_mfma_f32_16x16x32_bf16 v[44:47], v[142:145], v[188:191], v[44:47]
	v_mfma_f32_16x16x32_bf16 v[40:43], v[150:153], v[188:191], v[40:43]
	v_mfma_f32_16x16x32_bf16 v[28:31], v[142:145], v[196:199], v[28:31]
	v_mfma_f32_16x16x32_bf16 v[24:27], v[150:153], v[196:199], v[24:27]
	v_mfma_f32_16x16x32_bf16 v[12:15], v[142:145], v[204:207], v[12:15]
	v_mfma_f32_16x16x32_bf16 v[8:11], v[150:153], v[204:207], v[8:11]
	v_mfma_f32_16x16x32_bf16 v[60:63], v[146:149], v[184:187], v[60:63]
	v_mfma_f32_16x16x32_bf16 v[56:59], v[154:157], v[184:187], v[56:59]
	v_mfma_f32_16x16x32_bf16 v[44:47], v[146:149], v[192:195], v[44:47]
	v_mfma_f32_16x16x32_bf16 v[40:43], v[154:157], v[192:195], v[40:43]
	v_mfma_f32_16x16x32_bf16 v[28:31], v[146:149], v[200:203], v[28:31]
	v_mfma_f32_16x16x32_bf16 v[24:27], v[154:157], v[200:203], v[24:27]
	v_mfma_f32_16x16x32_bf16 v[12:15], v[146:149], v[208:211], v[12:15]
	v_mfma_f32_16x16x32_bf16 v[8:11], v[154:157], v[208:211], v[8:11]
	s_setprio 0
	s_setprio 1
	v_mfma_f32_16x16x32_bf16 v[52:55], v[164:167], v[180:183], v[52:55]
	v_mfma_f32_16x16x32_bf16 v[48:51], v[172:175], v[180:183], v[48:51]
	v_mfma_f32_16x16x32_bf16 v[36:39], v[164:167], v[188:191], v[36:39]
	v_mfma_f32_16x16x32_bf16 v[32:35], v[172:175], v[188:191], v[32:35]
	v_mfma_f32_16x16x32_bf16 v[20:23], v[164:167], v[196:199], v[20:23]
	v_mfma_f32_16x16x32_bf16 v[16:19], v[172:175], v[196:199], v[16:19]
	v_mfma_f32_16x16x32_bf16 v[4:7], v[164:167], v[204:207], v[4:7]
	v_mfma_f32_16x16x32_bf16 v[0:3], v[172:175], v[204:207], v[0:3]
	v_mfma_f32_16x16x32_bf16 v[52:55], v[168:171], v[184:187], v[52:55]
	v_mfma_f32_16x16x32_bf16 v[48:51], v[176:179], v[184:187], v[48:51]
	v_mfma_f32_16x16x32_bf16 v[36:39], v[168:171], v[192:195], v[36:39]
	v_mfma_f32_16x16x32_bf16 v[32:35], v[176:179], v[192:195], v[32:35]
	v_mfma_f32_16x16x32_bf16 v[20:23], v[168:171], v[200:203], v[20:23]
	v_mfma_f32_16x16x32_bf16 v[16:19], v[176:179], v[200:203], v[16:19]
	v_mfma_f32_16x16x32_bf16 v[4:7], v[168:171], v[208:211], v[4:7]
	v_mfma_f32_16x16x32_bf16 v[0:3], v[176:179], v[208:211], v[0:3]
	s_setprio 0
	s_barrier
	s_add_i32 s65, s65, 2
	s_add_u32 s34, s34, 0x100
	s_addc_u32 s35, s35, 0
	s_add_u32 s63, s63, 0x100
	s_addc_u32 s64, s64, 0
	s_cmp_gt_u32 s65, 13
	s_cbranch_scc0 .LBB0_673
	s_and_b64 vcc, exec, s[8:9]
	s_cbranch_vccz .LBB0_676
	s_barrier

;     __device__ bool next(int i, Unit& u) const { if (r0 + i >= r1) return false; return base.next(r0 + i, u); }
;     __device__ bool next(int i, Unit& u) const { const int L = i * G + c; if (L >= 256) return false; u.pm = L; u.pn = L >> 3; return true; }
; #define PG8_STAGE(bufoff, gbase, voff) do { _Pragma("unroll") for (int _i = 0; _i < 2; ++_i) \
;         __builtin_amdgcn_global_load_lds((const unsigned*)((const char*)(gbase) + (voff)[_i]), (LAS unsigned*)(lds + (bufoff) + ldsw + _i * 8192), 16, 0, 0); } while (0)
; #define PG8_LDA(dst, b, h) do { _Pragma("unroll") for (int m = 0; m < 4; ++m) _Pragma("unroll") for (int k = 0; k < 2; ++k) dst[m][k] = *(const LAS bf16x8*)(lds + PG8_SA(b, h) + aoff + m * 2048 + k * 1024); } while (0)
; #define PG8_LDB(dst, b, h) do { _Pragma("unroll") for (int n = 0; n < 2; ++n) _Pragma("unroll") for (int k = 0; k < 2; ++k) dst[n][k] = *(const LAS bf16x8*)(lds + PG8_SB(b, h) + boff + n * 2048 + k * 1024); } while (0)
; #define PG8_WAIT_V(n) asm volatile("s_waitcnt vmcnt(" #n ")" ::: "memory")
; #define PG8_WAIT_L(n) asm volatile("s_waitcnt lgkmcnt(" #n ")" ::: "memory")
; template <class Epi, class Sched>
; __device__ __forceinline__ void gemm_phase(LAS unsigned char* lds, const Gemm g, const Sched& S, const Epi& E, int wave_id) {
;     ...
;         const bool has_next = S.next(ui + 1, nxt);
;         const char* nA = has_next ? (const char*)g.A + (size_t)nxt.pm * tstepA : cA; const char* nB = has_next ? (const char*)g.Bt + (size_t)nxt.pn * tstepB : cB;
;         for (int t = 0; t < nt; t += 2) {
;             const bool last = (t == nt - 2);
;             const char* a1 = cA + (size_t)(t + 1) * kstep;
;             const char* a2 = last ? nA : cA + (size_t)(t + 2) * kstep; const char* b2 = last ? nB : cB + (size_t)(t + 2) * kstep;
;             const char* a3 = a2 + kstep; const char* b3 = b2 + kstep;
;             PG8_LDB(B0, 0, 0); PG8_LDB(B1, 0, 1); PG8_SCHED; PG8_LDA(At, 0, 0); PG8_STAGE(PG8_SA(1, 1), a1 + hstepA, voffA);
;             PG8_WAIT_V(8); PG8_WAIT_L(0); PG8_BAR; PG8_MMA(0, 0, At, B0); PG8_MMA(0, 1, At, B1); PG8_BAR; PG8_SCHED;
;             PG8_LDA(At, 0, 1); PG8_STAGE(PG8_SB(0, 0), b2, voffB); PG8_STAGE(PG8_SB(0, 1), b2 + hstepB, voffB); PG8_STAGE(PG8_SA(0, 0), a2, voffA);
;             PG8_WAIT_V(8); PG8_WAIT_L(0); PG8_BAR; PG8_MMA(1, 0, At, B0); PG8_MMA(1, 1, At, B1); PG8_BAR; PG8_SCHED;
.LBB0_727:
	s_ashr_i32 s21, s20, 31
	s_lshl_b64 s[24:25], s[20:21], 19
	s_add_u32 s24, s15, s24
	s_addc_u32 s25, s33, s25
	s_and_b64 s[26:27], s[22:23], exec
	s_cselect_b32 s21, s25, s31
	s_cselect_b32 s59, s24, s30
	s_ashr_i32 s17, s16, 31
	s_lshl_b64 s[26:27], s[16:17], 19
	s_add_u32 s26, s38, s26
	s_addc_u32 s27, s39, s27
	s_and_b64 s[36:37], s[22:23], exec
	s_cselect_b32 s17, s27, s35
	s_cselect_b32 s60, s26, s34
	s_add_u32 s30, s30, 0x40080
	s_addc_u32 s31, s31, 0
	s_add_u32 s61, s34, 0x100
	s_addc_u32 s62, s35, 0
	s_mov_b32 s63, -2
	s_waitcnt vmcnt(0)
	ds_read_b128 v[142:145], v161
	ds_read_b128 v[146:149], v161 offset:1024
	ds_read_b128 v[150:153], v161 offset:2048
	ds_read_b128 v[154:157], v161 offset:3072
	ds_read_b128 v[164:167], v162
	ds_read_b128 v[168:171], v162 offset:1024
	ds_read_b128 v[172:175], v162 offset:2048
	ds_read_b128 v[176:179], v162 offset:3072
	s_add_u32 s34, s30, 0xfffc0080
	s_addc_u32 s35, s31, -1
	s_cmp_eq_u32 s63, 12
	s_cselect_b32 s37, s21, s35
	s_cselect_b32 s36, s59, s34
	s_cselect_b32 s35, s17, s62
	s_cselect_b32 s34, s60, s61
	s_add_u32 s74, s36, 0x80
	s_addc_u32 s75, s37, 0
	s_add_u32 s72, s34, 0x80
	s_addc_u32 s73, s35, 0
	s_add_i32 m0, s29, 0xc000
	ds_read_b128 v[180:183], v163
	ds_read_b128 v[184:187], v163 offset:1024
	ds_read_b128 v[188:191], v163 offset:2048
	ds_read_b128 v[192:195], v163 offset:3072
	ds_read_b128 v[196:199], v163 offset:4096
	ds_read_b128 v[200:203], v163 offset:5120
	ds_read_b128 v[204:207], v163 offset:6144
	ds_read_b128 v[208:211], v163 offset:7168
	global_load_lds_dwordx4 v136, s[30:31]
	s_add_i32 m0, s29, 0xe000
	s_nop 0
	global_load_lds_dwordx4 v138, s[30:31]
	s_waitcnt vmcnt(8)
	s_waitcnt lgkmcnt(0)
	s_barrier
	s_setprio 1
	s_waitcnt lgkmcnt(0)
	v_mfma_f32_16x16x32_bf16 v[124:127], v[142:145], v[180:183], 0
	v_mfma_f32_16x16x32_bf16 v[120:123], v[150:153], v[180:183], 0
	v_mfma_f32_16x16x32_bf16 v[108:111], v[142:145], v[188:191], 0
	v_mfma_f32_16x16x32_bf16 v[104:107], v[150:153], v[188:191], 0
	v_mfma_f32_16x16x32_bf16 v[92:95], v[142:145], v[196:199], 0
	v_mfma_f32_16x16x32_bf16 v[88:91], v[150:153], v[196:199], 0
	v_mfma_f32_16x16x32_bf16 v[76:79], v[142:145], v[204:207], 0
	v_mfma_f32_16x16x32_bf16 v[72:75], v[150:153], v[204:207], 0
	v_mfma_f32_16x16x32_bf16 v[124:127], v[146:149], v[184:187], v[124:127]
	v_mfma_f32_16x16x32_bf16 v[120:123], v[154:157], v[184:187], v[120:123]
	v_mfma_f32_16x16x32_bf16 v[108:111], v[146:149], v[192:195], v[108:111]
	v_mfma_f32_16x16x32_bf16 v[104:107], v[154:157], v[192:195], v[104:107]
	v_mfma_f32_16x16x32_bf16 v[92:95], v[146:149], v[200:203], v[92:95]
	v_mfma_f32_16x16x32_bf16 v[88:91], v[154:157], v[200:203], v[88:91]
	v_mfma_f32_16x16x32_bf16 v[76:79], v[146:149], v[208:211], v[76:79]
	v_mfma_f32_16x16x32_bf16 v[72:75], v[154:157], v[208:211], v[72:75]
	s_setprio 0
	s_setprio 1
	v_mfma_f32_16x16x32_bf16 v[116:119], v[164:167], v[180:183], 0
	v_mfma_f32_16x16x32_bf16 v[112:115], v[172:175], v[180:183], 0
	v_mfma_f32_16x16x32_bf16 v[100:103], v[164:167], v[188:191], 0
	v_mfma_f32_16x16x32_bf16 v[96:99], v[172:175], v[188:191], 0
	v_mfma_f32_16x16x32_bf16 v[84:87], v[164:167], v[196:199], 0
	v_mfma_f32_16x16x32_bf16 v[80:83], v[172:175], v[196:199], 0
	v_mfma_f32_16x16x32_bf16 v[68:71], v[164:167], v[204:207], 0
	v_mfma_f32_16x16x32_bf16 v[64:67], v[172:175], v[204:207], 0
	v_mfma_f32_16x16x32_bf16 v[116:119], v[168:171], v[184:187], v[116:119]
	v_mfma_f32_16x16x32_bf16 v[112:115], v[176:179], v[184:187], v[112:115]
	v_mfma_f32_16x16x32_bf16 v[100:103], v[168:171], v[192:195], v[100:103]
	v_mfma_f32_16x16x32_bf16 v[96:99], v[176:179], v[192:195], v[96:99]
	v_mfma_f32_16x16x32_bf16 v[84:87], v[168:171], v[200:203], v[84:87]
	v_mfma_f32_16x16x32_bf16 v[80:83], v[176:179], v[200:203], v[80:83]
	v_mfma_f32_16x16x32_bf16 v[68:71], v[168:171], v[208:211], v[68:71]
	v_mfma_f32_16x16x32_bf16 v[64:67], v[176:179], v[208:211], v[64:67]
	s_setprio 0
	s_barrier
	s_add_i32 s64, s53, s44
	s_mov_b32 m0, s64
	ds_read_b128 v[180:183], v163 offset:16384
	ds_read_b128 v[184:187], v163 offset:17408
	ds_read_b128 v[188:191], v163 offset:18432
	ds_read_b128 v[192:195], v163 offset:19456
	ds_read_b128 v[196:199], v163 offset:20480
	ds_read_b128 v[200:203], v163 offset:21504
	ds_read_b128 v[204:207], v163 offset:22528
	ds_read_b128 v[208:211], v163 offset:23552
	global_load_lds_dwordx4 v130, s[34:35]
	s_add_i32 m0, s64, 0x2000
	s_add_u32 s64, s34, 0x40000
	s_addc_u32 s65, s35, 0
	s_add_i32 s66, s54, s44
	global_load_lds_dwordx4 v134, s[34:35]
	s_mov_b32 m0, s66
	s_nop 0
	global_load_lds_dwordx4 v130, s[64:65]
	s_add_i32 m0, s66, 0x2000
	s_nop 0
	global_load_lds_dwordx4 v134, s[64:65]
	s_mov_b32 m0, s29
	s_nop 0
	global_load_lds_dwordx4 v128, s[36:37]
	s_mov_b32 m0, s45
	s_nop 0
	global_load_lds_dwordx4 v132, s[36:37]
	s_waitcnt vmcnt(8)
	s_waitcnt lgkmcnt(0)
	s_barrier
; #define PG8_STAGE(bufoff, gbase, voff) do { _Pragma("unroll") for (int _i = 0; _i < 2; ++_i) \
;         __builtin_amdgcn_global_load_lds((const unsigned*)((const char*)(gbase) + (voff)[_i]), (LAS unsigned*)(lds + (bufoff) + ldsw + _i * 8192), 16, 0, 0); } while (0)
; #define PG8_LDA(dst, b, h) do { _Pragma("unroll") for (int m = 0; m < 4; ++m) _Pragma("unroll") for (int k = 0; k < 2; ++k) dst[m][k] = *(const LAS bf16x8*)(lds + PG8_SA(b, h) + aoff + m * 2048 + k * 1024); } while (0)
; #define PG8_LDB(dst, b, h) do { _Pragma("unroll") for (int n = 0; n < 2; ++n) _Pragma("unroll") for (int k = 0; k < 2; ++k) dst[n][k] = *(const LAS bf16x8*)(lds + PG8_SB(b, h) + boff + n * 2048 + k * 1024); } while (0)
; #define PG8_MMA(ai, bj, At, Bt) do { __builtin_amdgcn_s_setprio(1); _Pragma("unroll") for (int m = 0; m < 4; ++m) _Pragma("unroll") for (int n = 0; n < 2; ++n) _Pragma("unroll") for (int k = 0; k < 2; ++k) \
;         acc[ai][bj][m][n] = __builtin_amdgcn_mfma_f32_16x16x32_bf16(Bt[n][k], At[m][k], acc[ai][bj][m][n], 0, 0, 0); __builtin_amdgcn_s_setprio(0); } while (0)
; #define PG8_WAIT_V(n) asm volatile("s_waitcnt vmcnt(" #n ")" ::: "memory")
; #define PG8_WAIT_L(n) asm volatile("s_waitcnt lgkmcnt(" #n ")" ::: "memory")
; #define PG8_BAR __builtin_amdgcn_s_barrier()
; #define PG8_SCHED __builtin_amdgcn_sched_barrier(0)
; template <class Epi, class Sched>
; __device__ __forceinline__ void gemm_phase(LAS unsigned char* lds, const Gemm g, const Sched& S, const Epi& E, int wave_id) {
;     ...
;             PG8_LDB(B0, 1, 0); PG8_LDB(B1, 1, 1); PG8_SCHED; PG8_LDA(At, 1, 0); PG8_STAGE(PG8_SA(0, 1), a2 + hstepA, voffA);
;             PG8_WAIT_V(8); PG8_WAIT_L(0); PG8_BAR; PG8_MMA(0, 0, At, B0); PG8_MMA(0, 1, At, B1); PG8_BAR; PG8_SCHED;
	s_setprio 1
	s_waitcnt lgkmcnt(0)
	v_mfma_f32_16x16x32_bf16 v[60:63], v[142:145], v[180:183], 0
	v_mfma_f32_16x16x32_bf16 v[56:59], v[150:153], v[180:183], 0
	v_mfma_f32_16x16x32_bf16 v[44:47], v[142:145], v[188:191], 0
	v_mfma_f32_16x16x32_bf16 v[40:43], v[150:153], v[188:191], 0
	v_mfma_f32_16x16x32_bf16 v[28:31], v[142:145], v[196:199], 0
	v_mfma_f32_16x16x32_bf16 v[24:27], v[150:153], v[196:199], 0
	v_mfma_f32_16x16x32_bf16 v[12:15], v[142:145], v[204:207], 0
	v_mfma_f32_16x16x32_bf16 v[8:11], v[150:153], v[204:207], 0
	v_mfma_f32_16x16x32_bf16 v[60:63], v[146:149], v[184:187], v[60:63]
	v_mfma_f32_16x16x32_bf16 v[56:59], v[154:157], v[184:187], v[56:59]
	v_mfma_f32_16x16x32_bf16 v[44:47], v[146:149], v[192:195], v[44:47]
	v_mfma_f32_16x16x32_bf16 v[40:43], v[154:157], v[192:195], v[40:43]
	v_mfma_f32_16x16x32_bf16 v[28:31], v[146:149], v[200:203], v[28:31]
	v_mfma_f32_16x16x32_bf16 v[24:27], v[154:157], v[200:203], v[24:27]
	v_mfma_f32_16x16x32_bf16 v[12:15], v[146:149], v[208:211], v[12:15]
	v_mfma_f32_16x16x32_bf16 v[8:11], v[154:157], v[208:211], v[8:11]
	s_setprio 0
	s_setprio 1
	v_mfma_f32_16x16x32_bf16 v[52:55], v[164:167], v[180:183], 0
	v_mfma_f32_16x16x32_bf16 v[48:51], v[172:175], v[180:183], 0
	v_mfma_f32_16x16x32_bf16 v[36:39], v[164:167], v[188:191], 0
	v_mfma_f32_16x16x32_bf16 v[32:35], v[172:175], v[188:191], 0
	v_mfma_f32_16x16x32_bf16 v[20:23], v[164:167], v[196:199], 0
	v_mfma_f32_16x16x32_bf16 v[16:19], v[172:175], v[196:199], 0
	v_mfma_f32_16x16x32_bf16 v[4:7], v[164:167], v[204:207], 0
	v_mfma_f32_16x16x32_bf16 v[0:3], v[172:175], v[204:207], 0
	v_mfma_f32_16x16x32_bf16 v[52:55], v[168:171], v[184:187], v[52:55]
	v_mfma_f32_16x16x32_bf16 v[48:51], v[176:179], v[184:187], v[48:51]
	v_mfma_f32_16x16x32_bf16 v[36:39], v[168:171], v[192:195], v[36:39]
	v_mfma_f32_16x16x32_bf16 v[32:35], v[176:179], v[192:195], v[32:35]
	v_mfma_f32_16x16x32_bf16 v[20:23], v[168:171], v[200:203], v[20:23]
	v_mfma_f32_16x16x32_bf16 v[16:19], v[176:179], v[200:203], v[16:19]
	v_mfma_f32_16x16x32_bf16 v[4:7], v[168:171], v[208:211], v[4:7]
	v_mfma_f32_16x16x32_bf16 v[0:3], v[176:179], v[208:211], v[0:3]
	s_setprio 0
	s_barrier
	s_add_i32 s64, 0, 0x18000
	s_add_i32 s65, 0, 0x1c000
	v_add_u32_e32 v154, s64, v159
	v_add_u32_e32 v176, s65, v159
	ds_read_b128 v[142:145], v154
	ds_read_b128 v[146:149], v154 offset:1024
	ds_read_b128 v[150:153], v154 offset:2048
	ds_read_b128 v[154:157], v154 offset:3072
	ds_read_b128 v[164:167], v176
	ds_read_b128 v[168:171], v176 offset:1024
	ds_read_b128 v[172:175], v176 offset:2048
	ds_read_b128 v[176:179], v176 offset:3072
	s_add_u32 s36, s36, 0x40000
	s_addc_u32 s37, s37, 0
	s_mov_b32 m0, s46
	ds_read_b128 v[180:183], v163 offset:32768
	ds_read_b128 v[184:187], v163 offset:33792
	ds_read_b128 v[188:191], v163 offset:34816
	ds_read_b128 v[192:195], v163 offset:35840
	ds_read_b128 v[196:199], v163 offset:36864
	ds_read_b128 v[200:203], v163 offset:37888
	ds_read_b128 v[204:207], v163 offset:38912
	ds_read_b128 v[208:211], v163 offset:39936
	global_load_lds_dwordx4 v128, s[36:37]
	s_mov_b32 m0, s47
	s_nop 0
	global_load_lds_dwordx4 v132, s[36:37]
	s_waitcnt vmcnt(8)
	s_waitcnt lgkmcnt(0)
	s_barrier
	s_setprio 1
	s_waitcnt lgkmcnt(0)
	v_mfma_f32_16x16x32_bf16 v[124:127], v[142:145], v[180:183], v[124:127]
	v_mfma_f32_16x16x32_bf16 v[120:123], v[150:153], v[180:183], v[120:123]
	v_mfma_f32_16x16x32_bf16 v[108:111], v[142:145], v[188:191], v[108:111]
	v_mfma_f32_16x16x32_bf16 v[104:107], v[150:153], v[188:191], v[104:107]
	v_mfma_f32_16x16x32_bf16 v[92:95], v[142:145], v[196:199], v[92:95]
	v_mfma_f32_16x16x32_bf16 v[88:91], v[150:153], v[196:199], v[88:91]
	v_mfma_f32_16x16x32_bf16 v[76:79], v[142:145], v[204:207], v[76:79]
	v_mfma_f32_16x16x32_bf16 v[72:75], v[150:153], v[204:207], v[72:75]
	v_mfma_f32_16x16x32_bf16 v[124:127], v[146:149], v[184:187], v[124:127]
	v_mfma_f32_16x16x32_bf16 v[120:123], v[154:157], v[184:187], v[120:123]
	v_mfma_f32_16x16x32_bf16 v[108:111], v[146:149], v[192:195], v[108:111]
	v_mfma_f32_16x16x32_bf16 v[104:107], v[154:157], v[192:195], v[104:107]
	v_mfma_f32_16x16x32_bf16 v[92:95], v[146:149], v[200:203], v[92:95]
	v_mfma_f32_16x16x32_bf16 v[88:91], v[154:157], v[200:203], v[88:91]
	v_mfma_f32_16x16x32_bf16 v[76:79], v[146:149], v[208:211], v[76:79]
	v_mfma_f32_16x16x32_bf16 v[72:75], v[154:157], v[208:211], v[72:75]
	s_setprio 0
	s_setprio 1
	v_mfma_f32_16x16x32_bf16 v[116:119], v[164:167], v[180:183], v[116:119]
	v_mfma_f32_16x16x32_bf16 v[112:115], v[172:175], v[180:183], v[112:115]
	v_mfma_f32_16x16x32_bf16 v[100:103], v[164:167], v[188:191], v[100:103]
	v_mfma_f32_16x16x32_bf16 v[96:99], v[172:175], v[188:191], v[96:99]
	v_mfma_f32_16x16x32_bf16 v[84:87], v[164:167], v[196:199], v[84:87]
	v_mfma_f32_16x16x32_bf16 v[80:83], v[172:175], v[196:199], v[80:83]
	v_mfma_f32_16x16x32_bf16 v[68:71], v[164:167], v[204:207], v[68:71]
	v_mfma_f32_16x16x32_bf16 v[64:67], v[172:175], v[204:207], v[64:67]
	v_mfma_f32_16x16x32_bf16 v[116:119], v[168:171], v[184:187], v[116:119]
	v_mfma_f32_16x16x32_bf16 v[112:115], v[176:179], v[184:187], v[112:115]
	v_mfma_f32_16x16x32_bf16 v[100:103], v[168:171], v[192:195], v[100:103]
	v_mfma_f32_16x16x32_bf16 v[96:99], v[176:179], v[192:195], v[96:99]
	v_mfma_f32_16x16x32_bf16 v[84:87], v[168:171], v[200:203], v[84:87]
	v_mfma_f32_16x16x32_bf16 v[80:83], v[176:179], v[200:203], v[80:83]
	v_mfma_f32_16x16x32_bf16 v[68:71], v[168:171], v[208:211], v[68:71]
	v_mfma_f32_16x16x32_bf16 v[64:67], v[176:179], v[208:211], v[64:67]
	s_setprio 0
	s_barrier
; #define PG8_STAGE(bufoff, gbase, voff) do { _Pragma("unroll") for (int _i = 0; _i < 2; ++_i) \
;         __builtin_amdgcn_global_load_lds((const unsigned*)((const char*)(gbase) + (voff)[_i]), (LAS unsigned*)(lds + (bufoff) + ldsw + _i * 8192), 16, 0, 0); } while (0)
; #define PG8_LDA(dst, b, h) do { _Pragma("unroll") for (int m = 0; m < 4; ++m) _Pragma("unroll") for (int k = 0; k < 2; ++k) dst[m][k] = *(const LAS bf16x8*)(lds + PG8_SA(b, h) + aoff + m * 2048 + k * 1024); } while (0)
; #define PG8_LDB(dst, b, h) do { _Pragma("unroll") for (int n = 0; n < 2; ++n) _Pragma("unroll") for (int k = 0; k < 2; ++k) dst[n][k] = *(const LAS bf16x8*)(lds + PG8_SB(b, h) + boff + n * 2048 + k * 1024); } while (0)
; #define PG8_WAIT_V(n) asm volatile("s_waitcnt vmcnt(" #n ")" ::: "memory")
; #define PG8_BAR __builtin_amdgcn_s_barrier()
; template <class Epi, class Sched>
; __device__ __forceinline__ void gemm_phase(LAS unsigned char* lds, const Gemm g, const Sched& S, const Epi& E, int wave_id) {
;     ...
;         for (int t = 0; t < nt; t += 2) {
;             const bool last = (t == nt - 2);
;             const char* a1 = cA + (size_t)(t + 1) * kstep;
;             const char* a2 = last ? nA : cA + (size_t)(t + 2) * kstep; const char* b2 = last ? nB : cB + (size_t)(t + 2) * kstep;
;             const char* a3 = a2 + kstep; const char* b3 = b2 + kstep;
;             PG8_LDB(B0, 0, 0); PG8_LDB(B1, 0, 1); PG8_SCHED; PG8_LDA(At, 0, 0); PG8_STAGE(PG8_SA(1, 1), a1 + hstepA, voffA);
;             PG8_WAIT_V(8); PG8_WAIT_L(0); PG8_BAR; PG8_MMA(0, 0, At, B0); PG8_MMA(0, 1, At, B1); PG8_BAR; PG8_SCHED;
;             PG8_LDA(At, 0, 1); PG8_STAGE(PG8_SB(0, 0), b2, voffB); PG8_STAGE(PG8_SB(0, 1), b2 + hstepB, voffB); PG8_STAGE(PG8_SA(0, 0), a2, voffA);
;             PG8_WAIT_V(8); PG8_WAIT_L(0); PG8_BAR; PG8_MMA(1, 0, At, B0); PG8_MMA(1, 1, At, B1); PG8_BAR; PG8_SCHED;
;             PG8_LDB(B0, 1, 0); PG8_LDB(B1, 1, 1); PG8_SCHED; PG8_LDA(At, 1, 0); PG8_STAGE(PG8_SA(0, 1), a2 + hstepA, voffA);
;             PG8_WAIT_V(8); PG8_WAIT_L(0); PG8_BAR; PG8_MMA(0, 0, At, B0); PG8_MMA(0, 1, At, B1); PG8_BAR; PG8_SCHED;
;             PG8_LDA(At, 1, 1); PG8_STAGE(PG8_SB(1, 0), b3, voffB); PG8_STAGE(PG8_SB(1, 1), b3 + hstepB, voffB); PG8_STAGE(PG8_SA(1, 0), a3, voffA);
;             PG8_WAIT_V(8); PG8_WAIT_L(0); PG8_BAR; PG8_MMA(1, 0, At, B0); PG8_MMA(1, 1, At, B1); PG8_BAR; PG8_SCHED;
	s_add_i32 s36, s64, s44
	s_mov_b32 m0, s36
	ds_read_b128 v[180:183], v163 offset:49152
	ds_read_b128 v[184:187], v163 offset:50176
	ds_read_b128 v[188:191], v163 offset:51200
	ds_read_b128 v[192:195], v163 offset:52224
	ds_read_b128 v[196:199], v163 offset:53248
	ds_read_b128 v[200:203], v163 offset:54272
	ds_read_b128 v[204:207], v163 offset:55296
	ds_read_b128 v[208:211], v163 offset:56320
	global_load_lds_dwordx4 v130, s[72:73]
	s_add_i32 m0, s36, 0x2000
	s_add_u32 s34, s34, 0x40080
	s_addc_u32 s35, s35, 0
	s_add_i32 s36, s65, s44
	global_load_lds_dwordx4 v134, s[72:73]
	s_mov_b32 m0, s36
	s_nop 0
	global_load_lds_dwordx4 v130, s[34:35]
	s_add_i32 m0, s36, 0x2000
	s_nop 0
	global_load_lds_dwordx4 v134, s[34:35]
	s_mov_b32 m0, s50
	s_nop 0
	global_load_lds_dwordx4 v128, s[74:75]
	s_mov_b32 m0, s51
	s_nop 0
	global_load_lds_dwordx4 v132, s[74:75]
	s_waitcnt vmcnt(8)
	s_waitcnt lgkmcnt(0)
	s_barrier
	s_setprio 1
	s_waitcnt lgkmcnt(0)
	v_mfma_f32_16x16x32_bf16 v[60:63], v[142:145], v[180:183], v[60:63]
	v_mfma_f32_16x16x32_bf16 v[56:59], v[150:153], v[180:183], v[56:59]
	v_mfma_f32_16x16x32_bf16 v[44:47], v[142:145], v[188:191], v[44:47]
	v_mfma_f32_16x16x32_bf16 v[40:43], v[150:153], v[188:191], v[40:43]
	v_mfma_f32_16x16x32_bf16 v[28:31], v[142:145], v[196:199], v[28:31]
	v_mfma_f32_16x16x32_bf16 v[24:27], v[150:153], v[196:199], v[24:27]
	v_mfma_f32_16x16x32_bf16 v[12:15], v[142:145], v[204:207], v[12:15]
	v_mfma_f32_16x16x32_bf16 v[8:11], v[150:153], v[204:207], v[8:11]
	v_mfma_f32_16x16x32_bf16 v[60:63], v[146:149], v[184:187], v[60:63]
	v_mfma_f32_16x16x32_bf16 v[56:59], v[154:157], v[184:187], v[56:59]
	v_mfma_f32_16x16x32_bf16 v[44:47], v[146:149], v[192:195], v[44:47]
	v_mfma_f32_16x16x32_bf16 v[40:43], v[154:157], v[192:195], v[40:43]
	v_mfma_f32_16x16x32_bf16 v[28:31], v[146:149], v[200:203], v[28:31]
	v_mfma_f32_16x16x32_bf16 v[24:27], v[154:157], v[200:203], v[24:27]
	v_mfma_f32_16x16x32_bf16 v[12:15], v[146:149], v[208:211], v[12:15]
	v_mfma_f32_16x16x32_bf16 v[8:11], v[154:157], v[208:211], v[8:11]
	s_setprio 0
	s_setprio 1
	v_mfma_f32_16x16x32_bf16 v[52:55], v[164:167], v[180:183], v[52:55]
	v_mfma_f32_16x16x32_bf16 v[48:51], v[172:175], v[180:183], v[48:51]
	v_mfma_f32_16x16x32_bf16 v[36:39], v[164:167], v[188:191], v[36:39]
	v_mfma_f32_16x16x32_bf16 v[32:35], v[172:175], v[188:191], v[32:35]
	v_mfma_f32_16x16x32_bf16 v[20:23], v[164:167], v[196:199], v[20:23]
	v_mfma_f32_16x16x32_bf16 v[16:19], v[172:175], v[196:199], v[16:19]
	v_mfma_f32_16x16x32_bf16 v[4:7], v[164:167], v[204:207], v[4:7]
	v_mfma_f32_16x16x32_bf16 v[0:3], v[172:175], v[204:207], v[0:3]
	v_mfma_f32_16x16x32_bf16 v[52:55], v[168:171], v[184:187], v[52:55]
	v_mfma_f32_16x16x32_bf16 v[48:51], v[176:179], v[184:187], v[48:51]
	v_mfma_f32_16x16x32_bf16 v[36:39], v[168:171], v[192:195], v[36:39]
	v_mfma_f32_16x16x32_bf16 v[32:35], v[176:179], v[192:195], v[32:35]
	v_mfma_f32_16x16x32_bf16 v[20:23], v[168:171], v[200:203], v[20:23]
	v_mfma_f32_16x16x32_bf16 v[16:19], v[176:179], v[200:203], v[16:19]
	v_mfma_f32_16x16x32_bf16 v[4:7], v[168:171], v[208:211], v[4:7]
	v_mfma_f32_16x16x32_bf16 v[0:3], v[176:179], v[208:211], v[0:3]
	s_setprio 0
	s_barrier
	s_add_i32 s63, s63, 2
	s_add_u32 s30, s30, 0x100
	s_addc_u32 s31, s31, 0
	s_add_u32 s61, s61, 0x100
	s_addc_u32 s62, s62, 0
	s_cmp_gt_u32 s63, 13
.LBB0_728:
	ds_read_b128 v[142:145], v161
	ds_read_b128 v[146:149], v161 offset:1024
	ds_read_b128 v[150:153], v161 offset:2048
	ds_read_b128 v[154:157], v161 offset:3072
	ds_read_b128 v[164:167], v162
	ds_read_b128 v[168:171], v162 offset:1024
	ds_read_b128 v[172:175], v162 offset:2048
	ds_read_b128 v[176:179], v162 offset:3072
	s_add_u32 s34, s30, 0xfffc0080
	s_addc_u32 s35, s31, -1
	s_cmp_eq_u32 s63, 12
	s_cselect_b32 s37, s21, s35
	s_cselect_b32 s36, s59, s34
	s_cselect_b32 s35, s17, s62
	s_cselect_b32 s34, s60, s61
	s_add_u32 s74, s36, 0x80
	s_addc_u32 s75, s37, 0
	s_add_u32 s72, s34, 0x80
	s_addc_u32 s73, s35, 0
	s_add_i32 m0, s29, 0xc000
	ds_read_b128 v[180:183], v163
	ds_read_b128 v[184:187], v163 offset:1024
	ds_read_b128 v[188:191], v163 offset:2048
	ds_read_b128 v[192:195], v163 offset:3072
	ds_read_b128 v[196:199], v163 offset:4096
	ds_read_b128 v[200:203], v163 offset:5120
	ds_read_b128 v[204:207], v163 offset:6144
	ds_read_b128 v[208:211], v163 offset:7168
	global_load_lds_dwordx4 v136, s[30:31]
	s_add_i32 m0, s29, 0xe000
	s_nop 0
	global_load_lds_dwordx4 v138, s[30:31]
	s_waitcnt vmcnt(8)
	s_waitcnt lgkmcnt(0)
	s_barrier
; #define PG8_STAGE(bufoff, gbase, voff) do { _Pragma("unroll") for (int _i = 0; _i < 2; ++_i) \
;         __builtin_amdgcn_global_load_lds((const unsigned*)((const char*)(gbase) + (voff)[_i]), (LAS unsigned*)(lds + (bufoff) + ldsw + _i * 8192), 16, 0, 0); } while (0)
; #define PG8_LDA(dst, b, h) do { _Pragma("unroll") for (int m = 0; m < 4; ++m) _Pragma("unroll") for (int k = 0; k < 2; ++k) dst[m][k] = *(const LAS bf16x8*)(lds + PG8_SA(b, h) + aoff + m * 2048 + k * 1024); } while (0)
; #define PG8_LDB(dst, b, h) do { _Pragma("unroll") for (int n = 0; n < 2; ++n) _Pragma("unroll") for (int k = 0; k < 2; ++k) dst[n][k] = *(const LAS bf16x8*)(lds + PG8_SB(b, h) + boff + n * 2048 + k * 1024); } while (0)
; #define PG8_MMA(ai, bj, At, Bt) do { __builtin_amdgcn_s_setprio(1); _Pragma("unroll") for (int m = 0; m < 4; ++m) _Pragma("unroll") for (int n = 0; n < 2; ++n) _Pragma("unroll") for (int k = 0; k < 2; ++k) \
;         acc[ai][bj][m][n] = __builtin_amdgcn_mfma_f32_16x16x32_bf16(Bt[n][k], At[m][k], acc[ai][bj][m][n], 0, 0, 0); __builtin_amdgcn_s_setprio(0); } while (0)
; #define PG8_WAIT_V(n) asm volatile("s_waitcnt vmcnt(" #n ")" ::: "memory")
; #define PG8_WAIT_L(n) asm volatile("s_waitcnt lgkmcnt(" #n ")" ::: "memory")
; #define PG8_BAR __builtin_amdgcn_s_barrier()
; #define PG8_SCHED __builtin_amdgcn_sched_barrier(0)
; template <class Epi, class Sched>
; __device__ __forceinline__ void gemm_phase(LAS unsigned char* lds, const Gemm g, const Sched& S, const Epi& E, int wave_id) {
;     ...
;             PG8_WAIT_V(8); PG8_WAIT_L(0); PG8_BAR; PG8_MMA(0, 0, At, B0); PG8_MMA(0, 1, At, B1); PG8_BAR; PG8_SCHED;
;             PG8_LDA(At, 0, 1); PG8_STAGE(PG8_SB(0, 0), b2, voffB); PG8_STAGE(PG8_SB(0, 1), b2 + hstepB, voffB); PG8_STAGE(PG8_SA(0, 0), a2, voffA);
;             PG8_WAIT_V(8); PG8_WAIT_L(0); PG8_BAR; PG8_MMA(1, 0, At, B0); PG8_MMA(1, 1, At, B1); PG8_BAR; PG8_SCHED;
;             PG8_LDB(B0, 1, 0); PG8_LDB(B1, 1, 1); PG8_SCHED; PG8_LDA(At, 1, 0); PG8_STAGE(PG8_SA(0, 1), a2 + hstepA, voffA);
;             PG8_WAIT_V(8); PG8_WAIT_L(0); PG8_BAR; PG8_MMA(0, 0, At, B0); PG8_MMA(0, 1, At, B1); PG8_BAR; PG8_SCHED;
	s_setprio 1
	s_waitcnt lgkmcnt(0)
	v_mfma_f32_16x16x32_bf16 v[124:127], v[142:145], v[180:183], v[124:127]
	v_mfma_f32_16x16x32_bf16 v[120:123], v[150:153], v[180:183], v[120:123]
	v_mfma_f32_16x16x32_bf16 v[108:111], v[142:145], v[188:191], v[108:111]
	v_mfma_f32_16x16x32_bf16 v[104:107], v[150:153], v[188:191], v[104:107]
	v_mfma_f32_16x16x32_bf16 v[92:95], v[142:145], v[196:199], v[92:95]
	v_mfma_f32_16x16x32_bf16 v[88:91], v[150:153], v[196:199], v[88:91]
	v_mfma_f32_16x16x32_bf16 v[76:79], v[142:145], v[204:207], v[76:79]
	v_mfma_f32_16x16x32_bf16 v[72:75], v[150:153], v[204:207], v[72:75]
	v_mfma_f32_16x16x32_bf16 v[124:127], v[146:149], v[184:187], v[124:127]
	v_mfma_f32_16x16x32_bf16 v[120:123], v[154:157], v[184:187], v[120:123]
	v_mfma_f32_16x16x32_bf16 v[108:111], v[146:149], v[192:195], v[108:111]
	v_mfma_f32_16x16x32_bf16 v[104:107], v[154:157], v[192:195], v[104:107]
	v_mfma_f32_16x16x32_bf16 v[92:95], v[146:149], v[200:203], v[92:95]
	v_mfma_f32_16x16x32_bf16 v[88:91], v[154:157], v[200:203], v[88:91]
	v_mfma_f32_16x16x32_bf16 v[76:79], v[146:149], v[208:211], v[76:79]
	v_mfma_f32_16x16x32_bf16 v[72:75], v[154:157], v[208:211], v[72:75]
	s_setprio 0
	s_setprio 1
	v_mfma_f32_16x16x32_bf16 v[116:119], v[164:167], v[180:183], v[116:119]
	v_mfma_f32_16x16x32_bf16 v[112:115], v[172:175], v[180:183], v[112:115]
	v_mfma_f32_16x16x32_bf16 v[100:103], v[164:167], v[188:191], v[100:103]
	v_mfma_f32_16x16x32_bf16 v[96:99], v[172:175], v[188:191], v[96:99]
	v_mfma_f32_16x16x32_bf16 v[84:87], v[164:167], v[196:199], v[84:87]
	v_mfma_f32_16x16x32_bf16 v[80:83], v[172:175], v[196:199], v[80:83]
	v_mfma_f32_16x16x32_bf16 v[68:71], v[164:167], v[204:207], v[68:71]
	v_mfma_f32_16x16x32_bf16 v[64:67], v[172:175], v[204:207], v[64:67]
	v_mfma_f32_16x16x32_bf16 v[116:119], v[168:171], v[184:187], v[116:119]
	v_mfma_f32_16x16x32_bf16 v[112:115], v[176:179], v[184:187], v[112:115]
	v_mfma_f32_16x16x32_bf16 v[100:103], v[168:171], v[192:195], v[100:103]
	v_mfma_f32_16x16x32_bf16 v[96:99], v[176:179], v[192:195], v[96:99]
	v_mfma_f32_16x16x32_bf16 v[84:87], v[168:171], v[200:203], v[84:87]
	v_mfma_f32_16x16x32_bf16 v[80:83], v[176:179], v[200:203], v[80:83]
	v_mfma_f32_16x16x32_bf16 v[68:71], v[168:171], v[208:211], v[68:71]
	v_mfma_f32_16x16x32_bf16 v[64:67], v[176:179], v[208:211], v[64:67]
	s_setprio 0
	s_barrier
	s_add_i32 s64, s53, s44
	s_mov_b32 m0, s64
	ds_read_b128 v[180:183], v163 offset:16384
	ds_read_b128 v[184:187], v163 offset:17408
	ds_read_b128 v[188:191], v163 offset:18432
	ds_read_b128 v[192:195], v163 offset:19456
	ds_read_b128 v[196:199], v163 offset:20480
	ds_read_b128 v[200:203], v163 offset:21504
	ds_read_b128 v[204:207], v163 offset:22528
	ds_read_b128 v[208:211], v163 offset:23552
	global_load_lds_dwordx4 v130, s[34:35]
	s_add_i32 m0, s64, 0x2000
	s_add_u32 s64, s34, 0x40000
	s_addc_u32 s65, s35, 0
	s_add_i32 s66, s54, s44
	global_load_lds_dwordx4 v134, s[34:35]
	s_mov_b32 m0, s66
	s_nop 0
	global_load_lds_dwordx4 v130, s[64:65]
	s_add_i32 m0, s66, 0x2000
	s_nop 0
	global_load_lds_dwordx4 v134, s[64:65]
	s_mov_b32 m0, s29
	s_nop 0
	global_load_lds_dwordx4 v128, s[36:37]
	s_mov_b32 m0, s45
	s_nop 0
	global_load_lds_dwordx4 v132, s[36:37]
	s_waitcnt vmcnt(8)
	s_waitcnt lgkmcnt(0)
	s_barrier
	s_setprio 1
	s_waitcnt lgkmcnt(0)
	v_mfma_f32_16x16x32_bf16 v[60:63], v[142:145], v[180:183], v[60:63]
	v_mfma_f32_16x16x32_bf16 v[56:59], v[150:153], v[180:183], v[56:59]
	v_mfma_f32_16x16x32_bf16 v[44:47], v[142:145], v[188:191], v[44:47]
	v_mfma_f32_16x16x32_bf16 v[40:43], v[150:153], v[188:191], v[40:43]
	v_mfma_f32_16x16x32_bf16 v[28:31], v[142:145], v[196:199], v[28:31]
	v_mfma_f32_16x16x32_bf16 v[24:27], v[150:153], v[196:199], v[24:27]
	v_mfma_f32_16x16x32_bf16 v[12:15], v[142:145], v[204:207], v[12:15]
	v_mfma_f32_16x16x32_bf16 v[8:11], v[150:153], v[204:207], v[8:11]
	v_mfma_f32_16x16x32_bf16 v[60:63], v[146:149], v[184:187], v[60:63]
	v_mfma_f32_16x16x32_bf16 v[56:59], v[154:157], v[184:187], v[56:59]
	v_mfma_f32_16x16x32_bf16 v[44:47], v[146:149], v[192:195], v[44:47]
	v_mfma_f32_16x16x32_bf16 v[40:43], v[154:157], v[192:195], v[40:43]
	v_mfma_f32_16x16x32_bf16 v[28:31], v[146:149], v[200:203], v[28:31]
	v_mfma_f32_16x16x32_bf16 v[24:27], v[154:157], v[200:203], v[24:27]
	v_mfma_f32_16x16x32_bf16 v[12:15], v[146:149], v[208:211], v[12:15]
	v_mfma_f32_16x16x32_bf16 v[8:11], v[154:157], v[208:211], v[8:11]
	s_setprio 0
	s_setprio 1
	v_mfma_f32_16x16x32_bf16 v[52:55], v[164:167], v[180:183], v[52:55]
	v_mfma_f32_16x16x32_bf16 v[48:51], v[172:175], v[180:183], v[48:51]
	v_mfma_f32_16x16x32_bf16 v[36:39], v[164:167], v[188:191], v[36:39]
	v_mfma_f32_16x16x32_bf16 v[32:35], v[172:175], v[188:191], v[32:35]
	v_mfma_f32_16x16x32_bf16 v[20:23], v[164:167], v[196:199], v[20:23]
	v_mfma_f32_16x16x32_bf16 v[16:19], v[172:175], v[196:199], v[16:19]
	v_mfma_f32_16x16x32_bf16 v[4:7], v[164:167], v[204:207], v[4:7]
	v_mfma_f32_16x16x32_bf16 v[0:3], v[172:175], v[204:207], v[0:3]
	v_mfma_f32_16x16x32_bf16 v[52:55], v[168:171], v[184:187], v[52:55]
	v_mfma_f32_16x16x32_bf16 v[48:51], v[176:179], v[184:187], v[48:51]
	v_mfma_f32_16x16x32_bf16 v[36:39], v[168:171], v[192:195], v[36:39]
	v_mfma_f32_16x16x32_bf16 v[32:35], v[176:179], v[192:195], v[32:35]
	v_mfma_f32_16x16x32_bf16 v[20:23], v[168:171], v[200:203], v[20:23]
	v_mfma_f32_16x16x32_bf16 v[16:19], v[176:179], v[200:203], v[16:19]
	v_mfma_f32_16x16x32_bf16 v[4:7], v[168:171], v[208:211], v[4:7]
	v_mfma_f32_16x16x32_bf16 v[0:3], v[176:179], v[208:211], v[0:3]
	s_setprio 0
	s_barrier
; #define PG8_STAGE(bufoff, gbase, voff) do { _Pragma("unroll") for (int _i = 0; _i < 2; ++_i) \
;         __builtin_amdgcn_global_load_lds((const unsigned*)((const char*)(gbase) + (voff)[_i]), (LAS unsigned*)(lds + (bufoff) + ldsw + _i * 8192), 16, 0, 0); } while (0)
; #define PG8_LDA(dst, b, h) do { _Pragma("unroll") for (int m = 0; m < 4; ++m) _Pragma("unroll") for (int k = 0; k < 2; ++k) dst[m][k] = *(const LAS bf16x8*)(lds + PG8_SA(b, h) + aoff + m * 2048 + k * 1024); } while (0)
; #define PG8_LDB(dst, b, h) do { _Pragma("unroll") for (int n = 0; n < 2; ++n) _Pragma("unroll") for (int k = 0; k < 2; ++k) dst[n][k] = *(const LAS bf16x8*)(lds + PG8_SB(b, h) + boff + n * 2048 + k * 1024); } while (0)
; #define PG8_MMA(ai, bj, At, Bt) do { __builtin_amdgcn_s_setprio(1); _Pragma("unroll") for (int m = 0; m < 4; ++m) _Pragma("unroll") for (int n = 0; n < 2; ++n) _Pragma("unroll") for (int k = 0; k < 2; ++k) \
;         acc[ai][bj][m][n] = __builtin_amdgcn_mfma_f32_16x16x32_bf16(Bt[n][k], At[m][k], acc[ai][bj][m][n], 0, 0, 0); __builtin_amdgcn_s_setprio(0); } while (0)
; #define PG8_WAIT_V(n) asm volatile("s_waitcnt vmcnt(" #n ")" ::: "memory")
; #define PG8_WAIT_L(n) asm volatile("s_waitcnt lgkmcnt(" #n ")" ::: "memory")
; #define PG8_BAR __builtin_amdgcn_s_barrier()
; #define PG8_SCHED __builtin_amdgcn_sched_barrier(0)
; template <class Epi, class Sched>
; __device__ __forceinline__ void gemm_phase(LAS unsigned char* lds, const Gemm g, const Sched& S, const Epi& E, int wave_id) {
;     ...
;             PG8_LDB(B0, 1, 0); PG8_LDB(B1, 1, 1); PG8_SCHED; PG8_LDA(At, 1, 0); PG8_STAGE(PG8_SA(0, 1), a2 + hstepA, voffA);
;             PG8_WAIT_V(8); PG8_WAIT_L(0); PG8_BAR; PG8_MMA(0, 0, At, B0); PG8_MMA(0, 1, At, B1); PG8_BAR; PG8_SCHED;
;             PG8_LDA(At, 1, 1); PG8_STAGE(PG8_SB(1, 0), b3, voffB); PG8_STAGE(PG8_SB(1, 1), b3 + hstepB, voffB); PG8_STAGE(PG8_SA(1, 0), a3, voffA);
;             PG8_WAIT_V(8); PG8_WAIT_L(0); PG8_BAR; PG8_MMA(1, 0, At, B0); PG8_MMA(1, 1, At, B1); PG8_BAR; PG8_SCHED;
;         }
;         if (wr == 0) PG8_BAR;
	s_add_i32 s64, 0, 0x18000
	s_add_i32 s65, 0, 0x1c000
	v_add_u32_e32 v154, s64, v159
	v_add_u32_e32 v176, s65, v159
	ds_read_b128 v[142:145], v154
	ds_read_b128 v[146:149], v154 offset:1024
	ds_read_b128 v[150:153], v154 offset:2048
	ds_read_b128 v[154:157], v154 offset:3072
	ds_read_b128 v[164:167], v176
	ds_read_b128 v[168:171], v176 offset:1024
	ds_read_b128 v[172:175], v176 offset:2048
	ds_read_b128 v[176:179], v176 offset:3072
	s_add_u32 s36, s36, 0x40000
	s_addc_u32 s37, s37, 0
	s_mov_b32 m0, s46
	ds_read_b128 v[180:183], v163 offset:32768
	ds_read_b128 v[184:187], v163 offset:33792
	ds_read_b128 v[188:191], v163 offset:34816
	ds_read_b128 v[192:195], v163 offset:35840
	ds_read_b128 v[196:199], v163 offset:36864
	ds_read_b128 v[200:203], v163 offset:37888
	ds_read_b128 v[204:207], v163 offset:38912
	ds_read_b128 v[208:211], v163 offset:39936
	global_load_lds_dwordx4 v128, s[36:37]
	s_mov_b32 m0, s47
	s_nop 0
	global_load_lds_dwordx4 v132, s[36:37]
	s_waitcnt vmcnt(8)
	s_waitcnt lgkmcnt(0)
	s_barrier
	s_setprio 1
	s_waitcnt lgkmcnt(0)
	v_mfma_f32_16x16x32_bf16 v[124:127], v[142:145], v[180:183], v[124:127]
	v_mfma_f32_16x16x32_bf16 v[120:123], v[150:153], v[180:183], v[120:123]
	v_mfma_f32_16x16x32_bf16 v[108:111], v[142:145], v[188:191], v[108:111]
	v_mfma_f32_16x16x32_bf16 v[104:107], v[150:153], v[188:191], v[104:107]
	v_mfma_f32_16x16x32_bf16 v[92:95], v[142:145], v[196:199], v[92:95]
	v_mfma_f32_16x16x32_bf16 v[88:91], v[150:153], v[196:199], v[88:91]
	v_mfma_f32_16x16x32_bf16 v[76:79], v[142:145], v[204:207], v[76:79]
	v_mfma_f32_16x16x32_bf16 v[72:75], v[150:153], v[204:207], v[72:75]
	v_mfma_f32_16x16x32_bf16 v[124:127], v[146:149], v[184:187], v[124:127]
	v_mfma_f32_16x16x32_bf16 v[120:123], v[154:157], v[184:187], v[120:123]
	v_mfma_f32_16x16x32_bf16 v[108:111], v[146:149], v[192:195], v[108:111]
	v_mfma_f32_16x16x32_bf16 v[104:107], v[154:157], v[192:195], v[104:107]
	v_mfma_f32_16x16x32_bf16 v[92:95], v[146:149], v[200:203], v[92:95]
	v_mfma_f32_16x16x32_bf16 v[88:91], v[154:157], v[200:203], v[88:91]
	v_mfma_f32_16x16x32_bf16 v[76:79], v[146:149], v[208:211], v[76:79]
	v_mfma_f32_16x16x32_bf16 v[72:75], v[154:157], v[208:211], v[72:75]
	s_setprio 0
	s_setprio 1
	v_mfma_f32_16x16x32_bf16 v[116:119], v[164:167], v[180:183], v[116:119]
	v_mfma_f32_16x16x32_bf16 v[112:115], v[172:175], v[180:183], v[112:115]
	v_mfma_f32_16x16x32_bf16 v[100:103], v[164:167], v[188:191], v[100:103]
	v_mfma_f32_16x16x32_bf16 v[96:99], v[172:175], v[188:191], v[96:99]
	v_mfma_f32_16x16x32_bf16 v[84:87], v[164:167], v[196:199], v[84:87]
	v_mfma_f32_16x16x32_bf16 v[80:83], v[172:175], v[196:199], v[80:83]
	v_mfma_f32_16x16x32_bf16 v[68:71], v[164:167], v[204:207], v[68:71]
	v_mfma_f32_16x16x32_bf16 v[64:67], v[172:175], v[204:207], v[64:67]
	v_mfma_f32_16x16x32_bf16 v[116:119], v[168:171], v[184:187], v[116:119]
	v_mfma_f32_16x16x32_bf16 v[112:115], v[176:179], v[184:187], v[112:115]
	v_mfma_f32_16x16x32_bf16 v[100:103], v[168:171], v[192:195], v[100:103]
	v_mfma_f32_16x16x32_bf16 v[96:99], v[176:179], v[192:195], v[96:99]
	v_mfma_f32_16x16x32_bf16 v[84:87], v[168:171], v[200:203], v[84:87]
	v_mfma_f32_16x16x32_bf16 v[80:83], v[176:179], v[200:203], v[80:83]
	v_mfma_f32_16x16x32_bf16 v[68:71], v[168:171], v[208:211], v[68:71]
	v_mfma_f32_16x16x32_bf16 v[64:67], v[176:179], v[208:211], v[64:67]
	s_setprio 0
	s_barrier
	s_add_i32 s36, s64, s44
	s_mov_b32 m0, s36
	ds_read_b128 v[180:183], v163 offset:49152
	ds_read_b128 v[184:187], v163 offset:50176
	ds_read_b128 v[188:191], v163 offset:51200
	ds_read_b128 v[192:195], v163 offset:52224
	ds_read_b128 v[196:199], v163 offset:53248
	ds_read_b128 v[200:203], v163 offset:54272
	ds_read_b128 v[204:207], v163 offset:55296
	ds_read_b128 v[208:211], v163 offset:56320
	global_load_lds_dwordx4 v130, s[72:73]
	s_add_i32 m0, s36, 0x2000
	s_add_u32 s34, s34, 0x40080
	s_addc_u32 s35, s35, 0
	s_add_i32 s36, s65, s44
	global_load_lds_dwordx4 v134, s[72:73]
	s_mov_b32 m0, s36
	s_nop 0
	global_load_lds_dwordx4 v130, s[34:35]
	s_add_i32 m0, s36, 0x2000
	s_nop 0
	global_load_lds_dwordx4 v134, s[34:35]
	s_mov_b32 m0, s50
	s_nop 0
	global_load_lds_dwordx4 v128, s[74:75]
	s_mov_b32 m0, s51
	s_nop 0
	global_load_lds_dwordx4 v132, s[74:75]
	s_waitcnt vmcnt(8)
	s_waitcnt lgkmcnt(0)
	s_barrier
	s_setprio 1
	s_waitcnt lgkmcnt(0)
	v_mfma_f32_16x16x32_bf16 v[60:63], v[142:145], v[180:183], v[60:63]
	v_mfma_f32_16x16x32_bf16 v[56:59], v[150:153], v[180:183], v[56:59]
	v_mfma_f32_16x16x32_bf16 v[44:47], v[142:145], v[188:191], v[44:47]
	v_mfma_f32_16x16x32_bf16 v[40:43], v[150:153], v[188:191], v[40:43]
	v_mfma_f32_16x16x32_bf16 v[28:31], v[142:145], v[196:199], v[28:31]
	v_mfma_f32_16x16x32_bf16 v[24:27], v[150:153], v[196:199], v[24:27]
	v_mfma_f32_16x16x32_bf16 v[12:15], v[142:145], v[204:207], v[12:15]
	v_mfma_f32_16x16x32_bf16 v[8:11], v[150:153], v[204:207], v[8:11]
	v_mfma_f32_16x16x32_bf16 v[60:63], v[146:149], v[184:187], v[60:63]
	v_mfma_f32_16x16x32_bf16 v[56:59], v[154:157], v[184:187], v[56:59]
	v_mfma_f32_16x16x32_bf16 v[44:47], v[146:149], v[192:195], v[44:47]
	v_mfma_f32_16x16x32_bf16 v[40:43], v[154:157], v[192:195], v[40:43]
	v_mfma_f32_16x16x32_bf16 v[28:31], v[146:149], v[200:203], v[28:31]
	v_mfma_f32_16x16x32_bf16 v[24:27], v[154:157], v[200:203], v[24:27]
	v_mfma_f32_16x16x32_bf16 v[12:15], v[146:149], v[208:211], v[12:15]
	v_mfma_f32_16x16x32_bf16 v[8:11], v[154:157], v[208:211], v[8:11]
	s_setprio 0
	s_setprio 1
	v_mfma_f32_16x16x32_bf16 v[52:55], v[164:167], v[180:183], v[52:55]
	v_mfma_f32_16x16x32_bf16 v[48:51], v[172:175], v[180:183], v[48:51]
	v_mfma_f32_16x16x32_bf16 v[36:39], v[164:167], v[188:191], v[36:39]
	v_mfma_f32_16x16x32_bf16 v[32:35], v[172:175], v[188:191], v[32:35]
	v_mfma_f32_16x16x32_bf16 v[20:23], v[164:167], v[196:199], v[20:23]
	v_mfma_f32_16x16x32_bf16 v[16:19], v[172:175], v[196:199], v[16:19]
	v_mfma_f32_16x16x32_bf16 v[4:7], v[164:167], v[204:207], v[4:7]
	v_mfma_f32_16x16x32_bf16 v[0:3], v[172:175], v[204:207], v[0:3]
	v_mfma_f32_16x16x32_bf16 v[52:55], v[168:171], v[184:187], v[52:55]
	v_mfma_f32_16x16x32_bf16 v[48:51], v[176:179], v[184:187], v[48:51]
	v_mfma_f32_16x16x32_bf16 v[36:39], v[168:171], v[192:195], v[36:39]
	v_mfma_f32_16x16x32_bf16 v[32:35], v[176:179], v[192:195], v[32:35]
	v_mfma_f32_16x16x32_bf16 v[20:23], v[168:171], v[200:203], v[20:23]
	v_mfma_f32_16x16x32_bf16 v[16:19], v[176:179], v[200:203], v[16:19]
	v_mfma_f32_16x16x32_bf16 v[4:7], v[168:171], v[208:211], v[4:7]
	v_mfma_f32_16x16x32_bf16 v[0:3], v[176:179], v[208:211], v[0:3]
	s_setprio 0
	s_barrier
	s_add_i32 s63, s63, 2
	s_add_u32 s30, s30, 0x100
	s_addc_u32 s31, s31, 0
	s_add_u32 s61, s61, 0x100
	s_addc_u32 s62, s62, 0
	s_cmp_gt_u32 s63, 13
	s_cbranch_scc0 .LBB0_728
	s_and_b64 vcc, exec, s[8:9]
	s_cbranch_vccz .LBB0_731
	s_barrier

;     __device__ bool next(int i, Unit& u) const { if (r0 + i >= r1) return false; return base.next(r0 + i, u); }
;     __device__ bool next(int i, Unit& u) const { const int L = i * G + c; if (L >= 256) return false; u.pm = L; u.pn = L >> 3; return true; }
; #define PG8_STAGE(bufoff, gbase, voff) do { _Pragma("unroll") for (int _i = 0; _i < 2; ++_i) \
;         __builtin_amdgcn_global_load_lds((const unsigned*)((const char*)(gbase) + (voff)[_i]), (LAS unsigned*)(lds + (bufoff) + ldsw + _i * 8192), 16, 0, 0); } while (0)
; #define PG8_LDA(dst, b, h) do { _Pragma("unroll") for (int m = 0; m < 4; ++m) _Pragma("unroll") for (int k = 0; k < 2; ++k) dst[m][k] = *(const LAS bf16x8*)(lds + PG8_SA(b, h) + aoff + m * 2048 + k * 1024); } while (0)
; #define PG8_LDB(dst, b, h) do { _Pragma("unroll") for (int n = 0; n < 2; ++n) _Pragma("unroll") for (int k = 0; k < 2; ++k) dst[n][k] = *(const LAS bf16x8*)(lds + PG8_SB(b, h) + boff + n * 2048 + k * 1024); } while (0)
; #define PG8_WAIT_V(n) asm volatile("s_waitcnt vmcnt(" #n ")" ::: "memory")
; #define PG8_WAIT_L(n) asm volatile("s_waitcnt lgkmcnt(" #n ")" ::: "memory")
; template <class Epi, class Sched>
; __device__ __forceinline__ void gemm_phase(LAS unsigned char* lds, const Gemm g, const Sched& S, const Epi& E, int wave_id) {
;     ...
;         const bool has_next = S.next(ui + 1, nxt);
;         const char* nA = has_next ? (const char*)g.A + (size_t)nxt.pm * tstepA : cA; const char* nB = has_next ? (const char*)g.Bt + (size_t)nxt.pn * tstepB : cB;
;         for (int t = 0; t < nt; t += 2) {
;             const bool last = (t == nt - 2);
;             const char* a1 = cA + (size_t)(t + 1) * kstep;
;             const char* a2 = last ? nA : cA + (size_t)(t + 2) * kstep; const char* b2 = last ? nB : cB + (size_t)(t + 2) * kstep;
;             const char* a3 = a2 + kstep; const char* b3 = b2 + kstep;
;             PG8_LDB(B0, 0, 0); PG8_LDB(B1, 0, 1); PG8_SCHED; PG8_LDA(At, 0, 0); PG8_STAGE(PG8_SA(1, 1), a1 + hstepA, voffA);
;             PG8_WAIT_V(8); PG8_WAIT_L(0); PG8_BAR; PG8_MMA(0, 0, At, B0); PG8_MMA(0, 1, At, B1); PG8_BAR; PG8_SCHED;
;             PG8_LDA(At, 0, 1); PG8_STAGE(PG8_SB(0, 0), b2, voffB); PG8_STAGE(PG8_SB(0, 1), b2 + hstepB, voffB); PG8_STAGE(PG8_SA(0, 0), a2, voffA);
;             PG8_WAIT_V(8); PG8_WAIT_L(0); PG8_BAR; PG8_MMA(1, 0, At, B0); PG8_MMA(1, 1, At, B1); PG8_BAR; PG8_SCHED;
.LBB0_803:
	s_ashr_i32 s19, s18, 31
	s_andn2_b64 vcc, exec, s[36:37]
	s_lshl_b64 s[22:23], s[18:19], 19
	s_add_u32 s22, s2, s22
	s_addc_u32 s23, s21, s23
	s_and_b64 s[24:25], s[36:37], exec
	s_cselect_b32 s19, s23, s31
	s_cselect_b32 s51, s22, s30
	s_ashr_i32 s17, s16, 31
	s_lshl_b64 s[24:25], s[16:17], 19
	s_add_u32 s24, s33, s24
	s_addc_u32 s25, s38, s25
	v_cndmask_b32_e64 v0, 0, 1, s[36:37]
	s_and_b64 s[36:37], s[36:37], exec
	s_cselect_b32 s17, s25, s35
	s_cselect_b32 s52, s24, s34
	s_add_u32 s30, s30, 0x40080
	s_addc_u32 s31, s31, 0
	v_cmp_ne_u32_e64 s[4:5], 1, v0
	s_add_u32 s53, s34, 0x100
	s_addc_u32 s54, s35, 0
	s_mov_b32 s55, -2
	s_waitcnt vmcnt(0)
	ds_read_b128 v[140:143], v159
	ds_read_b128 v[144:147], v159 offset:1024
	ds_read_b128 v[148:151], v159 offset:2048
	ds_read_b128 v[152:155], v159 offset:3072
	ds_read_b128 v[162:165], v160
	ds_read_b128 v[166:169], v160 offset:1024
	ds_read_b128 v[170:173], v160 offset:2048
	ds_read_b128 v[174:177], v160 offset:3072
	s_add_u32 s34, s30, 0xfffc0080
	s_addc_u32 s35, s31, -1
	s_cmp_eq_u32 s55, 12
	s_cselect_b32 s37, s19, s35
	s_cselect_b32 s36, s51, s34
	s_cselect_b32 s35, s17, s54
	s_cselect_b32 s34, s52, s53
	s_add_u32 s64, s36, 0x80
	s_addc_u32 s65, s37, 0
	s_add_u32 s62, s34, 0x80
	s_addc_u32 s63, s35, 0
	s_add_i32 m0, s27, 0xc000
	ds_read_b128 v[178:181], v161
	ds_read_b128 v[182:185], v161 offset:1024
	ds_read_b128 v[186:189], v161 offset:2048
	ds_read_b128 v[190:193], v161 offset:3072
	ds_read_b128 v[194:197], v161 offset:4096
	ds_read_b128 v[198:201], v161 offset:5120
	ds_read_b128 v[202:205], v161 offset:6144
	ds_read_b128 v[206:209], v161 offset:7168
	global_load_lds_dwordx4 v136, s[30:31]
	s_add_i32 m0, s27, 0xe000
	s_nop 0
	global_load_lds_dwordx4 v138, s[30:31]
	s_waitcnt vmcnt(8)
	s_waitcnt lgkmcnt(0)
	s_barrier
	s_setprio 1
	s_waitcnt lgkmcnt(0)
	v_mfma_f32_16x16x32_bf16 v[124:127], v[140:143], v[178:181], 0
	v_mfma_f32_16x16x32_bf16 v[120:123], v[148:151], v[178:181], 0
	v_mfma_f32_16x16x32_bf16 v[108:111], v[140:143], v[186:189], 0
	v_mfma_f32_16x16x32_bf16 v[104:107], v[148:151], v[186:189], 0
	v_mfma_f32_16x16x32_bf16 v[92:95], v[140:143], v[194:197], 0
	v_mfma_f32_16x16x32_bf16 v[88:91], v[148:151], v[194:197], 0
	v_mfma_f32_16x16x32_bf16 v[76:79], v[140:143], v[202:205], 0
	v_mfma_f32_16x16x32_bf16 v[72:75], v[148:151], v[202:205], 0
	v_mfma_f32_16x16x32_bf16 v[124:127], v[144:147], v[182:185], v[124:127]
	v_mfma_f32_16x16x32_bf16 v[120:123], v[152:155], v[182:185], v[120:123]
	v_mfma_f32_16x16x32_bf16 v[108:111], v[144:147], v[190:193], v[108:111]
	v_mfma_f32_16x16x32_bf16 v[104:107], v[152:155], v[190:193], v[104:107]
	v_mfma_f32_16x16x32_bf16 v[92:95], v[144:147], v[198:201], v[92:95]
	v_mfma_f32_16x16x32_bf16 v[88:91], v[152:155], v[198:201], v[88:91]
	v_mfma_f32_16x16x32_bf16 v[76:79], v[144:147], v[206:209], v[76:79]
	v_mfma_f32_16x16x32_bf16 v[72:75], v[152:155], v[206:209], v[72:75]
	s_setprio 0
	s_setprio 1
	v_mfma_f32_16x16x32_bf16 v[116:119], v[162:165], v[178:181], 0
	v_mfma_f32_16x16x32_bf16 v[112:115], v[170:173], v[178:181], 0
	v_mfma_f32_16x16x32_bf16 v[100:103], v[162:165], v[186:189], 0
	v_mfma_f32_16x16x32_bf16 v[96:99], v[170:173], v[186:189], 0
	v_mfma_f32_16x16x32_bf16 v[84:87], v[162:165], v[194:197], 0
	v_mfma_f32_16x16x32_bf16 v[80:83], v[170:173], v[194:197], 0
	v_mfma_f32_16x16x32_bf16 v[68:71], v[162:165], v[202:205], 0
	v_mfma_f32_16x16x32_bf16 v[64:67], v[170:173], v[202:205], 0
	v_mfma_f32_16x16x32_bf16 v[116:119], v[166:169], v[182:185], v[116:119]
	v_mfma_f32_16x16x32_bf16 v[112:115], v[174:177], v[182:185], v[112:115]
	v_mfma_f32_16x16x32_bf16 v[100:103], v[166:169], v[190:193], v[100:103]
	v_mfma_f32_16x16x32_bf16 v[96:99], v[174:177], v[190:193], v[96:99]
	v_mfma_f32_16x16x32_bf16 v[84:87], v[166:169], v[198:201], v[84:87]
	v_mfma_f32_16x16x32_bf16 v[80:83], v[174:177], v[198:201], v[80:83]
	v_mfma_f32_16x16x32_bf16 v[68:71], v[166:169], v[206:209], v[68:71]
	v_mfma_f32_16x16x32_bf16 v[64:67], v[174:177], v[206:209], v[64:67]
	s_setprio 0
	s_barrier
	s_add_i32 s58, s48, s39
	s_mov_b32 m0, s58
	ds_read_b128 v[178:181], v161 offset:16384
	ds_read_b128 v[182:185], v161 offset:17408
	ds_read_b128 v[186:189], v161 offset:18432
	ds_read_b128 v[190:193], v161 offset:19456
	ds_read_b128 v[194:197], v161 offset:20480
	ds_read_b128 v[198:201], v161 offset:21504
	ds_read_b128 v[202:205], v161 offset:22528
	ds_read_b128 v[206:209], v161 offset:23552
	global_load_lds_dwordx4 v130, s[34:35]
	s_add_i32 m0, s58, 0x2000
	s_add_u32 s58, s34, 0x40000
	s_addc_u32 s59, s35, 0
	s_add_i32 s60, s49, s39
	global_load_lds_dwordx4 v134, s[34:35]
	s_mov_b32 m0, s60
	s_nop 0
	global_load_lds_dwordx4 v130, s[58:59]
	s_add_i32 m0, s60, 0x2000
	s_nop 0
	global_load_lds_dwordx4 v134, s[58:59]
	s_mov_b32 m0, s27
	s_nop 0
	global_load_lds_dwordx4 v128, s[36:37]
	s_mov_b32 m0, s29
	s_nop 0
	global_load_lds_dwordx4 v132, s[36:37]
	s_waitcnt vmcnt(8)
	s_waitcnt lgkmcnt(0)
	s_barrier
; #define PG8_STAGE(bufoff, gbase, voff) do { _Pragma("unroll") for (int _i = 0; _i < 2; ++_i) \
;         __builtin_amdgcn_global_load_lds((const unsigned*)((const char*)(gbase) + (voff)[_i]), (LAS unsigned*)(lds + (bufoff) + ldsw + _i * 8192), 16, 0, 0); } while (0)
; #define PG8_LDA(dst, b, h) do { _Pragma("unroll") for (int m = 0; m < 4; ++m) _Pragma("unroll") for (int k = 0; k < 2; ++k) dst[m][k] = *(const LAS bf16x8*)(lds + PG8_SA(b, h) + aoff + m * 2048 + k * 1024); } while (0)
; #define PG8_LDB(dst, b, h) do { _Pragma("unroll") for (int n = 0; n < 2; ++n) _Pragma("unroll") for (int k = 0; k < 2; ++k) dst[n][k] = *(const LAS bf16x8*)(lds + PG8_SB(b, h) + boff + n * 2048 + k * 1024); } while (0)
; #define PG8_MMA(ai, bj, At, Bt) do { __builtin_amdgcn_s_setprio(1); _Pragma("unroll") for (int m = 0; m < 4; ++m) _Pragma("unroll") for (int n = 0; n < 2; ++n) _Pragma("unroll") for (int k = 0; k < 2; ++k) \
;         acc[ai][bj][m][n] = __builtin_amdgcn_mfma_f32_16x16x32_bf16(Bt[n][k], At[m][k], acc[ai][bj][m][n], 0, 0, 0); __builtin_amdgcn_s_setprio(0); } while (0)
; #define PG8_WAIT_V(n) asm volatile("s_waitcnt vmcnt(" #n ")" ::: "memory")
; #define PG8_WAIT_L(n) asm volatile("s_waitcnt lgkmcnt(" #n ")" ::: "memory")
; #define PG8_BAR __builtin_amdgcn_s_barrier()
; #define PG8_SCHED __builtin_amdgcn_sched_barrier(0)
; template <class Epi, class Sched>
; __device__ __forceinline__ void gemm_phase(LAS unsigned char* lds, const Gemm g, const Sched& S, const Epi& E, int wave_id) {
;     ...
;             PG8_LDB(B0, 1, 0); PG8_LDB(B1, 1, 1); PG8_SCHED; PG8_LDA(At, 1, 0); PG8_STAGE(PG8_SA(0, 1), a2 + hstepA, voffA);
;             PG8_WAIT_V(8); PG8_WAIT_L(0); PG8_BAR; PG8_MMA(0, 0, At, B0); PG8_MMA(0, 1, At, B1); PG8_BAR; PG8_SCHED;
	s_setprio 1
	s_waitcnt lgkmcnt(0)
	v_mfma_f32_16x16x32_bf16 v[60:63], v[140:143], v[178:181], 0
	v_mfma_f32_16x16x32_bf16 v[56:59], v[148:151], v[178:181], 0
	v_mfma_f32_16x16x32_bf16 v[44:47], v[140:143], v[186:189], 0
	v_mfma_f32_16x16x32_bf16 v[40:43], v[148:151], v[186:189], 0
	v_mfma_f32_16x16x32_bf16 v[28:31], v[140:143], v[194:197], 0
	v_mfma_f32_16x16x32_bf16 v[24:27], v[148:151], v[194:197], 0
	v_mfma_f32_16x16x32_bf16 v[12:15], v[140:143], v[202:205], 0
	v_mfma_f32_16x16x32_bf16 v[8:11], v[148:151], v[202:205], 0
	v_mfma_f32_16x16x32_bf16 v[60:63], v[144:147], v[182:185], v[60:63]
	v_mfma_f32_16x16x32_bf16 v[56:59], v[152:155], v[182:185], v[56:59]
	v_mfma_f32_16x16x32_bf16 v[44:47], v[144:147], v[190:193], v[44:47]
	v_mfma_f32_16x16x32_bf16 v[40:43], v[152:155], v[190:193], v[40:43]
	v_mfma_f32_16x16x32_bf16 v[28:31], v[144:147], v[198:201], v[28:31]
	v_mfma_f32_16x16x32_bf16 v[24:27], v[152:155], v[198:201], v[24:27]
	v_mfma_f32_16x16x32_bf16 v[12:15], v[144:147], v[206:209], v[12:15]
	v_mfma_f32_16x16x32_bf16 v[8:11], v[152:155], v[206:209], v[8:11]
	s_setprio 0
	s_setprio 1
	v_mfma_f32_16x16x32_bf16 v[52:55], v[162:165], v[178:181], 0
	v_mfma_f32_16x16x32_bf16 v[48:51], v[170:173], v[178:181], 0
	v_mfma_f32_16x16x32_bf16 v[36:39], v[162:165], v[186:189], 0
	v_mfma_f32_16x16x32_bf16 v[32:35], v[170:173], v[186:189], 0
	v_mfma_f32_16x16x32_bf16 v[20:23], v[162:165], v[194:197], 0
	v_mfma_f32_16x16x32_bf16 v[16:19], v[170:173], v[194:197], 0
	v_mfma_f32_16x16x32_bf16 v[4:7], v[162:165], v[202:205], 0
	v_mfma_f32_16x16x32_bf16 v[0:3], v[170:173], v[202:205], 0
	v_mfma_f32_16x16x32_bf16 v[52:55], v[166:169], v[182:185], v[52:55]
	v_mfma_f32_16x16x32_bf16 v[48:51], v[174:177], v[182:185], v[48:51]
	v_mfma_f32_16x16x32_bf16 v[36:39], v[166:169], v[190:193], v[36:39]
	v_mfma_f32_16x16x32_bf16 v[32:35], v[174:177], v[190:193], v[32:35]
	v_mfma_f32_16x16x32_bf16 v[20:23], v[166:169], v[198:201], v[20:23]
	v_mfma_f32_16x16x32_bf16 v[16:19], v[174:177], v[198:201], v[16:19]
	v_mfma_f32_16x16x32_bf16 v[4:7], v[166:169], v[206:209], v[4:7]
	v_mfma_f32_16x16x32_bf16 v[0:3], v[174:177], v[206:209], v[0:3]
	s_setprio 0
	s_barrier
	s_add_i32 s58, 0, 0x18000
	s_add_i32 s59, 0, 0x1c000
	v_add_u32_e32 v152, s58, v157
	v_add_u32_e32 v174, s59, v157
	ds_read_b128 v[140:143], v152
	ds_read_b128 v[144:147], v152 offset:1024
	ds_read_b128 v[148:151], v152 offset:2048
	ds_read_b128 v[152:155], v152 offset:3072
	ds_read_b128 v[162:165], v174
	ds_read_b128 v[166:169], v174 offset:1024
	ds_read_b128 v[170:173], v174 offset:2048
	ds_read_b128 v[174:177], v174 offset:3072
	s_add_u32 s36, s36, 0x40000
	s_addc_u32 s37, s37, 0
	s_mov_b32 m0, s44
	ds_read_b128 v[178:181], v161 offset:32768
	ds_read_b128 v[182:185], v161 offset:33792
	ds_read_b128 v[186:189], v161 offset:34816
	ds_read_b128 v[190:193], v161 offset:35840
	ds_read_b128 v[194:197], v161 offset:36864
	ds_read_b128 v[198:201], v161 offset:37888
	ds_read_b128 v[202:205], v161 offset:38912
	ds_read_b128 v[206:209], v161 offset:39936
	global_load_lds_dwordx4 v128, s[36:37]
	s_mov_b32 m0, s45
	s_nop 0
	global_load_lds_dwordx4 v132, s[36:37]
	s_waitcnt vmcnt(8)
	s_waitcnt lgkmcnt(0)
	s_barrier
	s_setprio 1
	s_waitcnt lgkmcnt(0)
	v_mfma_f32_16x16x32_bf16 v[124:127], v[140:143], v[178:181], v[124:127]
	v_mfma_f32_16x16x32_bf16 v[120:123], v[148:151], v[178:181], v[120:123]
	v_mfma_f32_16x16x32_bf16 v[108:111], v[140:143], v[186:189], v[108:111]
	v_mfma_f32_16x16x32_bf16 v[104:107], v[148:151], v[186:189], v[104:107]
	v_mfma_f32_16x16x32_bf16 v[92:95], v[140:143], v[194:197], v[92:95]
	v_mfma_f32_16x16x32_bf16 v[88:91], v[148:151], v[194:197], v[88:91]
	v_mfma_f32_16x16x32_bf16 v[76:79], v[140:143], v[202:205], v[76:79]
	v_mfma_f32_16x16x32_bf16 v[72:75], v[148:151], v[202:205], v[72:75]
	v_mfma_f32_16x16x32_bf16 v[124:127], v[144:147], v[182:185], v[124:127]
	v_mfma_f32_16x16x32_bf16 v[120:123], v[152:155], v[182:185], v[120:123]
	v_mfma_f32_16x16x32_bf16 v[108:111], v[144:147], v[190:193], v[108:111]
	v_mfma_f32_16x16x32_bf16 v[104:107], v[152:155], v[190:193], v[104:107]
	v_mfma_f32_16x16x32_bf16 v[92:95], v[144:147], v[198:201], v[92:95]
	v_mfma_f32_16x16x32_bf16 v[88:91], v[152:155], v[198:201], v[88:91]
	v_mfma_f32_16x16x32_bf16 v[76:79], v[144:147], v[206:209], v[76:79]
	v_mfma_f32_16x16x32_bf16 v[72:75], v[152:155], v[206:209], v[72:75]
	s_setprio 0
	s_setprio 1
	v_mfma_f32_16x16x32_bf16 v[116:119], v[162:165], v[178:181], v[116:119]
	v_mfma_f32_16x16x32_bf16 v[112:115], v[170:173], v[178:181], v[112:115]
	v_mfma_f32_16x16x32_bf16 v[100:103], v[162:165], v[186:189], v[100:103]
	v_mfma_f32_16x16x32_bf16 v[96:99], v[170:173], v[186:189], v[96:99]
	v_mfma_f32_16x16x32_bf16 v[84:87], v[162:165], v[194:197], v[84:87]
	v_mfma_f32_16x16x32_bf16 v[80:83], v[170:173], v[194:197], v[80:83]
	v_mfma_f32_16x16x32_bf16 v[68:71], v[162:165], v[202:205], v[68:71]
	v_mfma_f32_16x16x32_bf16 v[64:67], v[170:173], v[202:205], v[64:67]
	v_mfma_f32_16x16x32_bf16 v[116:119], v[166:169], v[182:185], v[116:119]
	v_mfma_f32_16x16x32_bf16 v[112:115], v[174:177], v[182:185], v[112:115]
	v_mfma_f32_16x16x32_bf16 v[100:103], v[166:169], v[190:193], v[100:103]
	v_mfma_f32_16x16x32_bf16 v[96:99], v[174:177], v[190:193], v[96:99]
	v_mfma_f32_16x16x32_bf16 v[84:87], v[166:169], v[198:201], v[84:87]
	v_mfma_f32_16x16x32_bf16 v[80:83], v[174:177], v[198:201], v[80:83]
	v_mfma_f32_16x16x32_bf16 v[68:71], v[166:169], v[206:209], v[68:71]
	v_mfma_f32_16x16x32_bf16 v[64:67], v[174:177], v[206:209], v[64:67]
	s_setprio 0
	s_barrier
; #define PG8_STAGE(bufoff, gbase, voff) do { _Pragma("unroll") for (int _i = 0; _i < 2; ++_i) \
;         __builtin_amdgcn_global_load_lds((const unsigned*)((const char*)(gbase) + (voff)[_i]), (LAS unsigned*)(lds + (bufoff) + ldsw + _i * 8192), 16, 0, 0); } while (0)
; #define PG8_LDA(dst, b, h) do { _Pragma("unroll") for (int m = 0; m < 4; ++m) _Pragma("unroll") for (int k = 0; k < 2; ++k) dst[m][k] = *(const LAS bf16x8*)(lds + PG8_SA(b, h) + aoff + m * 2048 + k * 1024); } while (0)
; #define PG8_LDB(dst, b, h) do { _Pragma("unroll") for (int n = 0; n < 2; ++n) _Pragma("unroll") for (int k = 0; k < 2; ++k) dst[n][k] = *(const LAS bf16x8*)(lds + PG8_SB(b, h) + boff + n * 2048 + k * 1024); } while (0)
; #define PG8_WAIT_V(n) asm volatile("s_waitcnt vmcnt(" #n ")" ::: "memory")
; #define PG8_BAR __builtin_amdgcn_s_barrier()
; template <class Epi, class Sched>
; __device__ __forceinline__ void gemm_phase(LAS unsigned char* lds, const Gemm g, const Sched& S, const Epi& E, int wave_id) {
;     ...
;         for (int t = 0; t < nt; t += 2) {
;             const bool last = (t == nt - 2);
;             const char* a1 = cA + (size_t)(t + 1) * kstep;
;             const char* a2 = last ? nA : cA + (size_t)(t + 2) * kstep; const char* b2 = last ? nB : cB + (size_t)(t + 2) * kstep;
;             const char* a3 = a2 + kstep; const char* b3 = b2 + kstep;
;             PG8_LDB(B0, 0, 0); PG8_LDB(B1, 0, 1); PG8_SCHED; PG8_LDA(At, 0, 0); PG8_STAGE(PG8_SA(1, 1), a1 + hstepA, voffA);
;             PG8_WAIT_V(8); PG8_WAIT_L(0); PG8_BAR; PG8_MMA(0, 0, At, B0); PG8_MMA(0, 1, At, B1); PG8_BAR; PG8_SCHED;
;             PG8_LDA(At, 0, 1); PG8_STAGE(PG8_SB(0, 0), b2, voffB); PG8_STAGE(PG8_SB(0, 1), b2 + hstepB, voffB); PG8_STAGE(PG8_SA(0, 0), a2, voffA);
;             PG8_WAIT_V(8); PG8_WAIT_L(0); PG8_BAR; PG8_MMA(1, 0, At, B0); PG8_MMA(1, 1, At, B1); PG8_BAR; PG8_SCHED;
;             PG8_LDB(B0, 1, 0); PG8_LDB(B1, 1, 1); PG8_SCHED; PG8_LDA(At, 1, 0); PG8_STAGE(PG8_SA(0, 1), a2 + hstepA, voffA);
;             PG8_WAIT_V(8); PG8_WAIT_L(0); PG8_BAR; PG8_MMA(0, 0, At, B0); PG8_MMA(0, 1, At, B1); PG8_BAR; PG8_SCHED;
;             PG8_LDA(At, 1, 1); PG8_STAGE(PG8_SB(1, 0), b3, voffB); PG8_STAGE(PG8_SB(1, 1), b3 + hstepB, voffB); PG8_STAGE(PG8_SA(1, 0), a3, voffA);
;             PG8_WAIT_V(8); PG8_WAIT_L(0); PG8_BAR; PG8_MMA(1, 0, At, B0); PG8_MMA(1, 1, At, B1); PG8_BAR; PG8_SCHED;
	s_add_i32 s36, s58, s39
	s_mov_b32 m0, s36
	ds_read_b128 v[178:181], v161 offset:49152
	ds_read_b128 v[182:185], v161 offset:50176
	ds_read_b128 v[186:189], v161 offset:51200
	ds_read_b128 v[190:193], v161 offset:52224
	ds_read_b128 v[194:197], v161 offset:53248
	ds_read_b128 v[198:201], v161 offset:54272
	ds_read_b128 v[202:205], v161 offset:55296
	ds_read_b128 v[206:209], v161 offset:56320
	global_load_lds_dwordx4 v130, s[62:63]
	s_add_i32 m0, s36, 0x2000
	s_add_u32 s34, s34, 0x40080
	s_addc_u32 s35, s35, 0
	s_add_i32 s36, s59, s39
	global_load_lds_dwordx4 v134, s[62:63]
	s_mov_b32 m0, s36
	s_nop 0
	global_load_lds_dwordx4 v130, s[34:35]
	s_add_i32 m0, s36, 0x2000
	s_nop 0
	global_load_lds_dwordx4 v134, s[34:35]
	s_mov_b32 m0, s46
	s_nop 0
	global_load_lds_dwordx4 v128, s[64:65]
	s_mov_b32 m0, s47
	s_nop 0
	global_load_lds_dwordx4 v132, s[64:65]
	s_waitcnt vmcnt(8)
	s_waitcnt lgkmcnt(0)
	s_barrier
	s_setprio 1
	s_waitcnt lgkmcnt(0)
	v_mfma_f32_16x16x32_bf16 v[60:63], v[140:143], v[178:181], v[60:63]
	v_mfma_f32_16x16x32_bf16 v[56:59], v[148:151], v[178:181], v[56:59]
	v_mfma_f32_16x16x32_bf16 v[44:47], v[140:143], v[186:189], v[44:47]
	v_mfma_f32_16x16x32_bf16 v[40:43], v[148:151], v[186:189], v[40:43]
	v_mfma_f32_16x16x32_bf16 v[28:31], v[140:143], v[194:197], v[28:31]
	v_mfma_f32_16x16x32_bf16 v[24:27], v[148:151], v[194:197], v[24:27]
	v_mfma_f32_16x16x32_bf16 v[12:15], v[140:143], v[202:205], v[12:15]
	v_mfma_f32_16x16x32_bf16 v[8:11], v[148:151], v[202:205], v[8:11]
	v_mfma_f32_16x16x32_bf16 v[60:63], v[144:147], v[182:185], v[60:63]
	v_mfma_f32_16x16x32_bf16 v[56:59], v[152:155], v[182:185], v[56:59]
	v_mfma_f32_16x16x32_bf16 v[44:47], v[144:147], v[190:193], v[44:47]
	v_mfma_f32_16x16x32_bf16 v[40:43], v[152:155], v[190:193], v[40:43]
	v_mfma_f32_16x16x32_bf16 v[28:31], v[144:147], v[198:201], v[28:31]
	v_mfma_f32_16x16x32_bf16 v[24:27], v[152:155], v[198:201], v[24:27]
	v_mfma_f32_16x16x32_bf16 v[12:15], v[144:147], v[206:209], v[12:15]
	v_mfma_f32_16x16x32_bf16 v[8:11], v[152:155], v[206:209], v[8:11]
	s_setprio 0
	s_setprio 1
	v_mfma_f32_16x16x32_bf16 v[52:55], v[162:165], v[178:181], v[52:55]
	v_mfma_f32_16x16x32_bf16 v[48:51], v[170:173], v[178:181], v[48:51]
	v_mfma_f32_16x16x32_bf16 v[36:39], v[162:165], v[186:189], v[36:39]
	v_mfma_f32_16x16x32_bf16 v[32:35], v[170:173], v[186:189], v[32:35]
	v_mfma_f32_16x16x32_bf16 v[20:23], v[162:165], v[194:197], v[20:23]
	v_mfma_f32_16x16x32_bf16 v[16:19], v[170:173], v[194:197], v[16:19]
	v_mfma_f32_16x16x32_bf16 v[4:7], v[162:165], v[202:205], v[4:7]
	v_mfma_f32_16x16x32_bf16 v[0:3], v[170:173], v[202:205], v[0:3]
	v_mfma_f32_16x16x32_bf16 v[52:55], v[166:169], v[182:185], v[52:55]
	v_mfma_f32_16x16x32_bf16 v[48:51], v[174:177], v[182:185], v[48:51]
	v_mfma_f32_16x16x32_bf16 v[36:39], v[166:169], v[190:193], v[36:39]
	v_mfma_f32_16x16x32_bf16 v[32:35], v[174:177], v[190:193], v[32:35]
	v_mfma_f32_16x16x32_bf16 v[20:23], v[166:169], v[198:201], v[20:23]
	v_mfma_f32_16x16x32_bf16 v[16:19], v[174:177], v[198:201], v[16:19]
	v_mfma_f32_16x16x32_bf16 v[4:7], v[166:169], v[206:209], v[4:7]
	v_mfma_f32_16x16x32_bf16 v[0:3], v[174:177], v[206:209], v[0:3]
	s_setprio 0
	s_barrier
	s_add_i32 s55, s55, 2
	s_add_u32 s30, s30, 0x100
	s_addc_u32 s31, s31, 0
	s_add_u32 s53, s53, 0x100
	s_addc_u32 s54, s54, 0
	s_cmp_gt_u32 s55, 13
.LBB0_804:
	ds_read_b128 v[140:143], v159
	ds_read_b128 v[144:147], v159 offset:1024
	ds_read_b128 v[148:151], v159 offset:2048
	ds_read_b128 v[152:155], v159 offset:3072
	ds_read_b128 v[162:165], v160
	ds_read_b128 v[166:169], v160 offset:1024
	ds_read_b128 v[170:173], v160 offset:2048
	ds_read_b128 v[174:177], v160 offset:3072
	s_add_u32 s34, s30, 0xfffc0080
	s_addc_u32 s35, s31, -1
	s_cmp_eq_u32 s55, 12
	s_cselect_b32 s37, s19, s35
	s_cselect_b32 s36, s51, s34
	s_cselect_b32 s35, s17, s54
	s_cselect_b32 s34, s52, s53
	s_add_u32 s64, s36, 0x80
	s_addc_u32 s65, s37, 0
	s_add_u32 s62, s34, 0x80
	s_addc_u32 s63, s35, 0
	s_add_i32 m0, s27, 0xc000
	ds_read_b128 v[178:181], v161
	ds_read_b128 v[182:185], v161 offset:1024
	ds_read_b128 v[186:189], v161 offset:2048
	ds_read_b128 v[190:193], v161 offset:3072
	ds_read_b128 v[194:197], v161 offset:4096
	ds_read_b128 v[198:201], v161 offset:5120
	ds_read_b128 v[202:205], v161 offset:6144
	ds_read_b128 v[206:209], v161 offset:7168
	global_load_lds_dwordx4 v136, s[30:31]
	s_add_i32 m0, s27, 0xe000
	s_nop 0
	global_load_lds_dwordx4 v138, s[30:31]
	s_waitcnt vmcnt(8)
	s_waitcnt lgkmcnt(0)
	s_barrier
; #define PG8_STAGE(bufoff, gbase, voff) do { _Pragma("unroll") for (int _i = 0; _i < 2; ++_i) \
;         __builtin_amdgcn_global_load_lds((const unsigned*)((const char*)(gbase) + (voff)[_i]), (LAS unsigned*)(lds + (bufoff) + ldsw + _i * 8192), 16, 0, 0); } while (0)
; #define PG8_LDA(dst, b, h) do { _Pragma("unroll") for (int m = 0; m < 4; ++m) _Pragma("unroll") for (int k = 0; k < 2; ++k) dst[m][k] = *(const LAS bf16x8*)(lds + PG8_SA(b, h) + aoff + m * 2048 + k * 1024); } while (0)
; #define PG8_LDB(dst, b, h) do { _Pragma("unroll") for (int n = 0; n < 2; ++n) _Pragma("unroll") for (int k = 0; k < 2; ++k) dst[n][k] = *(const LAS bf16x8*)(lds + PG8_SB(b, h) + boff + n * 2048 + k * 1024); } while (0)
; #define PG8_MMA(ai, bj, At, Bt) do { __builtin_amdgcn_s_setprio(1); _Pragma("unroll") for (int m = 0; m < 4; ++m) _Pragma("unroll") for (int n = 0; n < 2; ++n) _Pragma("unroll") for (int k = 0; k < 2; ++k) \
;         acc[ai][bj][m][n] = __builtin_amdgcn_mfma_f32_16x16x32_bf16(Bt[n][k], At[m][k], acc[ai][bj][m][n], 0, 0, 0); __builtin_amdgcn_s_setprio(0); } while (0)
; #define PG8_WAIT_V(n) asm volatile("s_waitcnt vmcnt(" #n ")" ::: "memory")
; #define PG8_WAIT_L(n) asm volatile("s_waitcnt lgkmcnt(" #n ")" ::: "memory")
; #define PG8_BAR __builtin_amdgcn_s_barrier()
; #define PG8_SCHED __builtin_amdgcn_sched_barrier(0)
; template <class Epi, class Sched>
; __device__ __forceinline__ void gemm_phase(LAS unsigned char* lds, const Gemm g, const Sched& S, const Epi& E, int wave_id) {
;     ...
;             PG8_WAIT_V(8); PG8_WAIT_L(0); PG8_BAR; PG8_MMA(0, 0, At, B0); PG8_MMA(0, 1, At, B1); PG8_BAR; PG8_SCHED;
;             PG8_LDA(At, 0, 1); PG8_STAGE(PG8_SB(0, 0), b2, voffB); PG8_STAGE(PG8_SB(0, 1), b2 + hstepB, voffB); PG8_STAGE(PG8_SA(0, 0), a2, voffA);
;             PG8_WAIT_V(8); PG8_WAIT_L(0); PG8_BAR; PG8_MMA(1, 0, At, B0); PG8_MMA(1, 1, At, B1); PG8_BAR; PG8_SCHED;
;             PG8_LDB(B0, 1, 0); PG8_LDB(B1, 1, 1); PG8_SCHED; PG8_LDA(At, 1, 0); PG8_STAGE(PG8_SA(0, 1), a2 + hstepA, voffA);
;             PG8_WAIT_V(8); PG8_WAIT_L(0); PG8_BAR; PG8_MMA(0, 0, At, B0); PG8_MMA(0, 1, At, B1); PG8_BAR; PG8_SCHED;
	s_setprio 1
	s_waitcnt lgkmcnt(0)
	v_mfma_f32_16x16x32_bf16 v[124:127], v[140:143], v[178:181], v[124:127]
	v_mfma_f32_16x16x32_bf16 v[120:123], v[148:151], v[178:181], v[120:123]
	v_mfma_f32_16x16x32_bf16 v[108:111], v[140:143], v[186:189], v[108:111]
	v_mfma_f32_16x16x32_bf16 v[104:107], v[148:151], v[186:189], v[104:107]
	v_mfma_f32_16x16x32_bf16 v[92:95], v[140:143], v[194:197], v[92:95]
	v_mfma_f32_16x16x32_bf16 v[88:91], v[148:151], v[194:197], v[88:91]
	v_mfma_f32_16x16x32_bf16 v[76:79], v[140:143], v[202:205], v[76:79]
	v_mfma_f32_16x16x32_bf16 v[72:75], v[148:151], v[202:205], v[72:75]
	v_mfma_f32_16x16x32_bf16 v[124:127], v[144:147], v[182:185], v[124:127]
	v_mfma_f32_16x16x32_bf16 v[120:123], v[152:155], v[182:185], v[120:123]
	v_mfma_f32_16x16x32_bf16 v[108:111], v[144:147], v[190:193], v[108:111]
	v_mfma_f32_16x16x32_bf16 v[104:107], v[152:155], v[190:193], v[104:107]
	v_mfma_f32_16x16x32_bf16 v[92:95], v[144:147], v[198:201], v[92:95]
	v_mfma_f32_16x16x32_bf16 v[88:91], v[152:155], v[198:201], v[88:91]
	v_mfma_f32_16x16x32_bf16 v[76:79], v[144:147], v[206:209], v[76:79]
	v_mfma_f32_16x16x32_bf16 v[72:75], v[152:155], v[206:209], v[72:75]
	s_setprio 0
	s_setprio 1
	v_mfma_f32_16x16x32_bf16 v[116:119], v[162:165], v[178:181], v[116:119]
	v_mfma_f32_16x16x32_bf16 v[112:115], v[170:173], v[178:181], v[112:115]
	v_mfma_f32_16x16x32_bf16 v[100:103], v[162:165], v[186:189], v[100:103]
	v_mfma_f32_16x16x32_bf16 v[96:99], v[170:173], v[186:189], v[96:99]
	v_mfma_f32_16x16x32_bf16 v[84:87], v[162:165], v[194:197], v[84:87]
	v_mfma_f32_16x16x32_bf16 v[80:83], v[170:173], v[194:197], v[80:83]
	v_mfma_f32_16x16x32_bf16 v[68:71], v[162:165], v[202:205], v[68:71]
	v_mfma_f32_16x16x32_bf16 v[64:67], v[170:173], v[202:205], v[64:67]
	v_mfma_f32_16x16x32_bf16 v[116:119], v[166:169], v[182:185], v[116:119]
	v_mfma_f32_16x16x32_bf16 v[112:115], v[174:177], v[182:185], v[112:115]
	v_mfma_f32_16x16x32_bf16 v[100:103], v[166:169], v[190:193], v[100:103]
	v_mfma_f32_16x16x32_bf16 v[96:99], v[174:177], v[190:193], v[96:99]
	v_mfma_f32_16x16x32_bf16 v[84:87], v[166:169], v[198:201], v[84:87]
	v_mfma_f32_16x16x32_bf16 v[80:83], v[174:177], v[198:201], v[80:83]
	v_mfma_f32_16x16x32_bf16 v[68:71], v[166:169], v[206:209], v[68:71]
	v_mfma_f32_16x16x32_bf16 v[64:67], v[174:177], v[206:209], v[64:67]
	s_setprio 0
	s_barrier
	s_add_i32 s58, s48, s39
	s_mov_b32 m0, s58
	ds_read_b128 v[178:181], v161 offset:16384
	ds_read_b128 v[182:185], v161 offset:17408
	ds_read_b128 v[186:189], v161 offset:18432
	ds_read_b128 v[190:193], v161 offset:19456
	ds_read_b128 v[194:197], v161 offset:20480
	ds_read_b128 v[198:201], v161 offset:21504
	ds_read_b128 v[202:205], v161 offset:22528
	ds_read_b128 v[206:209], v161 offset:23552
	global_load_lds_dwordx4 v130, s[34:35]
	s_add_i32 m0, s58, 0x2000
	s_add_u32 s58, s34, 0x40000
	s_addc_u32 s59, s35, 0
	s_add_i32 s60, s49, s39
	global_load_lds_dwordx4 v134, s[34:35]
	s_mov_b32 m0, s60
	s_nop 0
	global_load_lds_dwordx4 v130, s[58:59]
	s_add_i32 m0, s60, 0x2000
	s_nop 0
	global_load_lds_dwordx4 v134, s[58:59]
	s_mov_b32 m0, s27
	s_nop 0
	global_load_lds_dwordx4 v128, s[36:37]
	s_mov_b32 m0, s29
	s_nop 0
	global_load_lds_dwordx4 v132, s[36:37]
	s_waitcnt vmcnt(8)
	s_waitcnt lgkmcnt(0)
	s_barrier
	s_setprio 1
	s_waitcnt lgkmcnt(0)
	v_mfma_f32_16x16x32_bf16 v[60:63], v[140:143], v[178:181], v[60:63]
	v_mfma_f32_16x16x32_bf16 v[56:59], v[148:151], v[178:181], v[56:59]
	v_mfma_f32_16x16x32_bf16 v[44:47], v[140:143], v[186:189], v[44:47]
	v_mfma_f32_16x16x32_bf16 v[40:43], v[148:151], v[186:189], v[40:43]
	v_mfma_f32_16x16x32_bf16 v[28:31], v[140:143], v[194:197], v[28:31]
	v_mfma_f32_16x16x32_bf16 v[24:27], v[148:151], v[194:197], v[24:27]
	v_mfma_f32_16x16x32_bf16 v[12:15], v[140:143], v[202:205], v[12:15]
	v_mfma_f32_16x16x32_bf16 v[8:11], v[148:151], v[202:205], v[8:11]
	v_mfma_f32_16x16x32_bf16 v[60:63], v[144:147], v[182:185], v[60:63]
	v_mfma_f32_16x16x32_bf16 v[56:59], v[152:155], v[182:185], v[56:59]
	v_mfma_f32_16x16x32_bf16 v[44:47], v[144:147], v[190:193], v[44:47]
	v_mfma_f32_16x16x32_bf16 v[40:43], v[152:155], v[190:193], v[40:43]
	v_mfma_f32_16x16x32_bf16 v[28:31], v[144:147], v[198:201], v[28:31]
	v_mfma_f32_16x16x32_bf16 v[24:27], v[152:155], v[198:201], v[24:27]
	v_mfma_f32_16x16x32_bf16 v[12:15], v[144:147], v[206:209], v[12:15]
	v_mfma_f32_16x16x32_bf16 v[8:11], v[152:155], v[206:209], v[8:11]
	s_setprio 0
	s_setprio 1
	v_mfma_f32_16x16x32_bf16 v[52:55], v[162:165], v[178:181], v[52:55]
	v_mfma_f32_16x16x32_bf16 v[48:51], v[170:173], v[178:181], v[48:51]
	v_mfma_f32_16x16x32_bf16 v[36:39], v[162:165], v[186:189], v[36:39]
	v_mfma_f32_16x16x32_bf16 v[32:35], v[170:173], v[186:189], v[32:35]
	v_mfma_f32_16x16x32_bf16 v[20:23], v[162:165], v[194:197], v[20:23]
	v_mfma_f32_16x16x32_bf16 v[16:19], v[170:173], v[194:197], v[16:19]
	v_mfma_f32_16x16x32_bf16 v[4:7], v[162:165], v[202:205], v[4:7]
	v_mfma_f32_16x16x32_bf16 v[0:3], v[170:173], v[202:205], v[0:3]
	v_mfma_f32_16x16x32_bf16 v[52:55], v[166:169], v[182:185], v[52:55]
	v_mfma_f32_16x16x32_bf16 v[48:51], v[174:177], v[182:185], v[48:51]
	v_mfma_f32_16x16x32_bf16 v[36:39], v[166:169], v[190:193], v[36:39]
	v_mfma_f32_16x16x32_bf16 v[32:35], v[174:177], v[190:193], v[32:35]
	v_mfma_f32_16x16x32_bf16 v[20:23], v[166:169], v[198:201], v[20:23]
	v_mfma_f32_16x16x32_bf16 v[16:19], v[174:177], v[198:201], v[16:19]
	v_mfma_f32_16x16x32_bf16 v[4:7], v[166:169], v[206:209], v[4:7]
	v_mfma_f32_16x16x32_bf16 v[0:3], v[174:177], v[206:209], v[0:3]
	s_setprio 0
	s_barrier
; #define PG8_STAGE(bufoff, gbase, voff) do { _Pragma("unroll") for (int _i = 0; _i < 2; ++_i) \
;         __builtin_amdgcn_global_load_lds((const unsigned*)((const char*)(gbase) + (voff)[_i]), (LAS unsigned*)(lds + (bufoff) + ldsw + _i * 8192), 16, 0, 0); } while (0)
; #define PG8_LDA(dst, b, h) do { _Pragma("unroll") for (int m = 0; m < 4; ++m) _Pragma("unroll") for (int k = 0; k < 2; ++k) dst[m][k] = *(const LAS bf16x8*)(lds + PG8_SA(b, h) + aoff + m * 2048 + k * 1024); } while (0)
; #define PG8_LDB(dst, b, h) do { _Pragma("unroll") for (int n = 0; n < 2; ++n) _Pragma("unroll") for (int k = 0; k < 2; ++k) dst[n][k] = *(const LAS bf16x8*)(lds + PG8_SB(b, h) + boff + n * 2048 + k * 1024); } while (0)
; #define PG8_MMA(ai, bj, At, Bt) do { __builtin_amdgcn_s_setprio(1); _Pragma("unroll") for (int m = 0; m < 4; ++m) _Pragma("unroll") for (int n = 0; n < 2; ++n) _Pragma("unroll") for (int k = 0; k < 2; ++k) \
;         acc[ai][bj][m][n] = __builtin_amdgcn_mfma_f32_16x16x32_bf16(Bt[n][k], At[m][k], acc[ai][bj][m][n], 0, 0, 0); __builtin_amdgcn_s_setprio(0); } while (0)
; #define PG8_WAIT_V(n) asm volatile("s_waitcnt vmcnt(" #n ")" ::: "memory")
; #define PG8_WAIT_L(n) asm volatile("s_waitcnt lgkmcnt(" #n ")" ::: "memory")
; #define PG8_BAR __builtin_amdgcn_s_barrier()
; #define PG8_SCHED __builtin_amdgcn_sched_barrier(0)
; template <class Epi, class Sched>
; __device__ __forceinline__ void gemm_phase(LAS unsigned char* lds, const Gemm g, const Sched& S, const Epi& E, int wave_id) {
;     ...
;             PG8_LDB(B0, 1, 0); PG8_LDB(B1, 1, 1); PG8_SCHED; PG8_LDA(At, 1, 0); PG8_STAGE(PG8_SA(0, 1), a2 + hstepA, voffA);
;             PG8_WAIT_V(8); PG8_WAIT_L(0); PG8_BAR; PG8_MMA(0, 0, At, B0); PG8_MMA(0, 1, At, B1); PG8_BAR; PG8_SCHED;
;             PG8_LDA(At, 1, 1); PG8_STAGE(PG8_SB(1, 0), b3, voffB); PG8_STAGE(PG8_SB(1, 1), b3 + hstepB, voffB); PG8_STAGE(PG8_SA(1, 0), a3, voffA);
;             PG8_WAIT_V(8); PG8_WAIT_L(0); PG8_BAR; PG8_MMA(1, 0, At, B0); PG8_MMA(1, 1, At, B1); PG8_BAR; PG8_SCHED;
;         }
;         if (wr == 0) PG8_BAR;
	s_add_i32 s58, 0, 0x18000
	s_add_i32 s59, 0, 0x1c000
	v_add_u32_e32 v152, s58, v157
	v_add_u32_e32 v174, s59, v157
	ds_read_b128 v[140:143], v152
	ds_read_b128 v[144:147], v152 offset:1024
	ds_read_b128 v[148:151], v152 offset:2048
	ds_read_b128 v[152:155], v152 offset:3072
	ds_read_b128 v[162:165], v174
	ds_read_b128 v[166:169], v174 offset:1024
	ds_read_b128 v[170:173], v174 offset:2048
	ds_read_b128 v[174:177], v174 offset:3072
	s_add_u32 s36, s36, 0x40000
	s_addc_u32 s37, s37, 0
	s_mov_b32 m0, s44
	ds_read_b128 v[178:181], v161 offset:32768
	ds_read_b128 v[182:185], v161 offset:33792
	ds_read_b128 v[186:189], v161 offset:34816
	ds_read_b128 v[190:193], v161 offset:35840
	ds_read_b128 v[194:197], v161 offset:36864
	ds_read_b128 v[198:201], v161 offset:37888
	ds_read_b128 v[202:205], v161 offset:38912
	ds_read_b128 v[206:209], v161 offset:39936
	global_load_lds_dwordx4 v128, s[36:37]
	s_mov_b32 m0, s45
	s_nop 0
	global_load_lds_dwordx4 v132, s[36:37]
	s_waitcnt vmcnt(8)
	s_waitcnt lgkmcnt(0)
	s_barrier
	s_setprio 1
	s_waitcnt lgkmcnt(0)
	v_mfma_f32_16x16x32_bf16 v[124:127], v[140:143], v[178:181], v[124:127]
	v_mfma_f32_16x16x32_bf16 v[120:123], v[148:151], v[178:181], v[120:123]
	v_mfma_f32_16x16x32_bf16 v[108:111], v[140:143], v[186:189], v[108:111]
	v_mfma_f32_16x16x32_bf16 v[104:107], v[148:151], v[186:189], v[104:107]
	v_mfma_f32_16x16x32_bf16 v[92:95], v[140:143], v[194:197], v[92:95]
	v_mfma_f32_16x16x32_bf16 v[88:91], v[148:151], v[194:197], v[88:91]
	v_mfma_f32_16x16x32_bf16 v[76:79], v[140:143], v[202:205], v[76:79]
	v_mfma_f32_16x16x32_bf16 v[72:75], v[148:151], v[202:205], v[72:75]
	v_mfma_f32_16x16x32_bf16 v[124:127], v[144:147], v[182:185], v[124:127]
	v_mfma_f32_16x16x32_bf16 v[120:123], v[152:155], v[182:185], v[120:123]
	v_mfma_f32_16x16x32_bf16 v[108:111], v[144:147], v[190:193], v[108:111]
	v_mfma_f32_16x16x32_bf16 v[104:107], v[152:155], v[190:193], v[104:107]
	v_mfma_f32_16x16x32_bf16 v[92:95], v[144:147], v[198:201], v[92:95]
	v_mfma_f32_16x16x32_bf16 v[88:91], v[152:155], v[198:201], v[88:91]
	v_mfma_f32_16x16x32_bf16 v[76:79], v[144:147], v[206:209], v[76:79]
	v_mfma_f32_16x16x32_bf16 v[72:75], v[152:155], v[206:209], v[72:75]
	s_setprio 0
	s_setprio 1
	v_mfma_f32_16x16x32_bf16 v[116:119], v[162:165], v[178:181], v[116:119]
	v_mfma_f32_16x16x32_bf16 v[112:115], v[170:173], v[178:181], v[112:115]
	v_mfma_f32_16x16x32_bf16 v[100:103], v[162:165], v[186:189], v[100:103]
	v_mfma_f32_16x16x32_bf16 v[96:99], v[170:173], v[186:189], v[96:99]
	v_mfma_f32_16x16x32_bf16 v[84:87], v[162:165], v[194:197], v[84:87]
	v_mfma_f32_16x16x32_bf16 v[80:83], v[170:173], v[194:197], v[80:83]
	v_mfma_f32_16x16x32_bf16 v[68:71], v[162:165], v[202:205], v[68:71]
	v_mfma_f32_16x16x32_bf16 v[64:67], v[170:173], v[202:205], v[64:67]
	v_mfma_f32_16x16x32_bf16 v[116:119], v[166:169], v[182:185], v[116:119]
	v_mfma_f32_16x16x32_bf16 v[112:115], v[174:177], v[182:185], v[112:115]
	v_mfma_f32_16x16x32_bf16 v[100:103], v[166:169], v[190:193], v[100:103]
	v_mfma_f32_16x16x32_bf16 v[96:99], v[174:177], v[190:193], v[96:99]
	v_mfma_f32_16x16x32_bf16 v[84:87], v[166:169], v[198:201], v[84:87]
	v_mfma_f32_16x16x32_bf16 v[80:83], v[174:177], v[198:201], v[80:83]
	v_mfma_f32_16x16x32_bf16 v[68:71], v[166:169], v[206:209], v[68:71]
	v_mfma_f32_16x16x32_bf16 v[64:67], v[174:177], v[206:209], v[64:67]
	s_setprio 0
	s_barrier
	s_add_i32 s36, s58, s39
	s_mov_b32 m0, s36
	ds_read_b128 v[178:181], v161 offset:49152
	ds_read_b128 v[182:185], v161 offset:50176
	ds_read_b128 v[186:189], v161 offset:51200
	ds_read_b128 v[190:193], v161 offset:52224
	ds_read_b128 v[194:197], v161 offset:53248
	ds_read_b128 v[198:201], v161 offset:54272
	ds_read_b128 v[202:205], v161 offset:55296
	ds_read_b128 v[206:209], v161 offset:56320
	global_load_lds_dwordx4 v130, s[62:63]
	s_add_i32 m0, s36, 0x2000
	s_add_u32 s34, s34, 0x40080
	s_addc_u32 s35, s35, 0
	s_add_i32 s36, s59, s39
	global_load_lds_dwordx4 v134, s[62:63]
	s_mov_b32 m0, s36
	s_nop 0
	global_load_lds_dwordx4 v130, s[34:35]
	s_add_i32 m0, s36, 0x2000
	s_nop 0
	global_load_lds_dwordx4 v134, s[34:35]
	s_mov_b32 m0, s46
	s_nop 0
	global_load_lds_dwordx4 v128, s[64:65]
	s_mov_b32 m0, s47
	s_nop 0
	global_load_lds_dwordx4 v132, s[64:65]
	s_waitcnt vmcnt(8)
	s_waitcnt lgkmcnt(0)
	s_barrier
	s_setprio 1
	s_waitcnt lgkmcnt(0)
	v_mfma_f32_16x16x32_bf16 v[60:63], v[140:143], v[178:181], v[60:63]
	v_mfma_f32_16x16x32_bf16 v[56:59], v[148:151], v[178:181], v[56:59]
	v_mfma_f32_16x16x32_bf16 v[44:47], v[140:143], v[186:189], v[44:47]
	v_mfma_f32_16x16x32_bf16 v[40:43], v[148:151], v[186:189], v[40:43]
	v_mfma_f32_16x16x32_bf16 v[28:31], v[140:143], v[194:197], v[28:31]
	v_mfma_f32_16x16x32_bf16 v[24:27], v[148:151], v[194:197], v[24:27]
	v_mfma_f32_16x16x32_bf16 v[12:15], v[140:143], v[202:205], v[12:15]
	v_mfma_f32_16x16x32_bf16 v[8:11], v[148:151], v[202:205], v[8:11]
	v_mfma_f32_16x16x32_bf16 v[60:63], v[144:147], v[182:185], v[60:63]
	v_mfma_f32_16x16x32_bf16 v[56:59], v[152:155], v[182:185], v[56:59]
	v_mfma_f32_16x16x32_bf16 v[44:47], v[144:147], v[190:193], v[44:47]
	v_mfma_f32_16x16x32_bf16 v[40:43], v[152:155], v[190:193], v[40:43]
	v_mfma_f32_16x16x32_bf16 v[28:31], v[144:147], v[198:201], v[28:31]
	v_mfma_f32_16x16x32_bf16 v[24:27], v[152:155], v[198:201], v[24:27]
	v_mfma_f32_16x16x32_bf16 v[12:15], v[144:147], v[206:209], v[12:15]
	v_mfma_f32_16x16x32_bf16 v[8:11], v[152:155], v[206:209], v[8:11]
	s_setprio 0
	s_setprio 1
	v_mfma_f32_16x16x32_bf16 v[52:55], v[162:165], v[178:181], v[52:55]
	v_mfma_f32_16x16x32_bf16 v[48:51], v[170:173], v[178:181], v[48:51]
	v_mfma_f32_16x16x32_bf16 v[36:39], v[162:165], v[186:189], v[36:39]
	v_mfma_f32_16x16x32_bf16 v[32:35], v[170:173], v[186:189], v[32:35]
	v_mfma_f32_16x16x32_bf16 v[20:23], v[162:165], v[194:197], v[20:23]
	v_mfma_f32_16x16x32_bf16 v[16:19], v[170:173], v[194:197], v[16:19]
	v_mfma_f32_16x16x32_bf16 v[4:7], v[162:165], v[202:205], v[4:7]
	v_mfma_f32_16x16x32_bf16 v[0:3], v[170:173], v[202:205], v[0:3]
	v_mfma_f32_16x16x32_bf16 v[52:55], v[166:169], v[182:185], v[52:55]
	v_mfma_f32_16x16x32_bf16 v[48:51], v[174:177], v[182:185], v[48:51]
	v_mfma_f32_16x16x32_bf16 v[36:39], v[166:169], v[190:193], v[36:39]
	v_mfma_f32_16x16x32_bf16 v[32:35], v[174:177], v[190:193], v[32:35]
	v_mfma_f32_16x16x32_bf16 v[20:23], v[166:169], v[198:201], v[20:23]
	v_mfma_f32_16x16x32_bf16 v[16:19], v[174:177], v[198:201], v[16:19]
	v_mfma_f32_16x16x32_bf16 v[4:7], v[166:169], v[206:209], v[4:7]
	v_mfma_f32_16x16x32_bf16 v[0:3], v[174:177], v[206:209], v[0:3]
	s_setprio 0
	s_barrier
	s_add_i32 s55, s55, 2
	s_add_u32 s30, s30, 0x100
	s_addc_u32 s31, s31, 0
	s_add_u32 s53, s53, 0x100
	s_addc_u32 s54, s54, 0
	s_cmp_gt_u32 s55, 13
	s_cbranch_scc0 .LBB0_804
	s_and_b64 vcc, exec, s[10:11]
	s_cbranch_vccz .LBB0_807
	s_barrier

;     __device__ bool next(int i, Unit& u) const { if (r0 + i >= r1) return false; return base.next(r0 + i, u); }
;     __device__ bool next(int i, Unit& u) const { const int L = i * G + c; if (L >= 256) return false; u.pm = L; u.pn = L >> 3; return true; }
; #define PG8_STAGE(bufoff, gbase, voff) do { _Pragma("unroll") for (int _i = 0; _i < 2; ++_i) \
;         __builtin_amdgcn_global_load_lds((const unsigned*)((const char*)(gbase) + (voff)[_i]), (LAS unsigned*)(lds + (bufoff) + ldsw + _i * 8192), 16, 0, 0); } while (0)
; #define PG8_LDA(dst, b, h) do { _Pragma("unroll") for (int m = 0; m < 4; ++m) _Pragma("unroll") for (int k = 0; k < 2; ++k) dst[m][k] = *(const LAS bf16x8*)(lds + PG8_SA(b, h) + aoff + m * 2048 + k * 1024); } while (0)
; #define PG8_LDB(dst, b, h) do { _Pragma("unroll") for (int n = 0; n < 2; ++n) _Pragma("unroll") for (int k = 0; k < 2; ++k) dst[n][k] = *(const LAS bf16x8*)(lds + PG8_SB(b, h) + boff + n * 2048 + k * 1024); } while (0)
; #define PG8_WAIT_V(n) asm volatile("s_waitcnt vmcnt(" #n ")" ::: "memory")
; #define PG8_WAIT_L(n) asm volatile("s_waitcnt lgkmcnt(" #n ")" ::: "memory")
; template <class Epi, class Sched>
; __device__ __forceinline__ void gemm_phase(LAS unsigned char* lds, const Gemm g, const Sched& S, const Epi& E, int wave_id) {
;     ...
;         const bool has_next = S.next(ui + 1, nxt);
;         const char* nA = has_next ? (const char*)g.A + (size_t)nxt.pm * tstepA : cA; const char* nB = has_next ? (const char*)g.Bt + (size_t)nxt.pn * tstepB : cB;
;         for (int t = 0; t < nt; t += 2) {
;             const bool last = (t == nt - 2);
;             const char* a1 = cA + (size_t)(t + 1) * kstep;
;             const char* a2 = last ? nA : cA + (size_t)(t + 2) * kstep; const char* b2 = last ? nB : cB + (size_t)(t + 2) * kstep;
;             const char* a3 = a2 + kstep; const char* b3 = b2 + kstep;
;             PG8_LDB(B0, 0, 0); PG8_LDB(B1, 0, 1); PG8_SCHED; PG8_LDA(At, 0, 0); PG8_STAGE(PG8_SA(1, 1), a1 + hstepA, voffA);
;             PG8_WAIT_V(8); PG8_WAIT_L(0); PG8_BAR; PG8_MMA(0, 0, At, B0); PG8_MMA(0, 1, At, B1); PG8_BAR; PG8_SCHED;
;             PG8_LDA(At, 0, 1); PG8_STAGE(PG8_SB(0, 0), b2, voffB); PG8_STAGE(PG8_SB(0, 1), b2 + hstepB, voffB); PG8_STAGE(PG8_SA(0, 0), a2, voffA);
;             PG8_WAIT_V(8); PG8_WAIT_L(0); PG8_BAR; PG8_MMA(1, 0, At, B0); PG8_MMA(1, 1, At, B1); PG8_BAR; PG8_SCHED;
.LBB0_862:
	s_ashr_i32 s19, s18, 31
	s_andn2_b64 vcc, exec, s[36:37]
	s_lshl_b64 s[22:23], s[18:19], 19
	s_add_u32 s22, s2, s22
	s_addc_u32 s23, s3, s23
	s_and_b64 s[24:25], s[36:37], exec
	s_cselect_b32 s19, s23, s31
	s_cselect_b32 s46, s22, s30
	s_ashr_i32 s17, s16, 31
	s_lshl_b64 s[24:25], s[16:17], 19
	s_add_u32 s24, s21, s24
	s_addc_u32 s25, s33, s25
	v_cndmask_b32_e64 v0, 0, 1, s[36:37]
	s_and_b64 s[36:37], s[36:37], exec
	s_cselect_b32 s17, s25, s35
	s_cselect_b32 s47, s24, s34
	s_add_u32 s30, s30, 0x40080
	s_addc_u32 s31, s31, 0
	v_cmp_ne_u32_e64 s[4:5], 1, v0
	s_add_u32 s48, s34, 0x100
	s_addc_u32 s49, s35, 0
	s_mov_b32 s50, -2
	s_waitcnt vmcnt(0)
	ds_read_b128 v[140:143], v159
	ds_read_b128 v[144:147], v159 offset:1024
	ds_read_b128 v[148:151], v159 offset:2048
	ds_read_b128 v[152:155], v159 offset:3072
	ds_read_b128 v[162:165], v160
	ds_read_b128 v[166:169], v160 offset:1024
	ds_read_b128 v[170:173], v160 offset:2048
	ds_read_b128 v[174:177], v160 offset:3072
	s_add_u32 s34, s30, 0xfffc0080
	s_addc_u32 s35, s31, -1
	s_cmp_eq_u32 s50, 12
	s_cselect_b32 s37, s19, s35
	s_cselect_b32 s36, s46, s34
	s_cselect_b32 s35, s17, s49
	s_cselect_b32 s34, s47, s48
	s_add_u32 s58, s36, 0x80
	s_addc_u32 s59, s37, 0
	s_add_u32 s54, s34, 0x80
	s_addc_u32 s55, s35, 0
	s_add_i32 m0, s27, 0xc000
	ds_read_b128 v[178:181], v161
	ds_read_b128 v[182:185], v161 offset:1024
	ds_read_b128 v[186:189], v161 offset:2048
	ds_read_b128 v[190:193], v161 offset:3072
	ds_read_b128 v[194:197], v161 offset:4096
	ds_read_b128 v[198:201], v161 offset:5120
	ds_read_b128 v[202:205], v161 offset:6144
	ds_read_b128 v[206:209], v161 offset:7168
	global_load_lds_dwordx4 v136, s[30:31]
	s_add_i32 m0, s27, 0xe000
	s_nop 0
	global_load_lds_dwordx4 v138, s[30:31]
	s_waitcnt vmcnt(8)
	s_waitcnt lgkmcnt(0)
	s_barrier
	s_setprio 1
	s_waitcnt lgkmcnt(0)
	v_mfma_f32_16x16x32_bf16 v[124:127], v[140:143], v[178:181], 0
	v_mfma_f32_16x16x32_bf16 v[120:123], v[148:151], v[178:181], 0
	v_mfma_f32_16x16x32_bf16 v[108:111], v[140:143], v[186:189], 0
	v_mfma_f32_16x16x32_bf16 v[104:107], v[148:151], v[186:189], 0
	v_mfma_f32_16x16x32_bf16 v[92:95], v[140:143], v[194:197], 0
	v_mfma_f32_16x16x32_bf16 v[88:91], v[148:151], v[194:197], 0
	v_mfma_f32_16x16x32_bf16 v[76:79], v[140:143], v[202:205], 0
	v_mfma_f32_16x16x32_bf16 v[72:75], v[148:151], v[202:205], 0
	v_mfma_f32_16x16x32_bf16 v[124:127], v[144:147], v[182:185], v[124:127]
	v_mfma_f32_16x16x32_bf16 v[120:123], v[152:155], v[182:185], v[120:123]
	v_mfma_f32_16x16x32_bf16 v[108:111], v[144:147], v[190:193], v[108:111]
	v_mfma_f32_16x16x32_bf16 v[104:107], v[152:155], v[190:193], v[104:107]
	v_mfma_f32_16x16x32_bf16 v[92:95], v[144:147], v[198:201], v[92:95]
	v_mfma_f32_16x16x32_bf16 v[88:91], v[152:155], v[198:201], v[88:91]
	v_mfma_f32_16x16x32_bf16 v[76:79], v[144:147], v[206:209], v[76:79]
	v_mfma_f32_16x16x32_bf16 v[72:75], v[152:155], v[206:209], v[72:75]
	s_setprio 0
	s_setprio 1
	v_mfma_f32_16x16x32_bf16 v[116:119], v[162:165], v[178:181], 0
	v_mfma_f32_16x16x32_bf16 v[112:115], v[170:173], v[178:181], 0
	v_mfma_f32_16x16x32_bf16 v[100:103], v[162:165], v[186:189], 0
	v_mfma_f32_16x16x32_bf16 v[96:99], v[170:173], v[186:189], 0
	v_mfma_f32_16x16x32_bf16 v[84:87], v[162:165], v[194:197], 0
	v_mfma_f32_16x16x32_bf16 v[80:83], v[170:173], v[194:197], 0
	v_mfma_f32_16x16x32_bf16 v[68:71], v[162:165], v[202:205], 0
	v_mfma_f32_16x16x32_bf16 v[64:67], v[170:173], v[202:205], 0
	v_mfma_f32_16x16x32_bf16 v[116:119], v[166:169], v[182:185], v[116:119]
	v_mfma_f32_16x16x32_bf16 v[112:115], v[174:177], v[182:185], v[112:115]
	v_mfma_f32_16x16x32_bf16 v[100:103], v[166:169], v[190:193], v[100:103]
	v_mfma_f32_16x16x32_bf16 v[96:99], v[174:177], v[190:193], v[96:99]
	v_mfma_f32_16x16x32_bf16 v[84:87], v[166:169], v[198:201], v[84:87]
	v_mfma_f32_16x16x32_bf16 v[80:83], v[174:177], v[198:201], v[80:83]
	v_mfma_f32_16x16x32_bf16 v[68:71], v[166:169], v[206:209], v[68:71]
	v_mfma_f32_16x16x32_bf16 v[64:67], v[174:177], v[206:209], v[64:67]
	s_setprio 0
	s_barrier
	s_add_i32 s51, s43, s38
	s_mov_b32 m0, s51
	ds_read_b128 v[178:181], v161 offset:16384
	ds_read_b128 v[182:185], v161 offset:17408
	ds_read_b128 v[186:189], v161 offset:18432
	ds_read_b128 v[190:193], v161 offset:19456
	ds_read_b128 v[194:197], v161 offset:20480
	ds_read_b128 v[198:201], v161 offset:21504
	ds_read_b128 v[202:205], v161 offset:22528
	ds_read_b128 v[206:209], v161 offset:23552
	global_load_lds_dwordx4 v130, s[34:35]
	s_add_i32 m0, s51, 0x2000
	s_add_u32 s52, s34, 0x40000
	s_addc_u32 s53, s35, 0
	s_add_i32 s51, s44, s38
	global_load_lds_dwordx4 v134, s[34:35]
	s_mov_b32 m0, s51
	s_nop 0
	global_load_lds_dwordx4 v130, s[52:53]
	s_add_i32 m0, s51, 0x2000
	s_nop 0
	global_load_lds_dwordx4 v134, s[52:53]
	s_mov_b32 m0, s27
	s_nop 0
	global_load_lds_dwordx4 v128, s[36:37]
	s_mov_b32 m0, s29
	s_nop 0
	global_load_lds_dwordx4 v132, s[36:37]
	s_waitcnt vmcnt(8)
	s_waitcnt lgkmcnt(0)
	s_barrier
; #define PG8_STAGE(bufoff, gbase, voff) do { _Pragma("unroll") for (int _i = 0; _i < 2; ++_i) \
;         __builtin_amdgcn_global_load_lds((const unsigned*)((const char*)(gbase) + (voff)[_i]), (LAS unsigned*)(lds + (bufoff) + ldsw + _i * 8192), 16, 0, 0); } while (0)
; #define PG8_LDA(dst, b, h) do { _Pragma("unroll") for (int m = 0; m < 4; ++m) _Pragma("unroll") for (int k = 0; k < 2; ++k) dst[m][k] = *(const LAS bf16x8*)(lds + PG8_SA(b, h) + aoff + m * 2048 + k * 1024); } while (0)
; #define PG8_LDB(dst, b, h) do { _Pragma("unroll") for (int n = 0; n < 2; ++n) _Pragma("unroll") for (int k = 0; k < 2; ++k) dst[n][k] = *(const LAS bf16x8*)(lds + PG8_SB(b, h) + boff + n * 2048 + k * 1024); } while (0)
; #define PG8_MMA(ai, bj, At, Bt) do { __builtin_amdgcn_s_setprio(1); _Pragma("unroll") for (int m = 0; m < 4; ++m) _Pragma("unroll") for (int n = 0; n < 2; ++n) _Pragma("unroll") for (int k = 0; k < 2; ++k) \
;         acc[ai][bj][m][n] = __builtin_amdgcn_mfma_f32_16x16x32_bf16(Bt[n][k], At[m][k], acc[ai][bj][m][n], 0, 0, 0); __builtin_amdgcn_s_setprio(0); } while (0)
; #define PG8_WAIT_V(n) asm volatile("s_waitcnt vmcnt(" #n ")" ::: "memory")
; #define PG8_WAIT_L(n) asm volatile("s_waitcnt lgkmcnt(" #n ")" ::: "memory")
; #define PG8_BAR __builtin_amdgcn_s_barrier()
; #define PG8_SCHED __builtin_amdgcn_sched_barrier(0)
; template <class Epi, class Sched>
; __device__ __forceinline__ void gemm_phase(LAS unsigned char* lds, const Gemm g, const Sched& S, const Epi& E, int wave_id) {
;     ...
;             PG8_LDB(B0, 1, 0); PG8_LDB(B1, 1, 1); PG8_SCHED; PG8_LDA(At, 1, 0); PG8_STAGE(PG8_SA(0, 1), a2 + hstepA, voffA);
;             PG8_WAIT_V(8); PG8_WAIT_L(0); PG8_BAR; PG8_MMA(0, 0, At, B0); PG8_MMA(0, 1, At, B1); PG8_BAR; PG8_SCHED;
	s_setprio 1
	s_waitcnt lgkmcnt(0)
	v_mfma_f32_16x16x32_bf16 v[60:63], v[140:143], v[178:181], 0
	v_mfma_f32_16x16x32_bf16 v[56:59], v[148:151], v[178:181], 0
	v_mfma_f32_16x16x32_bf16 v[44:47], v[140:143], v[186:189], 0
	v_mfma_f32_16x16x32_bf16 v[40:43], v[148:151], v[186:189], 0
	v_mfma_f32_16x16x32_bf16 v[28:31], v[140:143], v[194:197], 0
	v_mfma_f32_16x16x32_bf16 v[24:27], v[148:151], v[194:197], 0
	v_mfma_f32_16x16x32_bf16 v[12:15], v[140:143], v[202:205], 0
	v_mfma_f32_16x16x32_bf16 v[8:11], v[148:151], v[202:205], 0
	v_mfma_f32_16x16x32_bf16 v[60:63], v[144:147], v[182:185], v[60:63]
	v_mfma_f32_16x16x32_bf16 v[56:59], v[152:155], v[182:185], v[56:59]
	v_mfma_f32_16x16x32_bf16 v[44:47], v[144:147], v[190:193], v[44:47]
	v_mfma_f32_16x16x32_bf16 v[40:43], v[152:155], v[190:193], v[40:43]
	v_mfma_f32_16x16x32_bf16 v[28:31], v[144:147], v[198:201], v[28:31]
	v_mfma_f32_16x16x32_bf16 v[24:27], v[152:155], v[198:201], v[24:27]
	v_mfma_f32_16x16x32_bf16 v[12:15], v[144:147], v[206:209], v[12:15]
	v_mfma_f32_16x16x32_bf16 v[8:11], v[152:155], v[206:209], v[8:11]
	s_setprio 0
	s_setprio 1
	v_mfma_f32_16x16x32_bf16 v[52:55], v[162:165], v[178:181], 0
	v_mfma_f32_16x16x32_bf16 v[48:51], v[170:173], v[178:181], 0
	v_mfma_f32_16x16x32_bf16 v[36:39], v[162:165], v[186:189], 0
	v_mfma_f32_16x16x32_bf16 v[32:35], v[170:173], v[186:189], 0
	v_mfma_f32_16x16x32_bf16 v[20:23], v[162:165], v[194:197], 0
	v_mfma_f32_16x16x32_bf16 v[16:19], v[170:173], v[194:197], 0
	v_mfma_f32_16x16x32_bf16 v[4:7], v[162:165], v[202:205], 0
	v_mfma_f32_16x16x32_bf16 v[0:3], v[170:173], v[202:205], 0
	v_mfma_f32_16x16x32_bf16 v[52:55], v[166:169], v[182:185], v[52:55]
	v_mfma_f32_16x16x32_bf16 v[48:51], v[174:177], v[182:185], v[48:51]
	v_mfma_f32_16x16x32_bf16 v[36:39], v[166:169], v[190:193], v[36:39]
	v_mfma_f32_16x16x32_bf16 v[32:35], v[174:177], v[190:193], v[32:35]
	v_mfma_f32_16x16x32_bf16 v[20:23], v[166:169], v[198:201], v[20:23]
	v_mfma_f32_16x16x32_bf16 v[16:19], v[174:177], v[198:201], v[16:19]
	v_mfma_f32_16x16x32_bf16 v[4:7], v[166:169], v[206:209], v[4:7]
	v_mfma_f32_16x16x32_bf16 v[0:3], v[174:177], v[206:209], v[0:3]
	s_setprio 0
	s_barrier
	s_add_i32 s51, 0, 0x18000
	s_add_i32 s52, 0, 0x1c000
	v_add_u32_e32 v152, s51, v157
	v_add_u32_e32 v174, s52, v157
	ds_read_b128 v[140:143], v152
	ds_read_b128 v[144:147], v152 offset:1024
	ds_read_b128 v[148:151], v152 offset:2048
	ds_read_b128 v[152:155], v152 offset:3072
	ds_read_b128 v[162:165], v174
	ds_read_b128 v[166:169], v174 offset:1024
	ds_read_b128 v[170:173], v174 offset:2048
	ds_read_b128 v[174:177], v174 offset:3072
	s_add_u32 s36, s36, 0x40000
	s_addc_u32 s37, s37, 0
	s_mov_b32 m0, s39
	ds_read_b128 v[178:181], v161 offset:32768
	ds_read_b128 v[182:185], v161 offset:33792
	ds_read_b128 v[186:189], v161 offset:34816
	ds_read_b128 v[190:193], v161 offset:35840
	ds_read_b128 v[194:197], v161 offset:36864
	ds_read_b128 v[198:201], v161 offset:37888
	ds_read_b128 v[202:205], v161 offset:38912
	ds_read_b128 v[206:209], v161 offset:39936
	global_load_lds_dwordx4 v128, s[36:37]
	s_mov_b32 m0, s40
	s_nop 0
	global_load_lds_dwordx4 v132, s[36:37]
	s_waitcnt vmcnt(8)
	s_waitcnt lgkmcnt(0)
	s_barrier
	s_setprio 1
	s_waitcnt lgkmcnt(0)
	v_mfma_f32_16x16x32_bf16 v[124:127], v[140:143], v[178:181], v[124:127]
	v_mfma_f32_16x16x32_bf16 v[120:123], v[148:151], v[178:181], v[120:123]
	v_mfma_f32_16x16x32_bf16 v[108:111], v[140:143], v[186:189], v[108:111]
	v_mfma_f32_16x16x32_bf16 v[104:107], v[148:151], v[186:189], v[104:107]
	v_mfma_f32_16x16x32_bf16 v[92:95], v[140:143], v[194:197], v[92:95]
	v_mfma_f32_16x16x32_bf16 v[88:91], v[148:151], v[194:197], v[88:91]
	v_mfma_f32_16x16x32_bf16 v[76:79], v[140:143], v[202:205], v[76:79]
	v_mfma_f32_16x16x32_bf16 v[72:75], v[148:151], v[202:205], v[72:75]
	v_mfma_f32_16x16x32_bf16 v[124:127], v[144:147], v[182:185], v[124:127]
	v_mfma_f32_16x16x32_bf16 v[120:123], v[152:155], v[182:185], v[120:123]
	v_mfma_f32_16x16x32_bf16 v[108:111], v[144:147], v[190:193], v[108:111]
	v_mfma_f32_16x16x32_bf16 v[104:107], v[152:155], v[190:193], v[104:107]
	v_mfma_f32_16x16x32_bf16 v[92:95], v[144:147], v[198:201], v[92:95]
	v_mfma_f32_16x16x32_bf16 v[88:91], v[152:155], v[198:201], v[88:91]
	v_mfma_f32_16x16x32_bf16 v[76:79], v[144:147], v[206:209], v[76:79]
	v_mfma_f32_16x16x32_bf16 v[72:75], v[152:155], v[206:209], v[72:75]
	s_setprio 0
	s_setprio 1
	v_mfma_f32_16x16x32_bf16 v[116:119], v[162:165], v[178:181], v[116:119]
	v_mfma_f32_16x16x32_bf16 v[112:115], v[170:173], v[178:181], v[112:115]
	v_mfma_f32_16x16x32_bf16 v[100:103], v[162:165], v[186:189], v[100:103]
	v_mfma_f32_16x16x32_bf16 v[96:99], v[170:173], v[186:189], v[96:99]
	v_mfma_f32_16x16x32_bf16 v[84:87], v[162:165], v[194:197], v[84:87]
	v_mfma_f32_16x16x32_bf16 v[80:83], v[170:173], v[194:197], v[80:83]
	v_mfma_f32_16x16x32_bf16 v[68:71], v[162:165], v[202:205], v[68:71]
	v_mfma_f32_16x16x32_bf16 v[64:67], v[170:173], v[202:205], v[64:67]
	v_mfma_f32_16x16x32_bf16 v[116:119], v[166:169], v[182:185], v[116:119]
	v_mfma_f32_16x16x32_bf16 v[112:115], v[174:177], v[182:185], v[112:115]
	v_mfma_f32_16x16x32_bf16 v[100:103], v[166:169], v[190:193], v[100:103]
	v_mfma_f32_16x16x32_bf16 v[96:99], v[174:177], v[190:193], v[96:99]
	v_mfma_f32_16x16x32_bf16 v[84:87], v[166:169], v[198:201], v[84:87]
	v_mfma_f32_16x16x32_bf16 v[80:83], v[174:177], v[198:201], v[80:83]
	v_mfma_f32_16x16x32_bf16 v[68:71], v[166:169], v[206:209], v[68:71]
	v_mfma_f32_16x16x32_bf16 v[64:67], v[174:177], v[206:209], v[64:67]
	s_setprio 0
	s_barrier
; #define PG8_STAGE(bufoff, gbase, voff) do { _Pragma("unroll") for (int _i = 0; _i < 2; ++_i) \
;         __builtin_amdgcn_global_load_lds((const unsigned*)((const char*)(gbase) + (voff)[_i]), (LAS unsigned*)(lds + (bufoff) + ldsw + _i * 8192), 16, 0, 0); } while (0)
; #define PG8_LDA(dst, b, h) do { _Pragma("unroll") for (int m = 0; m < 4; ++m) _Pragma("unroll") for (int k = 0; k < 2; ++k) dst[m][k] = *(const LAS bf16x8*)(lds + PG8_SA(b, h) + aoff + m * 2048 + k * 1024); } while (0)
; #define PG8_LDB(dst, b, h) do { _Pragma("unroll") for (int n = 0; n < 2; ++n) _Pragma("unroll") for (int k = 0; k < 2; ++k) dst[n][k] = *(const LAS bf16x8*)(lds + PG8_SB(b, h) + boff + n * 2048 + k * 1024); } while (0)
; #define PG8_WAIT_V(n) asm volatile("s_waitcnt vmcnt(" #n ")" ::: "memory")
; #define PG8_BAR __builtin_amdgcn_s_barrier()
; template <class Epi, class Sched>
; __device__ __forceinline__ void gemm_phase(LAS unsigned char* lds, const Gemm g, const Sched& S, const Epi& E, int wave_id) {
;     ...
;         for (int t = 0; t < nt; t += 2) {
;             const bool last = (t == nt - 2);
;             const char* a1 = cA + (size_t)(t + 1) * kstep;
;             const char* a2 = last ? nA : cA + (size_t)(t + 2) * kstep; const char* b2 = last ? nB : cB + (size_t)(t + 2) * kstep;
;             const char* a3 = a2 + kstep; const char* b3 = b2 + kstep;
;             PG8_LDB(B0, 0, 0); PG8_LDB(B1, 0, 1); PG8_SCHED; PG8_LDA(At, 0, 0); PG8_STAGE(PG8_SA(1, 1), a1 + hstepA, voffA);
;             PG8_WAIT_V(8); PG8_WAIT_L(0); PG8_BAR; PG8_MMA(0, 0, At, B0); PG8_MMA(0, 1, At, B1); PG8_BAR; PG8_SCHED;
;             PG8_LDA(At, 0, 1); PG8_STAGE(PG8_SB(0, 0), b2, voffB); PG8_STAGE(PG8_SB(0, 1), b2 + hstepB, voffB); PG8_STAGE(PG8_SA(0, 0), a2, voffA);
;             PG8_WAIT_V(8); PG8_WAIT_L(0); PG8_BAR; PG8_MMA(1, 0, At, B0); PG8_MMA(1, 1, At, B1); PG8_BAR; PG8_SCHED;
;             PG8_LDB(B0, 1, 0); PG8_LDB(B1, 1, 1); PG8_SCHED; PG8_LDA(At, 1, 0); PG8_STAGE(PG8_SA(0, 1), a2 + hstepA, voffA);
;             PG8_WAIT_V(8); PG8_WAIT_L(0); PG8_BAR; PG8_MMA(0, 0, At, B0); PG8_MMA(0, 1, At, B1); PG8_BAR; PG8_SCHED;
;             PG8_LDA(At, 1, 1); PG8_STAGE(PG8_SB(1, 0), b3, voffB); PG8_STAGE(PG8_SB(1, 1), b3 + hstepB, voffB); PG8_STAGE(PG8_SA(1, 0), a3, voffA);
;             PG8_WAIT_V(8); PG8_WAIT_L(0); PG8_BAR; PG8_MMA(1, 0, At, B0); PG8_MMA(1, 1, At, B1); PG8_BAR; PG8_SCHED;
	s_add_i32 s36, s51, s38
	s_mov_b32 m0, s36
	ds_read_b128 v[178:181], v161 offset:49152
	ds_read_b128 v[182:185], v161 offset:50176
	ds_read_b128 v[186:189], v161 offset:51200
	ds_read_b128 v[190:193], v161 offset:52224
	ds_read_b128 v[194:197], v161 offset:53248
	ds_read_b128 v[198:201], v161 offset:54272
	ds_read_b128 v[202:205], v161 offset:55296
	ds_read_b128 v[206:209], v161 offset:56320
	global_load_lds_dwordx4 v130, s[54:55]
	s_add_i32 m0, s36, 0x2000
	s_add_u32 s34, s34, 0x40080
	s_addc_u32 s35, s35, 0
	s_add_i32 s36, s52, s38
	global_load_lds_dwordx4 v134, s[54:55]
	s_mov_b32 m0, s36
	s_nop 0
	global_load_lds_dwordx4 v130, s[34:35]
	s_add_i32 m0, s36, 0x2000
	s_nop 0
	global_load_lds_dwordx4 v134, s[34:35]
	s_mov_b32 m0, s41
	s_nop 0
	global_load_lds_dwordx4 v128, s[58:59]
	s_mov_b32 m0, s42
	s_nop 0
	global_load_lds_dwordx4 v132, s[58:59]
	s_waitcnt vmcnt(8)
	s_waitcnt lgkmcnt(0)
	s_barrier
	s_setprio 1
	s_waitcnt lgkmcnt(0)
	v_mfma_f32_16x16x32_bf16 v[60:63], v[140:143], v[178:181], v[60:63]
	v_mfma_f32_16x16x32_bf16 v[56:59], v[148:151], v[178:181], v[56:59]
	v_mfma_f32_16x16x32_bf16 v[44:47], v[140:143], v[186:189], v[44:47]
	v_mfma_f32_16x16x32_bf16 v[40:43], v[148:151], v[186:189], v[40:43]
	v_mfma_f32_16x16x32_bf16 v[28:31], v[140:143], v[194:197], v[28:31]
	v_mfma_f32_16x16x32_bf16 v[24:27], v[148:151], v[194:197], v[24:27]
	v_mfma_f32_16x16x32_bf16 v[12:15], v[140:143], v[202:205], v[12:15]
	v_mfma_f32_16x16x32_bf16 v[8:11], v[148:151], v[202:205], v[8:11]
	v_mfma_f32_16x16x32_bf16 v[60:63], v[144:147], v[182:185], v[60:63]
	v_mfma_f32_16x16x32_bf16 v[56:59], v[152:155], v[182:185], v[56:59]
	v_mfma_f32_16x16x32_bf16 v[44:47], v[144:147], v[190:193], v[44:47]
	v_mfma_f32_16x16x32_bf16 v[40:43], v[152:155], v[190:193], v[40:43]
	v_mfma_f32_16x16x32_bf16 v[28:31], v[144:147], v[198:201], v[28:31]
	v_mfma_f32_16x16x32_bf16 v[24:27], v[152:155], v[198:201], v[24:27]
	v_mfma_f32_16x16x32_bf16 v[12:15], v[144:147], v[206:209], v[12:15]
	v_mfma_f32_16x16x32_bf16 v[8:11], v[152:155], v[206:209], v[8:11]
	s_setprio 0
	s_setprio 1
	v_mfma_f32_16x16x32_bf16 v[52:55], v[162:165], v[178:181], v[52:55]
	v_mfma_f32_16x16x32_bf16 v[48:51], v[170:173], v[178:181], v[48:51]
	v_mfma_f32_16x16x32_bf16 v[36:39], v[162:165], v[186:189], v[36:39]
	v_mfma_f32_16x16x32_bf16 v[32:35], v[170:173], v[186:189], v[32:35]
	v_mfma_f32_16x16x32_bf16 v[20:23], v[162:165], v[194:197], v[20:23]
	v_mfma_f32_16x16x32_bf16 v[16:19], v[170:173], v[194:197], v[16:19]
	v_mfma_f32_16x16x32_bf16 v[4:7], v[162:165], v[202:205], v[4:7]
	v_mfma_f32_16x16x32_bf16 v[0:3], v[170:173], v[202:205], v[0:3]
	v_mfma_f32_16x16x32_bf16 v[52:55], v[166:169], v[182:185], v[52:55]
	v_mfma_f32_16x16x32_bf16 v[48:51], v[174:177], v[182:185], v[48:51]
	v_mfma_f32_16x16x32_bf16 v[36:39], v[166:169], v[190:193], v[36:39]
	v_mfma_f32_16x16x32_bf16 v[32:35], v[174:177], v[190:193], v[32:35]
	v_mfma_f32_16x16x32_bf16 v[20:23], v[166:169], v[198:201], v[20:23]
	v_mfma_f32_16x16x32_bf16 v[16:19], v[174:177], v[198:201], v[16:19]
	v_mfma_f32_16x16x32_bf16 v[4:7], v[166:169], v[206:209], v[4:7]
	v_mfma_f32_16x16x32_bf16 v[0:3], v[174:177], v[206:209], v[0:3]
	s_setprio 0
	s_barrier
	s_add_i32 s50, s50, 2
	s_add_u32 s30, s30, 0x100
	s_addc_u32 s31, s31, 0
	s_add_u32 s48, s48, 0x100
	s_addc_u32 s49, s49, 0
	s_cmp_gt_u32 s50, 13
.LBB0_863:
	ds_read_b128 v[140:143], v159
	ds_read_b128 v[144:147], v159 offset:1024
	ds_read_b128 v[148:151], v159 offset:2048
	ds_read_b128 v[152:155], v159 offset:3072
	ds_read_b128 v[162:165], v160
	ds_read_b128 v[166:169], v160 offset:1024
	ds_read_b128 v[170:173], v160 offset:2048
	ds_read_b128 v[174:177], v160 offset:3072
	s_add_u32 s34, s30, 0xfffc0080
	s_addc_u32 s35, s31, -1
	s_cmp_eq_u32 s50, 12
	s_cselect_b32 s37, s19, s35
	s_cselect_b32 s36, s46, s34
	s_cselect_b32 s35, s17, s49
	s_cselect_b32 s34, s47, s48
	s_add_u32 s58, s36, 0x80
	s_addc_u32 s59, s37, 0
	s_add_u32 s54, s34, 0x80
	s_addc_u32 s55, s35, 0
	s_add_i32 m0, s27, 0xc000
	ds_read_b128 v[178:181], v161
	ds_read_b128 v[182:185], v161 offset:1024
	ds_read_b128 v[186:189], v161 offset:2048
	ds_read_b128 v[190:193], v161 offset:3072
	ds_read_b128 v[194:197], v161 offset:4096
	ds_read_b128 v[198:201], v161 offset:5120
	ds_read_b128 v[202:205], v161 offset:6144
	ds_read_b128 v[206:209], v161 offset:7168
	global_load_lds_dwordx4 v136, s[30:31]
	s_add_i32 m0, s27, 0xe000
	s_nop 0
	global_load_lds_dwordx4 v138, s[30:31]
	s_waitcnt vmcnt(8)
	s_waitcnt lgkmcnt(0)
	s_barrier
; #define PG8_STAGE(bufoff, gbase, voff) do { _Pragma("unroll") for (int _i = 0; _i < 2; ++_i) \
;         __builtin_amdgcn_global_load_lds((const unsigned*)((const char*)(gbase) + (voff)[_i]), (LAS unsigned*)(lds + (bufoff) + ldsw + _i * 8192), 16, 0, 0); } while (0)
; #define PG8_LDA(dst, b, h) do { _Pragma("unroll") for (int m = 0; m < 4; ++m) _Pragma("unroll") for (int k = 0; k < 2; ++k) dst[m][k] = *(const LAS bf16x8*)(lds + PG8_SA(b, h) + aoff + m * 2048 + k * 1024); } while (0)
; #define PG8_LDB(dst, b, h) do { _Pragma("unroll") for (int n = 0; n < 2; ++n) _Pragma("unroll") for (int k = 0; k < 2; ++k) dst[n][k] = *(const LAS bf16x8*)(lds + PG8_SB(b, h) + boff + n * 2048 + k * 1024); } while (0)
; #define PG8_MMA(ai, bj, At, Bt) do { __builtin_amdgcn_s_setprio(1); _Pragma("unroll") for (int m = 0; m < 4; ++m) _Pragma("unroll") for (int n = 0; n < 2; ++n) _Pragma("unroll") for (int k = 0; k < 2; ++k) \
;         acc[ai][bj][m][n] = __builtin_amdgcn_mfma_f32_16x16x32_bf16(Bt[n][k], At[m][k], acc[ai][bj][m][n], 0, 0, 0); __builtin_amdgcn_s_setprio(0); } while (0)
; #define PG8_WAIT_V(n) asm volatile("s_waitcnt vmcnt(" #n ")" ::: "memory")
; #define PG8_WAIT_L(n) asm volatile("s_waitcnt lgkmcnt(" #n ")" ::: "memory")
; #define PG8_BAR __builtin_amdgcn_s_barrier()
; #define PG8_SCHED __builtin_amdgcn_sched_barrier(0)
; template <class Epi, class Sched>
; __device__ __forceinline__ void gemm_phase(LAS unsigned char* lds, const Gemm g, const Sched& S, const Epi& E, int wave_id) {
;     ...
;             PG8_WAIT_V(8); PG8_WAIT_L(0); PG8_BAR; PG8_MMA(0, 0, At, B0); PG8_MMA(0, 1, At, B1); PG8_BAR; PG8_SCHED;
;             PG8_LDA(At, 0, 1); PG8_STAGE(PG8_SB(0, 0), b2, voffB); PG8_STAGE(PG8_SB(0, 1), b2 + hstepB, voffB); PG8_STAGE(PG8_SA(0, 0), a2, voffA);
;             PG8_WAIT_V(8); PG8_WAIT_L(0); PG8_BAR; PG8_MMA(1, 0, At, B0); PG8_MMA(1, 1, At, B1); PG8_BAR; PG8_SCHED;
;             PG8_LDB(B0, 1, 0); PG8_LDB(B1, 1, 1); PG8_SCHED; PG8_LDA(At, 1, 0); PG8_STAGE(PG8_SA(0, 1), a2 + hstepA, voffA);
;             PG8_WAIT_V(8); PG8_WAIT_L(0); PG8_BAR; PG8_MMA(0, 0, At, B0); PG8_MMA(0, 1, At, B1); PG8_BAR; PG8_SCHED;
	s_setprio 1
	s_waitcnt lgkmcnt(0)
	v_mfma_f32_16x16x32_bf16 v[124:127], v[140:143], v[178:181], v[124:127]
	v_mfma_f32_16x16x32_bf16 v[120:123], v[148:151], v[178:181], v[120:123]
	v_mfma_f32_16x16x32_bf16 v[108:111], v[140:143], v[186:189], v[108:111]
	v_mfma_f32_16x16x32_bf16 v[104:107], v[148:151], v[186:189], v[104:107]
	v_mfma_f32_16x16x32_bf16 v[92:95], v[140:143], v[194:197], v[92:95]
	v_mfma_f32_16x16x32_bf16 v[88:91], v[148:151], v[194:197], v[88:91]
	v_mfma_f32_16x16x32_bf16 v[76:79], v[140:143], v[202:205], v[76:79]
	v_mfma_f32_16x16x32_bf16 v[72:75], v[148:151], v[202:205], v[72:75]
	v_mfma_f32_16x16x32_bf16 v[124:127], v[144:147], v[182:185], v[124:127]
	v_mfma_f32_16x16x32_bf16 v[120:123], v[152:155], v[182:185], v[120:123]
	v_mfma_f32_16x16x32_bf16 v[108:111], v[144:147], v[190:193], v[108:111]
	v_mfma_f32_16x16x32_bf16 v[104:107], v[152:155], v[190:193], v[104:107]
	v_mfma_f32_16x16x32_bf16 v[92:95], v[144:147], v[198:201], v[92:95]
	v_mfma_f32_16x16x32_bf16 v[88:91], v[152:155], v[198:201], v[88:91]
	v_mfma_f32_16x16x32_bf16 v[76:79], v[144:147], v[206:209], v[76:79]
	v_mfma_f32_16x16x32_bf16 v[72:75], v[152:155], v[206:209], v[72:75]
	s_setprio 0
	s_setprio 1
	v_mfma_f32_16x16x32_bf16 v[116:119], v[162:165], v[178:181], v[116:119]
	v_mfma_f32_16x16x32_bf16 v[112:115], v[170:173], v[178:181], v[112:115]
	v_mfma_f32_16x16x32_bf16 v[100:103], v[162:165], v[186:189], v[100:103]
	v_mfma_f32_16x16x32_bf16 v[96:99], v[170:173], v[186:189], v[96:99]
	v_mfma_f32_16x16x32_bf16 v[84:87], v[162:165], v[194:197], v[84:87]
	v_mfma_f32_16x16x32_bf16 v[80:83], v[170:173], v[194:197], v[80:83]
	v_mfma_f32_16x16x32_bf16 v[68:71], v[162:165], v[202:205], v[68:71]
	v_mfma_f32_16x16x32_bf16 v[64:67], v[170:173], v[202:205], v[64:67]
	v_mfma_f32_16x16x32_bf16 v[116:119], v[166:169], v[182:185], v[116:119]
	v_mfma_f32_16x16x32_bf16 v[112:115], v[174:177], v[182:185], v[112:115]
	v_mfma_f32_16x16x32_bf16 v[100:103], v[166:169], v[190:193], v[100:103]
	v_mfma_f32_16x16x32_bf16 v[96:99], v[174:177], v[190:193], v[96:99]
	v_mfma_f32_16x16x32_bf16 v[84:87], v[166:169], v[198:201], v[84:87]
	v_mfma_f32_16x16x32_bf16 v[80:83], v[174:177], v[198:201], v[80:83]
	v_mfma_f32_16x16x32_bf16 v[68:71], v[166:169], v[206:209], v[68:71]
	v_mfma_f32_16x16x32_bf16 v[64:67], v[174:177], v[206:209], v[64:67]
	s_setprio 0
	s_barrier
	s_add_i32 s51, s43, s38
	s_mov_b32 m0, s51
	ds_read_b128 v[178:181], v161 offset:16384
	ds_read_b128 v[182:185], v161 offset:17408
	ds_read_b128 v[186:189], v161 offset:18432
	ds_read_b128 v[190:193], v161 offset:19456
	ds_read_b128 v[194:197], v161 offset:20480
	ds_read_b128 v[198:201], v161 offset:21504
	ds_read_b128 v[202:205], v161 offset:22528
	ds_read_b128 v[206:209], v161 offset:23552
	global_load_lds_dwordx4 v130, s[34:35]
	s_add_i32 m0, s51, 0x2000
	s_add_u32 s52, s34, 0x40000
	s_addc_u32 s53, s35, 0
	s_add_i32 s51, s44, s38
	global_load_lds_dwordx4 v134, s[34:35]
	s_mov_b32 m0, s51
	s_nop 0
	global_load_lds_dwordx4 v130, s[52:53]
	s_add_i32 m0, s51, 0x2000
	s_nop 0
	global_load_lds_dwordx4 v134, s[52:53]
	s_mov_b32 m0, s27
	s_nop 0
	global_load_lds_dwordx4 v128, s[36:37]
	s_mov_b32 m0, s29
	s_nop 0
	global_load_lds_dwordx4 v132, s[36:37]
	s_waitcnt vmcnt(8)
	s_waitcnt lgkmcnt(0)
	s_barrier
	s_setprio 1
	s_waitcnt lgkmcnt(0)
	v_mfma_f32_16x16x32_bf16 v[60:63], v[140:143], v[178:181], v[60:63]
	v_mfma_f32_16x16x32_bf16 v[56:59], v[148:151], v[178:181], v[56:59]
	v_mfma_f32_16x16x32_bf16 v[44:47], v[140:143], v[186:189], v[44:47]
	v_mfma_f32_16x16x32_bf16 v[40:43], v[148:151], v[186:189], v[40:43]
	v_mfma_f32_16x16x32_bf16 v[28:31], v[140:143], v[194:197], v[28:31]
	v_mfma_f32_16x16x32_bf16 v[24:27], v[148:151], v[194:197], v[24:27]
	v_mfma_f32_16x16x32_bf16 v[12:15], v[140:143], v[202:205], v[12:15]
	v_mfma_f32_16x16x32_bf16 v[8:11], v[148:151], v[202:205], v[8:11]
	v_mfma_f32_16x16x32_bf16 v[60:63], v[144:147], v[182:185], v[60:63]
	v_mfma_f32_16x16x32_bf16 v[56:59], v[152:155], v[182:185], v[56:59]
	v_mfma_f32_16x16x32_bf16 v[44:47], v[144:147], v[190:193], v[44:47]
	v_mfma_f32_16x16x32_bf16 v[40:43], v[152:155], v[190:193], v[40:43]
	v_mfma_f32_16x16x32_bf16 v[28:31], v[144:147], v[198:201], v[28:31]
	v_mfma_f32_16x16x32_bf16 v[24:27], v[152:155], v[198:201], v[24:27]
	v_mfma_f32_16x16x32_bf16 v[12:15], v[144:147], v[206:209], v[12:15]
	v_mfma_f32_16x16x32_bf16 v[8:11], v[152:155], v[206:209], v[8:11]
	s_setprio 0
	s_setprio 1
	v_mfma_f32_16x16x32_bf16 v[52:55], v[162:165], v[178:181], v[52:55]
	v_mfma_f32_16x16x32_bf16 v[48:51], v[170:173], v[178:181], v[48:51]
	v_mfma_f32_16x16x32_bf16 v[36:39], v[162:165], v[186:189], v[36:39]
	v_mfma_f32_16x16x32_bf16 v[32:35], v[170:173], v[186:189], v[32:35]
	v_mfma_f32_16x16x32_bf16 v[20:23], v[162:165], v[194:197], v[20:23]
	v_mfma_f32_16x16x32_bf16 v[16:19], v[170:173], v[194:197], v[16:19]
	v_mfma_f32_16x16x32_bf16 v[4:7], v[162:165], v[202:205], v[4:7]
	v_mfma_f32_16x16x32_bf16 v[0:3], v[170:173], v[202:205], v[0:3]
	v_mfma_f32_16x16x32_bf16 v[52:55], v[166:169], v[182:185], v[52:55]
	v_mfma_f32_16x16x32_bf16 v[48:51], v[174:177], v[182:185], v[48:51]
	v_mfma_f32_16x16x32_bf16 v[36:39], v[166:169], v[190:193], v[36:39]
	v_mfma_f32_16x16x32_bf16 v[32:35], v[174:177], v[190:193], v[32:35]
	v_mfma_f32_16x16x32_bf16 v[20:23], v[166:169], v[198:201], v[20:23]
	v_mfma_f32_16x16x32_bf16 v[16:19], v[174:177], v[198:201], v[16:19]
	v_mfma_f32_16x16x32_bf16 v[4:7], v[166:169], v[206:209], v[4:7]
	v_mfma_f32_16x16x32_bf16 v[0:3], v[174:177], v[206:209], v[0:3]
	s_setprio 0
	s_barrier
; #define PG8_STAGE(bufoff, gbase, voff) do { _Pragma("unroll") for (int _i = 0; _i < 2; ++_i) \
;         __builtin_amdgcn_global_load_lds((const unsigned*)((const char*)(gbase) + (voff)[_i]), (LAS unsigned*)(lds + (bufoff) + ldsw + _i * 8192), 16, 0, 0); } while (0)
; #define PG8_LDA(dst, b, h) do { _Pragma("unroll") for (int m = 0; m < 4; ++m) _Pragma("unroll") for (int k = 0; k < 2; ++k) dst[m][k] = *(const LAS bf16x8*)(lds + PG8_SA(b, h) + aoff + m * 2048 + k * 1024); } while (0)
; #define PG8_LDB(dst, b, h) do { _Pragma("unroll") for (int n = 0; n < 2; ++n) _Pragma("unroll") for (int k = 0; k < 2; ++k) dst[n][k] = *(const LAS bf16x8*)(lds + PG8_SB(b, h) + boff + n * 2048 + k * 1024); } while (0)
; #define PG8_MMA(ai, bj, At, Bt) do { __builtin_amdgcn_s_setprio(1); _Pragma("unroll") for (int m = 0; m < 4; ++m) _Pragma("unroll") for (int n = 0; n < 2; ++n) _Pragma("unroll") for (int k = 0; k < 2; ++k) \
;         acc[ai][bj][m][n] = __builtin_amdgcn_mfma_f32_16x16x32_bf16(Bt[n][k], At[m][k], acc[ai][bj][m][n], 0, 0, 0); __builtin_amdgcn_s_setprio(0); } while (0)
; #define PG8_WAIT_V(n) asm volatile("s_waitcnt vmcnt(" #n ")" ::: "memory")
; #define PG8_WAIT_L(n) asm volatile("s_waitcnt lgkmcnt(" #n ")" ::: "memory")
; #define PG8_BAR __builtin_amdgcn_s_barrier()
; #define PG8_SCHED __builtin_amdgcn_sched_barrier(0)
; template <class Epi, class Sched>
; __device__ __forceinline__ void gemm_phase(LAS unsigned char* lds, const Gemm g, const Sched& S, const Epi& E, int wave_id) {
;     ...
;             PG8_LDB(B0, 1, 0); PG8_LDB(B1, 1, 1); PG8_SCHED; PG8_LDA(At, 1, 0); PG8_STAGE(PG8_SA(0, 1), a2 + hstepA, voffA);
;             PG8_WAIT_V(8); PG8_WAIT_L(0); PG8_BAR; PG8_MMA(0, 0, At, B0); PG8_MMA(0, 1, At, B1); PG8_BAR; PG8_SCHED;
;             PG8_LDA(At, 1, 1); PG8_STAGE(PG8_SB(1, 0), b3, voffB); PG8_STAGE(PG8_SB(1, 1), b3 + hstepB, voffB); PG8_STAGE(PG8_SA(1, 0), a3, voffA);
;             PG8_WAIT_V(8); PG8_WAIT_L(0); PG8_BAR; PG8_MMA(1, 0, At, B0); PG8_MMA(1, 1, At, B1); PG8_BAR; PG8_SCHED;
;         }
;         if (wr == 0) PG8_BAR;
	s_add_i32 s51, 0, 0x18000
	s_add_i32 s52, 0, 0x1c000
	v_add_u32_e32 v152, s51, v157
	v_add_u32_e32 v174, s52, v157
	ds_read_b128 v[140:143], v152
	ds_read_b128 v[144:147], v152 offset:1024
	ds_read_b128 v[148:151], v152 offset:2048
	ds_read_b128 v[152:155], v152 offset:3072
	ds_read_b128 v[162:165], v174
	ds_read_b128 v[166:169], v174 offset:1024
	ds_read_b128 v[170:173], v174 offset:2048
	ds_read_b128 v[174:177], v174 offset:3072
	s_add_u32 s36, s36, 0x40000
	s_addc_u32 s37, s37, 0
	s_mov_b32 m0, s39
	ds_read_b128 v[178:181], v161 offset:32768
	ds_read_b128 v[182:185], v161 offset:33792
	ds_read_b128 v[186:189], v161 offset:34816
	ds_read_b128 v[190:193], v161 offset:35840
	ds_read_b128 v[194:197], v161 offset:36864
	ds_read_b128 v[198:201], v161 offset:37888
	ds_read_b128 v[202:205], v161 offset:38912
	ds_read_b128 v[206:209], v161 offset:39936
	global_load_lds_dwordx4 v128, s[36:37]
	s_mov_b32 m0, s40
	s_nop 0
	global_load_lds_dwordx4 v132, s[36:37]
	s_waitcnt vmcnt(8)
	s_waitcnt lgkmcnt(0)
	s_barrier
	s_setprio 1
	s_waitcnt lgkmcnt(0)
	v_mfma_f32_16x16x32_bf16 v[124:127], v[140:143], v[178:181], v[124:127]
	v_mfma_f32_16x16x32_bf16 v[120:123], v[148:151], v[178:181], v[120:123]
	v_mfma_f32_16x16x32_bf16 v[108:111], v[140:143], v[186:189], v[108:111]
	v_mfma_f32_16x16x32_bf16 v[104:107], v[148:151], v[186:189], v[104:107]
	v_mfma_f32_16x16x32_bf16 v[92:95], v[140:143], v[194:197], v[92:95]
	v_mfma_f32_16x16x32_bf16 v[88:91], v[148:151], v[194:197], v[88:91]
	v_mfma_f32_16x16x32_bf16 v[76:79], v[140:143], v[202:205], v[76:79]
	v_mfma_f32_16x16x32_bf16 v[72:75], v[148:151], v[202:205], v[72:75]
	v_mfma_f32_16x16x32_bf16 v[124:127], v[144:147], v[182:185], v[124:127]
	v_mfma_f32_16x16x32_bf16 v[120:123], v[152:155], v[182:185], v[120:123]
	v_mfma_f32_16x16x32_bf16 v[108:111], v[144:147], v[190:193], v[108:111]
	v_mfma_f32_16x16x32_bf16 v[104:107], v[152:155], v[190:193], v[104:107]
	v_mfma_f32_16x16x32_bf16 v[92:95], v[144:147], v[198:201], v[92:95]
	v_mfma_f32_16x16x32_bf16 v[88:91], v[152:155], v[198:201], v[88:91]
	v_mfma_f32_16x16x32_bf16 v[76:79], v[144:147], v[206:209], v[76:79]
	v_mfma_f32_16x16x32_bf16 v[72:75], v[152:155], v[206:209], v[72:75]
	s_setprio 0
	s_setprio 1
	v_mfma_f32_16x16x32_bf16 v[116:119], v[162:165], v[178:181], v[116:119]
	v_mfma_f32_16x16x32_bf16 v[112:115], v[170:173], v[178:181], v[112:115]
	v_mfma_f32_16x16x32_bf16 v[100:103], v[162:165], v[186:189], v[100:103]
	v_mfma_f32_16x16x32_bf16 v[96:99], v[170:173], v[186:189], v[96:99]
	v_mfma_f32_16x16x32_bf16 v[84:87], v[162:165], v[194:197], v[84:87]
	v_mfma_f32_16x16x32_bf16 v[80:83], v[170:173], v[194:197], v[80:83]
	v_mfma_f32_16x16x32_bf16 v[68:71], v[162:165], v[202:205], v[68:71]
	v_mfma_f32_16x16x32_bf16 v[64:67], v[170:173], v[202:205], v[64:67]
	v_mfma_f32_16x16x32_bf16 v[116:119], v[166:169], v[182:185], v[116:119]
	v_mfma_f32_16x16x32_bf16 v[112:115], v[174:177], v[182:185], v[112:115]
	v_mfma_f32_16x16x32_bf16 v[100:103], v[166:169], v[190:193], v[100:103]
	v_mfma_f32_16x16x32_bf16 v[96:99], v[174:177], v[190:193], v[96:99]
	v_mfma_f32_16x16x32_bf16 v[84:87], v[166:169], v[198:201], v[84:87]
	v_mfma_f32_16x16x32_bf16 v[80:83], v[174:177], v[198:201], v[80:83]
	v_mfma_f32_16x16x32_bf16 v[68:71], v[166:169], v[206:209], v[68:71]
	v_mfma_f32_16x16x32_bf16 v[64:67], v[174:177], v[206:209], v[64:67]
	s_setprio 0
	s_barrier
	s_add_i32 s36, s51, s38
	s_mov_b32 m0, s36
	ds_read_b128 v[178:181], v161 offset:49152
	ds_read_b128 v[182:185], v161 offset:50176
	ds_read_b128 v[186:189], v161 offset:51200
	ds_read_b128 v[190:193], v161 offset:52224
	ds_read_b128 v[194:197], v161 offset:53248
	ds_read_b128 v[198:201], v161 offset:54272
	ds_read_b128 v[202:205], v161 offset:55296
	ds_read_b128 v[206:209], v161 offset:56320
	global_load_lds_dwordx4 v130, s[54:55]
	s_add_i32 m0, s36, 0x2000
	s_add_u32 s34, s34, 0x40080
	s_addc_u32 s35, s35, 0
	s_add_i32 s36, s52, s38
	global_load_lds_dwordx4 v134, s[54:55]
	s_mov_b32 m0, s36
	s_nop 0
	global_load_lds_dwordx4 v130, s[34:35]
	s_add_i32 m0, s36, 0x2000
	s_nop 0
	global_load_lds_dwordx4 v134, s[34:35]
	s_mov_b32 m0, s41
	s_nop 0
	global_load_lds_dwordx4 v128, s[58:59]
	s_mov_b32 m0, s42
	s_nop 0
	global_load_lds_dwordx4 v132, s[58:59]
	s_waitcnt vmcnt(8)
	s_waitcnt lgkmcnt(0)
	s_barrier
	s_setprio 1
	s_waitcnt lgkmcnt(0)
	v_mfma_f32_16x16x32_bf16 v[60:63], v[140:143], v[178:181], v[60:63]
	v_mfma_f32_16x16x32_bf16 v[56:59], v[148:151], v[178:181], v[56:59]
	v_mfma_f32_16x16x32_bf16 v[44:47], v[140:143], v[186:189], v[44:47]
	v_mfma_f32_16x16x32_bf16 v[40:43], v[148:151], v[186:189], v[40:43]
	v_mfma_f32_16x16x32_bf16 v[28:31], v[140:143], v[194:197], v[28:31]
	v_mfma_f32_16x16x32_bf16 v[24:27], v[148:151], v[194:197], v[24:27]
	v_mfma_f32_16x16x32_bf16 v[12:15], v[140:143], v[202:205], v[12:15]
	v_mfma_f32_16x16x32_bf16 v[8:11], v[148:151], v[202:205], v[8:11]
	v_mfma_f32_16x16x32_bf16 v[60:63], v[144:147], v[182:185], v[60:63]
	v_mfma_f32_16x16x32_bf16 v[56:59], v[152:155], v[182:185], v[56:59]
	v_mfma_f32_16x16x32_bf16 v[44:47], v[144:147], v[190:193], v[44:47]
	v_mfma_f32_16x16x32_bf16 v[40:43], v[152:155], v[190:193], v[40:43]
	v_mfma_f32_16x16x32_bf16 v[28:31], v[144:147], v[198:201], v[28:31]
	v_mfma_f32_16x16x32_bf16 v[24:27], v[152:155], v[198:201], v[24:27]
	v_mfma_f32_16x16x32_bf16 v[12:15], v[144:147], v[206:209], v[12:15]
	v_mfma_f32_16x16x32_bf16 v[8:11], v[152:155], v[206:209], v[8:11]
	s_setprio 0
	s_setprio 1
	v_mfma_f32_16x16x32_bf16 v[52:55], v[162:165], v[178:181], v[52:55]
	v_mfma_f32_16x16x32_bf16 v[48:51], v[170:173], v[178:181], v[48:51]
	v_mfma_f32_16x16x32_bf16 v[36:39], v[162:165], v[186:189], v[36:39]
	v_mfma_f32_16x16x32_bf16 v[32:35], v[170:173], v[186:189], v[32:35]
	v_mfma_f32_16x16x32_bf16 v[20:23], v[162:165], v[194:197], v[20:23]
	v_mfma_f32_16x16x32_bf16 v[16:19], v[170:173], v[194:197], v[16:19]
	v_mfma_f32_16x16x32_bf16 v[4:7], v[162:165], v[202:205], v[4:7]
	v_mfma_f32_16x16x32_bf16 v[0:3], v[170:173], v[202:205], v[0:3]
	v_mfma_f32_16x16x32_bf16 v[52:55], v[166:169], v[182:185], v[52:55]
	v_mfma_f32_16x16x32_bf16 v[48:51], v[174:177], v[182:185], v[48:51]
	v_mfma_f32_16x16x32_bf16 v[36:39], v[166:169], v[190:193], v[36:39]
	v_mfma_f32_16x16x32_bf16 v[32:35], v[174:177], v[190:193], v[32:35]
	v_mfma_f32_16x16x32_bf16 v[20:23], v[166:169], v[198:201], v[20:23]
	v_mfma_f32_16x16x32_bf16 v[16:19], v[174:177], v[198:201], v[16:19]
	v_mfma_f32_16x16x32_bf16 v[4:7], v[166:169], v[206:209], v[4:7]
	v_mfma_f32_16x16x32_bf16 v[0:3], v[174:177], v[206:209], v[0:3]
	s_setprio 0
	s_barrier
	s_add_i32 s50, s50, 2
	s_add_u32 s30, s30, 0x100
	s_addc_u32 s31, s31, 0
	s_add_u32 s48, s48, 0x100
	s_addc_u32 s49, s49, 0
	s_cmp_gt_u32 s50, 13
	s_cbranch_scc0 .LBB0_863
	s_and_b64 vcc, exec, s[10:11]
	s_cbranch_vccz .LBB0_866
	s_barrier

;     __device__ bool next(int i, Unit& u) const { if (r0 + i >= r1) return false; return base.next(r0 + i, u); }
;     __device__ bool next(int i, Unit& u) const { const int L = i * G + c; if (L >= 256) return false; u.pm = L; u.pn = L >> 3; return true; }
; #define PG8_STAGE(bufoff, gbase, voff) do { _Pragma("unroll") for (int _i = 0; _i < 2; ++_i) \
;         __builtin_amdgcn_global_load_lds((const unsigned*)((const char*)(gbase) + (voff)[_i]), (LAS unsigned*)(lds + (bufoff) + ldsw + _i * 8192), 16, 0, 0); } while (0)
; #define PG8_LDA(dst, b, h) do { _Pragma("unroll") for (int m = 0; m < 4; ++m) _Pragma("unroll") for (int k = 0; k < 2; ++k) dst[m][k] = *(const LAS bf16x8*)(lds + PG8_SA(b, h) + aoff + m * 2048 + k * 1024); } while (0)
; #define PG8_LDB(dst, b, h) do { _Pragma("unroll") for (int n = 0; n < 2; ++n) _Pragma("unroll") for (int k = 0; k < 2; ++k) dst[n][k] = *(const LAS bf16x8*)(lds + PG8_SB(b, h) + boff + n * 2048 + k * 1024); } while (0)
; #define PG8_WAIT_V(n) asm volatile("s_waitcnt vmcnt(" #n ")" ::: "memory")
; #define PG8_WAIT_L(n) asm volatile("s_waitcnt lgkmcnt(" #n ")" ::: "memory")
; template <class Epi, class Sched>
; __device__ __forceinline__ void gemm_phase(LAS unsigned char* lds, const Gemm g, const Sched& S, const Epi& E, int wave_id) {
;     ...
;         const bool has_next = S.next(ui + 1, nxt);
;         const char* nA = has_next ? (const char*)g.A + (size_t)nxt.pm * tstepA : cA; const char* nB = has_next ? (const char*)g.Bt + (size_t)nxt.pn * tstepB : cB;
;         for (int t = 0; t < nt; t += 2) {
;             const bool last = (t == nt - 2);
;             const char* a1 = cA + (size_t)(t + 1) * kstep;
;             const char* a2 = last ? nA : cA + (size_t)(t + 2) * kstep; const char* b2 = last ? nB : cB + (size_t)(t + 2) * kstep;
;             const char* a3 = a2 + kstep; const char* b3 = b2 + kstep;
;             PG8_LDB(B0, 0, 0); PG8_LDB(B1, 0, 1); PG8_SCHED; PG8_LDA(At, 0, 0); PG8_STAGE(PG8_SA(1, 1), a1 + hstepA, voffA);
;             PG8_WAIT_V(8); PG8_WAIT_L(0); PG8_BAR; PG8_MMA(0, 0, At, B0); PG8_MMA(0, 1, At, B1); PG8_BAR; PG8_SCHED;
;             PG8_LDA(At, 0, 1); PG8_STAGE(PG8_SB(0, 0), b2, voffB); PG8_STAGE(PG8_SB(0, 1), b2 + hstepB, voffB); PG8_STAGE(PG8_SA(0, 0), a2, voffA);
;             PG8_WAIT_V(8); PG8_WAIT_L(0); PG8_BAR; PG8_MMA(1, 0, At, B0); PG8_MMA(1, 1, At, B1); PG8_BAR; PG8_SCHED;
.LBB0_959:
	s_ashr_i32 s17, s16, 31
	s_lshl_b64 s[18:19], s[16:17], 19
	s_add_u32 s18, s31, s18
	s_addc_u32 s19, s34, s19
	s_and_b64 s[20:21], s[4:5], exec
	s_cselect_b32 s17, s19, s25
	s_cselect_b32 s49, s18, s24
	s_ashr_i32 s15, s14, 31
	s_lshl_b64 s[20:21], s[14:15], 19
	s_add_u32 s20, s35, s20
	s_addc_u32 s21, s36, s21
	s_and_b64 s[28:29], s[4:5], exec
	s_cselect_b32 s15, s21, s27
	s_cselect_b32 s50, s20, s26
	s_add_u32 s24, s24, 0x40080
	s_addc_u32 s25, s25, 0
	s_add_u32 s51, s26, 0x100
	s_addc_u32 s52, s27, 0
	s_mov_b32 s53, -2
	ds_read_b128 v[156:159], v151
	ds_read_b128 v[160:163], v151 offset:1024
	ds_read_b128 v[164:167], v151 offset:2048
	ds_read_b128 v[168:171], v151 offset:3072
	ds_read_b128 v[172:175], v152
	ds_read_b128 v[176:179], v152 offset:1024
	ds_read_b128 v[180:183], v152 offset:2048
	ds_read_b128 v[184:187], v152 offset:3072
	s_add_u32 s26, s24, 0xfffc0080
	s_addc_u32 s27, s25, -1
	s_cmp_eq_u32 s53, 12
	s_cselect_b32 s29, s17, s27
	s_cselect_b32 s28, s49, s26
	s_cselect_b32 s27, s15, s52
	s_cselect_b32 s26, s50, s51
	s_add_u32 s62, s28, 0x80
	s_addc_u32 s63, s29, 0
	s_add_u32 s60, s26, 0x80
	s_addc_u32 s61, s27, 0
	s_add_i32 m0, s37, 0xc000
	ds_read_b128 v[188:191], v153
	ds_read_b128 v[192:195], v153 offset:1024
	ds_read_b128 v[196:199], v153 offset:2048
	ds_read_b128 v[200:203], v153 offset:3072
	ds_read_b128 v[204:207], v153 offset:4096
	ds_read_b128 v[208:211], v153 offset:5120
	ds_read_b128 v[212:215], v153 offset:6144
	ds_read_b128 v[216:219], v153 offset:7168
	global_load_lds_dwordx4 v142, s[24:25]
	s_add_i32 m0, s37, 0xe000
	s_nop 0
	global_load_lds_dwordx4 v144, s[24:25]
	s_waitcnt vmcnt(8)
	s_waitcnt lgkmcnt(0)
	s_barrier
	s_setprio 1
	s_waitcnt lgkmcnt(0)
	v_mfma_f32_16x16x32_bf16 v[124:127], v[156:159], v[188:191], 0
	v_mfma_f32_16x16x32_bf16 v[120:123], v[164:167], v[188:191], 0
	v_mfma_f32_16x16x32_bf16 v[108:111], v[156:159], v[196:199], 0
	v_mfma_f32_16x16x32_bf16 v[104:107], v[164:167], v[196:199], 0
	v_mfma_f32_16x16x32_bf16 v[92:95], v[156:159], v[204:207], 0
	v_mfma_f32_16x16x32_bf16 v[88:91], v[164:167], v[204:207], 0
	v_mfma_f32_16x16x32_bf16 v[76:79], v[156:159], v[212:215], 0
	v_mfma_f32_16x16x32_bf16 v[72:75], v[164:167], v[212:215], 0
	v_mfma_f32_16x16x32_bf16 v[124:127], v[160:163], v[192:195], v[124:127]
	v_mfma_f32_16x16x32_bf16 v[120:123], v[168:171], v[192:195], v[120:123]
	v_mfma_f32_16x16x32_bf16 v[108:111], v[160:163], v[200:203], v[108:111]
	v_mfma_f32_16x16x32_bf16 v[104:107], v[168:171], v[200:203], v[104:107]
	v_mfma_f32_16x16x32_bf16 v[92:95], v[160:163], v[208:211], v[92:95]
	v_mfma_f32_16x16x32_bf16 v[88:91], v[168:171], v[208:211], v[88:91]
	v_mfma_f32_16x16x32_bf16 v[76:79], v[160:163], v[216:219], v[76:79]
	v_mfma_f32_16x16x32_bf16 v[72:75], v[168:171], v[216:219], v[72:75]
	s_setprio 0
	s_setprio 1
	v_mfma_f32_16x16x32_bf16 v[116:119], v[172:175], v[188:191], 0
	v_mfma_f32_16x16x32_bf16 v[112:115], v[180:183], v[188:191], 0
	v_mfma_f32_16x16x32_bf16 v[100:103], v[172:175], v[196:199], 0
	v_mfma_f32_16x16x32_bf16 v[96:99], v[180:183], v[196:199], 0
	v_mfma_f32_16x16x32_bf16 v[84:87], v[172:175], v[204:207], 0
	v_mfma_f32_16x16x32_bf16 v[80:83], v[180:183], v[204:207], 0
	v_mfma_f32_16x16x32_bf16 v[68:71], v[172:175], v[212:215], 0
	v_mfma_f32_16x16x32_bf16 v[64:67], v[180:183], v[212:215], 0
	v_mfma_f32_16x16x32_bf16 v[116:119], v[176:179], v[192:195], v[116:119]
	v_mfma_f32_16x16x32_bf16 v[112:115], v[184:187], v[192:195], v[112:115]
	v_mfma_f32_16x16x32_bf16 v[100:103], v[176:179], v[200:203], v[100:103]
	v_mfma_f32_16x16x32_bf16 v[96:99], v[184:187], v[200:203], v[96:99]
	v_mfma_f32_16x16x32_bf16 v[84:87], v[176:179], v[208:211], v[84:87]
	v_mfma_f32_16x16x32_bf16 v[80:83], v[184:187], v[208:211], v[80:83]
	v_mfma_f32_16x16x32_bf16 v[68:71], v[176:179], v[216:219], v[68:71]
	v_mfma_f32_16x16x32_bf16 v[64:67], v[184:187], v[216:219], v[64:67]
	s_setprio 0
	s_barrier
	s_add_i32 s54, s47, s2
	s_mov_b32 m0, s54
	ds_read_b128 v[188:191], v153 offset:16384
	ds_read_b128 v[192:195], v153 offset:17408
	ds_read_b128 v[196:199], v153 offset:18432
	ds_read_b128 v[200:203], v153 offset:19456
	ds_read_b128 v[204:207], v153 offset:20480
	ds_read_b128 v[208:211], v153 offset:21504
	ds_read_b128 v[212:215], v153 offset:22528
	ds_read_b128 v[216:219], v153 offset:23552
	global_load_lds_dwordx4 v130, s[26:27]
	s_add_i32 m0, s54, 0x2000
	s_add_u32 s54, s26, 0x40000
	s_addc_u32 s55, s27, 0
	s_add_i32 s58, s48, s2
	global_load_lds_dwordx4 v134, s[26:27]
	s_mov_b32 m0, s58
	s_nop 0
	global_load_lds_dwordx4 v130, s[54:55]
	s_add_i32 m0, s58, 0x2000
	s_nop 0
	global_load_lds_dwordx4 v134, s[54:55]
	s_mov_b32 m0, s37
	s_nop 0
	global_load_lds_dwordx4 v128, s[28:29]
	s_mov_b32 m0, s38
	s_nop 0
	global_load_lds_dwordx4 v132, s[28:29]
	s_waitcnt vmcnt(8)
	s_waitcnt lgkmcnt(0)
	s_barrier
; #define PG8_STAGE(bufoff, gbase, voff) do { _Pragma("unroll") for (int _i = 0; _i < 2; ++_i) \
;         __builtin_amdgcn_global_load_lds((const unsigned*)((const char*)(gbase) + (voff)[_i]), (LAS unsigned*)(lds + (bufoff) + ldsw + _i * 8192), 16, 0, 0); } while (0)
; #define PG8_LDA(dst, b, h) do { _Pragma("unroll") for (int m = 0; m < 4; ++m) _Pragma("unroll") for (int k = 0; k < 2; ++k) dst[m][k] = *(const LAS bf16x8*)(lds + PG8_SA(b, h) + aoff + m * 2048 + k * 1024); } while (0)
; #define PG8_LDB(dst, b, h) do { _Pragma("unroll") for (int n = 0; n < 2; ++n) _Pragma("unroll") for (int k = 0; k < 2; ++k) dst[n][k] = *(const LAS bf16x8*)(lds + PG8_SB(b, h) + boff + n * 2048 + k * 1024); } while (0)
; #define PG8_MMA(ai, bj, At, Bt) do { __builtin_amdgcn_s_setprio(1); _Pragma("unroll") for (int m = 0; m < 4; ++m) _Pragma("unroll") for (int n = 0; n < 2; ++n) _Pragma("unroll") for (int k = 0; k < 2; ++k) \
;         acc[ai][bj][m][n] = __builtin_amdgcn_mfma_f32_16x16x32_bf16(Bt[n][k], At[m][k], acc[ai][bj][m][n], 0, 0, 0); __builtin_amdgcn_s_setprio(0); } while (0)
; #define PG8_WAIT_V(n) asm volatile("s_waitcnt vmcnt(" #n ")" ::: "memory")
; #define PG8_WAIT_L(n) asm volatile("s_waitcnt lgkmcnt(" #n ")" ::: "memory")
; #define PG8_BAR __builtin_amdgcn_s_barrier()
; #define PG8_SCHED __builtin_amdgcn_sched_barrier(0)
; template <class Epi, class Sched>
; __device__ __forceinline__ void gemm_phase(LAS unsigned char* lds, const Gemm g, const Sched& S, const Epi& E, int wave_id) {
;     ...
;             PG8_WAIT_V(8); PG8_WAIT_L(0); PG8_BAR; PG8_MMA(1, 0, At, B0); PG8_MMA(1, 1, At, B1); PG8_BAR; PG8_SCHED;
;             PG8_LDB(B0, 1, 0); PG8_LDB(B1, 1, 1); PG8_SCHED; PG8_LDA(At, 1, 0); PG8_STAGE(PG8_SA(0, 1), a2 + hstepA, voffA);
;             PG8_WAIT_V(8); PG8_WAIT_L(0); PG8_BAR; PG8_MMA(0, 0, At, B0); PG8_MMA(0, 1, At, B1); PG8_BAR; PG8_SCHED;
	s_setprio 1
	s_waitcnt lgkmcnt(0)
	v_mfma_f32_16x16x32_bf16 v[60:63], v[156:159], v[188:191], 0
	v_mfma_f32_16x16x32_bf16 v[56:59], v[164:167], v[188:191], 0
	v_mfma_f32_16x16x32_bf16 v[44:47], v[156:159], v[196:199], 0
	v_mfma_f32_16x16x32_bf16 v[40:43], v[164:167], v[196:199], 0
	v_mfma_f32_16x16x32_bf16 v[28:31], v[156:159], v[204:207], 0
	v_mfma_f32_16x16x32_bf16 v[24:27], v[164:167], v[204:207], 0
	v_mfma_f32_16x16x32_bf16 v[12:15], v[156:159], v[212:215], 0
	v_mfma_f32_16x16x32_bf16 v[8:11], v[164:167], v[212:215], 0
	v_mfma_f32_16x16x32_bf16 v[60:63], v[160:163], v[192:195], v[60:63]
	v_mfma_f32_16x16x32_bf16 v[56:59], v[168:171], v[192:195], v[56:59]
	v_mfma_f32_16x16x32_bf16 v[44:47], v[160:163], v[200:203], v[44:47]
	v_mfma_f32_16x16x32_bf16 v[40:43], v[168:171], v[200:203], v[40:43]
	v_mfma_f32_16x16x32_bf16 v[28:31], v[160:163], v[208:211], v[28:31]
	v_mfma_f32_16x16x32_bf16 v[24:27], v[168:171], v[208:211], v[24:27]
	v_mfma_f32_16x16x32_bf16 v[12:15], v[160:163], v[216:219], v[12:15]
	v_mfma_f32_16x16x32_bf16 v[8:11], v[168:171], v[216:219], v[8:11]
	s_setprio 0
	s_setprio 1
	v_mfma_f32_16x16x32_bf16 v[52:55], v[172:175], v[188:191], 0
	v_mfma_f32_16x16x32_bf16 v[48:51], v[180:183], v[188:191], 0
	v_mfma_f32_16x16x32_bf16 v[36:39], v[172:175], v[196:199], 0
	v_mfma_f32_16x16x32_bf16 v[32:35], v[180:183], v[196:199], 0
	v_mfma_f32_16x16x32_bf16 v[20:23], v[172:175], v[204:207], 0
	v_mfma_f32_16x16x32_bf16 v[16:19], v[180:183], v[204:207], 0
	v_mfma_f32_16x16x32_bf16 v[4:7], v[172:175], v[212:215], 0
	v_mfma_f32_16x16x32_bf16 v[0:3], v[180:183], v[212:215], 0
	v_mfma_f32_16x16x32_bf16 v[52:55], v[176:179], v[192:195], v[52:55]
	v_mfma_f32_16x16x32_bf16 v[48:51], v[184:187], v[192:195], v[48:51]
	v_mfma_f32_16x16x32_bf16 v[36:39], v[176:179], v[200:203], v[36:39]
	v_mfma_f32_16x16x32_bf16 v[32:35], v[184:187], v[200:203], v[32:35]
	v_mfma_f32_16x16x32_bf16 v[20:23], v[176:179], v[208:211], v[20:23]
	v_mfma_f32_16x16x32_bf16 v[16:19], v[184:187], v[208:211], v[16:19]
	v_mfma_f32_16x16x32_bf16 v[4:7], v[176:179], v[216:219], v[4:7]
	v_mfma_f32_16x16x32_bf16 v[0:3], v[184:187], v[216:219], v[0:3]
	s_setprio 0
	s_barrier
	s_add_i32 s54, 0, 0x18000
	s_add_i32 s55, 0, 0x1c000
	v_add_u32_e32 v168, s54, v150
	v_add_u32_e32 v184, s55, v150
	ds_read_b128 v[156:159], v168
	ds_read_b128 v[160:163], v168 offset:1024
	ds_read_b128 v[164:167], v168 offset:2048
	ds_read_b128 v[168:171], v168 offset:3072
	ds_read_b128 v[172:175], v184
	ds_read_b128 v[176:179], v184 offset:1024
	ds_read_b128 v[180:183], v184 offset:2048
	ds_read_b128 v[184:187], v184 offset:3072
	s_add_u32 s28, s28, 0x40000
	s_addc_u32 s29, s29, 0
	s_mov_b32 m0, s39
	ds_read_b128 v[188:191], v153 offset:32768
	ds_read_b128 v[192:195], v153 offset:33792
	ds_read_b128 v[196:199], v153 offset:34816
	ds_read_b128 v[200:203], v153 offset:35840
	ds_read_b128 v[204:207], v153 offset:36864
	ds_read_b128 v[208:211], v153 offset:37888
	ds_read_b128 v[212:215], v153 offset:38912
	ds_read_b128 v[216:219], v153 offset:39936
	global_load_lds_dwordx4 v128, s[28:29]
	s_mov_b32 m0, s40
	s_nop 0
	global_load_lds_dwordx4 v132, s[28:29]
	s_waitcnt vmcnt(8)
	s_waitcnt lgkmcnt(0)
	s_barrier
	s_setprio 1
	s_waitcnt lgkmcnt(0)
	v_mfma_f32_16x16x32_bf16 v[124:127], v[156:159], v[188:191], v[124:127]
	v_mfma_f32_16x16x32_bf16 v[120:123], v[164:167], v[188:191], v[120:123]
	v_mfma_f32_16x16x32_bf16 v[108:111], v[156:159], v[196:199], v[108:111]
	v_mfma_f32_16x16x32_bf16 v[104:107], v[164:167], v[196:199], v[104:107]
	v_mfma_f32_16x16x32_bf16 v[92:95], v[156:159], v[204:207], v[92:95]
	v_mfma_f32_16x16x32_bf16 v[88:91], v[164:167], v[204:207], v[88:91]
	v_mfma_f32_16x16x32_bf16 v[76:79], v[156:159], v[212:215], v[76:79]
	v_mfma_f32_16x16x32_bf16 v[72:75], v[164:167], v[212:215], v[72:75]
	v_mfma_f32_16x16x32_bf16 v[124:127], v[160:163], v[192:195], v[124:127]
	v_mfma_f32_16x16x32_bf16 v[120:123], v[168:171], v[192:195], v[120:123]
	v_mfma_f32_16x16x32_bf16 v[108:111], v[160:163], v[200:203], v[108:111]
	v_mfma_f32_16x16x32_bf16 v[104:107], v[168:171], v[200:203], v[104:107]
	v_mfma_f32_16x16x32_bf16 v[92:95], v[160:163], v[208:211], v[92:95]
	v_mfma_f32_16x16x32_bf16 v[88:91], v[168:171], v[208:211], v[88:91]
	v_mfma_f32_16x16x32_bf16 v[76:79], v[160:163], v[216:219], v[76:79]
	v_mfma_f32_16x16x32_bf16 v[72:75], v[168:171], v[216:219], v[72:75]
	s_setprio 0
	s_setprio 1
	v_mfma_f32_16x16x32_bf16 v[116:119], v[172:175], v[188:191], v[116:119]
	v_mfma_f32_16x16x32_bf16 v[112:115], v[180:183], v[188:191], v[112:115]
	v_mfma_f32_16x16x32_bf16 v[100:103], v[172:175], v[196:199], v[100:103]
	v_mfma_f32_16x16x32_bf16 v[96:99], v[180:183], v[196:199], v[96:99]
	v_mfma_f32_16x16x32_bf16 v[84:87], v[172:175], v[204:207], v[84:87]
	v_mfma_f32_16x16x32_bf16 v[80:83], v[180:183], v[204:207], v[80:83]
	v_mfma_f32_16x16x32_bf16 v[68:71], v[172:175], v[212:215], v[68:71]
	v_mfma_f32_16x16x32_bf16 v[64:67], v[180:183], v[212:215], v[64:67]
	v_mfma_f32_16x16x32_bf16 v[116:119], v[176:179], v[192:195], v[116:119]
	v_mfma_f32_16x16x32_bf16 v[112:115], v[184:187], v[192:195], v[112:115]
	v_mfma_f32_16x16x32_bf16 v[100:103], v[176:179], v[200:203], v[100:103]
	v_mfma_f32_16x16x32_bf16 v[96:99], v[184:187], v[200:203], v[96:99]
	v_mfma_f32_16x16x32_bf16 v[84:87], v[176:179], v[208:211], v[84:87]
	v_mfma_f32_16x16x32_bf16 v[80:83], v[184:187], v[208:211], v[80:83]
	v_mfma_f32_16x16x32_bf16 v[68:71], v[176:179], v[216:219], v[68:71]
	v_mfma_f32_16x16x32_bf16 v[64:67], v[184:187], v[216:219], v[64:67]
	s_setprio 0
	s_barrier
; #define PG8_STAGE(bufoff, gbase, voff) do { _Pragma("unroll") for (int _i = 0; _i < 2; ++_i) \
;         __builtin_amdgcn_global_load_lds((const unsigned*)((const char*)(gbase) + (voff)[_i]), (LAS unsigned*)(lds + (bufoff) + ldsw + _i * 8192), 16, 0, 0); } while (0)
; #define PG8_LDA(dst, b, h) do { _Pragma("unroll") for (int m = 0; m < 4; ++m) _Pragma("unroll") for (int k = 0; k < 2; ++k) dst[m][k] = *(const LAS bf16x8*)(lds + PG8_SA(b, h) + aoff + m * 2048 + k * 1024); } while (0)
; #define PG8_LDB(dst, b, h) do { _Pragma("unroll") for (int n = 0; n < 2; ++n) _Pragma("unroll") for (int k = 0; k < 2; ++k) dst[n][k] = *(const LAS bf16x8*)(lds + PG8_SB(b, h) + boff + n * 2048 + k * 1024); } while (0)
; #define PG8_MMA(ai, bj, At, Bt) do { __builtin_amdgcn_s_setprio(1); _Pragma("unroll") for (int m = 0; m < 4; ++m) _Pragma("unroll") for (int n = 0; n < 2; ++n) _Pragma("unroll") for (int k = 0; k < 2; ++k) \
;         acc[ai][bj][m][n] = __builtin_amdgcn_mfma_f32_16x16x32_bf16(Bt[n][k], At[m][k], acc[ai][bj][m][n], 0, 0, 0); __builtin_amdgcn_s_setprio(0); } while (0)
; #define PG8_WAIT_V(n) asm volatile("s_waitcnt vmcnt(" #n ")" ::: "memory")
; #define PG8_WAIT_L(n) asm volatile("s_waitcnt lgkmcnt(" #n ")" ::: "memory")
; #define PG8_BAR __builtin_amdgcn_s_barrier()
; #define PG8_SCHED __builtin_amdgcn_sched_barrier(0)
; template <class Epi, class Sched>
; __device__ __forceinline__ void gemm_phase(LAS unsigned char* lds, const Gemm g, const Sched& S, const Epi& E, int wave_id) {
;     ...
;             PG8_LDB(B0, 0, 0); PG8_LDB(B1, 0, 1); PG8_SCHED; PG8_LDA(At, 0, 0); PG8_STAGE(PG8_SA(1, 1), a1 + hstepA, voffA);
;             PG8_WAIT_V(8); PG8_WAIT_L(0); PG8_BAR; PG8_MMA(0, 0, At, B0); PG8_MMA(0, 1, At, B1); PG8_BAR; PG8_SCHED;
;     ...
;             PG8_LDB(B0, 1, 0); PG8_LDB(B1, 1, 1); PG8_SCHED; PG8_LDA(At, 1, 0); PG8_STAGE(PG8_SA(0, 1), a2 + hstepA, voffA);
;             PG8_WAIT_V(8); PG8_WAIT_L(0); PG8_BAR; PG8_MMA(0, 0, At, B0); PG8_MMA(0, 1, At, B1); PG8_BAR; PG8_SCHED;
;             PG8_LDA(At, 1, 1); PG8_STAGE(PG8_SB(1, 0), b3, voffB); PG8_STAGE(PG8_SB(1, 1), b3 + hstepB, voffB); PG8_STAGE(PG8_SA(1, 0), a3, voffA);
;             PG8_WAIT_V(8); PG8_WAIT_L(0); PG8_BAR; PG8_MMA(1, 0, At, B0); PG8_MMA(1, 1, At, B1); PG8_BAR; PG8_SCHED;
	s_add_i32 s28, s54, s2
	s_mov_b32 m0, s28
	ds_read_b128 v[188:191], v153 offset:49152
	ds_read_b128 v[192:195], v153 offset:50176
	ds_read_b128 v[196:199], v153 offset:51200
	ds_read_b128 v[200:203], v153 offset:52224
	ds_read_b128 v[204:207], v153 offset:53248
	ds_read_b128 v[208:211], v153 offset:54272
	ds_read_b128 v[212:215], v153 offset:55296
	ds_read_b128 v[216:219], v153 offset:56320
	global_load_lds_dwordx4 v130, s[60:61]
	s_add_i32 m0, s28, 0x2000
	s_add_u32 s26, s26, 0x40080
	s_addc_u32 s27, s27, 0
	s_add_i32 s28, s55, s2
	global_load_lds_dwordx4 v134, s[60:61]
	s_mov_b32 m0, s28
	s_nop 0
	global_load_lds_dwordx4 v130, s[26:27]
	s_add_i32 m0, s28, 0x2000
	s_nop 0
	global_load_lds_dwordx4 v134, s[26:27]
	s_mov_b32 m0, s45
	s_nop 0
	global_load_lds_dwordx4 v128, s[62:63]
	s_mov_b32 m0, s46
	s_nop 0
	global_load_lds_dwordx4 v132, s[62:63]
	s_waitcnt vmcnt(8)
	s_waitcnt lgkmcnt(0)
	s_barrier
	s_setprio 1
	s_waitcnt lgkmcnt(0)
	v_mfma_f32_16x16x32_bf16 v[60:63], v[156:159], v[188:191], v[60:63]
	v_mfma_f32_16x16x32_bf16 v[56:59], v[164:167], v[188:191], v[56:59]
	v_mfma_f32_16x16x32_bf16 v[44:47], v[156:159], v[196:199], v[44:47]
	v_mfma_f32_16x16x32_bf16 v[40:43], v[164:167], v[196:199], v[40:43]
	v_mfma_f32_16x16x32_bf16 v[28:31], v[156:159], v[204:207], v[28:31]
	v_mfma_f32_16x16x32_bf16 v[24:27], v[164:167], v[204:207], v[24:27]
	v_mfma_f32_16x16x32_bf16 v[12:15], v[156:159], v[212:215], v[12:15]
	v_mfma_f32_16x16x32_bf16 v[8:11], v[164:167], v[212:215], v[8:11]
	v_mfma_f32_16x16x32_bf16 v[60:63], v[160:163], v[192:195], v[60:63]
	v_mfma_f32_16x16x32_bf16 v[56:59], v[168:171], v[192:195], v[56:59]
	v_mfma_f32_16x16x32_bf16 v[44:47], v[160:163], v[200:203], v[44:47]
	v_mfma_f32_16x16x32_bf16 v[40:43], v[168:171], v[200:203], v[40:43]
	v_mfma_f32_16x16x32_bf16 v[28:31], v[160:163], v[208:211], v[28:31]
	v_mfma_f32_16x16x32_bf16 v[24:27], v[168:171], v[208:211], v[24:27]
	v_mfma_f32_16x16x32_bf16 v[12:15], v[160:163], v[216:219], v[12:15]
	v_mfma_f32_16x16x32_bf16 v[8:11], v[168:171], v[216:219], v[8:11]
	s_setprio 0
	s_setprio 1
	v_mfma_f32_16x16x32_bf16 v[52:55], v[172:175], v[188:191], v[52:55]
	v_mfma_f32_16x16x32_bf16 v[48:51], v[180:183], v[188:191], v[48:51]
	v_mfma_f32_16x16x32_bf16 v[36:39], v[172:175], v[196:199], v[36:39]
	v_mfma_f32_16x16x32_bf16 v[32:35], v[180:183], v[196:199], v[32:35]
	v_mfma_f32_16x16x32_bf16 v[20:23], v[172:175], v[204:207], v[20:23]
	v_mfma_f32_16x16x32_bf16 v[16:19], v[180:183], v[204:207], v[16:19]
	v_mfma_f32_16x16x32_bf16 v[4:7], v[172:175], v[212:215], v[4:7]
	v_mfma_f32_16x16x32_bf16 v[0:3], v[180:183], v[212:215], v[0:3]
	v_mfma_f32_16x16x32_bf16 v[52:55], v[176:179], v[192:195], v[52:55]
	v_mfma_f32_16x16x32_bf16 v[48:51], v[184:187], v[192:195], v[48:51]
	v_mfma_f32_16x16x32_bf16 v[36:39], v[176:179], v[200:203], v[36:39]
	v_mfma_f32_16x16x32_bf16 v[32:35], v[184:187], v[200:203], v[32:35]
	v_mfma_f32_16x16x32_bf16 v[20:23], v[176:179], v[208:211], v[20:23]
	v_mfma_f32_16x16x32_bf16 v[16:19], v[184:187], v[208:211], v[16:19]
	v_mfma_f32_16x16x32_bf16 v[4:7], v[176:179], v[216:219], v[4:7]
	v_mfma_f32_16x16x32_bf16 v[0:3], v[184:187], v[216:219], v[0:3]
	s_setprio 0
	s_barrier
	s_add_i32 s53, s53, 2
	s_add_u32 s24, s24, 0x100
	s_addc_u32 s25, s25, 0
	s_add_u32 s51, s51, 0x100
	s_addc_u32 s52, s52, 0
	s_cmp_gt_u32 s53, 13
.LBB0_960:
	ds_read_b128 v[156:159], v151
	ds_read_b128 v[160:163], v151 offset:1024
	ds_read_b128 v[164:167], v151 offset:2048
	ds_read_b128 v[168:171], v151 offset:3072
	ds_read_b128 v[172:175], v152
	ds_read_b128 v[176:179], v152 offset:1024
	ds_read_b128 v[180:183], v152 offset:2048
	ds_read_b128 v[184:187], v152 offset:3072
	s_add_u32 s26, s24, 0xfffc0080
	s_addc_u32 s27, s25, -1
	s_cmp_eq_u32 s53, 12
	s_cselect_b32 s29, s17, s27
	s_cselect_b32 s28, s49, s26
	s_cselect_b32 s27, s15, s52
	s_cselect_b32 s26, s50, s51
	s_add_u32 s62, s28, 0x80
	s_addc_u32 s63, s29, 0
	s_add_u32 s60, s26, 0x80
	s_addc_u32 s61, s27, 0
	s_add_i32 m0, s37, 0xc000
	ds_read_b128 v[188:191], v153
	ds_read_b128 v[192:195], v153 offset:1024
	ds_read_b128 v[196:199], v153 offset:2048
	ds_read_b128 v[200:203], v153 offset:3072
	ds_read_b128 v[204:207], v153 offset:4096
	ds_read_b128 v[208:211], v153 offset:5120
	ds_read_b128 v[212:215], v153 offset:6144
	ds_read_b128 v[216:219], v153 offset:7168
	global_load_lds_dwordx4 v142, s[24:25]
	s_add_i32 m0, s37, 0xe000
	s_nop 0
	global_load_lds_dwordx4 v144, s[24:25]
	s_waitcnt vmcnt(8)
	s_waitcnt lgkmcnt(0)
	s_barrier
; #define PG8_STAGE(bufoff, gbase, voff) do { _Pragma("unroll") for (int _i = 0; _i < 2; ++_i) \
;         __builtin_amdgcn_global_load_lds((const unsigned*)((const char*)(gbase) + (voff)[_i]), (LAS unsigned*)(lds + (bufoff) + ldsw + _i * 8192), 16, 0, 0); } while (0)
; #define PG8_LDA(dst, b, h) do { _Pragma("unroll") for (int m = 0; m < 4; ++m) _Pragma("unroll") for (int k = 0; k < 2; ++k) dst[m][k] = *(const LAS bf16x8*)(lds + PG8_SA(b, h) + aoff + m * 2048 + k * 1024); } while (0)
; #define PG8_LDB(dst, b, h) do { _Pragma("unroll") for (int n = 0; n < 2; ++n) _Pragma("unroll") for (int k = 0; k < 2; ++k) dst[n][k] = *(const LAS bf16x8*)(lds + PG8_SB(b, h) + boff + n * 2048 + k * 1024); } while (0)
; #define PG8_MMA(ai, bj, At, Bt) do { __builtin_amdgcn_s_setprio(1); _Pragma("unroll") for (int m = 0; m < 4; ++m) _Pragma("unroll") for (int n = 0; n < 2; ++n) _Pragma("unroll") for (int k = 0; k < 2; ++k) \
;         acc[ai][bj][m][n] = __builtin_amdgcn_mfma_f32_16x16x32_bf16(Bt[n][k], At[m][k], acc[ai][bj][m][n], 0, 0, 0); __builtin_amdgcn_s_setprio(0); } while (0)
; #define PG8_WAIT_V(n) asm volatile("s_waitcnt vmcnt(" #n ")" ::: "memory")
; #define PG8_WAIT_L(n) asm volatile("s_waitcnt lgkmcnt(" #n ")" ::: "memory")
; #define PG8_BAR __builtin_amdgcn_s_barrier()
; #define PG8_SCHED __builtin_amdgcn_sched_barrier(0)
; template <class Epi, class Sched>
; __device__ __forceinline__ void gemm_phase(LAS unsigned char* lds, const Gemm g, const Sched& S, const Epi& E, int wave_id) {
;     ...
;             PG8_LDB(B0, 0, 0); PG8_LDB(B1, 0, 1); PG8_SCHED; PG8_LDA(At, 0, 0); PG8_STAGE(PG8_SA(1, 1), a1 + hstepA, voffA);
;             PG8_WAIT_V(8); PG8_WAIT_L(0); PG8_BAR; PG8_MMA(0, 0, At, B0); PG8_MMA(0, 1, At, B1); PG8_BAR; PG8_SCHED;
;             PG8_LDA(At, 0, 1); PG8_STAGE(PG8_SB(0, 0), b2, voffB); PG8_STAGE(PG8_SB(0, 1), b2 + hstepB, voffB); PG8_STAGE(PG8_SA(0, 0), a2, voffA);
;             PG8_WAIT_V(8); PG8_WAIT_L(0); PG8_BAR; PG8_MMA(1, 0, At, B0); PG8_MMA(1, 1, At, B1); PG8_BAR; PG8_SCHED;
	s_setprio 1
	s_waitcnt lgkmcnt(0)
	v_mfma_f32_16x16x32_bf16 v[124:127], v[156:159], v[188:191], v[124:127]
	v_mfma_f32_16x16x32_bf16 v[120:123], v[164:167], v[188:191], v[120:123]
	v_mfma_f32_16x16x32_bf16 v[108:111], v[156:159], v[196:199], v[108:111]
	v_mfma_f32_16x16x32_bf16 v[104:107], v[164:167], v[196:199], v[104:107]
	v_mfma_f32_16x16x32_bf16 v[92:95], v[156:159], v[204:207], v[92:95]
	v_mfma_f32_16x16x32_bf16 v[88:91], v[164:167], v[204:207], v[88:91]
	v_mfma_f32_16x16x32_bf16 v[76:79], v[156:159], v[212:215], v[76:79]
	v_mfma_f32_16x16x32_bf16 v[72:75], v[164:167], v[212:215], v[72:75]
	v_mfma_f32_16x16x32_bf16 v[124:127], v[160:163], v[192:195], v[124:127]
	v_mfma_f32_16x16x32_bf16 v[120:123], v[168:171], v[192:195], v[120:123]
	v_mfma_f32_16x16x32_bf16 v[108:111], v[160:163], v[200:203], v[108:111]
	v_mfma_f32_16x16x32_bf16 v[104:107], v[168:171], v[200:203], v[104:107]
	v_mfma_f32_16x16x32_bf16 v[92:95], v[160:163], v[208:211], v[92:95]
	v_mfma_f32_16x16x32_bf16 v[88:91], v[168:171], v[208:211], v[88:91]
	v_mfma_f32_16x16x32_bf16 v[76:79], v[160:163], v[216:219], v[76:79]
	v_mfma_f32_16x16x32_bf16 v[72:75], v[168:171], v[216:219], v[72:75]
	s_setprio 0
	s_setprio 1
	v_mfma_f32_16x16x32_bf16 v[116:119], v[172:175], v[188:191], v[116:119]
	v_mfma_f32_16x16x32_bf16 v[112:115], v[180:183], v[188:191], v[112:115]
	v_mfma_f32_16x16x32_bf16 v[100:103], v[172:175], v[196:199], v[100:103]
	v_mfma_f32_16x16x32_bf16 v[96:99], v[180:183], v[196:199], v[96:99]
	v_mfma_f32_16x16x32_bf16 v[84:87], v[172:175], v[204:207], v[84:87]
	v_mfma_f32_16x16x32_bf16 v[80:83], v[180:183], v[204:207], v[80:83]
	v_mfma_f32_16x16x32_bf16 v[68:71], v[172:175], v[212:215], v[68:71]
	v_mfma_f32_16x16x32_bf16 v[64:67], v[180:183], v[212:215], v[64:67]
	v_mfma_f32_16x16x32_bf16 v[116:119], v[176:179], v[192:195], v[116:119]
	v_mfma_f32_16x16x32_bf16 v[112:115], v[184:187], v[192:195], v[112:115]
	v_mfma_f32_16x16x32_bf16 v[100:103], v[176:179], v[200:203], v[100:103]
	v_mfma_f32_16x16x32_bf16 v[96:99], v[184:187], v[200:203], v[96:99]
	v_mfma_f32_16x16x32_bf16 v[84:87], v[176:179], v[208:211], v[84:87]
	v_mfma_f32_16x16x32_bf16 v[80:83], v[184:187], v[208:211], v[80:83]
	v_mfma_f32_16x16x32_bf16 v[68:71], v[176:179], v[216:219], v[68:71]
	v_mfma_f32_16x16x32_bf16 v[64:67], v[184:187], v[216:219], v[64:67]
	s_setprio 0
	s_barrier
	s_add_i32 s54, s47, s2
	s_mov_b32 m0, s54
	ds_read_b128 v[188:191], v153 offset:16384
	ds_read_b128 v[192:195], v153 offset:17408
	ds_read_b128 v[196:199], v153 offset:18432
	ds_read_b128 v[200:203], v153 offset:19456
	ds_read_b128 v[204:207], v153 offset:20480
	ds_read_b128 v[208:211], v153 offset:21504
	ds_read_b128 v[212:215], v153 offset:22528
	ds_read_b128 v[216:219], v153 offset:23552
	global_load_lds_dwordx4 v130, s[26:27]
	s_add_i32 m0, s54, 0x2000
	s_add_u32 s54, s26, 0x40000
	s_addc_u32 s55, s27, 0
	s_add_i32 s58, s48, s2
	global_load_lds_dwordx4 v134, s[26:27]
	s_mov_b32 m0, s58
	s_nop 0
	global_load_lds_dwordx4 v130, s[54:55]
	s_add_i32 m0, s58, 0x2000
	s_nop 0
	global_load_lds_dwordx4 v134, s[54:55]
	s_mov_b32 m0, s37
	s_nop 0
	global_load_lds_dwordx4 v128, s[28:29]
	s_mov_b32 m0, s38
	s_nop 0
	global_load_lds_dwordx4 v132, s[28:29]
	s_waitcnt vmcnt(8)
	s_waitcnt lgkmcnt(0)
	s_barrier
	s_setprio 1
	s_waitcnt lgkmcnt(0)
	v_mfma_f32_16x16x32_bf16 v[60:63], v[156:159], v[188:191], v[60:63]
	v_mfma_f32_16x16x32_bf16 v[56:59], v[164:167], v[188:191], v[56:59]
	v_mfma_f32_16x16x32_bf16 v[44:47], v[156:159], v[196:199], v[44:47]
	v_mfma_f32_16x16x32_bf16 v[40:43], v[164:167], v[196:199], v[40:43]
	v_mfma_f32_16x16x32_bf16 v[28:31], v[156:159], v[204:207], v[28:31]
	v_mfma_f32_16x16x32_bf16 v[24:27], v[164:167], v[204:207], v[24:27]
	v_mfma_f32_16x16x32_bf16 v[12:15], v[156:159], v[212:215], v[12:15]
	v_mfma_f32_16x16x32_bf16 v[8:11], v[164:167], v[212:215], v[8:11]
	v_mfma_f32_16x16x32_bf16 v[60:63], v[160:163], v[192:195], v[60:63]
	v_mfma_f32_16x16x32_bf16 v[56:59], v[168:171], v[192:195], v[56:59]
	v_mfma_f32_16x16x32_bf16 v[44:47], v[160:163], v[200:203], v[44:47]
	v_mfma_f32_16x16x32_bf16 v[40:43], v[168:171], v[200:203], v[40:43]
	v_mfma_f32_16x16x32_bf16 v[28:31], v[160:163], v[208:211], v[28:31]
	v_mfma_f32_16x16x32_bf16 v[24:27], v[168:171], v[208:211], v[24:27]
	v_mfma_f32_16x16x32_bf16 v[12:15], v[160:163], v[216:219], v[12:15]
	v_mfma_f32_16x16x32_bf16 v[8:11], v[168:171], v[216:219], v[8:11]
	s_setprio 0
	s_setprio 1
	v_mfma_f32_16x16x32_bf16 v[52:55], v[172:175], v[188:191], v[52:55]
	v_mfma_f32_16x16x32_bf16 v[48:51], v[180:183], v[188:191], v[48:51]
	v_mfma_f32_16x16x32_bf16 v[36:39], v[172:175], v[196:199], v[36:39]
	v_mfma_f32_16x16x32_bf16 v[32:35], v[180:183], v[196:199], v[32:35]
	v_mfma_f32_16x16x32_bf16 v[20:23], v[172:175], v[204:207], v[20:23]
	v_mfma_f32_16x16x32_bf16 v[16:19], v[180:183], v[204:207], v[16:19]
	v_mfma_f32_16x16x32_bf16 v[4:7], v[172:175], v[212:215], v[4:7]
	v_mfma_f32_16x16x32_bf16 v[0:3], v[180:183], v[212:215], v[0:3]
	v_mfma_f32_16x16x32_bf16 v[52:55], v[176:179], v[192:195], v[52:55]
	v_mfma_f32_16x16x32_bf16 v[48:51], v[184:187], v[192:195], v[48:51]
	v_mfma_f32_16x16x32_bf16 v[36:39], v[176:179], v[200:203], v[36:39]
	v_mfma_f32_16x16x32_bf16 v[32:35], v[184:187], v[200:203], v[32:35]
	v_mfma_f32_16x16x32_bf16 v[20:23], v[176:179], v[208:211], v[20:23]
	v_mfma_f32_16x16x32_bf16 v[16:19], v[184:187], v[208:211], v[16:19]
	v_mfma_f32_16x16x32_bf16 v[4:7], v[176:179], v[216:219], v[4:7]
	v_mfma_f32_16x16x32_bf16 v[0:3], v[184:187], v[216:219], v[0:3]
	s_setprio 0
	s_barrier
; #define PG8_STAGE(bufoff, gbase, voff) do { _Pragma("unroll") for (int _i = 0; _i < 2; ++_i) \
;         __builtin_amdgcn_global_load_lds((const unsigned*)((const char*)(gbase) + (voff)[_i]), (LAS unsigned*)(lds + (bufoff) + ldsw + _i * 8192), 16, 0, 0); } while (0)
; #define PG8_LDA(dst, b, h) do { _Pragma("unroll") for (int m = 0; m < 4; ++m) _Pragma("unroll") for (int k = 0; k < 2; ++k) dst[m][k] = *(const LAS bf16x8*)(lds + PG8_SA(b, h) + aoff + m * 2048 + k * 1024); } while (0)
; #define PG8_LDB(dst, b, h) do { _Pragma("unroll") for (int n = 0; n < 2; ++n) _Pragma("unroll") for (int k = 0; k < 2; ++k) dst[n][k] = *(const LAS bf16x8*)(lds + PG8_SB(b, h) + boff + n * 2048 + k * 1024); } while (0)
; #define PG8_MMA(ai, bj, At, Bt) do { __builtin_amdgcn_s_setprio(1); _Pragma("unroll") for (int m = 0; m < 4; ++m) _Pragma("unroll") for (int n = 0; n < 2; ++n) _Pragma("unroll") for (int k = 0; k < 2; ++k) \
;         acc[ai][bj][m][n] = __builtin_amdgcn_mfma_f32_16x16x32_bf16(Bt[n][k], At[m][k], acc[ai][bj][m][n], 0, 0, 0); __builtin_amdgcn_s_setprio(0); } while (0)
; #define PG8_WAIT_V(n) asm volatile("s_waitcnt vmcnt(" #n ")" ::: "memory")
; #define PG8_WAIT_L(n) asm volatile("s_waitcnt lgkmcnt(" #n ")" ::: "memory")
; #define PG8_BAR __builtin_amdgcn_s_barrier()
; #define PG8_SCHED __builtin_amdgcn_sched_barrier(0)
; template <class Epi, class Sched>
; __device__ __forceinline__ void gemm_phase(LAS unsigned char* lds, const Gemm g, const Sched& S, const Epi& E, int wave_id) {
;     ...
;             PG8_LDB(B0, 1, 0); PG8_LDB(B1, 1, 1); PG8_SCHED; PG8_LDA(At, 1, 0); PG8_STAGE(PG8_SA(0, 1), a2 + hstepA, voffA);
;             PG8_WAIT_V(8); PG8_WAIT_L(0); PG8_BAR; PG8_MMA(0, 0, At, B0); PG8_MMA(0, 1, At, B1); PG8_BAR; PG8_SCHED;
;             PG8_LDA(At, 1, 1); PG8_STAGE(PG8_SB(1, 0), b3, voffB); PG8_STAGE(PG8_SB(1, 1), b3 + hstepB, voffB); PG8_STAGE(PG8_SA(1, 0), a3, voffA);
;             PG8_WAIT_V(8); PG8_WAIT_L(0); PG8_BAR; PG8_MMA(1, 0, At, B0); PG8_MMA(1, 1, At, B1); PG8_BAR; PG8_SCHED;
	s_add_i32 s54, 0, 0x18000
	s_add_i32 s55, 0, 0x1c000
	v_add_u32_e32 v168, s54, v150
	v_add_u32_e32 v184, s55, v150
	ds_read_b128 v[156:159], v168
	ds_read_b128 v[160:163], v168 offset:1024
	ds_read_b128 v[164:167], v168 offset:2048
	ds_read_b128 v[168:171], v168 offset:3072
	ds_read_b128 v[172:175], v184
	ds_read_b128 v[176:179], v184 offset:1024
	ds_read_b128 v[180:183], v184 offset:2048
	ds_read_b128 v[184:187], v184 offset:3072
	s_add_u32 s28, s28, 0x40000
	s_addc_u32 s29, s29, 0
	s_mov_b32 m0, s39
	ds_read_b128 v[188:191], v153 offset:32768
	ds_read_b128 v[192:195], v153 offset:33792
	ds_read_b128 v[196:199], v153 offset:34816
	ds_read_b128 v[200:203], v153 offset:35840
	ds_read_b128 v[204:207], v153 offset:36864
	ds_read_b128 v[208:211], v153 offset:37888
	ds_read_b128 v[212:215], v153 offset:38912
	ds_read_b128 v[216:219], v153 offset:39936
	global_load_lds_dwordx4 v128, s[28:29]
	s_mov_b32 m0, s40
	s_nop 0
	global_load_lds_dwordx4 v132, s[28:29]
	s_waitcnt vmcnt(8)
	s_waitcnt lgkmcnt(0)
	s_barrier
	s_setprio 1
	s_waitcnt lgkmcnt(0)
	v_mfma_f32_16x16x32_bf16 v[124:127], v[156:159], v[188:191], v[124:127]
	v_mfma_f32_16x16x32_bf16 v[120:123], v[164:167], v[188:191], v[120:123]
	v_mfma_f32_16x16x32_bf16 v[108:111], v[156:159], v[196:199], v[108:111]
	v_mfma_f32_16x16x32_bf16 v[104:107], v[164:167], v[196:199], v[104:107]
	v_mfma_f32_16x16x32_bf16 v[92:95], v[156:159], v[204:207], v[92:95]
	v_mfma_f32_16x16x32_bf16 v[88:91], v[164:167], v[204:207], v[88:91]
	v_mfma_f32_16x16x32_bf16 v[76:79], v[156:159], v[212:215], v[76:79]
	v_mfma_f32_16x16x32_bf16 v[72:75], v[164:167], v[212:215], v[72:75]
	v_mfma_f32_16x16x32_bf16 v[124:127], v[160:163], v[192:195], v[124:127]
	v_mfma_f32_16x16x32_bf16 v[120:123], v[168:171], v[192:195], v[120:123]
	v_mfma_f32_16x16x32_bf16 v[108:111], v[160:163], v[200:203], v[108:111]
	v_mfma_f32_16x16x32_bf16 v[104:107], v[168:171], v[200:203], v[104:107]
	v_mfma_f32_16x16x32_bf16 v[92:95], v[160:163], v[208:211], v[92:95]
	v_mfma_f32_16x16x32_bf16 v[88:91], v[168:171], v[208:211], v[88:91]
	v_mfma_f32_16x16x32_bf16 v[76:79], v[160:163], v[216:219], v[76:79]
	v_mfma_f32_16x16x32_bf16 v[72:75], v[168:171], v[216:219], v[72:75]
	s_setprio 0
	s_setprio 1
	v_mfma_f32_16x16x32_bf16 v[116:119], v[172:175], v[188:191], v[116:119]
	v_mfma_f32_16x16x32_bf16 v[112:115], v[180:183], v[188:191], v[112:115]
	v_mfma_f32_16x16x32_bf16 v[100:103], v[172:175], v[196:199], v[100:103]
	v_mfma_f32_16x16x32_bf16 v[96:99], v[180:183], v[196:199], v[96:99]
	v_mfma_f32_16x16x32_bf16 v[84:87], v[172:175], v[204:207], v[84:87]
	v_mfma_f32_16x16x32_bf16 v[80:83], v[180:183], v[204:207], v[80:83]
	v_mfma_f32_16x16x32_bf16 v[68:71], v[172:175], v[212:215], v[68:71]
	v_mfma_f32_16x16x32_bf16 v[64:67], v[180:183], v[212:215], v[64:67]
	v_mfma_f32_16x16x32_bf16 v[116:119], v[176:179], v[192:195], v[116:119]
	v_mfma_f32_16x16x32_bf16 v[112:115], v[184:187], v[192:195], v[112:115]
	v_mfma_f32_16x16x32_bf16 v[100:103], v[176:179], v[200:203], v[100:103]
	v_mfma_f32_16x16x32_bf16 v[96:99], v[184:187], v[200:203], v[96:99]
	v_mfma_f32_16x16x32_bf16 v[84:87], v[176:179], v[208:211], v[84:87]
	v_mfma_f32_16x16x32_bf16 v[80:83], v[184:187], v[208:211], v[80:83]
	v_mfma_f32_16x16x32_bf16 v[68:71], v[176:179], v[216:219], v[68:71]
	v_mfma_f32_16x16x32_bf16 v[64:67], v[184:187], v[216:219], v[64:67]
	s_setprio 0
	s_barrier
	s_add_i32 s28, s54, s2
	s_mov_b32 m0, s28
	ds_read_b128 v[188:191], v153 offset:49152
	ds_read_b128 v[192:195], v153 offset:50176
	ds_read_b128 v[196:199], v153 offset:51200
	ds_read_b128 v[200:203], v153 offset:52224
	ds_read_b128 v[204:207], v153 offset:53248
	ds_read_b128 v[208:211], v153 offset:54272
	ds_read_b128 v[212:215], v153 offset:55296
	ds_read_b128 v[216:219], v153 offset:56320
	global_load_lds_dwordx4 v130, s[60:61]
	s_add_i32 m0, s28, 0x2000
	s_add_u32 s26, s26, 0x40080
	s_addc_u32 s27, s27, 0
	s_add_i32 s28, s55, s2
	global_load_lds_dwordx4 v134, s[60:61]
	s_mov_b32 m0, s28
	s_nop 0
	global_load_lds_dwordx4 v130, s[26:27]
	s_add_i32 m0, s28, 0x2000
	s_nop 0
	global_load_lds_dwordx4 v134, s[26:27]
	s_mov_b32 m0, s45
	s_nop 0
	global_load_lds_dwordx4 v128, s[62:63]
	s_mov_b32 m0, s46
	s_nop 0
	global_load_lds_dwordx4 v132, s[62:63]
	s_waitcnt vmcnt(8)
	s_waitcnt lgkmcnt(0)
	s_barrier
	s_setprio 1
	s_waitcnt lgkmcnt(0)
	v_mfma_f32_16x16x32_bf16 v[60:63], v[156:159], v[188:191], v[60:63]
	v_mfma_f32_16x16x32_bf16 v[56:59], v[164:167], v[188:191], v[56:59]
	v_mfma_f32_16x16x32_bf16 v[44:47], v[156:159], v[196:199], v[44:47]
	v_mfma_f32_16x16x32_bf16 v[40:43], v[164:167], v[196:199], v[40:43]
	v_mfma_f32_16x16x32_bf16 v[28:31], v[156:159], v[204:207], v[28:31]
	v_mfma_f32_16x16x32_bf16 v[24:27], v[164:167], v[204:207], v[24:27]
	v_mfma_f32_16x16x32_bf16 v[12:15], v[156:159], v[212:215], v[12:15]
	v_mfma_f32_16x16x32_bf16 v[8:11], v[164:167], v[212:215], v[8:11]
	v_mfma_f32_16x16x32_bf16 v[60:63], v[160:163], v[192:195], v[60:63]
	v_mfma_f32_16x16x32_bf16 v[56:59], v[168:171], v[192:195], v[56:59]
	v_mfma_f32_16x16x32_bf16 v[44:47], v[160:163], v[200:203], v[44:47]
	v_mfma_f32_16x16x32_bf16 v[40:43], v[168:171], v[200:203], v[40:43]
	v_mfma_f32_16x16x32_bf16 v[28:31], v[160:163], v[208:211], v[28:31]
	v_mfma_f32_16x16x32_bf16 v[24:27], v[168:171], v[208:211], v[24:27]
	v_mfma_f32_16x16x32_bf16 v[12:15], v[160:163], v[216:219], v[12:15]
	v_mfma_f32_16x16x32_bf16 v[8:11], v[168:171], v[216:219], v[8:11]
	s_setprio 0
	s_setprio 1
	v_mfma_f32_16x16x32_bf16 v[52:55], v[172:175], v[188:191], v[52:55]
	v_mfma_f32_16x16x32_bf16 v[48:51], v[180:183], v[188:191], v[48:51]
	v_mfma_f32_16x16x32_bf16 v[36:39], v[172:175], v[196:199], v[36:39]
	v_mfma_f32_16x16x32_bf16 v[32:35], v[180:183], v[196:199], v[32:35]
	v_mfma_f32_16x16x32_bf16 v[20:23], v[172:175], v[204:207], v[20:23]
	v_mfma_f32_16x16x32_bf16 v[16:19], v[180:183], v[204:207], v[16:19]
	v_mfma_f32_16x16x32_bf16 v[4:7], v[172:175], v[212:215], v[4:7]
	v_mfma_f32_16x16x32_bf16 v[0:3], v[180:183], v[212:215], v[0:3]
	v_mfma_f32_16x16x32_bf16 v[52:55], v[176:179], v[192:195], v[52:55]
	v_mfma_f32_16x16x32_bf16 v[48:51], v[184:187], v[192:195], v[48:51]
	v_mfma_f32_16x16x32_bf16 v[36:39], v[176:179], v[200:203], v[36:39]
	v_mfma_f32_16x16x32_bf16 v[32:35], v[184:187], v[200:203], v[32:35]
	v_mfma_f32_16x16x32_bf16 v[20:23], v[176:179], v[208:211], v[20:23]
	v_mfma_f32_16x16x32_bf16 v[16:19], v[184:187], v[208:211], v[16:19]
	v_mfma_f32_16x16x32_bf16 v[4:7], v[176:179], v[216:219], v[4:7]
	v_mfma_f32_16x16x32_bf16 v[0:3], v[184:187], v[216:219], v[0:3]
	s_setprio 0
	s_barrier
	s_add_i32 s53, s53, 2
	s_add_u32 s24, s24, 0x100
	s_addc_u32 s25, s25, 0
	s_add_u32 s51, s51, 0x100
	s_addc_u32 s52, s52, 0
	s_cmp_gt_u32 s53, 13
	s_cbranch_scc0 .LBB0_960
	s_and_b64 vcc, exec, s[12:13]
	s_cbranch_vccz .LBB0_963
	s_barrier

;     __device__ bool next(int i, Unit& u) const { if (r0 + i >= r1) return false; return base.next(r0 + i, u); }
;     __device__ bool next(int i, Unit& u) const { const int L = i * G + c; if (L >= 256) return false; u.pm = L; u.pn = L >> 3; return true; }
; #define PG8_STAGE(bufoff, gbase, voff) do { _Pragma("unroll") for (int _i = 0; _i < 2; ++_i) \
;         __builtin_amdgcn_global_load_lds((const unsigned*)((const char*)(gbase) + (voff)[_i]), (LAS unsigned*)(lds + (bufoff) + ldsw + _i * 8192), 16, 0, 0); } while (0)
; #define PG8_LDA(dst, b, h) do { _Pragma("unroll") for (int m = 0; m < 4; ++m) _Pragma("unroll") for (int k = 0; k < 2; ++k) dst[m][k] = *(const LAS bf16x8*)(lds + PG8_SA(b, h) + aoff + m * 2048 + k * 1024); } while (0)
; #define PG8_LDB(dst, b, h) do { _Pragma("unroll") for (int n = 0; n < 2; ++n) _Pragma("unroll") for (int k = 0; k < 2; ++k) dst[n][k] = *(const LAS bf16x8*)(lds + PG8_SB(b, h) + boff + n * 2048 + k * 1024); } while (0)
; #define PG8_WAIT_V(n) asm volatile("s_waitcnt vmcnt(" #n ")" ::: "memory")
; #define PG8_WAIT_L(n) asm volatile("s_waitcnt lgkmcnt(" #n ")" ::: "memory")
; template <class Epi, class Sched>
; __device__ __forceinline__ void gemm_phase(LAS unsigned char* lds, const Gemm g, const Sched& S, const Epi& E, int wave_id) {
;     ...
;         const bool has_next = S.next(ui + 1, nxt);
;         const char* nA = has_next ? (const char*)g.A + (size_t)nxt.pm * tstepA : cA; const char* nB = has_next ? (const char*)g.Bt + (size_t)nxt.pn * tstepB : cB;
;         for (int t = 0; t < nt; t += 2) {
;             const bool last = (t == nt - 2);
;             const char* a1 = cA + (size_t)(t + 1) * kstep;
;             const char* a2 = last ? nA : cA + (size_t)(t + 2) * kstep; const char* b2 = last ? nB : cB + (size_t)(t + 2) * kstep;
;             const char* a3 = a2 + kstep; const char* b3 = b2 + kstep;
;             PG8_LDB(B0, 0, 0); PG8_LDB(B1, 0, 1); PG8_SCHED; PG8_LDA(At, 0, 0); PG8_STAGE(PG8_SA(1, 1), a1 + hstepA, voffA);
;             PG8_WAIT_V(8); PG8_WAIT_L(0); PG8_BAR; PG8_MMA(0, 0, At, B0); PG8_MMA(0, 1, At, B1); PG8_BAR; PG8_SCHED;
;             PG8_LDA(At, 0, 1); PG8_STAGE(PG8_SB(0, 0), b2, voffB); PG8_STAGE(PG8_SB(0, 1), b2 + hstepB, voffB); PG8_STAGE(PG8_SA(0, 0), a2, voffA);
;             PG8_WAIT_V(8); PG8_WAIT_L(0); PG8_BAR; PG8_MMA(1, 0, At, B0); PG8_MMA(1, 1, At, B1); PG8_BAR; PG8_SCHED;
.LBB0_1040:
	s_ashr_i32 s19, s18, 31
	s_lshl_b64 s[20:21], s[18:19], 18
	s_add_u32 s20, s3, s20
	s_addc_u32 s21, s33, s21
	s_and_b64 s[22:23], s[4:5], exec
	s_cselect_b32 s19, s21, s27
	s_cselect_b32 s48, s20, s26
	s_ashr_i32 s17, s16, 31
	s_lshl_b64 s[22:23], s[16:17], 18
	s_add_u32 s22, s34, s22
	s_addc_u32 s23, s35, s23
	s_and_b64 s[30:31], s[4:5], exec
	s_cselect_b32 s17, s23, s29
	s_cselect_b32 s49, s22, s28
	s_add_u32 s26, s26, 0x20080
	s_addc_u32 s27, s27, 0
	s_add_u32 s50, s28, 0x100
	s_addc_u32 s51, s29, 0
	s_mov_b32 s52, -2
	s_waitcnt vmcnt(0)
	ds_read_b128 v[116:119], v201
	ds_read_b128 v[120:123], v201 offset:1024
	ds_read_b128 v[124:127], v201 offset:2048
	ds_read_b128 v[136:139], v201 offset:3072
	ds_read_b128 v[140:143], v202
	ds_read_b128 v[148:151], v202 offset:1024
	ds_read_b128 v[152:155], v202 offset:2048
	ds_read_b128 v[156:159], v202 offset:3072
	s_add_u32 s28, s26, 0xfffe0080
	s_addc_u32 s29, s27, -1
	s_cmp_eq_u32 s52, 4
	s_cselect_b32 s31, s19, s29
	s_cselect_b32 s30, s48, s28
	s_cselect_b32 s29, s17, s51
	s_cselect_b32 s28, s49, s50
	s_add_u32 s60, s30, 0x80
	s_addc_u32 s61, s31, 0
	s_add_u32 s58, s28, 0x80
	s_addc_u32 s59, s29, 0
	s_add_i32 m0, s25, 0xc000
	ds_read_b128 v[160:163], v203
	ds_read_b128 v[164:167], v203 offset:1024
	ds_read_b128 v[186:189], v203 offset:2048
	ds_read_b128 v[190:193], v203 offset:3072
	ds_read_b128 v[194:197], v203 offset:4096
	ds_read_b128 v[204:207], v203 offset:5120
	ds_read_b128 v[208:211], v203 offset:6144
	ds_read_b128 v[212:215], v203 offset:7168
	global_load_lds_dwordx4 v178, s[26:27]
	s_add_i32 m0, s25, 0xe000
	s_nop 0
	global_load_lds_dwordx4 v180, s[26:27]
	s_waitcnt vmcnt(8)
	s_waitcnt lgkmcnt(0)
	s_barrier
	s_setprio 1
	s_waitcnt lgkmcnt(0)
	v_mfma_f32_16x16x32_bf16 v[144:147], v[116:119], v[160:163], 0
	v_mfma_f32_16x16x32_bf16 v[128:131], v[124:127], v[160:163], 0
	v_mfma_f32_16x16x32_bf16 v[108:111], v[116:119], v[186:189], 0
	v_mfma_f32_16x16x32_bf16 v[100:103], v[124:127], v[186:189], 0
	v_mfma_f32_16x16x32_bf16 v[92:95], v[116:119], v[194:197], 0
	v_mfma_f32_16x16x32_bf16 v[84:87], v[124:127], v[194:197], 0
	v_mfma_f32_16x16x32_bf16 v[76:79], v[116:119], v[208:211], 0
	v_mfma_f32_16x16x32_bf16 v[68:71], v[124:127], v[208:211], 0
	v_mfma_f32_16x16x32_bf16 v[144:147], v[120:123], v[164:167], v[144:147]
	v_mfma_f32_16x16x32_bf16 v[128:131], v[136:139], v[164:167], v[128:131]
	v_mfma_f32_16x16x32_bf16 v[108:111], v[120:123], v[190:193], v[108:111]
	v_mfma_f32_16x16x32_bf16 v[100:103], v[136:139], v[190:193], v[100:103]
	v_mfma_f32_16x16x32_bf16 v[92:95], v[120:123], v[204:207], v[92:95]
	v_mfma_f32_16x16x32_bf16 v[84:87], v[136:139], v[204:207], v[84:87]
	v_mfma_f32_16x16x32_bf16 v[76:79], v[120:123], v[212:215], v[76:79]
	v_mfma_f32_16x16x32_bf16 v[68:71], v[136:139], v[212:215], v[68:71]
	s_setprio 0
	s_setprio 1
	v_mfma_f32_16x16x32_bf16 v[132:135], v[140:143], v[160:163], 0
	v_mfma_f32_16x16x32_bf16 v[112:115], v[152:155], v[160:163], 0
	v_mfma_f32_16x16x32_bf16 v[104:107], v[140:143], v[186:189], 0
	v_mfma_f32_16x16x32_bf16 v[96:99], v[152:155], v[186:189], 0
	v_mfma_f32_16x16x32_bf16 v[88:91], v[140:143], v[194:197], 0
	v_mfma_f32_16x16x32_bf16 v[80:83], v[152:155], v[194:197], 0
	v_mfma_f32_16x16x32_bf16 v[72:75], v[140:143], v[208:211], 0
	v_mfma_f32_16x16x32_bf16 v[64:67], v[152:155], v[208:211], 0
	v_mfma_f32_16x16x32_bf16 v[132:135], v[148:151], v[164:167], v[132:135]
	v_mfma_f32_16x16x32_bf16 v[112:115], v[156:159], v[164:167], v[112:115]
	v_mfma_f32_16x16x32_bf16 v[104:107], v[148:151], v[190:193], v[104:107]
	v_mfma_f32_16x16x32_bf16 v[96:99], v[156:159], v[190:193], v[96:99]
	v_mfma_f32_16x16x32_bf16 v[88:91], v[148:151], v[204:207], v[88:91]
	v_mfma_f32_16x16x32_bf16 v[80:83], v[156:159], v[204:207], v[80:83]
	v_mfma_f32_16x16x32_bf16 v[72:75], v[148:151], v[212:215], v[72:75]
	v_mfma_f32_16x16x32_bf16 v[64:67], v[156:159], v[212:215], v[64:67]
	s_setprio 0
	s_barrier
	s_add_i32 s53, s45, s36
	s_mov_b32 m0, s53
	ds_read_b128 v[160:163], v203 offset:16384
	ds_read_b128 v[164:167], v203 offset:17408
	ds_read_b128 v[186:189], v203 offset:18432
	ds_read_b128 v[190:193], v203 offset:19456
	ds_read_b128 v[194:197], v203 offset:20480
	ds_read_b128 v[204:207], v203 offset:21504
	ds_read_b128 v[208:211], v203 offset:22528
	ds_read_b128 v[212:215], v203 offset:23552
	global_load_lds_dwordx4 v170, s[28:29]
	s_add_i32 m0, s53, 0x2000
	s_add_u32 s54, s28, 0x20000
	s_addc_u32 s55, s29, 0
	s_add_i32 s53, s46, s36
	global_load_lds_dwordx4 v174, s[28:29]
	s_mov_b32 m0, s53
	s_nop 0
	global_load_lds_dwordx4 v170, s[54:55]
	s_add_i32 m0, s53, 0x2000
	s_nop 0
	global_load_lds_dwordx4 v174, s[54:55]
	s_mov_b32 m0, s25
	s_nop 0
	global_load_lds_dwordx4 v168, s[30:31]
	s_mov_b32 m0, s37
	s_nop 0
	global_load_lds_dwordx4 v172, s[30:31]
	s_waitcnt vmcnt(8)
	s_waitcnt lgkmcnt(0)
	s_barrier
; #define PG8_STAGE(bufoff, gbase, voff) do { _Pragma("unroll") for (int _i = 0; _i < 2; ++_i) \
;         __builtin_amdgcn_global_load_lds((const unsigned*)((const char*)(gbase) + (voff)[_i]), (LAS unsigned*)(lds + (bufoff) + ldsw + _i * 8192), 16, 0, 0); } while (0)
; #define PG8_LDA(dst, b, h) do { _Pragma("unroll") for (int m = 0; m < 4; ++m) _Pragma("unroll") for (int k = 0; k < 2; ++k) dst[m][k] = *(const LAS bf16x8*)(lds + PG8_SA(b, h) + aoff + m * 2048 + k * 1024); } while (0)
; #define PG8_LDB(dst, b, h) do { _Pragma("unroll") for (int n = 0; n < 2; ++n) _Pragma("unroll") for (int k = 0; k < 2; ++k) dst[n][k] = *(const LAS bf16x8*)(lds + PG8_SB(b, h) + boff + n * 2048 + k * 1024); } while (0)
; #define PG8_MMA(ai, bj, At, Bt) do { __builtin_amdgcn_s_setprio(1); _Pragma("unroll") for (int m = 0; m < 4; ++m) _Pragma("unroll") for (int n = 0; n < 2; ++n) _Pragma("unroll") for (int k = 0; k < 2; ++k) \
;         acc[ai][bj][m][n] = __builtin_amdgcn_mfma_f32_16x16x32_bf16(Bt[n][k], At[m][k], acc[ai][bj][m][n], 0, 0, 0); __builtin_amdgcn_s_setprio(0); } while (0)
; #define PG8_WAIT_V(n) asm volatile("s_waitcnt vmcnt(" #n ")" ::: "memory")
; #define PG8_WAIT_L(n) asm volatile("s_waitcnt lgkmcnt(" #n ")" ::: "memory")
; #define PG8_BAR __builtin_amdgcn_s_barrier()
; #define PG8_SCHED __builtin_amdgcn_sched_barrier(0)
; template <class Epi, class Sched>
; __device__ __forceinline__ void gemm_phase(LAS unsigned char* lds, const Gemm g, const Sched& S, const Epi& E, int wave_id) {
;     ...
;             PG8_WAIT_V(8); PG8_WAIT_L(0); PG8_BAR; PG8_MMA(1, 0, At, B0); PG8_MMA(1, 1, At, B1); PG8_BAR; PG8_SCHED;
;             PG8_LDB(B0, 1, 0); PG8_LDB(B1, 1, 1); PG8_SCHED; PG8_LDA(At, 1, 0); PG8_STAGE(PG8_SA(0, 1), a2 + hstepA, voffA);
;             PG8_WAIT_V(8); PG8_WAIT_L(0); PG8_BAR; PG8_MMA(0, 0, At, B0); PG8_MMA(0, 1, At, B1); PG8_BAR; PG8_SCHED;
	s_setprio 1
	s_waitcnt lgkmcnt(0)
	v_mfma_f32_16x16x32_bf16 v[60:63], v[116:119], v[160:163], 0
	v_mfma_f32_16x16x32_bf16 v[52:55], v[124:127], v[160:163], 0
	v_mfma_f32_16x16x32_bf16 v[44:47], v[116:119], v[186:189], 0
	v_mfma_f32_16x16x32_bf16 v[36:39], v[124:127], v[186:189], 0
	v_mfma_f32_16x16x32_bf16 v[28:31], v[116:119], v[194:197], 0
	v_mfma_f32_16x16x32_bf16 v[20:23], v[124:127], v[194:197], 0
	v_mfma_f32_16x16x32_bf16 v[12:15], v[116:119], v[208:211], 0
	v_mfma_f32_16x16x32_bf16 v[4:7], v[124:127], v[208:211], 0
	v_mfma_f32_16x16x32_bf16 v[60:63], v[120:123], v[164:167], v[60:63]
	v_mfma_f32_16x16x32_bf16 v[52:55], v[136:139], v[164:167], v[52:55]
	v_mfma_f32_16x16x32_bf16 v[44:47], v[120:123], v[190:193], v[44:47]
	v_mfma_f32_16x16x32_bf16 v[36:39], v[136:139], v[190:193], v[36:39]
	v_mfma_f32_16x16x32_bf16 v[28:31], v[120:123], v[204:207], v[28:31]
	v_mfma_f32_16x16x32_bf16 v[20:23], v[136:139], v[204:207], v[20:23]
	v_mfma_f32_16x16x32_bf16 v[12:15], v[120:123], v[212:215], v[12:15]
	v_mfma_f32_16x16x32_bf16 v[4:7], v[136:139], v[212:215], v[4:7]
	s_setprio 0
	s_setprio 1
	v_mfma_f32_16x16x32_bf16 v[56:59], v[140:143], v[160:163], 0
	v_mfma_f32_16x16x32_bf16 v[48:51], v[152:155], v[160:163], 0
	v_mfma_f32_16x16x32_bf16 v[40:43], v[140:143], v[186:189], 0
	v_mfma_f32_16x16x32_bf16 v[32:35], v[152:155], v[186:189], 0
	v_mfma_f32_16x16x32_bf16 v[24:27], v[140:143], v[194:197], 0
	v_mfma_f32_16x16x32_bf16 v[16:19], v[152:155], v[194:197], 0
	v_mfma_f32_16x16x32_bf16 v[8:11], v[140:143], v[208:211], 0
	v_mfma_f32_16x16x32_bf16 v[0:3], v[152:155], v[208:211], 0
	v_mfma_f32_16x16x32_bf16 v[56:59], v[148:151], v[164:167], v[56:59]
	v_mfma_f32_16x16x32_bf16 v[48:51], v[156:159], v[164:167], v[48:51]
	v_mfma_f32_16x16x32_bf16 v[40:43], v[148:151], v[190:193], v[40:43]
	v_mfma_f32_16x16x32_bf16 v[32:35], v[156:159], v[190:193], v[32:35]
	v_mfma_f32_16x16x32_bf16 v[24:27], v[148:151], v[204:207], v[24:27]
	v_mfma_f32_16x16x32_bf16 v[16:19], v[156:159], v[204:207], v[16:19]
	v_mfma_f32_16x16x32_bf16 v[8:11], v[148:151], v[212:215], v[8:11]
	v_mfma_f32_16x16x32_bf16 v[0:3], v[156:159], v[212:215], v[0:3]
	s_setprio 0
	s_barrier
	s_add_i32 s53, 0, 0x18000
	s_add_i32 s54, 0, 0x1c000
	v_add_u32_e32 v136, s53, v199
	v_add_u32_e32 v156, s54, v199
	ds_read_b128 v[116:119], v136
	ds_read_b128 v[120:123], v136 offset:1024
	ds_read_b128 v[124:127], v136 offset:2048
	ds_read_b128 v[136:139], v136 offset:3072
	ds_read_b128 v[140:143], v156
	ds_read_b128 v[148:151], v156 offset:1024
	ds_read_b128 v[152:155], v156 offset:2048
	ds_read_b128 v[156:159], v156 offset:3072
	s_add_u32 s30, s30, 0x20000
	s_addc_u32 s31, s31, 0
	s_mov_b32 m0, s38
	ds_read_b128 v[160:163], v203 offset:32768
	ds_read_b128 v[164:167], v203 offset:33792
	ds_read_b128 v[186:189], v203 offset:34816
	ds_read_b128 v[190:193], v203 offset:35840
	ds_read_b128 v[194:197], v203 offset:36864
	ds_read_b128 v[204:207], v203 offset:37888
	ds_read_b128 v[208:211], v203 offset:38912
	ds_read_b128 v[212:215], v203 offset:39936
	global_load_lds_dwordx4 v168, s[30:31]
	s_mov_b32 m0, s39
	s_nop 0
	global_load_lds_dwordx4 v172, s[30:31]
	s_waitcnt vmcnt(8)
	s_waitcnt lgkmcnt(0)
	s_barrier
	s_setprio 1
	s_waitcnt lgkmcnt(0)
	v_mfma_f32_16x16x32_bf16 v[144:147], v[116:119], v[160:163], v[144:147]
	v_mfma_f32_16x16x32_bf16 v[128:131], v[124:127], v[160:163], v[128:131]
	v_mfma_f32_16x16x32_bf16 v[108:111], v[116:119], v[186:189], v[108:111]
	v_mfma_f32_16x16x32_bf16 v[100:103], v[124:127], v[186:189], v[100:103]
	v_mfma_f32_16x16x32_bf16 v[92:95], v[116:119], v[194:197], v[92:95]
	v_mfma_f32_16x16x32_bf16 v[84:87], v[124:127], v[194:197], v[84:87]
	v_mfma_f32_16x16x32_bf16 v[76:79], v[116:119], v[208:211], v[76:79]
	v_mfma_f32_16x16x32_bf16 v[68:71], v[124:127], v[208:211], v[68:71]
	v_mfma_f32_16x16x32_bf16 v[144:147], v[120:123], v[164:167], v[144:147]
	v_mfma_f32_16x16x32_bf16 v[128:131], v[136:139], v[164:167], v[128:131]
	v_mfma_f32_16x16x32_bf16 v[108:111], v[120:123], v[190:193], v[108:111]
	v_mfma_f32_16x16x32_bf16 v[100:103], v[136:139], v[190:193], v[100:103]
	v_mfma_f32_16x16x32_bf16 v[92:95], v[120:123], v[204:207], v[92:95]
	v_mfma_f32_16x16x32_bf16 v[84:87], v[136:139], v[204:207], v[84:87]
	v_mfma_f32_16x16x32_bf16 v[76:79], v[120:123], v[212:215], v[76:79]
	v_mfma_f32_16x16x32_bf16 v[68:71], v[136:139], v[212:215], v[68:71]
	s_setprio 0
	s_setprio 1
	v_mfma_f32_16x16x32_bf16 v[132:135], v[140:143], v[160:163], v[132:135]
	v_mfma_f32_16x16x32_bf16 v[112:115], v[152:155], v[160:163], v[112:115]
	v_mfma_f32_16x16x32_bf16 v[104:107], v[140:143], v[186:189], v[104:107]
	v_mfma_f32_16x16x32_bf16 v[96:99], v[152:155], v[186:189], v[96:99]
	v_mfma_f32_16x16x32_bf16 v[88:91], v[140:143], v[194:197], v[88:91]
	v_mfma_f32_16x16x32_bf16 v[80:83], v[152:155], v[194:197], v[80:83]
	v_mfma_f32_16x16x32_bf16 v[72:75], v[140:143], v[208:211], v[72:75]
	v_mfma_f32_16x16x32_bf16 v[64:67], v[152:155], v[208:211], v[64:67]
	v_mfma_f32_16x16x32_bf16 v[132:135], v[148:151], v[164:167], v[132:135]
	v_mfma_f32_16x16x32_bf16 v[112:115], v[156:159], v[164:167], v[112:115]
	v_mfma_f32_16x16x32_bf16 v[104:107], v[148:151], v[190:193], v[104:107]
	v_mfma_f32_16x16x32_bf16 v[96:99], v[156:159], v[190:193], v[96:99]
	v_mfma_f32_16x16x32_bf16 v[88:91], v[148:151], v[204:207], v[88:91]
	v_mfma_f32_16x16x32_bf16 v[80:83], v[156:159], v[204:207], v[80:83]
	v_mfma_f32_16x16x32_bf16 v[72:75], v[148:151], v[212:215], v[72:75]
	v_mfma_f32_16x16x32_bf16 v[64:67], v[156:159], v[212:215], v[64:67]
	s_setprio 0
	s_barrier
; #define PG8_STAGE(bufoff, gbase, voff) do { _Pragma("unroll") for (int _i = 0; _i < 2; ++_i) \
;         __builtin_amdgcn_global_load_lds((const unsigned*)((const char*)(gbase) + (voff)[_i]), (LAS unsigned*)(lds + (bufoff) + ldsw + _i * 8192), 16, 0, 0); } while (0)
; #define PG8_LDA(dst, b, h) do { _Pragma("unroll") for (int m = 0; m < 4; ++m) _Pragma("unroll") for (int k = 0; k < 2; ++k) dst[m][k] = *(const LAS bf16x8*)(lds + PG8_SA(b, h) + aoff + m * 2048 + k * 1024); } while (0)
; #define PG8_LDB(dst, b, h) do { _Pragma("unroll") for (int n = 0; n < 2; ++n) _Pragma("unroll") for (int k = 0; k < 2; ++k) dst[n][k] = *(const LAS bf16x8*)(lds + PG8_SB(b, h) + boff + n * 2048 + k * 1024); } while (0)
; #define PG8_MMA(ai, bj, At, Bt) do { __builtin_amdgcn_s_setprio(1); _Pragma("unroll") for (int m = 0; m < 4; ++m) _Pragma("unroll") for (int n = 0; n < 2; ++n) _Pragma("unroll") for (int k = 0; k < 2; ++k) \
;         acc[ai][bj][m][n] = __builtin_amdgcn_mfma_f32_16x16x32_bf16(Bt[n][k], At[m][k], acc[ai][bj][m][n], 0, 0, 0); __builtin_amdgcn_s_setprio(0); } while (0)
; #define PG8_WAIT_V(n) asm volatile("s_waitcnt vmcnt(" #n ")" ::: "memory")
; #define PG8_WAIT_L(n) asm volatile("s_waitcnt lgkmcnt(" #n ")" ::: "memory")
; #define PG8_BAR __builtin_amdgcn_s_barrier()
; #define PG8_SCHED __builtin_amdgcn_sched_barrier(0)
; template <class Epi, class Sched>
; __device__ __forceinline__ void gemm_phase(LAS unsigned char* lds, const Gemm g, const Sched& S, const Epi& E, int wave_id) {
;     ...
;             PG8_LDB(B0, 0, 0); PG8_LDB(B1, 0, 1); PG8_SCHED; PG8_LDA(At, 0, 0); PG8_STAGE(PG8_SA(1, 1), a1 + hstepA, voffA);
;             PG8_WAIT_V(8); PG8_WAIT_L(0); PG8_BAR; PG8_MMA(0, 0, At, B0); PG8_MMA(0, 1, At, B1); PG8_BAR; PG8_SCHED;
;     ...
;             PG8_LDB(B0, 1, 0); PG8_LDB(B1, 1, 1); PG8_SCHED; PG8_LDA(At, 1, 0); PG8_STAGE(PG8_SA(0, 1), a2 + hstepA, voffA);
;             PG8_WAIT_V(8); PG8_WAIT_L(0); PG8_BAR; PG8_MMA(0, 0, At, B0); PG8_MMA(0, 1, At, B1); PG8_BAR; PG8_SCHED;
;             PG8_LDA(At, 1, 1); PG8_STAGE(PG8_SB(1, 0), b3, voffB); PG8_STAGE(PG8_SB(1, 1), b3 + hstepB, voffB); PG8_STAGE(PG8_SA(1, 0), a3, voffA);
;             PG8_WAIT_V(8); PG8_WAIT_L(0); PG8_BAR; PG8_MMA(1, 0, At, B0); PG8_MMA(1, 1, At, B1); PG8_BAR; PG8_SCHED;
	s_add_i32 s30, s53, s36
	s_mov_b32 m0, s30
	ds_read_b128 v[160:163], v203 offset:49152
	ds_read_b128 v[164:167], v203 offset:50176
	ds_read_b128 v[186:189], v203 offset:51200
	ds_read_b128 v[190:193], v203 offset:52224
	ds_read_b128 v[194:197], v203 offset:53248
	ds_read_b128 v[204:207], v203 offset:54272
	ds_read_b128 v[208:211], v203 offset:55296
	ds_read_b128 v[212:215], v203 offset:56320
	global_load_lds_dwordx4 v170, s[58:59]
	s_add_i32 m0, s30, 0x2000
	s_add_u32 s28, s28, 0x20080
	s_addc_u32 s29, s29, 0
	s_add_i32 s30, s54, s36
	global_load_lds_dwordx4 v174, s[58:59]
	s_mov_b32 m0, s30
	s_nop 0
	global_load_lds_dwordx4 v170, s[28:29]
	s_add_i32 m0, s30, 0x2000
	s_nop 0
	global_load_lds_dwordx4 v174, s[28:29]
	s_mov_b32 m0, s41
	s_nop 0
	global_load_lds_dwordx4 v168, s[60:61]
	s_mov_b32 m0, s42
	s_nop 0
	global_load_lds_dwordx4 v172, s[60:61]
	s_waitcnt vmcnt(8)
	s_waitcnt lgkmcnt(0)
	s_barrier
	s_setprio 1
	s_waitcnt lgkmcnt(0)
	v_mfma_f32_16x16x32_bf16 v[60:63], v[116:119], v[160:163], v[60:63]
	v_mfma_f32_16x16x32_bf16 v[52:55], v[124:127], v[160:163], v[52:55]
	v_mfma_f32_16x16x32_bf16 v[44:47], v[116:119], v[186:189], v[44:47]
	v_mfma_f32_16x16x32_bf16 v[36:39], v[124:127], v[186:189], v[36:39]
	v_mfma_f32_16x16x32_bf16 v[28:31], v[116:119], v[194:197], v[28:31]
	v_mfma_f32_16x16x32_bf16 v[20:23], v[124:127], v[194:197], v[20:23]
	v_mfma_f32_16x16x32_bf16 v[12:15], v[116:119], v[208:211], v[12:15]
	v_mfma_f32_16x16x32_bf16 v[4:7], v[124:127], v[208:211], v[4:7]
	v_mfma_f32_16x16x32_bf16 v[60:63], v[120:123], v[164:167], v[60:63]
	v_mfma_f32_16x16x32_bf16 v[52:55], v[136:139], v[164:167], v[52:55]
	v_mfma_f32_16x16x32_bf16 v[44:47], v[120:123], v[190:193], v[44:47]
	v_mfma_f32_16x16x32_bf16 v[36:39], v[136:139], v[190:193], v[36:39]
	v_mfma_f32_16x16x32_bf16 v[28:31], v[120:123], v[204:207], v[28:31]
	v_mfma_f32_16x16x32_bf16 v[20:23], v[136:139], v[204:207], v[20:23]
	v_mfma_f32_16x16x32_bf16 v[12:15], v[120:123], v[212:215], v[12:15]
	v_mfma_f32_16x16x32_bf16 v[4:7], v[136:139], v[212:215], v[4:7]
	s_setprio 0
	s_setprio 1
	v_mfma_f32_16x16x32_bf16 v[56:59], v[140:143], v[160:163], v[56:59]
	v_mfma_f32_16x16x32_bf16 v[48:51], v[152:155], v[160:163], v[48:51]
	v_mfma_f32_16x16x32_bf16 v[40:43], v[140:143], v[186:189], v[40:43]
	v_mfma_f32_16x16x32_bf16 v[32:35], v[152:155], v[186:189], v[32:35]
	v_mfma_f32_16x16x32_bf16 v[24:27], v[140:143], v[194:197], v[24:27]
	v_mfma_f32_16x16x32_bf16 v[16:19], v[152:155], v[194:197], v[16:19]
	v_mfma_f32_16x16x32_bf16 v[8:11], v[140:143], v[208:211], v[8:11]
	v_mfma_f32_16x16x32_bf16 v[0:3], v[152:155], v[208:211], v[0:3]
	v_mfma_f32_16x16x32_bf16 v[56:59], v[148:151], v[164:167], v[56:59]
	v_mfma_f32_16x16x32_bf16 v[48:51], v[156:159], v[164:167], v[48:51]
	v_mfma_f32_16x16x32_bf16 v[40:43], v[148:151], v[190:193], v[40:43]
	v_mfma_f32_16x16x32_bf16 v[32:35], v[156:159], v[190:193], v[32:35]
	v_mfma_f32_16x16x32_bf16 v[24:27], v[148:151], v[204:207], v[24:27]
	v_mfma_f32_16x16x32_bf16 v[16:19], v[156:159], v[204:207], v[16:19]
	v_mfma_f32_16x16x32_bf16 v[8:11], v[148:151], v[212:215], v[8:11]
	v_mfma_f32_16x16x32_bf16 v[0:3], v[156:159], v[212:215], v[0:3]
	s_setprio 0
	s_barrier
	s_add_i32 s52, s52, 2
	s_add_u32 s26, s26, 0x100
	s_addc_u32 s27, s27, 0
	s_add_u32 s50, s50, 0x100
	s_addc_u32 s51, s51, 0
	s_cmp_gt_u32 s52, 5
.LBB0_1041:
	ds_read_b128 v[116:119], v201
	ds_read_b128 v[120:123], v201 offset:1024
	ds_read_b128 v[124:127], v201 offset:2048
	ds_read_b128 v[136:139], v201 offset:3072
	ds_read_b128 v[140:143], v202
	ds_read_b128 v[148:151], v202 offset:1024
	ds_read_b128 v[152:155], v202 offset:2048
	ds_read_b128 v[156:159], v202 offset:3072
	s_add_u32 s28, s26, 0xfffe0080
	s_addc_u32 s29, s27, -1
	s_cmp_eq_u32 s52, 4
	s_cselect_b32 s31, s19, s29
	s_cselect_b32 s30, s48, s28
	s_cselect_b32 s29, s17, s51
	s_cselect_b32 s28, s49, s50
	s_add_u32 s60, s30, 0x80
	s_addc_u32 s61, s31, 0
	s_add_u32 s58, s28, 0x80
	s_addc_u32 s59, s29, 0
	s_add_i32 m0, s25, 0xc000
	ds_read_b128 v[160:163], v203
	ds_read_b128 v[164:167], v203 offset:1024
	ds_read_b128 v[186:189], v203 offset:2048
	ds_read_b128 v[190:193], v203 offset:3072
	ds_read_b128 v[194:197], v203 offset:4096
	ds_read_b128 v[204:207], v203 offset:5120
	ds_read_b128 v[208:211], v203 offset:6144
	ds_read_b128 v[212:215], v203 offset:7168
	global_load_lds_dwordx4 v178, s[26:27]
	s_add_i32 m0, s25, 0xe000
	s_nop 0
	global_load_lds_dwordx4 v180, s[26:27]
	s_waitcnt vmcnt(8)
	s_waitcnt lgkmcnt(0)
	s_barrier
; #define PG8_STAGE(bufoff, gbase, voff) do { _Pragma("unroll") for (int _i = 0; _i < 2; ++_i) \
;         __builtin_amdgcn_global_load_lds((const unsigned*)((const char*)(gbase) + (voff)[_i]), (LAS unsigned*)(lds + (bufoff) + ldsw + _i * 8192), 16, 0, 0); } while (0)
; #define PG8_LDA(dst, b, h) do { _Pragma("unroll") for (int m = 0; m < 4; ++m) _Pragma("unroll") for (int k = 0; k < 2; ++k) dst[m][k] = *(const LAS bf16x8*)(lds + PG8_SA(b, h) + aoff + m * 2048 + k * 1024); } while (0)
; #define PG8_LDB(dst, b, h) do { _Pragma("unroll") for (int n = 0; n < 2; ++n) _Pragma("unroll") for (int k = 0; k < 2; ++k) dst[n][k] = *(const LAS bf16x8*)(lds + PG8_SB(b, h) + boff + n * 2048 + k * 1024); } while (0)
; #define PG8_MMA(ai, bj, At, Bt) do { __builtin_amdgcn_s_setprio(1); _Pragma("unroll") for (int m = 0; m < 4; ++m) _Pragma("unroll") for (int n = 0; n < 2; ++n) _Pragma("unroll") for (int k = 0; k < 2; ++k) \
;         acc[ai][bj][m][n] = __builtin_amdgcn_mfma_f32_16x16x32_bf16(Bt[n][k], At[m][k], acc[ai][bj][m][n], 0, 0, 0); __builtin_amdgcn_s_setprio(0); } while (0)
; #define PG8_WAIT_V(n) asm volatile("s_waitcnt vmcnt(" #n ")" ::: "memory")
; #define PG8_WAIT_L(n) asm volatile("s_waitcnt lgkmcnt(" #n ")" ::: "memory")
; #define PG8_BAR __builtin_amdgcn_s_barrier()
; #define PG8_SCHED __builtin_amdgcn_sched_barrier(0)
; template <class Epi, class Sched>
; __device__ __forceinline__ void gemm_phase(LAS unsigned char* lds, const Gemm g, const Sched& S, const Epi& E, int wave_id) {
;     ...
;             PG8_LDB(B0, 0, 0); PG8_LDB(B1, 0, 1); PG8_SCHED; PG8_LDA(At, 0, 0); PG8_STAGE(PG8_SA(1, 1), a1 + hstepA, voffA);
;             PG8_WAIT_V(8); PG8_WAIT_L(0); PG8_BAR; PG8_MMA(0, 0, At, B0); PG8_MMA(0, 1, At, B1); PG8_BAR; PG8_SCHED;
;             PG8_LDA(At, 0, 1); PG8_STAGE(PG8_SB(0, 0), b2, voffB); PG8_STAGE(PG8_SB(0, 1), b2 + hstepB, voffB); PG8_STAGE(PG8_SA(0, 0), a2, voffA);
;             PG8_WAIT_V(8); PG8_WAIT_L(0); PG8_BAR; PG8_MMA(1, 0, At, B0); PG8_MMA(1, 1, At, B1); PG8_BAR; PG8_SCHED;
	s_setprio 1
	s_waitcnt lgkmcnt(0)
	v_mfma_f32_16x16x32_bf16 v[144:147], v[116:119], v[160:163], v[144:147]
	v_mfma_f32_16x16x32_bf16 v[128:131], v[124:127], v[160:163], v[128:131]
	v_mfma_f32_16x16x32_bf16 v[108:111], v[116:119], v[186:189], v[108:111]
	v_mfma_f32_16x16x32_bf16 v[100:103], v[124:127], v[186:189], v[100:103]
	v_mfma_f32_16x16x32_bf16 v[92:95], v[116:119], v[194:197], v[92:95]
	v_mfma_f32_16x16x32_bf16 v[84:87], v[124:127], v[194:197], v[84:87]
	v_mfma_f32_16x16x32_bf16 v[76:79], v[116:119], v[208:211], v[76:79]
	v_mfma_f32_16x16x32_bf16 v[68:71], v[124:127], v[208:211], v[68:71]
	v_mfma_f32_16x16x32_bf16 v[144:147], v[120:123], v[164:167], v[144:147]
	v_mfma_f32_16x16x32_bf16 v[128:131], v[136:139], v[164:167], v[128:131]
	v_mfma_f32_16x16x32_bf16 v[108:111], v[120:123], v[190:193], v[108:111]
	v_mfma_f32_16x16x32_bf16 v[100:103], v[136:139], v[190:193], v[100:103]
	v_mfma_f32_16x16x32_bf16 v[92:95], v[120:123], v[204:207], v[92:95]
	v_mfma_f32_16x16x32_bf16 v[84:87], v[136:139], v[204:207], v[84:87]
	v_mfma_f32_16x16x32_bf16 v[76:79], v[120:123], v[212:215], v[76:79]
	v_mfma_f32_16x16x32_bf16 v[68:71], v[136:139], v[212:215], v[68:71]
	s_setprio 0
	s_setprio 1
	v_mfma_f32_16x16x32_bf16 v[132:135], v[140:143], v[160:163], v[132:135]
	v_mfma_f32_16x16x32_bf16 v[112:115], v[152:155], v[160:163], v[112:115]
	v_mfma_f32_16x16x32_bf16 v[104:107], v[140:143], v[186:189], v[104:107]
	v_mfma_f32_16x16x32_bf16 v[96:99], v[152:155], v[186:189], v[96:99]
	v_mfma_f32_16x16x32_bf16 v[88:91], v[140:143], v[194:197], v[88:91]
	v_mfma_f32_16x16x32_bf16 v[80:83], v[152:155], v[194:197], v[80:83]
	v_mfma_f32_16x16x32_bf16 v[72:75], v[140:143], v[208:211], v[72:75]
	v_mfma_f32_16x16x32_bf16 v[64:67], v[152:155], v[208:211], v[64:67]
	v_mfma_f32_16x16x32_bf16 v[132:135], v[148:151], v[164:167], v[132:135]
	v_mfma_f32_16x16x32_bf16 v[112:115], v[156:159], v[164:167], v[112:115]
	v_mfma_f32_16x16x32_bf16 v[104:107], v[148:151], v[190:193], v[104:107]
	v_mfma_f32_16x16x32_bf16 v[96:99], v[156:159], v[190:193], v[96:99]
	v_mfma_f32_16x16x32_bf16 v[88:91], v[148:151], v[204:207], v[88:91]
	v_mfma_f32_16x16x32_bf16 v[80:83], v[156:159], v[204:207], v[80:83]
	v_mfma_f32_16x16x32_bf16 v[72:75], v[148:151], v[212:215], v[72:75]
	v_mfma_f32_16x16x32_bf16 v[64:67], v[156:159], v[212:215], v[64:67]
	s_setprio 0
	s_barrier
	s_add_i32 s53, s45, s36
	s_mov_b32 m0, s53
	ds_read_b128 v[160:163], v203 offset:16384
	ds_read_b128 v[164:167], v203 offset:17408
	ds_read_b128 v[186:189], v203 offset:18432
	ds_read_b128 v[190:193], v203 offset:19456
	ds_read_b128 v[194:197], v203 offset:20480
	ds_read_b128 v[204:207], v203 offset:21504
	ds_read_b128 v[208:211], v203 offset:22528
	ds_read_b128 v[212:215], v203 offset:23552
	global_load_lds_dwordx4 v170, s[28:29]
	s_add_i32 m0, s53, 0x2000
	s_add_u32 s54, s28, 0x20000
	s_addc_u32 s55, s29, 0
	s_add_i32 s53, s46, s36
	global_load_lds_dwordx4 v174, s[28:29]
	s_mov_b32 m0, s53
	s_nop 0
	global_load_lds_dwordx4 v170, s[54:55]
	s_add_i32 m0, s53, 0x2000
	s_nop 0
	global_load_lds_dwordx4 v174, s[54:55]
	s_mov_b32 m0, s25
	s_nop 0
	global_load_lds_dwordx4 v168, s[30:31]
	s_mov_b32 m0, s37
	s_nop 0
	global_load_lds_dwordx4 v172, s[30:31]
	s_waitcnt vmcnt(8)
	s_waitcnt lgkmcnt(0)
	s_barrier
	s_setprio 1
	s_waitcnt lgkmcnt(0)
	v_mfma_f32_16x16x32_bf16 v[60:63], v[116:119], v[160:163], v[60:63]
	v_mfma_f32_16x16x32_bf16 v[52:55], v[124:127], v[160:163], v[52:55]
	v_mfma_f32_16x16x32_bf16 v[44:47], v[116:119], v[186:189], v[44:47]
	v_mfma_f32_16x16x32_bf16 v[36:39], v[124:127], v[186:189], v[36:39]
	v_mfma_f32_16x16x32_bf16 v[28:31], v[116:119], v[194:197], v[28:31]
	v_mfma_f32_16x16x32_bf16 v[20:23], v[124:127], v[194:197], v[20:23]
	v_mfma_f32_16x16x32_bf16 v[12:15], v[116:119], v[208:211], v[12:15]
	v_mfma_f32_16x16x32_bf16 v[4:7], v[124:127], v[208:211], v[4:7]
	v_mfma_f32_16x16x32_bf16 v[60:63], v[120:123], v[164:167], v[60:63]
	v_mfma_f32_16x16x32_bf16 v[52:55], v[136:139], v[164:167], v[52:55]
	v_mfma_f32_16x16x32_bf16 v[44:47], v[120:123], v[190:193], v[44:47]
	v_mfma_f32_16x16x32_bf16 v[36:39], v[136:139], v[190:193], v[36:39]
	v_mfma_f32_16x16x32_bf16 v[28:31], v[120:123], v[204:207], v[28:31]
	v_mfma_f32_16x16x32_bf16 v[20:23], v[136:139], v[204:207], v[20:23]
	v_mfma_f32_16x16x32_bf16 v[12:15], v[120:123], v[212:215], v[12:15]
	v_mfma_f32_16x16x32_bf16 v[4:7], v[136:139], v[212:215], v[4:7]
	s_setprio 0
	s_setprio 1
	v_mfma_f32_16x16x32_bf16 v[56:59], v[140:143], v[160:163], v[56:59]
	v_mfma_f32_16x16x32_bf16 v[48:51], v[152:155], v[160:163], v[48:51]
	v_mfma_f32_16x16x32_bf16 v[40:43], v[140:143], v[186:189], v[40:43]
	v_mfma_f32_16x16x32_bf16 v[32:35], v[152:155], v[186:189], v[32:35]
	v_mfma_f32_16x16x32_bf16 v[24:27], v[140:143], v[194:197], v[24:27]
	v_mfma_f32_16x16x32_bf16 v[16:19], v[152:155], v[194:197], v[16:19]
	v_mfma_f32_16x16x32_bf16 v[8:11], v[140:143], v[208:211], v[8:11]
	v_mfma_f32_16x16x32_bf16 v[0:3], v[152:155], v[208:211], v[0:3]
	v_mfma_f32_16x16x32_bf16 v[56:59], v[148:151], v[164:167], v[56:59]
	v_mfma_f32_16x16x32_bf16 v[48:51], v[156:159], v[164:167], v[48:51]
	v_mfma_f32_16x16x32_bf16 v[40:43], v[148:151], v[190:193], v[40:43]
	v_mfma_f32_16x16x32_bf16 v[32:35], v[156:159], v[190:193], v[32:35]
	v_mfma_f32_16x16x32_bf16 v[24:27], v[148:151], v[204:207], v[24:27]
	v_mfma_f32_16x16x32_bf16 v[16:19], v[156:159], v[204:207], v[16:19]
	v_mfma_f32_16x16x32_bf16 v[8:11], v[148:151], v[212:215], v[8:11]
	v_mfma_f32_16x16x32_bf16 v[0:3], v[156:159], v[212:215], v[0:3]
	s_setprio 0
	s_barrier
; #define PG8_STAGE(bufoff, gbase, voff) do { _Pragma("unroll") for (int _i = 0; _i < 2; ++_i) \
;         __builtin_amdgcn_global_load_lds((const unsigned*)((const char*)(gbase) + (voff)[_i]), (LAS unsigned*)(lds + (bufoff) + ldsw + _i * 8192), 16, 0, 0); } while (0)
; #define PG8_LDA(dst, b, h) do { _Pragma("unroll") for (int m = 0; m < 4; ++m) _Pragma("unroll") for (int k = 0; k < 2; ++k) dst[m][k] = *(const LAS bf16x8*)(lds + PG8_SA(b, h) + aoff + m * 2048 + k * 1024); } while (0)
; #define PG8_LDB(dst, b, h) do { _Pragma("unroll") for (int n = 0; n < 2; ++n) _Pragma("unroll") for (int k = 0; k < 2; ++k) dst[n][k] = *(const LAS bf16x8*)(lds + PG8_SB(b, h) + boff + n * 2048 + k * 1024); } while (0)
; #define PG8_MMA(ai, bj, At, Bt) do { __builtin_amdgcn_s_setprio(1); _Pragma("unroll") for (int m = 0; m < 4; ++m) _Pragma("unroll") for (int n = 0; n < 2; ++n) _Pragma("unroll") for (int k = 0; k < 2; ++k) \
;         acc[ai][bj][m][n] = __builtin_amdgcn_mfma_f32_16x16x32_bf16(Bt[n][k], At[m][k], acc[ai][bj][m][n], 0, 0, 0); __builtin_amdgcn_s_setprio(0); } while (0)
; #define PG8_WAIT_V(n) asm volatile("s_waitcnt vmcnt(" #n ")" ::: "memory")
; #define PG8_WAIT_L(n) asm volatile("s_waitcnt lgkmcnt(" #n ")" ::: "memory")
; #define PG8_BAR __builtin_amdgcn_s_barrier()
; #define PG8_SCHED __builtin_amdgcn_sched_barrier(0)
; template <class Epi, class Sched>
; __device__ __forceinline__ void gemm_phase(LAS unsigned char* lds, const Gemm g, const Sched& S, const Epi& E, int wave_id) {
;     ...
;             PG8_LDB(B0, 1, 0); PG8_LDB(B1, 1, 1); PG8_SCHED; PG8_LDA(At, 1, 0); PG8_STAGE(PG8_SA(0, 1), a2 + hstepA, voffA);
;             PG8_WAIT_V(8); PG8_WAIT_L(0); PG8_BAR; PG8_MMA(0, 0, At, B0); PG8_MMA(0, 1, At, B1); PG8_BAR; PG8_SCHED;
;             PG8_LDA(At, 1, 1); PG8_STAGE(PG8_SB(1, 0), b3, voffB); PG8_STAGE(PG8_SB(1, 1), b3 + hstepB, voffB); PG8_STAGE(PG8_SA(1, 0), a3, voffA);
;             PG8_WAIT_V(8); PG8_WAIT_L(0); PG8_BAR; PG8_MMA(1, 0, At, B0); PG8_MMA(1, 1, At, B1); PG8_BAR; PG8_SCHED;
	s_add_i32 s53, 0, 0x18000
	s_add_i32 s54, 0, 0x1c000
	v_add_u32_e32 v136, s53, v199
	v_add_u32_e32 v156, s54, v199
	ds_read_b128 v[116:119], v136
	ds_read_b128 v[120:123], v136 offset:1024
	ds_read_b128 v[124:127], v136 offset:2048
	ds_read_b128 v[136:139], v136 offset:3072
	ds_read_b128 v[140:143], v156
	ds_read_b128 v[148:151], v156 offset:1024
	ds_read_b128 v[152:155], v156 offset:2048
	ds_read_b128 v[156:159], v156 offset:3072
	s_add_u32 s30, s30, 0x20000
	s_addc_u32 s31, s31, 0
	s_mov_b32 m0, s38
	ds_read_b128 v[160:163], v203 offset:32768
	ds_read_b128 v[164:167], v203 offset:33792
	ds_read_b128 v[186:189], v203 offset:34816
	ds_read_b128 v[190:193], v203 offset:35840
	ds_read_b128 v[194:197], v203 offset:36864
	ds_read_b128 v[204:207], v203 offset:37888
	ds_read_b128 v[208:211], v203 offset:38912
	ds_read_b128 v[212:215], v203 offset:39936
	global_load_lds_dwordx4 v168, s[30:31]
	s_mov_b32 m0, s39
	s_nop 0
	global_load_lds_dwordx4 v172, s[30:31]
	s_waitcnt vmcnt(8)
	s_waitcnt lgkmcnt(0)
	s_barrier
	s_setprio 1
	s_waitcnt lgkmcnt(0)
	v_mfma_f32_16x16x32_bf16 v[144:147], v[116:119], v[160:163], v[144:147]
	v_mfma_f32_16x16x32_bf16 v[128:131], v[124:127], v[160:163], v[128:131]
	v_mfma_f32_16x16x32_bf16 v[108:111], v[116:119], v[186:189], v[108:111]
	v_mfma_f32_16x16x32_bf16 v[100:103], v[124:127], v[186:189], v[100:103]
	v_mfma_f32_16x16x32_bf16 v[92:95], v[116:119], v[194:197], v[92:95]
	v_mfma_f32_16x16x32_bf16 v[84:87], v[124:127], v[194:197], v[84:87]
	v_mfma_f32_16x16x32_bf16 v[76:79], v[116:119], v[208:211], v[76:79]
	v_mfma_f32_16x16x32_bf16 v[68:71], v[124:127], v[208:211], v[68:71]
	v_mfma_f32_16x16x32_bf16 v[144:147], v[120:123], v[164:167], v[144:147]
	v_mfma_f32_16x16x32_bf16 v[128:131], v[136:139], v[164:167], v[128:131]
	v_mfma_f32_16x16x32_bf16 v[108:111], v[120:123], v[190:193], v[108:111]
	v_mfma_f32_16x16x32_bf16 v[100:103], v[136:139], v[190:193], v[100:103]
	v_mfma_f32_16x16x32_bf16 v[92:95], v[120:123], v[204:207], v[92:95]
	v_mfma_f32_16x16x32_bf16 v[84:87], v[136:139], v[204:207], v[84:87]
	v_mfma_f32_16x16x32_bf16 v[76:79], v[120:123], v[212:215], v[76:79]
	v_mfma_f32_16x16x32_bf16 v[68:71], v[136:139], v[212:215], v[68:71]
	s_setprio 0
	s_setprio 1
	v_mfma_f32_16x16x32_bf16 v[132:135], v[140:143], v[160:163], v[132:135]
	v_mfma_f32_16x16x32_bf16 v[112:115], v[152:155], v[160:163], v[112:115]
	v_mfma_f32_16x16x32_bf16 v[104:107], v[140:143], v[186:189], v[104:107]
	v_mfma_f32_16x16x32_bf16 v[96:99], v[152:155], v[186:189], v[96:99]
	v_mfma_f32_16x16x32_bf16 v[88:91], v[140:143], v[194:197], v[88:91]
	v_mfma_f32_16x16x32_bf16 v[80:83], v[152:155], v[194:197], v[80:83]
	v_mfma_f32_16x16x32_bf16 v[72:75], v[140:143], v[208:211], v[72:75]
	v_mfma_f32_16x16x32_bf16 v[64:67], v[152:155], v[208:211], v[64:67]
	v_mfma_f32_16x16x32_bf16 v[132:135], v[148:151], v[164:167], v[132:135]
	v_mfma_f32_16x16x32_bf16 v[112:115], v[156:159], v[164:167], v[112:115]
	v_mfma_f32_16x16x32_bf16 v[104:107], v[148:151], v[190:193], v[104:107]
	v_mfma_f32_16x16x32_bf16 v[96:99], v[156:159], v[190:193], v[96:99]
	v_mfma_f32_16x16x32_bf16 v[88:91], v[148:151], v[204:207], v[88:91]
	v_mfma_f32_16x16x32_bf16 v[80:83], v[156:159], v[204:207], v[80:83]
	v_mfma_f32_16x16x32_bf16 v[72:75], v[148:151], v[212:215], v[72:75]
	v_mfma_f32_16x16x32_bf16 v[64:67], v[156:159], v[212:215], v[64:67]
	s_setprio 0
	s_barrier
	s_add_i32 s30, s53, s36
	s_mov_b32 m0, s30
	ds_read_b128 v[160:163], v203 offset:49152
	ds_read_b128 v[164:167], v203 offset:50176
	ds_read_b128 v[186:189], v203 offset:51200
	ds_read_b128 v[190:193], v203 offset:52224
	ds_read_b128 v[194:197], v203 offset:53248
	ds_read_b128 v[204:207], v203 offset:54272
	ds_read_b128 v[208:211], v203 offset:55296
	ds_read_b128 v[212:215], v203 offset:56320
	global_load_lds_dwordx4 v170, s[58:59]
	s_add_i32 m0, s30, 0x2000
	s_add_u32 s28, s28, 0x20080
	s_addc_u32 s29, s29, 0
	s_add_i32 s30, s54, s36
	global_load_lds_dwordx4 v174, s[58:59]
	s_mov_b32 m0, s30
	s_nop 0
	global_load_lds_dwordx4 v170, s[28:29]
	s_add_i32 m0, s30, 0x2000
	s_nop 0
	global_load_lds_dwordx4 v174, s[28:29]
	s_mov_b32 m0, s41
	s_nop 0
	global_load_lds_dwordx4 v168, s[60:61]
	s_mov_b32 m0, s42
	s_nop 0
	global_load_lds_dwordx4 v172, s[60:61]
	s_waitcnt vmcnt(8)
	s_waitcnt lgkmcnt(0)
	s_barrier
	s_setprio 1
	s_waitcnt lgkmcnt(0)
	v_mfma_f32_16x16x32_bf16 v[60:63], v[116:119], v[160:163], v[60:63]
	v_mfma_f32_16x16x32_bf16 v[52:55], v[124:127], v[160:163], v[52:55]
	v_mfma_f32_16x16x32_bf16 v[44:47], v[116:119], v[186:189], v[44:47]
	v_mfma_f32_16x16x32_bf16 v[36:39], v[124:127], v[186:189], v[36:39]
	v_mfma_f32_16x16x32_bf16 v[28:31], v[116:119], v[194:197], v[28:31]
	v_mfma_f32_16x16x32_bf16 v[20:23], v[124:127], v[194:197], v[20:23]
	v_mfma_f32_16x16x32_bf16 v[12:15], v[116:119], v[208:211], v[12:15]
	v_mfma_f32_16x16x32_bf16 v[4:7], v[124:127], v[208:211], v[4:7]
	v_mfma_f32_16x16x32_bf16 v[60:63], v[120:123], v[164:167], v[60:63]
	v_mfma_f32_16x16x32_bf16 v[52:55], v[136:139], v[164:167], v[52:55]
	v_mfma_f32_16x16x32_bf16 v[44:47], v[120:123], v[190:193], v[44:47]
	v_mfma_f32_16x16x32_bf16 v[36:39], v[136:139], v[190:193], v[36:39]
	v_mfma_f32_16x16x32_bf16 v[28:31], v[120:123], v[204:207], v[28:31]
	v_mfma_f32_16x16x32_bf16 v[20:23], v[136:139], v[204:207], v[20:23]
	v_mfma_f32_16x16x32_bf16 v[12:15], v[120:123], v[212:215], v[12:15]
	v_mfma_f32_16x16x32_bf16 v[4:7], v[136:139], v[212:215], v[4:7]
	s_setprio 0
	s_setprio 1
	v_mfma_f32_16x16x32_bf16 v[56:59], v[140:143], v[160:163], v[56:59]
	v_mfma_f32_16x16x32_bf16 v[48:51], v[152:155], v[160:163], v[48:51]
	v_mfma_f32_16x16x32_bf16 v[40:43], v[140:143], v[186:189], v[40:43]
	v_mfma_f32_16x16x32_bf16 v[32:35], v[152:155], v[186:189], v[32:35]
	v_mfma_f32_16x16x32_bf16 v[24:27], v[140:143], v[194:197], v[24:27]
	v_mfma_f32_16x16x32_bf16 v[16:19], v[152:155], v[194:197], v[16:19]
	v_mfma_f32_16x16x32_bf16 v[8:11], v[140:143], v[208:211], v[8:11]
	v_mfma_f32_16x16x32_bf16 v[0:3], v[152:155], v[208:211], v[0:3]
	v_mfma_f32_16x16x32_bf16 v[56:59], v[148:151], v[164:167], v[56:59]
	v_mfma_f32_16x16x32_bf16 v[48:51], v[156:159], v[164:167], v[48:51]
	v_mfma_f32_16x16x32_bf16 v[40:43], v[148:151], v[190:193], v[40:43]
	v_mfma_f32_16x16x32_bf16 v[32:35], v[156:159], v[190:193], v[32:35]
	v_mfma_f32_16x16x32_bf16 v[24:27], v[148:151], v[204:207], v[24:27]
	v_mfma_f32_16x16x32_bf16 v[16:19], v[156:159], v[204:207], v[16:19]
	v_mfma_f32_16x16x32_bf16 v[8:11], v[148:151], v[212:215], v[8:11]
	v_mfma_f32_16x16x32_bf16 v[0:3], v[156:159], v[212:215], v[0:3]
	s_setprio 0
	s_barrier
	s_add_i32 s52, s52, 2
	s_add_u32 s26, s26, 0x100
	s_addc_u32 s27, s27, 0
	s_add_u32 s50, s50, 0x100
	s_addc_u32 s51, s51, 0
	s_cmp_gt_u32 s52, 5
	s_cbranch_scc0 .LBB0_1041
	s_and_b64 vcc, exec, s[12:13]
	s_cbranch_vccz .LBB0_1044
	s_barrier

;     __device__ bool next(int i, Unit& u) const { if (r0 + i >= r1) return false; return base.next(r0 + i, u); }
;     __device__ bool next(int i, Unit& u) const { const int L = i * G + c; if (L >= 256) return false; u.pm = L; u.pn = L >> 3; return true; }
; #define PG8_STAGE(bufoff, gbase, voff) do { _Pragma("unroll") for (int _i = 0; _i < 2; ++_i) \
;         __builtin_amdgcn_global_load_lds((const unsigned*)((const char*)(gbase) + (voff)[_i]), (LAS unsigned*)(lds + (bufoff) + ldsw + _i * 8192), 16, 0, 0); } while (0)
; #define PG8_LDA(dst, b, h) do { _Pragma("unroll") for (int m = 0; m < 4; ++m) _Pragma("unroll") for (int k = 0; k < 2; ++k) dst[m][k] = *(const LAS bf16x8*)(lds + PG8_SA(b, h) + aoff + m * 2048 + k * 1024); } while (0)
; #define PG8_LDB(dst, b, h) do { _Pragma("unroll") for (int n = 0; n < 2; ++n) _Pragma("unroll") for (int k = 0; k < 2; ++k) dst[n][k] = *(const LAS bf16x8*)(lds + PG8_SB(b, h) + boff + n * 2048 + k * 1024); } while (0)
; #define PG8_WAIT_V(n) asm volatile("s_waitcnt vmcnt(" #n ")" ::: "memory")
; #define PG8_WAIT_L(n) asm volatile("s_waitcnt lgkmcnt(" #n ")" ::: "memory")
; template <class Epi, class Sched>
; __device__ __forceinline__ void gemm_phase(LAS unsigned char* lds, const Gemm g, const Sched& S, const Epi& E, int wave_id) {
;     ...
;         const bool has_next = S.next(ui + 1, nxt);
;         const char* nA = has_next ? (const char*)g.A + (size_t)nxt.pm * tstepA : cA; const char* nB = has_next ? (const char*)g.Bt + (size_t)nxt.pn * tstepB : cB;
;         for (int t = 0; t < nt; t += 2) {
;             const bool last = (t == nt - 2);
;             const char* a1 = cA + (size_t)(t + 1) * kstep;
;             const char* a2 = last ? nA : cA + (size_t)(t + 2) * kstep; const char* b2 = last ? nB : cB + (size_t)(t + 2) * kstep;
;             const char* a3 = a2 + kstep; const char* b3 = b2 + kstep;
;             PG8_LDB(B0, 0, 0); PG8_LDB(B1, 0, 1); PG8_SCHED; PG8_LDA(At, 0, 0); PG8_STAGE(PG8_SA(1, 1), a1 + hstepA, voffA);
;             PG8_WAIT_V(8); PG8_WAIT_L(0); PG8_BAR; PG8_MMA(0, 0, At, B0); PG8_MMA(0, 1, At, B1); PG8_BAR; PG8_SCHED;
;             PG8_LDA(At, 0, 1); PG8_STAGE(PG8_SB(0, 0), b2, voffB); PG8_STAGE(PG8_SB(0, 1), b2 + hstepB, voffB); PG8_STAGE(PG8_SA(0, 0), a2, voffA);
;             PG8_WAIT_V(8); PG8_WAIT_L(0); PG8_BAR; PG8_MMA(1, 0, At, B0); PG8_MMA(1, 1, At, B1); PG8_BAR; PG8_SCHED;
.LBB0_1145:
	s_ashr_i32 s21, s20, 31
	s_lshl_b64 s[22:23], s[20:21], 18
	s_add_u32 s22, s3, s22
	s_addc_u32 s23, s17, s23
	s_and_b64 s[24:25], s[4:5], exec
	s_cselect_b32 s21, s23, s29
	s_cselect_b32 s56, s22, s28
	s_ashr_i32 s19, s18, 31
	s_lshl_b64 s[24:25], s[18:19], 18
	s_add_u32 s24, s33, s24
	s_addc_u32 s25, s36, s25
	s_and_b64 s[34:35], s[4:5], exec
	s_cselect_b32 s19, s25, s31
	s_cselect_b32 s57, s24, s30
	s_add_u32 s28, s28, 0x20080
	s_addc_u32 s29, s29, 0
	s_add_u32 s58, s30, 0x100
	s_addc_u32 s59, s31, 0
	s_mov_b32 s60, -2
	s_waitcnt vmcnt(0)
	ds_read_b128 v[128:131], v206
	ds_read_b128 v[132:135], v206 offset:1024
	ds_read_b128 v[136:139], v206 offset:2048
	ds_read_b128 v[140:143], v206 offset:3072
	ds_read_b128 v[144:147], v207
	ds_read_b128 v[148:151], v207 offset:1024
	ds_read_b128 v[178:181], v207 offset:2048
	ds_read_b128 v[182:185], v207 offset:3072
	s_add_u32 s30, s28, 0xfffe0080
	s_addc_u32 s31, s29, -1
	s_cmp_eq_u32 s60, 4
	s_cselect_b32 s35, s21, s31
	s_cselect_b32 s34, s56, s30
	s_cselect_b32 s31, s19, s59
	s_cselect_b32 s30, s57, s58
	s_add_u32 s72, s34, 0x80
	s_addc_u32 s73, s35, 0
	s_add_u32 s64, s30, 0x80
	s_addc_u32 s65, s31, 0
	s_add_i32 m0, s38, 0xc000
	ds_read_b128 v[186:189], v208
	ds_read_b128 v[190:193], v208 offset:1024
	ds_read_b128 v[194:197], v208 offset:2048
	ds_read_b128 v[198:201], v208 offset:3072
	ds_read_b128 v[212:215], v208 offset:4096
	ds_read_b128 v[216:219], v208 offset:5120
	ds_read_b128 v[220:223], v208 offset:6144
	ds_read_b128 v[224:227], v208 offset:7168
	global_load_lds_dwordx4 v170, s[28:29]
	s_add_i32 m0, s38, 0xe000
	s_nop 0
	global_load_lds_dwordx4 v172, s[28:29]
	s_waitcnt vmcnt(8)
	s_waitcnt lgkmcnt(0)
	s_barrier
	s_setprio 1
	s_waitcnt lgkmcnt(0)
	v_mfma_f32_16x16x32_bf16 v[124:127], v[128:131], v[186:189], 0
	v_mfma_f32_16x16x32_bf16 v[120:123], v[136:139], v[186:189], 0
	v_mfma_f32_16x16x32_bf16 v[108:111], v[128:131], v[194:197], 0
	v_mfma_f32_16x16x32_bf16 v[104:107], v[136:139], v[194:197], 0
	v_mfma_f32_16x16x32_bf16 v[92:95], v[128:131], v[212:215], 0
	v_mfma_f32_16x16x32_bf16 v[88:91], v[136:139], v[212:215], 0
	v_mfma_f32_16x16x32_bf16 v[76:79], v[128:131], v[220:223], 0
	v_mfma_f32_16x16x32_bf16 v[72:75], v[136:139], v[220:223], 0
	v_mfma_f32_16x16x32_bf16 v[124:127], v[132:135], v[190:193], v[124:127]
	v_mfma_f32_16x16x32_bf16 v[120:123], v[140:143], v[190:193], v[120:123]
	v_mfma_f32_16x16x32_bf16 v[108:111], v[132:135], v[198:201], v[108:111]
	v_mfma_f32_16x16x32_bf16 v[104:107], v[140:143], v[198:201], v[104:107]
	v_mfma_f32_16x16x32_bf16 v[92:95], v[132:135], v[216:219], v[92:95]
	v_mfma_f32_16x16x32_bf16 v[88:91], v[140:143], v[216:219], v[88:91]
	v_mfma_f32_16x16x32_bf16 v[76:79], v[132:135], v[224:227], v[76:79]
	v_mfma_f32_16x16x32_bf16 v[72:75], v[140:143], v[224:227], v[72:75]
	s_setprio 0
	s_setprio 1
	v_mfma_f32_16x16x32_bf16 v[116:119], v[144:147], v[186:189], 0
	v_mfma_f32_16x16x32_bf16 v[112:115], v[178:181], v[186:189], 0
	v_mfma_f32_16x16x32_bf16 v[100:103], v[144:147], v[194:197], 0
	v_mfma_f32_16x16x32_bf16 v[96:99], v[178:181], v[194:197], 0
	v_mfma_f32_16x16x32_bf16 v[84:87], v[144:147], v[212:215], 0
	v_mfma_f32_16x16x32_bf16 v[80:83], v[178:181], v[212:215], 0
	v_mfma_f32_16x16x32_bf16 v[68:71], v[144:147], v[220:223], 0
	v_mfma_f32_16x16x32_bf16 v[64:67], v[178:181], v[220:223], 0
	v_mfma_f32_16x16x32_bf16 v[116:119], v[148:151], v[190:193], v[116:119]
	v_mfma_f32_16x16x32_bf16 v[112:115], v[182:185], v[190:193], v[112:115]
	v_mfma_f32_16x16x32_bf16 v[100:103], v[148:151], v[198:201], v[100:103]
	v_mfma_f32_16x16x32_bf16 v[96:99], v[182:185], v[198:201], v[96:99]
	v_mfma_f32_16x16x32_bf16 v[84:87], v[148:151], v[216:219], v[84:87]
	v_mfma_f32_16x16x32_bf16 v[80:83], v[182:185], v[216:219], v[80:83]
	v_mfma_f32_16x16x32_bf16 v[68:71], v[148:151], v[224:227], v[68:71]
	v_mfma_f32_16x16x32_bf16 v[64:67], v[182:185], v[224:227], v[64:67]
	s_setprio 0
	s_barrier
	s_add_i32 s61, s54, s37
	s_mov_b32 m0, s61
	ds_read_b128 v[186:189], v208 offset:16384
	ds_read_b128 v[190:193], v208 offset:17408
	ds_read_b128 v[194:197], v208 offset:18432
	ds_read_b128 v[198:201], v208 offset:19456
	ds_read_b128 v[212:215], v208 offset:20480
	ds_read_b128 v[216:219], v208 offset:21504
	ds_read_b128 v[220:223], v208 offset:22528
	ds_read_b128 v[224:227], v208 offset:23552
	global_load_lds_dwordx4 v154, s[30:31]
	s_add_i32 m0, s61, 0x2000
	s_add_u32 s62, s30, 0x20000
	s_addc_u32 s63, s31, 0
	s_add_i32 s61, s55, s37
	global_load_lds_dwordx4 v158, s[30:31]
	s_mov_b32 m0, s61
	s_nop 0
	global_load_lds_dwordx4 v154, s[62:63]
	s_add_i32 m0, s61, 0x2000
	s_nop 0
	global_load_lds_dwordx4 v158, s[62:63]
	s_mov_b32 m0, s38
	s_nop 0
	global_load_lds_dwordx4 v152, s[34:35]
	s_mov_b32 m0, s39
	s_nop 0
	global_load_lds_dwordx4 v156, s[34:35]
	s_waitcnt vmcnt(8)
	s_waitcnt lgkmcnt(0)
	s_barrier
; #define PG8_STAGE(bufoff, gbase, voff) do { _Pragma("unroll") for (int _i = 0; _i < 2; ++_i) \
;         __builtin_amdgcn_global_load_lds((const unsigned*)((const char*)(gbase) + (voff)[_i]), (LAS unsigned*)(lds + (bufoff) + ldsw + _i * 8192), 16, 0, 0); } while (0)
; #define PG8_LDA(dst, b, h) do { _Pragma("unroll") for (int m = 0; m < 4; ++m) _Pragma("unroll") for (int k = 0; k < 2; ++k) dst[m][k] = *(const LAS bf16x8*)(lds + PG8_SA(b, h) + aoff + m * 2048 + k * 1024); } while (0)
; #define PG8_LDB(dst, b, h) do { _Pragma("unroll") for (int n = 0; n < 2; ++n) _Pragma("unroll") for (int k = 0; k < 2; ++k) dst[n][k] = *(const LAS bf16x8*)(lds + PG8_SB(b, h) + boff + n * 2048 + k * 1024); } while (0)
; #define PG8_MMA(ai, bj, At, Bt) do { __builtin_amdgcn_s_setprio(1); _Pragma("unroll") for (int m = 0; m < 4; ++m) _Pragma("unroll") for (int n = 0; n < 2; ++n) _Pragma("unroll") for (int k = 0; k < 2; ++k) \
;         acc[ai][bj][m][n] = __builtin_amdgcn_mfma_f32_16x16x32_bf16(Bt[n][k], At[m][k], acc[ai][bj][m][n], 0, 0, 0); __builtin_amdgcn_s_setprio(0); } while (0)
; #define PG8_WAIT_V(n) asm volatile("s_waitcnt vmcnt(" #n ")" ::: "memory")
; #define PG8_WAIT_L(n) asm volatile("s_waitcnt lgkmcnt(" #n ")" ::: "memory")
; #define PG8_BAR __builtin_amdgcn_s_barrier()
; #define PG8_SCHED __builtin_amdgcn_sched_barrier(0)
; template <class Epi, class Sched>
; __device__ __forceinline__ void gemm_phase(LAS unsigned char* lds, const Gemm g, const Sched& S, const Epi& E, int wave_id) {
;     ...
;             PG8_WAIT_V(8); PG8_WAIT_L(0); PG8_BAR; PG8_MMA(1, 0, At, B0); PG8_MMA(1, 1, At, B1); PG8_BAR; PG8_SCHED;
;             PG8_LDB(B0, 1, 0); PG8_LDB(B1, 1, 1); PG8_SCHED; PG8_LDA(At, 1, 0); PG8_STAGE(PG8_SA(0, 1), a2 + hstepA, voffA);
;             PG8_WAIT_V(8); PG8_WAIT_L(0); PG8_BAR; PG8_MMA(0, 0, At, B0); PG8_MMA(0, 1, At, B1); PG8_BAR; PG8_SCHED;
	s_setprio 1
	s_waitcnt lgkmcnt(0)
	v_mfma_f32_16x16x32_bf16 v[60:63], v[128:131], v[186:189], 0
	v_mfma_f32_16x16x32_bf16 v[56:59], v[136:139], v[186:189], 0
	v_mfma_f32_16x16x32_bf16 v[44:47], v[128:131], v[194:197], 0
	v_mfma_f32_16x16x32_bf16 v[40:43], v[136:139], v[194:197], 0
	v_mfma_f32_16x16x32_bf16 v[28:31], v[128:131], v[212:215], 0
	v_mfma_f32_16x16x32_bf16 v[24:27], v[136:139], v[212:215], 0
	v_mfma_f32_16x16x32_bf16 v[12:15], v[128:131], v[220:223], 0
	v_mfma_f32_16x16x32_bf16 v[8:11], v[136:139], v[220:223], 0
	v_mfma_f32_16x16x32_bf16 v[60:63], v[132:135], v[190:193], v[60:63]
	v_mfma_f32_16x16x32_bf16 v[56:59], v[140:143], v[190:193], v[56:59]
	v_mfma_f32_16x16x32_bf16 v[44:47], v[132:135], v[198:201], v[44:47]
	v_mfma_f32_16x16x32_bf16 v[40:43], v[140:143], v[198:201], v[40:43]
	v_mfma_f32_16x16x32_bf16 v[28:31], v[132:135], v[216:219], v[28:31]
	v_mfma_f32_16x16x32_bf16 v[24:27], v[140:143], v[216:219], v[24:27]
	v_mfma_f32_16x16x32_bf16 v[12:15], v[132:135], v[224:227], v[12:15]
	v_mfma_f32_16x16x32_bf16 v[8:11], v[140:143], v[224:227], v[8:11]
	s_setprio 0
	s_setprio 1
	v_mfma_f32_16x16x32_bf16 v[52:55], v[144:147], v[186:189], 0
	v_mfma_f32_16x16x32_bf16 v[48:51], v[178:181], v[186:189], 0
	v_mfma_f32_16x16x32_bf16 v[36:39], v[144:147], v[194:197], 0
	v_mfma_f32_16x16x32_bf16 v[32:35], v[178:181], v[194:197], 0
	v_mfma_f32_16x16x32_bf16 v[20:23], v[144:147], v[212:215], 0
	v_mfma_f32_16x16x32_bf16 v[16:19], v[178:181], v[212:215], 0
	v_mfma_f32_16x16x32_bf16 v[4:7], v[144:147], v[220:223], 0
	v_mfma_f32_16x16x32_bf16 v[0:3], v[178:181], v[220:223], 0
	v_mfma_f32_16x16x32_bf16 v[52:55], v[148:151], v[190:193], v[52:55]
	v_mfma_f32_16x16x32_bf16 v[48:51], v[182:185], v[190:193], v[48:51]
	v_mfma_f32_16x16x32_bf16 v[36:39], v[148:151], v[198:201], v[36:39]
	v_mfma_f32_16x16x32_bf16 v[32:35], v[182:185], v[198:201], v[32:35]
	v_mfma_f32_16x16x32_bf16 v[20:23], v[148:151], v[216:219], v[20:23]
	v_mfma_f32_16x16x32_bf16 v[16:19], v[182:185], v[216:219], v[16:19]
	v_mfma_f32_16x16x32_bf16 v[4:7], v[148:151], v[224:227], v[4:7]
	v_mfma_f32_16x16x32_bf16 v[0:3], v[182:185], v[224:227], v[0:3]
	s_setprio 0
	s_barrier
	s_add_i32 s61, 0, 0x18000
	s_add_i32 s62, 0, 0x1c000
	v_add_u32_e32 v140, s61, v205
	v_add_u32_e32 v182, s62, v205
	ds_read_b128 v[128:131], v140
	ds_read_b128 v[132:135], v140 offset:1024
	ds_read_b128 v[136:139], v140 offset:2048
	ds_read_b128 v[140:143], v140 offset:3072
	ds_read_b128 v[144:147], v182
	ds_read_b128 v[148:151], v182 offset:1024
	ds_read_b128 v[178:181], v182 offset:2048
	ds_read_b128 v[182:185], v182 offset:3072
	s_add_u32 s34, s34, 0x20000
	s_addc_u32 s35, s35, 0
	s_mov_b32 m0, s40
	ds_read_b128 v[186:189], v208 offset:32768
	ds_read_b128 v[190:193], v208 offset:33792
	ds_read_b128 v[194:197], v208 offset:34816
	ds_read_b128 v[198:201], v208 offset:35840
	ds_read_b128 v[212:215], v208 offset:36864
	ds_read_b128 v[216:219], v208 offset:37888
	ds_read_b128 v[220:223], v208 offset:38912
	ds_read_b128 v[224:227], v208 offset:39936
	global_load_lds_dwordx4 v152, s[34:35]
	s_mov_b32 m0, s41
	s_nop 0
	global_load_lds_dwordx4 v156, s[34:35]
	s_waitcnt vmcnt(8)
	s_waitcnt lgkmcnt(0)
	s_barrier
	s_setprio 1
	s_waitcnt lgkmcnt(0)
	v_mfma_f32_16x16x32_bf16 v[124:127], v[128:131], v[186:189], v[124:127]
	v_mfma_f32_16x16x32_bf16 v[120:123], v[136:139], v[186:189], v[120:123]
	v_mfma_f32_16x16x32_bf16 v[108:111], v[128:131], v[194:197], v[108:111]
	v_mfma_f32_16x16x32_bf16 v[104:107], v[136:139], v[194:197], v[104:107]
	v_mfma_f32_16x16x32_bf16 v[92:95], v[128:131], v[212:215], v[92:95]
	v_mfma_f32_16x16x32_bf16 v[88:91], v[136:139], v[212:215], v[88:91]
	v_mfma_f32_16x16x32_bf16 v[76:79], v[128:131], v[220:223], v[76:79]
	v_mfma_f32_16x16x32_bf16 v[72:75], v[136:139], v[220:223], v[72:75]
	v_mfma_f32_16x16x32_bf16 v[124:127], v[132:135], v[190:193], v[124:127]
	v_mfma_f32_16x16x32_bf16 v[120:123], v[140:143], v[190:193], v[120:123]
	v_mfma_f32_16x16x32_bf16 v[108:111], v[132:135], v[198:201], v[108:111]
	v_mfma_f32_16x16x32_bf16 v[104:107], v[140:143], v[198:201], v[104:107]
	v_mfma_f32_16x16x32_bf16 v[92:95], v[132:135], v[216:219], v[92:95]
	v_mfma_f32_16x16x32_bf16 v[88:91], v[140:143], v[216:219], v[88:91]
	v_mfma_f32_16x16x32_bf16 v[76:79], v[132:135], v[224:227], v[76:79]
	v_mfma_f32_16x16x32_bf16 v[72:75], v[140:143], v[224:227], v[72:75]
	s_setprio 0
	s_setprio 1
	v_mfma_f32_16x16x32_bf16 v[116:119], v[144:147], v[186:189], v[116:119]
	v_mfma_f32_16x16x32_bf16 v[112:115], v[178:181], v[186:189], v[112:115]
	v_mfma_f32_16x16x32_bf16 v[100:103], v[144:147], v[194:197], v[100:103]
	v_mfma_f32_16x16x32_bf16 v[96:99], v[178:181], v[194:197], v[96:99]
	v_mfma_f32_16x16x32_bf16 v[84:87], v[144:147], v[212:215], v[84:87]
	v_mfma_f32_16x16x32_bf16 v[80:83], v[178:181], v[212:215], v[80:83]
	v_mfma_f32_16x16x32_bf16 v[68:71], v[144:147], v[220:223], v[68:71]
	v_mfma_f32_16x16x32_bf16 v[64:67], v[178:181], v[220:223], v[64:67]
	v_mfma_f32_16x16x32_bf16 v[116:119], v[148:151], v[190:193], v[116:119]
	v_mfma_f32_16x16x32_bf16 v[112:115], v[182:185], v[190:193], v[112:115]
	v_mfma_f32_16x16x32_bf16 v[100:103], v[148:151], v[198:201], v[100:103]
	v_mfma_f32_16x16x32_bf16 v[96:99], v[182:185], v[198:201], v[96:99]
	v_mfma_f32_16x16x32_bf16 v[84:87], v[148:151], v[216:219], v[84:87]
	v_mfma_f32_16x16x32_bf16 v[80:83], v[182:185], v[216:219], v[80:83]
	v_mfma_f32_16x16x32_bf16 v[68:71], v[148:151], v[224:227], v[68:71]
	v_mfma_f32_16x16x32_bf16 v[64:67], v[182:185], v[224:227], v[64:67]
	s_setprio 0
	s_barrier
; #define PG8_STAGE(bufoff, gbase, voff) do { _Pragma("unroll") for (int _i = 0; _i < 2; ++_i) \
;         __builtin_amdgcn_global_load_lds((const unsigned*)((const char*)(gbase) + (voff)[_i]), (LAS unsigned*)(lds + (bufoff) + ldsw + _i * 8192), 16, 0, 0); } while (0)
; #define PG8_LDA(dst, b, h) do { _Pragma("unroll") for (int m = 0; m < 4; ++m) _Pragma("unroll") for (int k = 0; k < 2; ++k) dst[m][k] = *(const LAS bf16x8*)(lds + PG8_SA(b, h) + aoff + m * 2048 + k * 1024); } while (0)
; #define PG8_LDB(dst, b, h) do { _Pragma("unroll") for (int n = 0; n < 2; ++n) _Pragma("unroll") for (int k = 0; k < 2; ++k) dst[n][k] = *(const LAS bf16x8*)(lds + PG8_SB(b, h) + boff + n * 2048 + k * 1024); } while (0)
; #define PG8_MMA(ai, bj, At, Bt) do { __builtin_amdgcn_s_setprio(1); _Pragma("unroll") for (int m = 0; m < 4; ++m) _Pragma("unroll") for (int n = 0; n < 2; ++n) _Pragma("unroll") for (int k = 0; k < 2; ++k) \
;         acc[ai][bj][m][n] = __builtin_amdgcn_mfma_f32_16x16x32_bf16(Bt[n][k], At[m][k], acc[ai][bj][m][n], 0, 0, 0); __builtin_amdgcn_s_setprio(0); } while (0)
; #define PG8_WAIT_V(n) asm volatile("s_waitcnt vmcnt(" #n ")" ::: "memory")
; #define PG8_WAIT_L(n) asm volatile("s_waitcnt lgkmcnt(" #n ")" ::: "memory")
; #define PG8_BAR __builtin_amdgcn_s_barrier()
; #define PG8_SCHED __builtin_amdgcn_sched_barrier(0)
; template <class Epi, class Sched>
; __device__ __forceinline__ void gemm_phase(LAS unsigned char* lds, const Gemm g, const Sched& S, const Epi& E, int wave_id) {
;     ...
;             PG8_LDB(B0, 0, 0); PG8_LDB(B1, 0, 1); PG8_SCHED; PG8_LDA(At, 0, 0); PG8_STAGE(PG8_SA(1, 1), a1 + hstepA, voffA);
;             PG8_WAIT_V(8); PG8_WAIT_L(0); PG8_BAR; PG8_MMA(0, 0, At, B0); PG8_MMA(0, 1, At, B1); PG8_BAR; PG8_SCHED;
;     ...
;             PG8_LDB(B0, 1, 0); PG8_LDB(B1, 1, 1); PG8_SCHED; PG8_LDA(At, 1, 0); PG8_STAGE(PG8_SA(0, 1), a2 + hstepA, voffA);
;             PG8_WAIT_V(8); PG8_WAIT_L(0); PG8_BAR; PG8_MMA(0, 0, At, B0); PG8_MMA(0, 1, At, B1); PG8_BAR; PG8_SCHED;
;             PG8_LDA(At, 1, 1); PG8_STAGE(PG8_SB(1, 0), b3, voffB); PG8_STAGE(PG8_SB(1, 1), b3 + hstepB, voffB); PG8_STAGE(PG8_SA(1, 0), a3, voffA);
;             PG8_WAIT_V(8); PG8_WAIT_L(0); PG8_BAR; PG8_MMA(1, 0, At, B0); PG8_MMA(1, 1, At, B1); PG8_BAR; PG8_SCHED;
	s_add_i32 s34, s61, s37
	s_mov_b32 m0, s34
	ds_read_b128 v[186:189], v208 offset:49152
	ds_read_b128 v[190:193], v208 offset:50176
	ds_read_b128 v[194:197], v208 offset:51200
	ds_read_b128 v[198:201], v208 offset:52224
	ds_read_b128 v[212:215], v208 offset:53248
	ds_read_b128 v[216:219], v208 offset:54272
	ds_read_b128 v[220:223], v208 offset:55296
	ds_read_b128 v[224:227], v208 offset:56320
	global_load_lds_dwordx4 v154, s[64:65]
	s_add_i32 m0, s34, 0x2000
	s_add_u32 s30, s30, 0x20080
	s_addc_u32 s31, s31, 0
	s_add_i32 s34, s62, s37
	global_load_lds_dwordx4 v158, s[64:65]
	s_mov_b32 m0, s34
	s_nop 0
	global_load_lds_dwordx4 v154, s[30:31]
	s_add_i32 m0, s34, 0x2000
	s_nop 0
	global_load_lds_dwordx4 v158, s[30:31]
	s_mov_b32 m0, s44
	s_nop 0
	global_load_lds_dwordx4 v152, s[72:73]
	s_mov_b32 m0, s45
	s_nop 0
	global_load_lds_dwordx4 v156, s[72:73]
	s_waitcnt vmcnt(8)
	s_waitcnt lgkmcnt(0)
	s_barrier
	s_setprio 1
	s_waitcnt lgkmcnt(0)
	v_mfma_f32_16x16x32_bf16 v[60:63], v[128:131], v[186:189], v[60:63]
	v_mfma_f32_16x16x32_bf16 v[56:59], v[136:139], v[186:189], v[56:59]
	v_mfma_f32_16x16x32_bf16 v[44:47], v[128:131], v[194:197], v[44:47]
	v_mfma_f32_16x16x32_bf16 v[40:43], v[136:139], v[194:197], v[40:43]
	v_mfma_f32_16x16x32_bf16 v[28:31], v[128:131], v[212:215], v[28:31]
	v_mfma_f32_16x16x32_bf16 v[24:27], v[136:139], v[212:215], v[24:27]
	v_mfma_f32_16x16x32_bf16 v[12:15], v[128:131], v[220:223], v[12:15]
	v_mfma_f32_16x16x32_bf16 v[8:11], v[136:139], v[220:223], v[8:11]
	v_mfma_f32_16x16x32_bf16 v[60:63], v[132:135], v[190:193], v[60:63]
	v_mfma_f32_16x16x32_bf16 v[56:59], v[140:143], v[190:193], v[56:59]
	v_mfma_f32_16x16x32_bf16 v[44:47], v[132:135], v[198:201], v[44:47]
	v_mfma_f32_16x16x32_bf16 v[40:43], v[140:143], v[198:201], v[40:43]
	v_mfma_f32_16x16x32_bf16 v[28:31], v[132:135], v[216:219], v[28:31]
	v_mfma_f32_16x16x32_bf16 v[24:27], v[140:143], v[216:219], v[24:27]
	v_mfma_f32_16x16x32_bf16 v[12:15], v[132:135], v[224:227], v[12:15]
	v_mfma_f32_16x16x32_bf16 v[8:11], v[140:143], v[224:227], v[8:11]
	s_setprio 0
	s_setprio 1
	v_mfma_f32_16x16x32_bf16 v[52:55], v[144:147], v[186:189], v[52:55]
	v_mfma_f32_16x16x32_bf16 v[48:51], v[178:181], v[186:189], v[48:51]
	v_mfma_f32_16x16x32_bf16 v[36:39], v[144:147], v[194:197], v[36:39]
	v_mfma_f32_16x16x32_bf16 v[32:35], v[178:181], v[194:197], v[32:35]
	v_mfma_f32_16x16x32_bf16 v[20:23], v[144:147], v[212:215], v[20:23]
	v_mfma_f32_16x16x32_bf16 v[16:19], v[178:181], v[212:215], v[16:19]
	v_mfma_f32_16x16x32_bf16 v[4:7], v[144:147], v[220:223], v[4:7]
	v_mfma_f32_16x16x32_bf16 v[0:3], v[178:181], v[220:223], v[0:3]
	v_mfma_f32_16x16x32_bf16 v[52:55], v[148:151], v[190:193], v[52:55]
	v_mfma_f32_16x16x32_bf16 v[48:51], v[182:185], v[190:193], v[48:51]
	v_mfma_f32_16x16x32_bf16 v[36:39], v[148:151], v[198:201], v[36:39]
	v_mfma_f32_16x16x32_bf16 v[32:35], v[182:185], v[198:201], v[32:35]
	v_mfma_f32_16x16x32_bf16 v[20:23], v[148:151], v[216:219], v[20:23]
	v_mfma_f32_16x16x32_bf16 v[16:19], v[182:185], v[216:219], v[16:19]
	v_mfma_f32_16x16x32_bf16 v[4:7], v[148:151], v[224:227], v[4:7]
	v_mfma_f32_16x16x32_bf16 v[0:3], v[182:185], v[224:227], v[0:3]
	s_setprio 0
	s_barrier
	s_add_i32 s60, s60, 2
	s_add_u32 s28, s28, 0x100
	s_addc_u32 s29, s29, 0
	s_add_u32 s58, s58, 0x100
	s_addc_u32 s59, s59, 0
	s_cmp_gt_u32 s60, 5
.LBB0_1146:
	ds_read_b128 v[128:131], v206
	ds_read_b128 v[132:135], v206 offset:1024
	ds_read_b128 v[136:139], v206 offset:2048
	ds_read_b128 v[140:143], v206 offset:3072
	ds_read_b128 v[144:147], v207
	ds_read_b128 v[148:151], v207 offset:1024
	ds_read_b128 v[178:181], v207 offset:2048
	ds_read_b128 v[182:185], v207 offset:3072
	s_add_u32 s30, s28, 0xfffe0080
	s_addc_u32 s31, s29, -1
	s_cmp_eq_u32 s60, 4
	s_cselect_b32 s35, s21, s31
	s_cselect_b32 s34, s56, s30
	s_cselect_b32 s31, s19, s59
	s_cselect_b32 s30, s57, s58
	s_add_u32 s72, s34, 0x80
	s_addc_u32 s73, s35, 0
	s_add_u32 s64, s30, 0x80
	s_addc_u32 s65, s31, 0
	s_add_i32 m0, s38, 0xc000
	ds_read_b128 v[186:189], v208
	ds_read_b128 v[190:193], v208 offset:1024
	ds_read_b128 v[194:197], v208 offset:2048
	ds_read_b128 v[198:201], v208 offset:3072
	ds_read_b128 v[212:215], v208 offset:4096
	ds_read_b128 v[216:219], v208 offset:5120
	ds_read_b128 v[220:223], v208 offset:6144
	ds_read_b128 v[224:227], v208 offset:7168
	global_load_lds_dwordx4 v170, s[28:29]
	s_add_i32 m0, s38, 0xe000
	s_nop 0
	global_load_lds_dwordx4 v172, s[28:29]
	s_waitcnt vmcnt(8)
	s_waitcnt lgkmcnt(0)
	s_barrier
; #define PG8_STAGE(bufoff, gbase, voff) do { _Pragma("unroll") for (int _i = 0; _i < 2; ++_i) \
;         __builtin_amdgcn_global_load_lds((const unsigned*)((const char*)(gbase) + (voff)[_i]), (LAS unsigned*)(lds + (bufoff) + ldsw + _i * 8192), 16, 0, 0); } while (0)
; #define PG8_LDA(dst, b, h) do { _Pragma("unroll") for (int m = 0; m < 4; ++m) _Pragma("unroll") for (int k = 0; k < 2; ++k) dst[m][k] = *(const LAS bf16x8*)(lds + PG8_SA(b, h) + aoff + m * 2048 + k * 1024); } while (0)
; #define PG8_LDB(dst, b, h) do { _Pragma("unroll") for (int n = 0; n < 2; ++n) _Pragma("unroll") for (int k = 0; k < 2; ++k) dst[n][k] = *(const LAS bf16x8*)(lds + PG8_SB(b, h) + boff + n * 2048 + k * 1024); } while (0)
; #define PG8_MMA(ai, bj, At, Bt) do { __builtin_amdgcn_s_setprio(1); _Pragma("unroll") for (int m = 0; m < 4; ++m) _Pragma("unroll") for (int n = 0; n < 2; ++n) _Pragma("unroll") for (int k = 0; k < 2; ++k) \
;         acc[ai][bj][m][n] = __builtin_amdgcn_mfma_f32_16x16x32_bf16(Bt[n][k], At[m][k], acc[ai][bj][m][n], 0, 0, 0); __builtin_amdgcn_s_setprio(0); } while (0)
; #define PG8_WAIT_V(n) asm volatile("s_waitcnt vmcnt(" #n ")" ::: "memory")
; #define PG8_WAIT_L(n) asm volatile("s_waitcnt lgkmcnt(" #n ")" ::: "memory")
; #define PG8_BAR __builtin_amdgcn_s_barrier()
; #define PG8_SCHED __builtin_amdgcn_sched_barrier(0)
; template <class Epi, class Sched>
; __device__ __forceinline__ void gemm_phase(LAS unsigned char* lds, const Gemm g, const Sched& S, const Epi& E, int wave_id) {
;     ...
;             PG8_LDB(B0, 0, 0); PG8_LDB(B1, 0, 1); PG8_SCHED; PG8_LDA(At, 0, 0); PG8_STAGE(PG8_SA(1, 1), a1 + hstepA, voffA);
;             PG8_WAIT_V(8); PG8_WAIT_L(0); PG8_BAR; PG8_MMA(0, 0, At, B0); PG8_MMA(0, 1, At, B1); PG8_BAR; PG8_SCHED;
;             PG8_LDA(At, 0, 1); PG8_STAGE(PG8_SB(0, 0), b2, voffB); PG8_STAGE(PG8_SB(0, 1), b2 + hstepB, voffB); PG8_STAGE(PG8_SA(0, 0), a2, voffA);
;             PG8_WAIT_V(8); PG8_WAIT_L(0); PG8_BAR; PG8_MMA(1, 0, At, B0); PG8_MMA(1, 1, At, B1); PG8_BAR; PG8_SCHED;
	s_setprio 1
	s_waitcnt lgkmcnt(0)
	v_mfma_f32_16x16x32_bf16 v[124:127], v[128:131], v[186:189], v[124:127]
	v_mfma_f32_16x16x32_bf16 v[120:123], v[136:139], v[186:189], v[120:123]
	v_mfma_f32_16x16x32_bf16 v[108:111], v[128:131], v[194:197], v[108:111]
	v_mfma_f32_16x16x32_bf16 v[104:107], v[136:139], v[194:197], v[104:107]
	v_mfma_f32_16x16x32_bf16 v[92:95], v[128:131], v[212:215], v[92:95]
	v_mfma_f32_16x16x32_bf16 v[88:91], v[136:139], v[212:215], v[88:91]
	v_mfma_f32_16x16x32_bf16 v[76:79], v[128:131], v[220:223], v[76:79]
	v_mfma_f32_16x16x32_bf16 v[72:75], v[136:139], v[220:223], v[72:75]
	v_mfma_f32_16x16x32_bf16 v[124:127], v[132:135], v[190:193], v[124:127]
	v_mfma_f32_16x16x32_bf16 v[120:123], v[140:143], v[190:193], v[120:123]
	v_mfma_f32_16x16x32_bf16 v[108:111], v[132:135], v[198:201], v[108:111]
	v_mfma_f32_16x16x32_bf16 v[104:107], v[140:143], v[198:201], v[104:107]
	v_mfma_f32_16x16x32_bf16 v[92:95], v[132:135], v[216:219], v[92:95]
	v_mfma_f32_16x16x32_bf16 v[88:91], v[140:143], v[216:219], v[88:91]
	v_mfma_f32_16x16x32_bf16 v[76:79], v[132:135], v[224:227], v[76:79]
	v_mfma_f32_16x16x32_bf16 v[72:75], v[140:143], v[224:227], v[72:75]
	s_setprio 0
	s_setprio 1
	v_mfma_f32_16x16x32_bf16 v[116:119], v[144:147], v[186:189], v[116:119]
	v_mfma_f32_16x16x32_bf16 v[112:115], v[178:181], v[186:189], v[112:115]
	v_mfma_f32_16x16x32_bf16 v[100:103], v[144:147], v[194:197], v[100:103]
	v_mfma_f32_16x16x32_bf16 v[96:99], v[178:181], v[194:197], v[96:99]
	v_mfma_f32_16x16x32_bf16 v[84:87], v[144:147], v[212:215], v[84:87]
	v_mfma_f32_16x16x32_bf16 v[80:83], v[178:181], v[212:215], v[80:83]
	v_mfma_f32_16x16x32_bf16 v[68:71], v[144:147], v[220:223], v[68:71]
	v_mfma_f32_16x16x32_bf16 v[64:67], v[178:181], v[220:223], v[64:67]
	v_mfma_f32_16x16x32_bf16 v[116:119], v[148:151], v[190:193], v[116:119]
	v_mfma_f32_16x16x32_bf16 v[112:115], v[182:185], v[190:193], v[112:115]
	v_mfma_f32_16x16x32_bf16 v[100:103], v[148:151], v[198:201], v[100:103]
	v_mfma_f32_16x16x32_bf16 v[96:99], v[182:185], v[198:201], v[96:99]
	v_mfma_f32_16x16x32_bf16 v[84:87], v[148:151], v[216:219], v[84:87]
	v_mfma_f32_16x16x32_bf16 v[80:83], v[182:185], v[216:219], v[80:83]
	v_mfma_f32_16x16x32_bf16 v[68:71], v[148:151], v[224:227], v[68:71]
	v_mfma_f32_16x16x32_bf16 v[64:67], v[182:185], v[224:227], v[64:67]
	s_setprio 0
	s_barrier
	s_add_i32 s61, s54, s37
	s_mov_b32 m0, s61
	ds_read_b128 v[186:189], v208 offset:16384
	ds_read_b128 v[190:193], v208 offset:17408
	ds_read_b128 v[194:197], v208 offset:18432
	ds_read_b128 v[198:201], v208 offset:19456
	ds_read_b128 v[212:215], v208 offset:20480
	ds_read_b128 v[216:219], v208 offset:21504
	ds_read_b128 v[220:223], v208 offset:22528
	ds_read_b128 v[224:227], v208 offset:23552
	global_load_lds_dwordx4 v154, s[30:31]
	s_add_i32 m0, s61, 0x2000
	s_add_u32 s62, s30, 0x20000
	s_addc_u32 s63, s31, 0
	s_add_i32 s61, s55, s37
	global_load_lds_dwordx4 v158, s[30:31]
	s_mov_b32 m0, s61
	s_nop 0
	global_load_lds_dwordx4 v154, s[62:63]
	s_add_i32 m0, s61, 0x2000
	s_nop 0
	global_load_lds_dwordx4 v158, s[62:63]
	s_mov_b32 m0, s38
	s_nop 0
	global_load_lds_dwordx4 v152, s[34:35]
	s_mov_b32 m0, s39
	s_nop 0
	global_load_lds_dwordx4 v156, s[34:35]
	s_waitcnt vmcnt(8)
	s_waitcnt lgkmcnt(0)
	s_barrier
	s_setprio 1
	s_waitcnt lgkmcnt(0)
	v_mfma_f32_16x16x32_bf16 v[60:63], v[128:131], v[186:189], v[60:63]
	v_mfma_f32_16x16x32_bf16 v[56:59], v[136:139], v[186:189], v[56:59]
	v_mfma_f32_16x16x32_bf16 v[44:47], v[128:131], v[194:197], v[44:47]
	v_mfma_f32_16x16x32_bf16 v[40:43], v[136:139], v[194:197], v[40:43]
	v_mfma_f32_16x16x32_bf16 v[28:31], v[128:131], v[212:215], v[28:31]
	v_mfma_f32_16x16x32_bf16 v[24:27], v[136:139], v[212:215], v[24:27]
	v_mfma_f32_16x16x32_bf16 v[12:15], v[128:131], v[220:223], v[12:15]
	v_mfma_f32_16x16x32_bf16 v[8:11], v[136:139], v[220:223], v[8:11]
	v_mfma_f32_16x16x32_bf16 v[60:63], v[132:135], v[190:193], v[60:63]
	v_mfma_f32_16x16x32_bf16 v[56:59], v[140:143], v[190:193], v[56:59]
	v_mfma_f32_16x16x32_bf16 v[44:47], v[132:135], v[198:201], v[44:47]
	v_mfma_f32_16x16x32_bf16 v[40:43], v[140:143], v[198:201], v[40:43]
	v_mfma_f32_16x16x32_bf16 v[28:31], v[132:135], v[216:219], v[28:31]
	v_mfma_f32_16x16x32_bf16 v[24:27], v[140:143], v[216:219], v[24:27]
	v_mfma_f32_16x16x32_bf16 v[12:15], v[132:135], v[224:227], v[12:15]
	v_mfma_f32_16x16x32_bf16 v[8:11], v[140:143], v[224:227], v[8:11]
	s_setprio 0
	s_setprio 1
	v_mfma_f32_16x16x32_bf16 v[52:55], v[144:147], v[186:189], v[52:55]
	v_mfma_f32_16x16x32_bf16 v[48:51], v[178:181], v[186:189], v[48:51]
	v_mfma_f32_16x16x32_bf16 v[36:39], v[144:147], v[194:197], v[36:39]
	v_mfma_f32_16x16x32_bf16 v[32:35], v[178:181], v[194:197], v[32:35]
	v_mfma_f32_16x16x32_bf16 v[20:23], v[144:147], v[212:215], v[20:23]
	v_mfma_f32_16x16x32_bf16 v[16:19], v[178:181], v[212:215], v[16:19]
	v_mfma_f32_16x16x32_bf16 v[4:7], v[144:147], v[220:223], v[4:7]
	v_mfma_f32_16x16x32_bf16 v[0:3], v[178:181], v[220:223], v[0:3]
	v_mfma_f32_16x16x32_bf16 v[52:55], v[148:151], v[190:193], v[52:55]
	v_mfma_f32_16x16x32_bf16 v[48:51], v[182:185], v[190:193], v[48:51]
	v_mfma_f32_16x16x32_bf16 v[36:39], v[148:151], v[198:201], v[36:39]
	v_mfma_f32_16x16x32_bf16 v[32:35], v[182:185], v[198:201], v[32:35]
	v_mfma_f32_16x16x32_bf16 v[20:23], v[148:151], v[216:219], v[20:23]
	v_mfma_f32_16x16x32_bf16 v[16:19], v[182:185], v[216:219], v[16:19]
	v_mfma_f32_16x16x32_bf16 v[4:7], v[148:151], v[224:227], v[4:7]
	v_mfma_f32_16x16x32_bf16 v[0:3], v[182:185], v[224:227], v[0:3]
	s_setprio 0
	s_barrier
; #define PG8_STAGE(bufoff, gbase, voff) do { _Pragma("unroll") for (int _i = 0; _i < 2; ++_i) \
;         __builtin_amdgcn_global_load_lds((const unsigned*)((const char*)(gbase) + (voff)[_i]), (LAS unsigned*)(lds + (bufoff) + ldsw + _i * 8192), 16, 0, 0); } while (0)
; #define PG8_LDA(dst, b, h) do { _Pragma("unroll") for (int m = 0; m < 4; ++m) _Pragma("unroll") for (int k = 0; k < 2; ++k) dst[m][k] = *(const LAS bf16x8*)(lds + PG8_SA(b, h) + aoff + m * 2048 + k * 1024); } while (0)
; #define PG8_LDB(dst, b, h) do { _Pragma("unroll") for (int n = 0; n < 2; ++n) _Pragma("unroll") for (int k = 0; k < 2; ++k) dst[n][k] = *(const LAS bf16x8*)(lds + PG8_SB(b, h) + boff + n * 2048 + k * 1024); } while (0)
; #define PG8_MMA(ai, bj, At, Bt) do { __builtin_amdgcn_s_setprio(1); _Pragma("unroll") for (int m = 0; m < 4; ++m) _Pragma("unroll") for (int n = 0; n < 2; ++n) _Pragma("unroll") for (int k = 0; k < 2; ++k) \
;         acc[ai][bj][m][n] = __builtin_amdgcn_mfma_f32_16x16x32_bf16(Bt[n][k], At[m][k], acc[ai][bj][m][n], 0, 0, 0); __builtin_amdgcn_s_setprio(0); } while (0)
; #define PG8_WAIT_V(n) asm volatile("s_waitcnt vmcnt(" #n ")" ::: "memory")
; #define PG8_WAIT_L(n) asm volatile("s_waitcnt lgkmcnt(" #n ")" ::: "memory")
; #define PG8_BAR __builtin_amdgcn_s_barrier()
; #define PG8_SCHED __builtin_amdgcn_sched_barrier(0)
; template <class Epi, class Sched>
; __device__ __forceinline__ void gemm_phase(LAS unsigned char* lds, const Gemm g, const Sched& S, const Epi& E, int wave_id) {
;     ...
;             PG8_LDB(B0, 1, 0); PG8_LDB(B1, 1, 1); PG8_SCHED; PG8_LDA(At, 1, 0); PG8_STAGE(PG8_SA(0, 1), a2 + hstepA, voffA);
;             PG8_WAIT_V(8); PG8_WAIT_L(0); PG8_BAR; PG8_MMA(0, 0, At, B0); PG8_MMA(0, 1, At, B1); PG8_BAR; PG8_SCHED;
;             PG8_LDA(At, 1, 1); PG8_STAGE(PG8_SB(1, 0), b3, voffB); PG8_STAGE(PG8_SB(1, 1), b3 + hstepB, voffB); PG8_STAGE(PG8_SA(1, 0), a3, voffA);
;             PG8_WAIT_V(8); PG8_WAIT_L(0); PG8_BAR; PG8_MMA(1, 0, At, B0); PG8_MMA(1, 1, At, B1); PG8_BAR; PG8_SCHED;
	s_add_i32 s61, 0, 0x18000
	s_add_i32 s62, 0, 0x1c000
	v_add_u32_e32 v140, s61, v205
	v_add_u32_e32 v182, s62, v205
	ds_read_b128 v[128:131], v140
	ds_read_b128 v[132:135], v140 offset:1024
	ds_read_b128 v[136:139], v140 offset:2048
	ds_read_b128 v[140:143], v140 offset:3072
	ds_read_b128 v[144:147], v182
	ds_read_b128 v[148:151], v182 offset:1024
	ds_read_b128 v[178:181], v182 offset:2048
	ds_read_b128 v[182:185], v182 offset:3072
	s_add_u32 s34, s34, 0x20000
	s_addc_u32 s35, s35, 0
	s_mov_b32 m0, s40
	ds_read_b128 v[186:189], v208 offset:32768
	ds_read_b128 v[190:193], v208 offset:33792
	ds_read_b128 v[194:197], v208 offset:34816
	ds_read_b128 v[198:201], v208 offset:35840
	ds_read_b128 v[212:215], v208 offset:36864
	ds_read_b128 v[216:219], v208 offset:37888
	ds_read_b128 v[220:223], v208 offset:38912
	ds_read_b128 v[224:227], v208 offset:39936
	global_load_lds_dwordx4 v152, s[34:35]
	v_lshl_add_u64 v[234:235], s[34:35], 0, v[156:157]
	s_mov_b32 m0, s41
	s_nop 0
	global_load_lds_dwordx4 v[234:235], off
	s_waitcnt vmcnt(8)
	s_waitcnt lgkmcnt(0)
	s_barrier
	s_setprio 1
	s_waitcnt lgkmcnt(0)
	v_mfma_f32_16x16x32_bf16 v[124:127], v[128:131], v[186:189], v[124:127]
	v_mfma_f32_16x16x32_bf16 v[120:123], v[136:139], v[186:189], v[120:123]
	v_mfma_f32_16x16x32_bf16 v[108:111], v[128:131], v[194:197], v[108:111]
	v_mfma_f32_16x16x32_bf16 v[104:107], v[136:139], v[194:197], v[104:107]
	v_mfma_f32_16x16x32_bf16 v[92:95], v[128:131], v[212:215], v[92:95]
	v_mfma_f32_16x16x32_bf16 v[88:91], v[136:139], v[212:215], v[88:91]
	v_mfma_f32_16x16x32_bf16 v[76:79], v[128:131], v[220:223], v[76:79]
	v_mfma_f32_16x16x32_bf16 v[72:75], v[136:139], v[220:223], v[72:75]
	v_mfma_f32_16x16x32_bf16 v[124:127], v[132:135], v[190:193], v[124:127]
	v_mfma_f32_16x16x32_bf16 v[120:123], v[140:143], v[190:193], v[120:123]
	v_mfma_f32_16x16x32_bf16 v[108:111], v[132:135], v[198:201], v[108:111]
	v_mfma_f32_16x16x32_bf16 v[104:107], v[140:143], v[198:201], v[104:107]
	v_mfma_f32_16x16x32_bf16 v[92:95], v[132:135], v[216:219], v[92:95]
	v_mfma_f32_16x16x32_bf16 v[88:91], v[140:143], v[216:219], v[88:91]
	v_mfma_f32_16x16x32_bf16 v[76:79], v[132:135], v[224:227], v[76:79]
	v_mfma_f32_16x16x32_bf16 v[72:75], v[140:143], v[224:227], v[72:75]
	s_setprio 0
	s_setprio 1
	v_mfma_f32_16x16x32_bf16 v[116:119], v[144:147], v[186:189], v[116:119]
	v_mfma_f32_16x16x32_bf16 v[112:115], v[178:181], v[186:189], v[112:115]
	v_mfma_f32_16x16x32_bf16 v[100:103], v[144:147], v[194:197], v[100:103]
	v_mfma_f32_16x16x32_bf16 v[96:99], v[178:181], v[194:197], v[96:99]
	v_mfma_f32_16x16x32_bf16 v[84:87], v[144:147], v[212:215], v[84:87]
	v_mfma_f32_16x16x32_bf16 v[80:83], v[178:181], v[212:215], v[80:83]
	v_mfma_f32_16x16x32_bf16 v[68:71], v[144:147], v[220:223], v[68:71]
	v_mfma_f32_16x16x32_bf16 v[64:67], v[178:181], v[220:223], v[64:67]
	v_mfma_f32_16x16x32_bf16 v[116:119], v[148:151], v[190:193], v[116:119]
	v_mfma_f32_16x16x32_bf16 v[112:115], v[182:185], v[190:193], v[112:115]
	v_mfma_f32_16x16x32_bf16 v[100:103], v[148:151], v[198:201], v[100:103]
	v_mfma_f32_16x16x32_bf16 v[96:99], v[182:185], v[198:201], v[96:99]
	v_mfma_f32_16x16x32_bf16 v[84:87], v[148:151], v[216:219], v[84:87]
	v_mfma_f32_16x16x32_bf16 v[80:83], v[182:185], v[216:219], v[80:83]
	v_mfma_f32_16x16x32_bf16 v[68:71], v[148:151], v[224:227], v[68:71]
	v_mfma_f32_16x16x32_bf16 v[64:67], v[182:185], v[224:227], v[64:67]
	s_setprio 0
	s_barrier
	s_add_i32 s34, s61, s37
	s_mov_b32 m0, s34
	ds_read_b128 v[186:189], v208 offset:49152
	ds_read_b128 v[190:193], v208 offset:50176
	ds_read_b128 v[194:197], v208 offset:51200
	ds_read_b128 v[198:201], v208 offset:52224
	ds_read_b128 v[212:215], v208 offset:53248
	ds_read_b128 v[216:219], v208 offset:54272
	ds_read_b128 v[220:223], v208 offset:55296
	ds_read_b128 v[224:227], v208 offset:56320
	global_load_lds_dwordx4 v154, s[64:65]
	s_add_i32 m0, s34, 0x2000
	s_add_u32 s30, s30, 0x20080
	s_addc_u32 s31, s31, 0
	s_add_i32 s34, s62, s37
	global_load_lds_dwordx4 v158, s[64:65]
	s_mov_b32 m0, s34
	s_nop 0
	global_load_lds_dwordx4 v154, s[30:31]
	s_add_i32 m0, s34, 0x2000
	s_nop 0
	global_load_lds_dwordx4 v158, s[30:31]
	s_mov_b32 m0, s44
	s_nop 0
	global_load_lds_dwordx4 v152, s[72:73]
	s_mov_b32 m0, s45
	s_nop 0
	global_load_lds_dwordx4 v156, s[72:73]
	s_waitcnt vmcnt(8)
	s_waitcnt lgkmcnt(0)
	s_barrier
	s_setprio 1
	s_waitcnt lgkmcnt(0)
	v_mfma_f32_16x16x32_bf16 v[60:63], v[128:131], v[186:189], v[60:63]
	v_mfma_f32_16x16x32_bf16 v[56:59], v[136:139], v[186:189], v[56:59]
	v_mfma_f32_16x16x32_bf16 v[44:47], v[128:131], v[194:197], v[44:47]
	v_mfma_f32_16x16x32_bf16 v[40:43], v[136:139], v[194:197], v[40:43]
	v_mfma_f32_16x16x32_bf16 v[28:31], v[128:131], v[212:215], v[28:31]
	v_mfma_f32_16x16x32_bf16 v[24:27], v[136:139], v[212:215], v[24:27]
	v_mfma_f32_16x16x32_bf16 v[12:15], v[128:131], v[220:223], v[12:15]
	v_mfma_f32_16x16x32_bf16 v[8:11], v[136:139], v[220:223], v[8:11]
	v_mfma_f32_16x16x32_bf16 v[60:63], v[132:135], v[190:193], v[60:63]
	v_mfma_f32_16x16x32_bf16 v[56:59], v[140:143], v[190:193], v[56:59]
	v_mfma_f32_16x16x32_bf16 v[44:47], v[132:135], v[198:201], v[44:47]
	v_mfma_f32_16x16x32_bf16 v[40:43], v[140:143], v[198:201], v[40:43]
	v_mfma_f32_16x16x32_bf16 v[28:31], v[132:135], v[216:219], v[28:31]
	v_mfma_f32_16x16x32_bf16 v[24:27], v[140:143], v[216:219], v[24:27]
	v_mfma_f32_16x16x32_bf16 v[12:15], v[132:135], v[224:227], v[12:15]
	v_mfma_f32_16x16x32_bf16 v[8:11], v[140:143], v[224:227], v[8:11]
	s_setprio 0
	s_setprio 1
	v_mfma_f32_16x16x32_bf16 v[52:55], v[144:147], v[186:189], v[52:55]
	v_mfma_f32_16x16x32_bf16 v[48:51], v[178:181], v[186:189], v[48:51]
	v_mfma_f32_16x16x32_bf16 v[36:39], v[144:147], v[194:197], v[36:39]
	v_mfma_f32_16x16x32_bf16 v[32:35], v[178:181], v[194:197], v[32:35]
	v_mfma_f32_16x16x32_bf16 v[20:23], v[144:147], v[212:215], v[20:23]
	v_mfma_f32_16x16x32_bf16 v[16:19], v[178:181], v[212:215], v[16:19]
	v_mfma_f32_16x16x32_bf16 v[4:7], v[144:147], v[220:223], v[4:7]
	v_mfma_f32_16x16x32_bf16 v[0:3], v[178:181], v[220:223], v[0:3]
	v_mfma_f32_16x16x32_bf16 v[52:55], v[148:151], v[190:193], v[52:55]
	v_mfma_f32_16x16x32_bf16 v[48:51], v[182:185], v[190:193], v[48:51]
	v_mfma_f32_16x16x32_bf16 v[36:39], v[148:151], v[198:201], v[36:39]
	v_mfma_f32_16x16x32_bf16 v[32:35], v[182:185], v[198:201], v[32:35]
	v_mfma_f32_16x16x32_bf16 v[20:23], v[148:151], v[216:219], v[20:23]
	v_mfma_f32_16x16x32_bf16 v[16:19], v[182:185], v[216:219], v[16:19]
	v_mfma_f32_16x16x32_bf16 v[4:7], v[148:151], v[224:227], v[4:7]
	v_mfma_f32_16x16x32_bf16 v[0:3], v[182:185], v[224:227], v[0:3]
	s_setprio 0
	s_barrier
	s_add_i32 s60, s60, 2
	s_add_u32 s28, s28, 0x100
	s_addc_u32 s29, s29, 0
	s_add_u32 s58, s58, 0x100
	s_addc_u32 s59, s59, 0
	s_cmp_gt_u32 s60, 5
	s_cbranch_scc0 .LBB0_1146
	s_and_b64 vcc, exec, s[14:15]
	s_cbranch_vccz .LBB0_1149
	s_barrier

;     __device__ bool next(int i, Unit& u) const { if (r0 + i >= r1) return false; return base.next(r0 + i, u); }
;     __device__ bool next(int i, Unit& u) const { const int L = i * G + c; if (L >= 256) return false; u.pm = L; u.pn = L >> 3; return true; }
; #define PG8_STAGE(bufoff, gbase, voff) do { _Pragma("unroll") for (int _i = 0; _i < 2; ++_i) \
;         __builtin_amdgcn_global_load_lds((const unsigned*)((const char*)(gbase) + (voff)[_i]), (LAS unsigned*)(lds + (bufoff) + ldsw + _i * 8192), 16, 0, 0); } while (0)
; #define PG8_LDA(dst, b, h) do { _Pragma("unroll") for (int m = 0; m < 4; ++m) _Pragma("unroll") for (int k = 0; k < 2; ++k) dst[m][k] = *(const LAS bf16x8*)(lds + PG8_SA(b, h) + aoff + m * 2048 + k * 1024); } while (0)
; #define PG8_LDB(dst, b, h) do { _Pragma("unroll") for (int n = 0; n < 2; ++n) _Pragma("unroll") for (int k = 0; k < 2; ++k) dst[n][k] = *(const LAS bf16x8*)(lds + PG8_SB(b, h) + boff + n * 2048 + k * 1024); } while (0)
; #define PG8_WAIT_V(n) asm volatile("s_waitcnt vmcnt(" #n ")" ::: "memory")
; #define PG8_WAIT_L(n) asm volatile("s_waitcnt lgkmcnt(" #n ")" ::: "memory")
; template <class Epi, class Sched>
; __device__ __forceinline__ void gemm_phase(LAS unsigned char* lds, const Gemm g, const Sched& S, const Epi& E, int wave_id) {
;     ...
;         const bool has_next = S.next(ui + 1, nxt);
;         const char* nA = has_next ? (const char*)g.A + (size_t)nxt.pm * tstepA : cA; const char* nB = has_next ? (const char*)g.Bt + (size_t)nxt.pn * tstepB : cB;
;         for (int t = 0; t < nt; t += 2) {
;             const bool last = (t == nt - 2);
;             const char* a1 = cA + (size_t)(t + 1) * kstep;
;             const char* a2 = last ? nA : cA + (size_t)(t + 2) * kstep; const char* b2 = last ? nB : cB + (size_t)(t + 2) * kstep;
;             const char* a3 = a2 + kstep; const char* b3 = b2 + kstep;
;             PG8_LDB(B0, 0, 0); PG8_LDB(B1, 0, 1); PG8_SCHED; PG8_LDA(At, 0, 0); PG8_STAGE(PG8_SA(1, 1), a1 + hstepA, voffA);
;             PG8_WAIT_V(8); PG8_WAIT_L(0); PG8_BAR; PG8_MMA(0, 0, At, B0); PG8_MMA(0, 1, At, B1); PG8_BAR; PG8_SCHED;
;             PG8_LDA(At, 0, 1); PG8_STAGE(PG8_SB(0, 0), b2, voffB); PG8_STAGE(PG8_SB(0, 1), b2 + hstepB, voffB); PG8_STAGE(PG8_SA(0, 0), a2, voffA);
;             PG8_WAIT_V(8); PG8_WAIT_L(0); PG8_BAR; PG8_MMA(1, 0, At, B0); PG8_MMA(1, 1, At, B1); PG8_BAR; PG8_SCHED;
.LBB0_1250:
	s_ashr_i32 s25, s24, 31
	s_lshl_b64 s[26:27], s[24:25], 19
	s_add_u32 s26, s45, s26
	s_addc_u32 s27, s46, s27
	s_and_b64 s[28:29], s[6:7], exec
	s_cselect_b32 s25, s27, s35
	s_cselect_b32 s63, s26, s34
	s_ashr_i32 s23, s22, 31
	s_lshl_b64 s[28:29], s[22:23], 19
	s_add_u32 s28, s47, s28
	s_addc_u32 s29, s48, s29
	s_and_b64 s[38:39], s[6:7], exec
	s_cselect_b32 s23, s29, s37
	s_cselect_b32 s64, s28, s36
	s_add_u32 s34, s34, 0x40080
	s_addc_u32 s35, s35, 0
	s_add_u32 s65, s36, 0x100
	s_addc_u32 s66, s37, 0
	s_mov_b32 s67, -2
	s_waitcnt lgkmcnt(0)
	s_waitcnt vmcnt(0)
	ds_read_b128 v[128:131], v178
	ds_read_b128 v[132:135], v178 offset:1024
	ds_read_b128 v[136:139], v178 offset:2048
	ds_read_b128 v[140:143], v178 offset:3072
	ds_read_b128 v[170:173], v179
	ds_read_b128 v[184:187], v179 offset:1024
	ds_read_b128 v[188:191], v179 offset:2048
	ds_read_b128 v[192:195], v179 offset:3072
	s_add_u32 s36, s34, 0xfffc0080
	s_addc_u32 s37, s35, -1
	s_cmp_eq_u32 s67, 12
	s_cselect_b32 s39, s25, s37
	s_cselect_b32 s38, s63, s36
	s_cselect_b32 s37, s23, s66
	s_cselect_b32 s36, s64, s65
	s_add_u32 s78, s38, 0x80
	s_addc_u32 s79, s39, 0
	s_add_u32 s76, s36, 0x80
	s_addc_u32 s77, s37, 0
	s_add_i32 m0, s49, 0xc000
	ds_read_b128 v[196:199], v180
	ds_read_b128 v[200:203], v180 offset:1024
	ds_read_b128 v[204:207], v180 offset:2048
	ds_read_b128 v[208:211], v180 offset:3072
	ds_read_b128 v[212:215], v180 offset:4096
	ds_read_b128 v[216:219], v180 offset:5120
	ds_read_b128 v[220:223], v180 offset:6144
	ds_read_b128 v[224:227], v180 offset:7168
	global_load_lds_dwordx4 v162, s[34:35]
	s_add_i32 m0, s49, 0xe000
	s_nop 0
	global_load_lds_dwordx4 v164, s[34:35]
	s_waitcnt vmcnt(8)
	s_waitcnt lgkmcnt(0)
	s_barrier
	s_setprio 1
	s_waitcnt lgkmcnt(0)
	v_mfma_f32_16x16x32_bf16 v[124:127], v[128:131], v[196:199], 0
	v_mfma_f32_16x16x32_bf16 v[120:123], v[136:139], v[196:199], 0
	v_mfma_f32_16x16x32_bf16 v[108:111], v[128:131], v[204:207], 0
	v_mfma_f32_16x16x32_bf16 v[104:107], v[136:139], v[204:207], 0
	v_mfma_f32_16x16x32_bf16 v[92:95], v[128:131], v[212:215], 0
	v_mfma_f32_16x16x32_bf16 v[88:91], v[136:139], v[212:215], 0
	v_mfma_f32_16x16x32_bf16 v[76:79], v[128:131], v[220:223], 0
	v_mfma_f32_16x16x32_bf16 v[72:75], v[136:139], v[220:223], 0
	v_mfma_f32_16x16x32_bf16 v[124:127], v[132:135], v[200:203], v[124:127]
	v_mfma_f32_16x16x32_bf16 v[120:123], v[140:143], v[200:203], v[120:123]
	v_mfma_f32_16x16x32_bf16 v[108:111], v[132:135], v[208:211], v[108:111]
	v_mfma_f32_16x16x32_bf16 v[104:107], v[140:143], v[208:211], v[104:107]
	v_mfma_f32_16x16x32_bf16 v[92:95], v[132:135], v[216:219], v[92:95]
	v_mfma_f32_16x16x32_bf16 v[88:91], v[140:143], v[216:219], v[88:91]
	v_mfma_f32_16x16x32_bf16 v[76:79], v[132:135], v[224:227], v[76:79]
	v_mfma_f32_16x16x32_bf16 v[72:75], v[140:143], v[224:227], v[72:75]
	s_setprio 0
	s_setprio 1
	v_mfma_f32_16x16x32_bf16 v[116:119], v[170:173], v[196:199], 0
	v_mfma_f32_16x16x32_bf16 v[112:115], v[188:191], v[196:199], 0
	v_mfma_f32_16x16x32_bf16 v[100:103], v[170:173], v[204:207], 0
	v_mfma_f32_16x16x32_bf16 v[96:99], v[188:191], v[204:207], 0
	v_mfma_f32_16x16x32_bf16 v[84:87], v[170:173], v[212:215], 0
	v_mfma_f32_16x16x32_bf16 v[80:83], v[188:191], v[212:215], 0
	v_mfma_f32_16x16x32_bf16 v[68:71], v[170:173], v[220:223], 0
	v_mfma_f32_16x16x32_bf16 v[64:67], v[188:191], v[220:223], 0
	v_mfma_f32_16x16x32_bf16 v[116:119], v[184:187], v[200:203], v[116:119]
	v_mfma_f32_16x16x32_bf16 v[112:115], v[192:195], v[200:203], v[112:115]
	v_mfma_f32_16x16x32_bf16 v[100:103], v[184:187], v[208:211], v[100:103]
	v_mfma_f32_16x16x32_bf16 v[96:99], v[192:195], v[208:211], v[96:99]
	v_mfma_f32_16x16x32_bf16 v[84:87], v[184:187], v[216:219], v[84:87]
	v_mfma_f32_16x16x32_bf16 v[80:83], v[192:195], v[216:219], v[80:83]
	v_mfma_f32_16x16x32_bf16 v[68:71], v[184:187], v[224:227], v[68:71]
	v_mfma_f32_16x16x32_bf16 v[64:67], v[192:195], v[224:227], v[64:67]
	s_setprio 0
	s_barrier
	s_add_i32 s72, s60, s2
	s_mov_b32 m0, s72
	ds_read_b128 v[196:199], v180 offset:16384
	ds_read_b128 v[200:203], v180 offset:17408
	ds_read_b128 v[204:207], v180 offset:18432
	ds_read_b128 v[208:211], v180 offset:19456
	ds_read_b128 v[212:215], v180 offset:20480
	ds_read_b128 v[216:219], v180 offset:21504
	ds_read_b128 v[220:223], v180 offset:22528
	ds_read_b128 v[224:227], v180 offset:23552
	global_load_lds_dwordx4 v146, s[36:37]
	s_add_i32 m0, s72, 0x2000
	s_add_u32 s72, s36, 0x40000
	s_addc_u32 s73, s37, 0
	s_add_i32 s74, s61, s2
	global_load_lds_dwordx4 v150, s[36:37]
	s_mov_b32 m0, s74
	s_nop 0
	global_load_lds_dwordx4 v146, s[72:73]
	s_add_i32 m0, s74, 0x2000
	s_nop 0
	global_load_lds_dwordx4 v150, s[72:73]
	s_mov_b32 m0, s49
	s_nop 0
	global_load_lds_dwordx4 v144, s[38:39]
	s_mov_b32 m0, s50
	s_nop 0
	global_load_lds_dwordx4 v148, s[38:39]
	s_waitcnt vmcnt(8)
	s_waitcnt lgkmcnt(0)
	s_barrier
; #define PG8_STAGE(bufoff, gbase, voff) do { _Pragma("unroll") for (int _i = 0; _i < 2; ++_i) \
;         __builtin_amdgcn_global_load_lds((const unsigned*)((const char*)(gbase) + (voff)[_i]), (LAS unsigned*)(lds + (bufoff) + ldsw + _i * 8192), 16, 0, 0); } while (0)
; #define PG8_LDA(dst, b, h) do { _Pragma("unroll") for (int m = 0; m < 4; ++m) _Pragma("unroll") for (int k = 0; k < 2; ++k) dst[m][k] = *(const LAS bf16x8*)(lds + PG8_SA(b, h) + aoff + m * 2048 + k * 1024); } while (0)
; #define PG8_LDB(dst, b, h) do { _Pragma("unroll") for (int n = 0; n < 2; ++n) _Pragma("unroll") for (int k = 0; k < 2; ++k) dst[n][k] = *(const LAS bf16x8*)(lds + PG8_SB(b, h) + boff + n * 2048 + k * 1024); } while (0)
; #define PG8_MMA(ai, bj, At, Bt) do { __builtin_amdgcn_s_setprio(1); _Pragma("unroll") for (int m = 0; m < 4; ++m) _Pragma("unroll") for (int n = 0; n < 2; ++n) _Pragma("unroll") for (int k = 0; k < 2; ++k) \
;         acc[ai][bj][m][n] = __builtin_amdgcn_mfma_f32_16x16x32_bf16(Bt[n][k], At[m][k], acc[ai][bj][m][n], 0, 0, 0); __builtin_amdgcn_s_setprio(0); } while (0)
; #define PG8_WAIT_V(n) asm volatile("s_waitcnt vmcnt(" #n ")" ::: "memory")
; #define PG8_WAIT_L(n) asm volatile("s_waitcnt lgkmcnt(" #n ")" ::: "memory")
; #define PG8_BAR __builtin_amdgcn_s_barrier()
; #define PG8_SCHED __builtin_amdgcn_sched_barrier(0)
; template <class Epi, class Sched>
; __device__ __forceinline__ void gemm_phase(LAS unsigned char* lds, const Gemm g, const Sched& S, const Epi& E, int wave_id) {
;     ...
;             PG8_WAIT_V(8); PG8_WAIT_L(0); PG8_BAR; PG8_MMA(1, 0, At, B0); PG8_MMA(1, 1, At, B1); PG8_BAR; PG8_SCHED;
;             PG8_LDB(B0, 1, 0); PG8_LDB(B1, 1, 1); PG8_SCHED; PG8_LDA(At, 1, 0); PG8_STAGE(PG8_SA(0, 1), a2 + hstepA, voffA);
;             PG8_WAIT_V(8); PG8_WAIT_L(0); PG8_BAR; PG8_MMA(0, 0, At, B0); PG8_MMA(0, 1, At, B1); PG8_BAR; PG8_SCHED;
	s_setprio 1
	s_waitcnt lgkmcnt(0)
	v_mfma_f32_16x16x32_bf16 v[60:63], v[128:131], v[196:199], 0
	v_mfma_f32_16x16x32_bf16 v[56:59], v[136:139], v[196:199], 0
	v_mfma_f32_16x16x32_bf16 v[44:47], v[128:131], v[204:207], 0
	v_mfma_f32_16x16x32_bf16 v[40:43], v[136:139], v[204:207], 0
	v_mfma_f32_16x16x32_bf16 v[28:31], v[128:131], v[212:215], 0
	v_mfma_f32_16x16x32_bf16 v[24:27], v[136:139], v[212:215], 0
	v_mfma_f32_16x16x32_bf16 v[12:15], v[128:131], v[220:223], 0
	v_mfma_f32_16x16x32_bf16 v[8:11], v[136:139], v[220:223], 0
	v_mfma_f32_16x16x32_bf16 v[60:63], v[132:135], v[200:203], v[60:63]
	v_mfma_f32_16x16x32_bf16 v[56:59], v[140:143], v[200:203], v[56:59]
	v_mfma_f32_16x16x32_bf16 v[44:47], v[132:135], v[208:211], v[44:47]
	v_mfma_f32_16x16x32_bf16 v[40:43], v[140:143], v[208:211], v[40:43]
	v_mfma_f32_16x16x32_bf16 v[28:31], v[132:135], v[216:219], v[28:31]
	v_mfma_f32_16x16x32_bf16 v[24:27], v[140:143], v[216:219], v[24:27]
	v_mfma_f32_16x16x32_bf16 v[12:15], v[132:135], v[224:227], v[12:15]
	v_mfma_f32_16x16x32_bf16 v[8:11], v[140:143], v[224:227], v[8:11]
	s_setprio 0
	s_setprio 1
	v_mfma_f32_16x16x32_bf16 v[52:55], v[170:173], v[196:199], 0
	v_mfma_f32_16x16x32_bf16 v[48:51], v[188:191], v[196:199], 0
	v_mfma_f32_16x16x32_bf16 v[36:39], v[170:173], v[204:207], 0
	v_mfma_f32_16x16x32_bf16 v[32:35], v[188:191], v[204:207], 0
	v_mfma_f32_16x16x32_bf16 v[20:23], v[170:173], v[212:215], 0
	v_mfma_f32_16x16x32_bf16 v[16:19], v[188:191], v[212:215], 0
	v_mfma_f32_16x16x32_bf16 v[4:7], v[170:173], v[220:223], 0
	v_mfma_f32_16x16x32_bf16 v[0:3], v[188:191], v[220:223], 0
	v_mfma_f32_16x16x32_bf16 v[52:55], v[184:187], v[200:203], v[52:55]
	v_mfma_f32_16x16x32_bf16 v[48:51], v[192:195], v[200:203], v[48:51]
	v_mfma_f32_16x16x32_bf16 v[36:39], v[184:187], v[208:211], v[36:39]
	v_mfma_f32_16x16x32_bf16 v[32:35], v[192:195], v[208:211], v[32:35]
	v_mfma_f32_16x16x32_bf16 v[20:23], v[184:187], v[216:219], v[20:23]
	v_mfma_f32_16x16x32_bf16 v[16:19], v[192:195], v[216:219], v[16:19]
	v_mfma_f32_16x16x32_bf16 v[4:7], v[184:187], v[224:227], v[4:7]
	v_mfma_f32_16x16x32_bf16 v[0:3], v[192:195], v[224:227], v[0:3]
	s_setprio 0
	s_barrier
	s_add_i32 s72, 0, 0x18000
	s_add_i32 s73, 0, 0x1c000
	v_add_u32_e32 v140, s72, v177
	v_add_u32_e32 v192, s73, v177
	ds_read_b128 v[128:131], v140
	ds_read_b128 v[132:135], v140 offset:1024
	ds_read_b128 v[136:139], v140 offset:2048
	ds_read_b128 v[140:143], v140 offset:3072
	ds_read_b128 v[170:173], v192
	ds_read_b128 v[184:187], v192 offset:1024
	ds_read_b128 v[188:191], v192 offset:2048
	ds_read_b128 v[192:195], v192 offset:3072
	s_add_u32 s38, s38, 0x40000
	s_addc_u32 s39, s39, 0
	s_mov_b32 m0, s51
	ds_read_b128 v[196:199], v180 offset:32768
	ds_read_b128 v[200:203], v180 offset:33792
	ds_read_b128 v[204:207], v180 offset:34816
	ds_read_b128 v[208:211], v180 offset:35840
	ds_read_b128 v[212:215], v180 offset:36864
	ds_read_b128 v[216:219], v180 offset:37888
	ds_read_b128 v[220:223], v180 offset:38912
	ds_read_b128 v[224:227], v180 offset:39936
	global_load_lds_dwordx4 v144, s[38:39]
	s_mov_b32 m0, s52
	s_nop 0
	global_load_lds_dwordx4 v148, s[38:39]
	s_waitcnt vmcnt(8)
	s_waitcnt lgkmcnt(0)
	s_barrier
	s_setprio 1
	s_waitcnt lgkmcnt(0)
	v_mfma_f32_16x16x32_bf16 v[124:127], v[128:131], v[196:199], v[124:127]
	v_mfma_f32_16x16x32_bf16 v[120:123], v[136:139], v[196:199], v[120:123]
	v_mfma_f32_16x16x32_bf16 v[108:111], v[128:131], v[204:207], v[108:111]
	v_mfma_f32_16x16x32_bf16 v[104:107], v[136:139], v[204:207], v[104:107]
	v_mfma_f32_16x16x32_bf16 v[92:95], v[128:131], v[212:215], v[92:95]
	v_mfma_f32_16x16x32_bf16 v[88:91], v[136:139], v[212:215], v[88:91]
	v_mfma_f32_16x16x32_bf16 v[76:79], v[128:131], v[220:223], v[76:79]
	v_mfma_f32_16x16x32_bf16 v[72:75], v[136:139], v[220:223], v[72:75]
	v_mfma_f32_16x16x32_bf16 v[124:127], v[132:135], v[200:203], v[124:127]
	v_mfma_f32_16x16x32_bf16 v[120:123], v[140:143], v[200:203], v[120:123]
	v_mfma_f32_16x16x32_bf16 v[108:111], v[132:135], v[208:211], v[108:111]
	v_mfma_f32_16x16x32_bf16 v[104:107], v[140:143], v[208:211], v[104:107]
	v_mfma_f32_16x16x32_bf16 v[92:95], v[132:135], v[216:219], v[92:95]
	v_mfma_f32_16x16x32_bf16 v[88:91], v[140:143], v[216:219], v[88:91]
	v_mfma_f32_16x16x32_bf16 v[76:79], v[132:135], v[224:227], v[76:79]
	v_mfma_f32_16x16x32_bf16 v[72:75], v[140:143], v[224:227], v[72:75]
	s_setprio 0
	s_setprio 1
	v_mfma_f32_16x16x32_bf16 v[116:119], v[170:173], v[196:199], v[116:119]
	v_mfma_f32_16x16x32_bf16 v[112:115], v[188:191], v[196:199], v[112:115]
	v_mfma_f32_16x16x32_bf16 v[100:103], v[170:173], v[204:207], v[100:103]
	v_mfma_f32_16x16x32_bf16 v[96:99], v[188:191], v[204:207], v[96:99]
	v_mfma_f32_16x16x32_bf16 v[84:87], v[170:173], v[212:215], v[84:87]
	v_mfma_f32_16x16x32_bf16 v[80:83], v[188:191], v[212:215], v[80:83]
	v_mfma_f32_16x16x32_bf16 v[68:71], v[170:173], v[220:223], v[68:71]
	v_mfma_f32_16x16x32_bf16 v[64:67], v[188:191], v[220:223], v[64:67]
	v_mfma_f32_16x16x32_bf16 v[116:119], v[184:187], v[200:203], v[116:119]
	v_mfma_f32_16x16x32_bf16 v[112:115], v[192:195], v[200:203], v[112:115]
	v_mfma_f32_16x16x32_bf16 v[100:103], v[184:187], v[208:211], v[100:103]
	v_mfma_f32_16x16x32_bf16 v[96:99], v[192:195], v[208:211], v[96:99]
	v_mfma_f32_16x16x32_bf16 v[84:87], v[184:187], v[216:219], v[84:87]
	v_mfma_f32_16x16x32_bf16 v[80:83], v[192:195], v[216:219], v[80:83]
	v_mfma_f32_16x16x32_bf16 v[68:71], v[184:187], v[224:227], v[68:71]
	v_mfma_f32_16x16x32_bf16 v[64:67], v[192:195], v[224:227], v[64:67]
	s_setprio 0
	s_barrier
; #define PG8_STAGE(bufoff, gbase, voff) do { _Pragma("unroll") for (int _i = 0; _i < 2; ++_i) \
;         __builtin_amdgcn_global_load_lds((const unsigned*)((const char*)(gbase) + (voff)[_i]), (LAS unsigned*)(lds + (bufoff) + ldsw + _i * 8192), 16, 0, 0); } while (0)
; #define PG8_LDA(dst, b, h) do { _Pragma("unroll") for (int m = 0; m < 4; ++m) _Pragma("unroll") for (int k = 0; k < 2; ++k) dst[m][k] = *(const LAS bf16x8*)(lds + PG8_SA(b, h) + aoff + m * 2048 + k * 1024); } while (0)
; #define PG8_LDB(dst, b, h) do { _Pragma("unroll") for (int n = 0; n < 2; ++n) _Pragma("unroll") for (int k = 0; k < 2; ++k) dst[n][k] = *(const LAS bf16x8*)(lds + PG8_SB(b, h) + boff + n * 2048 + k * 1024); } while (0)
; #define PG8_MMA(ai, bj, At, Bt) do { __builtin_amdgcn_s_setprio(1); _Pragma("unroll") for (int m = 0; m < 4; ++m) _Pragma("unroll") for (int n = 0; n < 2; ++n) _Pragma("unroll") for (int k = 0; k < 2; ++k) \
;         acc[ai][bj][m][n] = __builtin_amdgcn_mfma_f32_16x16x32_bf16(Bt[n][k], At[m][k], acc[ai][bj][m][n], 0, 0, 0); __builtin_amdgcn_s_setprio(0); } while (0)
; #define PG8_WAIT_V(n) asm volatile("s_waitcnt vmcnt(" #n ")" ::: "memory")
; #define PG8_WAIT_L(n) asm volatile("s_waitcnt lgkmcnt(" #n ")" ::: "memory")
; #define PG8_BAR __builtin_amdgcn_s_barrier()
; #define PG8_SCHED __builtin_amdgcn_sched_barrier(0)
; template <class Epi, class Sched>
; __device__ __forceinline__ void gemm_phase(LAS unsigned char* lds, const Gemm g, const Sched& S, const Epi& E, int wave_id) {
;     ...
;             PG8_LDB(B0, 0, 0); PG8_LDB(B1, 0, 1); PG8_SCHED; PG8_LDA(At, 0, 0); PG8_STAGE(PG8_SA(1, 1), a1 + hstepA, voffA);
;             PG8_WAIT_V(8); PG8_WAIT_L(0); PG8_BAR; PG8_MMA(0, 0, At, B0); PG8_MMA(0, 1, At, B1); PG8_BAR; PG8_SCHED;
;     ...
;             PG8_LDB(B0, 1, 0); PG8_LDB(B1, 1, 1); PG8_SCHED; PG8_LDA(At, 1, 0); PG8_STAGE(PG8_SA(0, 1), a2 + hstepA, voffA);
;             PG8_WAIT_V(8); PG8_WAIT_L(0); PG8_BAR; PG8_MMA(0, 0, At, B0); PG8_MMA(0, 1, At, B1); PG8_BAR; PG8_SCHED;
;             PG8_LDA(At, 1, 1); PG8_STAGE(PG8_SB(1, 0), b3, voffB); PG8_STAGE(PG8_SB(1, 1), b3 + hstepB, voffB); PG8_STAGE(PG8_SA(1, 0), a3, voffA);
;             PG8_WAIT_V(8); PG8_WAIT_L(0); PG8_BAR; PG8_MMA(1, 0, At, B0); PG8_MMA(1, 1, At, B1); PG8_BAR; PG8_SCHED;
	s_add_i32 s38, s72, s2
	s_mov_b32 m0, s38
	ds_read_b128 v[196:199], v180 offset:49152
	ds_read_b128 v[200:203], v180 offset:50176
	ds_read_b128 v[204:207], v180 offset:51200
	ds_read_b128 v[208:211], v180 offset:52224
	ds_read_b128 v[212:215], v180 offset:53248
	ds_read_b128 v[216:219], v180 offset:54272
	ds_read_b128 v[220:223], v180 offset:55296
	ds_read_b128 v[224:227], v180 offset:56320
	global_load_lds_dwordx4 v146, s[76:77]
	s_add_i32 m0, s38, 0x2000
	s_add_u32 s36, s36, 0x40080
	s_addc_u32 s37, s37, 0
	s_add_i32 s38, s73, s2
	global_load_lds_dwordx4 v150, s[76:77]
	s_mov_b32 m0, s38
	s_nop 0
	global_load_lds_dwordx4 v146, s[36:37]
	s_add_i32 m0, s38, 0x2000
	s_nop 0
	global_load_lds_dwordx4 v150, s[36:37]
	s_mov_b32 m0, s54
	s_nop 0
	global_load_lds_dwordx4 v144, s[78:79]
	s_mov_b32 m0, s55
	s_nop 0
	global_load_lds_dwordx4 v148, s[78:79]
	s_waitcnt vmcnt(8)
	s_waitcnt lgkmcnt(0)
	s_barrier
	s_setprio 1
	s_waitcnt lgkmcnt(0)
	v_mfma_f32_16x16x32_bf16 v[60:63], v[128:131], v[196:199], v[60:63]
	v_mfma_f32_16x16x32_bf16 v[56:59], v[136:139], v[196:199], v[56:59]
	v_mfma_f32_16x16x32_bf16 v[44:47], v[128:131], v[204:207], v[44:47]
	v_mfma_f32_16x16x32_bf16 v[40:43], v[136:139], v[204:207], v[40:43]
	v_mfma_f32_16x16x32_bf16 v[28:31], v[128:131], v[212:215], v[28:31]
	v_mfma_f32_16x16x32_bf16 v[24:27], v[136:139], v[212:215], v[24:27]
	v_mfma_f32_16x16x32_bf16 v[12:15], v[128:131], v[220:223], v[12:15]
	v_mfma_f32_16x16x32_bf16 v[8:11], v[136:139], v[220:223], v[8:11]
	v_mfma_f32_16x16x32_bf16 v[60:63], v[132:135], v[200:203], v[60:63]
	v_mfma_f32_16x16x32_bf16 v[56:59], v[140:143], v[200:203], v[56:59]
	v_mfma_f32_16x16x32_bf16 v[44:47], v[132:135], v[208:211], v[44:47]
	v_mfma_f32_16x16x32_bf16 v[40:43], v[140:143], v[208:211], v[40:43]
	v_mfma_f32_16x16x32_bf16 v[28:31], v[132:135], v[216:219], v[28:31]
	v_mfma_f32_16x16x32_bf16 v[24:27], v[140:143], v[216:219], v[24:27]
	v_mfma_f32_16x16x32_bf16 v[12:15], v[132:135], v[224:227], v[12:15]
	v_mfma_f32_16x16x32_bf16 v[8:11], v[140:143], v[224:227], v[8:11]
	s_setprio 0
	s_setprio 1
	v_mfma_f32_16x16x32_bf16 v[52:55], v[170:173], v[196:199], v[52:55]
	v_mfma_f32_16x16x32_bf16 v[48:51], v[188:191], v[196:199], v[48:51]
	v_mfma_f32_16x16x32_bf16 v[36:39], v[170:173], v[204:207], v[36:39]
	v_mfma_f32_16x16x32_bf16 v[32:35], v[188:191], v[204:207], v[32:35]
	v_mfma_f32_16x16x32_bf16 v[20:23], v[170:173], v[212:215], v[20:23]
	v_mfma_f32_16x16x32_bf16 v[16:19], v[188:191], v[212:215], v[16:19]
	v_mfma_f32_16x16x32_bf16 v[4:7], v[170:173], v[220:223], v[4:7]
	v_mfma_f32_16x16x32_bf16 v[0:3], v[188:191], v[220:223], v[0:3]
	v_mfma_f32_16x16x32_bf16 v[52:55], v[184:187], v[200:203], v[52:55]
	v_mfma_f32_16x16x32_bf16 v[48:51], v[192:195], v[200:203], v[48:51]
	v_mfma_f32_16x16x32_bf16 v[36:39], v[184:187], v[208:211], v[36:39]
	v_mfma_f32_16x16x32_bf16 v[32:35], v[192:195], v[208:211], v[32:35]
	v_mfma_f32_16x16x32_bf16 v[20:23], v[184:187], v[216:219], v[20:23]
	v_mfma_f32_16x16x32_bf16 v[16:19], v[192:195], v[216:219], v[16:19]
	v_mfma_f32_16x16x32_bf16 v[4:7], v[184:187], v[224:227], v[4:7]
	v_mfma_f32_16x16x32_bf16 v[0:3], v[192:195], v[224:227], v[0:3]
	s_setprio 0
	s_barrier
	s_add_i32 s67, s67, 2
	s_add_u32 s34, s34, 0x100
	s_addc_u32 s35, s35, 0
	s_add_u32 s65, s65, 0x100
	s_addc_u32 s66, s66, 0
	s_cmp_gt_u32 s67, 13
.LBB0_1251:
	ds_read_b128 v[128:131], v178
	ds_read_b128 v[132:135], v178 offset:1024
	ds_read_b128 v[136:139], v178 offset:2048
	ds_read_b128 v[140:143], v178 offset:3072
	ds_read_b128 v[170:173], v179
	ds_read_b128 v[184:187], v179 offset:1024
	ds_read_b128 v[188:191], v179 offset:2048
	ds_read_b128 v[192:195], v179 offset:3072
	s_add_u32 s36, s34, 0xfffc0080
	s_addc_u32 s37, s35, -1
	s_cmp_eq_u32 s67, 12
	s_cselect_b32 s39, s25, s37
	s_cselect_b32 s38, s63, s36
	s_cselect_b32 s37, s23, s66
	s_cselect_b32 s36, s64, s65
	s_add_u32 s78, s38, 0x80
	s_addc_u32 s79, s39, 0
	s_add_u32 s76, s36, 0x80
	s_addc_u32 s77, s37, 0
	s_add_i32 m0, s49, 0xc000
	ds_read_b128 v[196:199], v180
	ds_read_b128 v[200:203], v180 offset:1024
	ds_read_b128 v[204:207], v180 offset:2048
	ds_read_b128 v[208:211], v180 offset:3072
	ds_read_b128 v[212:215], v180 offset:4096
	ds_read_b128 v[216:219], v180 offset:5120
	ds_read_b128 v[220:223], v180 offset:6144
	ds_read_b128 v[224:227], v180 offset:7168
	global_load_lds_dwordx4 v162, s[34:35]
	s_add_i32 m0, s49, 0xe000
	s_nop 0
	global_load_lds_dwordx4 v164, s[34:35]
	s_waitcnt vmcnt(8)
	s_waitcnt lgkmcnt(0)
	s_barrier
; #define PG8_STAGE(bufoff, gbase, voff) do { _Pragma("unroll") for (int _i = 0; _i < 2; ++_i) \
;         __builtin_amdgcn_global_load_lds((const unsigned*)((const char*)(gbase) + (voff)[_i]), (LAS unsigned*)(lds + (bufoff) + ldsw + _i * 8192), 16, 0, 0); } while (0)
; #define PG8_LDA(dst, b, h) do { _Pragma("unroll") for (int m = 0; m < 4; ++m) _Pragma("unroll") for (int k = 0; k < 2; ++k) dst[m][k] = *(const LAS bf16x8*)(lds + PG8_SA(b, h) + aoff + m * 2048 + k * 1024); } while (0)
; #define PG8_LDB(dst, b, h) do { _Pragma("unroll") for (int n = 0; n < 2; ++n) _Pragma("unroll") for (int k = 0; k < 2; ++k) dst[n][k] = *(const LAS bf16x8*)(lds + PG8_SB(b, h) + boff + n * 2048 + k * 1024); } while (0)
; #define PG8_MMA(ai, bj, At, Bt) do { __builtin_amdgcn_s_setprio(1); _Pragma("unroll") for (int m = 0; m < 4; ++m) _Pragma("unroll") for (int n = 0; n < 2; ++n) _Pragma("unroll") for (int k = 0; k < 2; ++k) \
;         acc[ai][bj][m][n] = __builtin_amdgcn_mfma_f32_16x16x32_bf16(Bt[n][k], At[m][k], acc[ai][bj][m][n], 0, 0, 0); __builtin_amdgcn_s_setprio(0); } while (0)
; #define PG8_WAIT_V(n) asm volatile("s_waitcnt vmcnt(" #n ")" ::: "memory")
; #define PG8_WAIT_L(n) asm volatile("s_waitcnt lgkmcnt(" #n ")" ::: "memory")
; #define PG8_BAR __builtin_amdgcn_s_barrier()
; #define PG8_SCHED __builtin_amdgcn_sched_barrier(0)
; template <class Epi, class Sched>
; __device__ __forceinline__ void gemm_phase(LAS unsigned char* lds, const Gemm g, const Sched& S, const Epi& E, int wave_id) {
;     ...
;             PG8_LDB(B0, 0, 0); PG8_LDB(B1, 0, 1); PG8_SCHED; PG8_LDA(At, 0, 0); PG8_STAGE(PG8_SA(1, 1), a1 + hstepA, voffA);
;             PG8_WAIT_V(8); PG8_WAIT_L(0); PG8_BAR; PG8_MMA(0, 0, At, B0); PG8_MMA(0, 1, At, B1); PG8_BAR; PG8_SCHED;
;             PG8_LDA(At, 0, 1); PG8_STAGE(PG8_SB(0, 0), b2, voffB); PG8_STAGE(PG8_SB(0, 1), b2 + hstepB, voffB); PG8_STAGE(PG8_SA(0, 0), a2, voffA);
;             PG8_WAIT_V(8); PG8_WAIT_L(0); PG8_BAR; PG8_MMA(1, 0, At, B0); PG8_MMA(1, 1, At, B1); PG8_BAR; PG8_SCHED;
	s_setprio 1
	s_waitcnt lgkmcnt(0)
	v_mfma_f32_16x16x32_bf16 v[124:127], v[128:131], v[196:199], v[124:127]
	v_mfma_f32_16x16x32_bf16 v[120:123], v[136:139], v[196:199], v[120:123]
	v_mfma_f32_16x16x32_bf16 v[108:111], v[128:131], v[204:207], v[108:111]
	v_mfma_f32_16x16x32_bf16 v[104:107], v[136:139], v[204:207], v[104:107]
	v_mfma_f32_16x16x32_bf16 v[92:95], v[128:131], v[212:215], v[92:95]
	v_mfma_f32_16x16x32_bf16 v[88:91], v[136:139], v[212:215], v[88:91]
	v_mfma_f32_16x16x32_bf16 v[76:79], v[128:131], v[220:223], v[76:79]
	v_mfma_f32_16x16x32_bf16 v[72:75], v[136:139], v[220:223], v[72:75]
	v_mfma_f32_16x16x32_bf16 v[124:127], v[132:135], v[200:203], v[124:127]
	v_mfma_f32_16x16x32_bf16 v[120:123], v[140:143], v[200:203], v[120:123]
	v_mfma_f32_16x16x32_bf16 v[108:111], v[132:135], v[208:211], v[108:111]
	v_mfma_f32_16x16x32_bf16 v[104:107], v[140:143], v[208:211], v[104:107]
	v_mfma_f32_16x16x32_bf16 v[92:95], v[132:135], v[216:219], v[92:95]
	v_mfma_f32_16x16x32_bf16 v[88:91], v[140:143], v[216:219], v[88:91]
	v_mfma_f32_16x16x32_bf16 v[76:79], v[132:135], v[224:227], v[76:79]
	v_mfma_f32_16x16x32_bf16 v[72:75], v[140:143], v[224:227], v[72:75]
	s_setprio 0
	s_setprio 1
	v_mfma_f32_16x16x32_bf16 v[116:119], v[170:173], v[196:199], v[116:119]
	v_mfma_f32_16x16x32_bf16 v[112:115], v[188:191], v[196:199], v[112:115]
	v_mfma_f32_16x16x32_bf16 v[100:103], v[170:173], v[204:207], v[100:103]
	v_mfma_f32_16x16x32_bf16 v[96:99], v[188:191], v[204:207], v[96:99]
	v_mfma_f32_16x16x32_bf16 v[84:87], v[170:173], v[212:215], v[84:87]
	v_mfma_f32_16x16x32_bf16 v[80:83], v[188:191], v[212:215], v[80:83]
	v_mfma_f32_16x16x32_bf16 v[68:71], v[170:173], v[220:223], v[68:71]
	v_mfma_f32_16x16x32_bf16 v[64:67], v[188:191], v[220:223], v[64:67]
	v_mfma_f32_16x16x32_bf16 v[116:119], v[184:187], v[200:203], v[116:119]
	v_mfma_f32_16x16x32_bf16 v[112:115], v[192:195], v[200:203], v[112:115]
	v_mfma_f32_16x16x32_bf16 v[100:103], v[184:187], v[208:211], v[100:103]
	v_mfma_f32_16x16x32_bf16 v[96:99], v[192:195], v[208:211], v[96:99]
	v_mfma_f32_16x16x32_bf16 v[84:87], v[184:187], v[216:219], v[84:87]
	v_mfma_f32_16x16x32_bf16 v[80:83], v[192:195], v[216:219], v[80:83]
	v_mfma_f32_16x16x32_bf16 v[68:71], v[184:187], v[224:227], v[68:71]
	v_mfma_f32_16x16x32_bf16 v[64:67], v[192:195], v[224:227], v[64:67]
	s_setprio 0
	s_barrier
	s_add_i32 s72, s60, s2
	s_mov_b32 m0, s72
	ds_read_b128 v[196:199], v180 offset:16384
	ds_read_b128 v[200:203], v180 offset:17408
	ds_read_b128 v[204:207], v180 offset:18432
	ds_read_b128 v[208:211], v180 offset:19456
	ds_read_b128 v[212:215], v180 offset:20480
	ds_read_b128 v[216:219], v180 offset:21504
	ds_read_b128 v[220:223], v180 offset:22528
	ds_read_b128 v[224:227], v180 offset:23552
	global_load_lds_dwordx4 v146, s[36:37]
	s_add_i32 m0, s72, 0x2000
	s_add_u32 s72, s36, 0x40000
	s_addc_u32 s73, s37, 0
	s_add_i32 s74, s61, s2
	global_load_lds_dwordx4 v150, s[36:37]
	s_mov_b32 m0, s74
	s_nop 0
	global_load_lds_dwordx4 v146, s[72:73]
	s_add_i32 m0, s74, 0x2000
	s_nop 0
	global_load_lds_dwordx4 v150, s[72:73]
	s_mov_b32 m0, s49
	s_nop 0
	global_load_lds_dwordx4 v144, s[38:39]
	s_mov_b32 m0, s50
	s_nop 0
	global_load_lds_dwordx4 v148, s[38:39]
	s_waitcnt vmcnt(8)
	s_waitcnt lgkmcnt(0)
	s_barrier
	s_setprio 1
	s_waitcnt lgkmcnt(0)
	v_mfma_f32_16x16x32_bf16 v[60:63], v[128:131], v[196:199], v[60:63]
	v_mfma_f32_16x16x32_bf16 v[56:59], v[136:139], v[196:199], v[56:59]
	v_mfma_f32_16x16x32_bf16 v[44:47], v[128:131], v[204:207], v[44:47]
	v_mfma_f32_16x16x32_bf16 v[40:43], v[136:139], v[204:207], v[40:43]
	v_mfma_f32_16x16x32_bf16 v[28:31], v[128:131], v[212:215], v[28:31]
	v_mfma_f32_16x16x32_bf16 v[24:27], v[136:139], v[212:215], v[24:27]
	v_mfma_f32_16x16x32_bf16 v[12:15], v[128:131], v[220:223], v[12:15]
	v_mfma_f32_16x16x32_bf16 v[8:11], v[136:139], v[220:223], v[8:11]
	v_mfma_f32_16x16x32_bf16 v[60:63], v[132:135], v[200:203], v[60:63]
	v_mfma_f32_16x16x32_bf16 v[56:59], v[140:143], v[200:203], v[56:59]
	v_mfma_f32_16x16x32_bf16 v[44:47], v[132:135], v[208:211], v[44:47]
	v_mfma_f32_16x16x32_bf16 v[40:43], v[140:143], v[208:211], v[40:43]
	v_mfma_f32_16x16x32_bf16 v[28:31], v[132:135], v[216:219], v[28:31]
	v_mfma_f32_16x16x32_bf16 v[24:27], v[140:143], v[216:219], v[24:27]
	v_mfma_f32_16x16x32_bf16 v[12:15], v[132:135], v[224:227], v[12:15]
	v_mfma_f32_16x16x32_bf16 v[8:11], v[140:143], v[224:227], v[8:11]
	s_setprio 0
	s_setprio 1
	v_mfma_f32_16x16x32_bf16 v[52:55], v[170:173], v[196:199], v[52:55]
	v_mfma_f32_16x16x32_bf16 v[48:51], v[188:191], v[196:199], v[48:51]
	v_mfma_f32_16x16x32_bf16 v[36:39], v[170:173], v[204:207], v[36:39]
	v_mfma_f32_16x16x32_bf16 v[32:35], v[188:191], v[204:207], v[32:35]
	v_mfma_f32_16x16x32_bf16 v[20:23], v[170:173], v[212:215], v[20:23]
	v_mfma_f32_16x16x32_bf16 v[16:19], v[188:191], v[212:215], v[16:19]
	v_mfma_f32_16x16x32_bf16 v[4:7], v[170:173], v[220:223], v[4:7]
	v_mfma_f32_16x16x32_bf16 v[0:3], v[188:191], v[220:223], v[0:3]
	v_mfma_f32_16x16x32_bf16 v[52:55], v[184:187], v[200:203], v[52:55]
	v_mfma_f32_16x16x32_bf16 v[48:51], v[192:195], v[200:203], v[48:51]
	v_mfma_f32_16x16x32_bf16 v[36:39], v[184:187], v[208:211], v[36:39]
	v_mfma_f32_16x16x32_bf16 v[32:35], v[192:195], v[208:211], v[32:35]
	v_mfma_f32_16x16x32_bf16 v[20:23], v[184:187], v[216:219], v[20:23]
	v_mfma_f32_16x16x32_bf16 v[16:19], v[192:195], v[216:219], v[16:19]
	v_mfma_f32_16x16x32_bf16 v[4:7], v[184:187], v[224:227], v[4:7]
	v_mfma_f32_16x16x32_bf16 v[0:3], v[192:195], v[224:227], v[0:3]
	s_setprio 0
	s_barrier
; #define PG8_STAGE(bufoff, gbase, voff) do { _Pragma("unroll") for (int _i = 0; _i < 2; ++_i) \
;         __builtin_amdgcn_global_load_lds((const unsigned*)((const char*)(gbase) + (voff)[_i]), (LAS unsigned*)(lds + (bufoff) + ldsw + _i * 8192), 16, 0, 0); } while (0)
; #define PG8_LDA(dst, b, h) do { _Pragma("unroll") for (int m = 0; m < 4; ++m) _Pragma("unroll") for (int k = 0; k < 2; ++k) dst[m][k] = *(const LAS bf16x8*)(lds + PG8_SA(b, h) + aoff + m * 2048 + k * 1024); } while (0)
; #define PG8_LDB(dst, b, h) do { _Pragma("unroll") for (int n = 0; n < 2; ++n) _Pragma("unroll") for (int k = 0; k < 2; ++k) dst[n][k] = *(const LAS bf16x8*)(lds + PG8_SB(b, h) + boff + n * 2048 + k * 1024); } while (0)
; #define PG8_MMA(ai, bj, At, Bt) do { __builtin_amdgcn_s_setprio(1); _Pragma("unroll") for (int m = 0; m < 4; ++m) _Pragma("unroll") for (int n = 0; n < 2; ++n) _Pragma("unroll") for (int k = 0; k < 2; ++k) \
;         acc[ai][bj][m][n] = __builtin_amdgcn_mfma_f32_16x16x32_bf16(Bt[n][k], At[m][k], acc[ai][bj][m][n], 0, 0, 0); __builtin_amdgcn_s_setprio(0); } while (0)
; #define PG8_WAIT_V(n) asm volatile("s_waitcnt vmcnt(" #n ")" ::: "memory")
; #define PG8_WAIT_L(n) asm volatile("s_waitcnt lgkmcnt(" #n ")" ::: "memory")
; #define PG8_BAR __builtin_amdgcn_s_barrier()
; #define PG8_SCHED __builtin_amdgcn_sched_barrier(0)
; template <class Epi, class Sched>
; __device__ __forceinline__ void gemm_phase(LAS unsigned char* lds, const Gemm g, const Sched& S, const Epi& E, int wave_id) {
;     ...
;             PG8_LDB(B0, 1, 0); PG8_LDB(B1, 1, 1); PG8_SCHED; PG8_LDA(At, 1, 0); PG8_STAGE(PG8_SA(0, 1), a2 + hstepA, voffA);
;             PG8_WAIT_V(8); PG8_WAIT_L(0); PG8_BAR; PG8_MMA(0, 0, At, B0); PG8_MMA(0, 1, At, B1); PG8_BAR; PG8_SCHED;
;             PG8_LDA(At, 1, 1); PG8_STAGE(PG8_SB(1, 0), b3, voffB); PG8_STAGE(PG8_SB(1, 1), b3 + hstepB, voffB); PG8_STAGE(PG8_SA(1, 0), a3, voffA);
;             PG8_WAIT_V(8); PG8_WAIT_L(0); PG8_BAR; PG8_MMA(1, 0, At, B0); PG8_MMA(1, 1, At, B1); PG8_BAR; PG8_SCHED;
	s_add_i32 s72, 0, 0x18000
	s_add_i32 s73, 0, 0x1c000
	v_add_u32_e32 v140, s72, v177
	v_add_u32_e32 v192, s73, v177
	ds_read_b128 v[128:131], v140
	ds_read_b128 v[132:135], v140 offset:1024
	ds_read_b128 v[136:139], v140 offset:2048
	ds_read_b128 v[140:143], v140 offset:3072
	ds_read_b128 v[170:173], v192
	ds_read_b128 v[184:187], v192 offset:1024
	ds_read_b128 v[188:191], v192 offset:2048
	ds_read_b128 v[192:195], v192 offset:3072
	s_add_u32 s38, s38, 0x40000
	s_addc_u32 s39, s39, 0
	s_mov_b32 m0, s51
	ds_read_b128 v[196:199], v180 offset:32768
	ds_read_b128 v[200:203], v180 offset:33792
	ds_read_b128 v[204:207], v180 offset:34816
	ds_read_b128 v[208:211], v180 offset:35840
	ds_read_b128 v[212:215], v180 offset:36864
	ds_read_b128 v[216:219], v180 offset:37888
	ds_read_b128 v[220:223], v180 offset:38912
	ds_read_b128 v[224:227], v180 offset:39936
	global_load_lds_dwordx4 v144, s[38:39]
	s_mov_b32 m0, s52
	s_nop 0
	global_load_lds_dwordx4 v148, s[38:39]
	s_waitcnt vmcnt(8)
	s_waitcnt lgkmcnt(0)
	s_barrier
	s_setprio 1
	s_waitcnt lgkmcnt(0)
	v_mfma_f32_16x16x32_bf16 v[124:127], v[128:131], v[196:199], v[124:127]
	v_mfma_f32_16x16x32_bf16 v[120:123], v[136:139], v[196:199], v[120:123]
	v_mfma_f32_16x16x32_bf16 v[108:111], v[128:131], v[204:207], v[108:111]
	v_mfma_f32_16x16x32_bf16 v[104:107], v[136:139], v[204:207], v[104:107]
	v_mfma_f32_16x16x32_bf16 v[92:95], v[128:131], v[212:215], v[92:95]
	v_mfma_f32_16x16x32_bf16 v[88:91], v[136:139], v[212:215], v[88:91]
	v_mfma_f32_16x16x32_bf16 v[76:79], v[128:131], v[220:223], v[76:79]
	v_mfma_f32_16x16x32_bf16 v[72:75], v[136:139], v[220:223], v[72:75]
	v_mfma_f32_16x16x32_bf16 v[124:127], v[132:135], v[200:203], v[124:127]
	v_mfma_f32_16x16x32_bf16 v[120:123], v[140:143], v[200:203], v[120:123]
	v_mfma_f32_16x16x32_bf16 v[108:111], v[132:135], v[208:211], v[108:111]
	v_mfma_f32_16x16x32_bf16 v[104:107], v[140:143], v[208:211], v[104:107]
	v_mfma_f32_16x16x32_bf16 v[92:95], v[132:135], v[216:219], v[92:95]
	v_mfma_f32_16x16x32_bf16 v[88:91], v[140:143], v[216:219], v[88:91]
	v_mfma_f32_16x16x32_bf16 v[76:79], v[132:135], v[224:227], v[76:79]
	v_mfma_f32_16x16x32_bf16 v[72:75], v[140:143], v[224:227], v[72:75]
	s_setprio 0
	s_setprio 1
	v_mfma_f32_16x16x32_bf16 v[116:119], v[170:173], v[196:199], v[116:119]
	v_mfma_f32_16x16x32_bf16 v[112:115], v[188:191], v[196:199], v[112:115]
	v_mfma_f32_16x16x32_bf16 v[100:103], v[170:173], v[204:207], v[100:103]
	v_mfma_f32_16x16x32_bf16 v[96:99], v[188:191], v[204:207], v[96:99]
	v_mfma_f32_16x16x32_bf16 v[84:87], v[170:173], v[212:215], v[84:87]
	v_mfma_f32_16x16x32_bf16 v[80:83], v[188:191], v[212:215], v[80:83]
	v_mfma_f32_16x16x32_bf16 v[68:71], v[170:173], v[220:223], v[68:71]
	v_mfma_f32_16x16x32_bf16 v[64:67], v[188:191], v[220:223], v[64:67]
	v_mfma_f32_16x16x32_bf16 v[116:119], v[184:187], v[200:203], v[116:119]
	v_mfma_f32_16x16x32_bf16 v[112:115], v[192:195], v[200:203], v[112:115]
	v_mfma_f32_16x16x32_bf16 v[100:103], v[184:187], v[208:211], v[100:103]
	v_mfma_f32_16x16x32_bf16 v[96:99], v[192:195], v[208:211], v[96:99]
	v_mfma_f32_16x16x32_bf16 v[84:87], v[184:187], v[216:219], v[84:87]
	v_mfma_f32_16x16x32_bf16 v[80:83], v[192:195], v[216:219], v[80:83]
	v_mfma_f32_16x16x32_bf16 v[68:71], v[184:187], v[224:227], v[68:71]
	v_mfma_f32_16x16x32_bf16 v[64:67], v[192:195], v[224:227], v[64:67]
	s_setprio 0
	s_barrier
	s_add_i32 s38, s72, s2
	s_mov_b32 m0, s38
	ds_read_b128 v[196:199], v180 offset:49152
	ds_read_b128 v[200:203], v180 offset:50176
	ds_read_b128 v[204:207], v180 offset:51200
	ds_read_b128 v[208:211], v180 offset:52224
	ds_read_b128 v[212:215], v180 offset:53248
	ds_read_b128 v[216:219], v180 offset:54272
	ds_read_b128 v[220:223], v180 offset:55296
	ds_read_b128 v[224:227], v180 offset:56320
	global_load_lds_dwordx4 v146, s[76:77]
	s_add_i32 m0, s38, 0x2000
	s_add_u32 s36, s36, 0x40080
	s_addc_u32 s37, s37, 0
	s_add_i32 s38, s73, s2
	global_load_lds_dwordx4 v150, s[76:77]
	s_mov_b32 m0, s38
	s_nop 0
	global_load_lds_dwordx4 v146, s[36:37]
	s_add_i32 m0, s38, 0x2000
	s_nop 0
	global_load_lds_dwordx4 v150, s[36:37]
	s_mov_b32 m0, s54
	s_nop 0
	global_load_lds_dwordx4 v144, s[78:79]
	s_mov_b32 m0, s55
	s_nop 0
	global_load_lds_dwordx4 v148, s[78:79]
	s_waitcnt vmcnt(8)
	s_waitcnt lgkmcnt(0)
	s_barrier
	s_setprio 1
	s_waitcnt lgkmcnt(0)
	v_mfma_f32_16x16x32_bf16 v[60:63], v[128:131], v[196:199], v[60:63]
	v_mfma_f32_16x16x32_bf16 v[56:59], v[136:139], v[196:199], v[56:59]
	v_mfma_f32_16x16x32_bf16 v[44:47], v[128:131], v[204:207], v[44:47]
	v_mfma_f32_16x16x32_bf16 v[40:43], v[136:139], v[204:207], v[40:43]
	v_mfma_f32_16x16x32_bf16 v[28:31], v[128:131], v[212:215], v[28:31]
	v_mfma_f32_16x16x32_bf16 v[24:27], v[136:139], v[212:215], v[24:27]
	v_mfma_f32_16x16x32_bf16 v[12:15], v[128:131], v[220:223], v[12:15]
	v_mfma_f32_16x16x32_bf16 v[8:11], v[136:139], v[220:223], v[8:11]
	v_mfma_f32_16x16x32_bf16 v[60:63], v[132:135], v[200:203], v[60:63]
	v_mfma_f32_16x16x32_bf16 v[56:59], v[140:143], v[200:203], v[56:59]
	v_mfma_f32_16x16x32_bf16 v[44:47], v[132:135], v[208:211], v[44:47]
	v_mfma_f32_16x16x32_bf16 v[40:43], v[140:143], v[208:211], v[40:43]
	v_mfma_f32_16x16x32_bf16 v[28:31], v[132:135], v[216:219], v[28:31]
	v_mfma_f32_16x16x32_bf16 v[24:27], v[140:143], v[216:219], v[24:27]
	v_mfma_f32_16x16x32_bf16 v[12:15], v[132:135], v[224:227], v[12:15]
	v_mfma_f32_16x16x32_bf16 v[8:11], v[140:143], v[224:227], v[8:11]
	s_setprio 0
	s_setprio 1
	v_mfma_f32_16x16x32_bf16 v[52:55], v[170:173], v[196:199], v[52:55]
	v_mfma_f32_16x16x32_bf16 v[48:51], v[188:191], v[196:199], v[48:51]
	v_mfma_f32_16x16x32_bf16 v[36:39], v[170:173], v[204:207], v[36:39]
	v_mfma_f32_16x16x32_bf16 v[32:35], v[188:191], v[204:207], v[32:35]
	v_mfma_f32_16x16x32_bf16 v[20:23], v[170:173], v[212:215], v[20:23]
	v_mfma_f32_16x16x32_bf16 v[16:19], v[188:191], v[212:215], v[16:19]
	v_mfma_f32_16x16x32_bf16 v[4:7], v[170:173], v[220:223], v[4:7]
	v_mfma_f32_16x16x32_bf16 v[0:3], v[188:191], v[220:223], v[0:3]
	v_mfma_f32_16x16x32_bf16 v[52:55], v[184:187], v[200:203], v[52:55]
	v_mfma_f32_16x16x32_bf16 v[48:51], v[192:195], v[200:203], v[48:51]
	v_mfma_f32_16x16x32_bf16 v[36:39], v[184:187], v[208:211], v[36:39]
	v_mfma_f32_16x16x32_bf16 v[32:35], v[192:195], v[208:211], v[32:35]
	v_mfma_f32_16x16x32_bf16 v[20:23], v[184:187], v[216:219], v[20:23]
	v_mfma_f32_16x16x32_bf16 v[16:19], v[192:195], v[216:219], v[16:19]
	v_mfma_f32_16x16x32_bf16 v[4:7], v[184:187], v[224:227], v[4:7]
	v_mfma_f32_16x16x32_bf16 v[0:3], v[192:195], v[224:227], v[0:3]
	s_setprio 0
	s_barrier
	s_add_i32 s67, s67, 2
	s_add_u32 s34, s34, 0x100
	s_addc_u32 s35, s35, 0
	s_add_u32 s65, s65, 0x100
	s_addc_u32 s66, s66, 0
	s_cmp_gt_u32 s67, 13
	s_cbranch_scc0 .LBB0_1251
	s_and_b64 vcc, exec, s[18:19]
	s_cbranch_vccz .LBB0_1254
	s_barrier

;     __device__ bool next(int i, Unit& u) const { if (r0 + i >= r1) return false; return base.next(r0 + i, u); }
;     __device__ bool next(int i, Unit& u) const { const int L = i * G + c; if (L >= 256) return false; u.pm = L; u.pn = L >> 3; return true; }
; #define PG8_STAGE(bufoff, gbase, voff) do { _Pragma("unroll") for (int _i = 0; _i < 2; ++_i) \
;         __builtin_amdgcn_global_load_lds((const unsigned*)((const char*)(gbase) + (voff)[_i]), (LAS unsigned*)(lds + (bufoff) + ldsw + _i * 8192), 16, 0, 0); } while (0)
; #define PG8_LDA(dst, b, h) do { _Pragma("unroll") for (int m = 0; m < 4; ++m) _Pragma("unroll") for (int k = 0; k < 2; ++k) dst[m][k] = *(const LAS bf16x8*)(lds + PG8_SA(b, h) + aoff + m * 2048 + k * 1024); } while (0)
; #define PG8_LDB(dst, b, h) do { _Pragma("unroll") for (int n = 0; n < 2; ++n) _Pragma("unroll") for (int k = 0; k < 2; ++k) dst[n][k] = *(const LAS bf16x8*)(lds + PG8_SB(b, h) + boff + n * 2048 + k * 1024); } while (0)
; #define PG8_WAIT_V(n) asm volatile("s_waitcnt vmcnt(" #n ")" ::: "memory")
; #define PG8_WAIT_L(n) asm volatile("s_waitcnt lgkmcnt(" #n ")" ::: "memory")
; template <class Epi, class Sched>
; __device__ __forceinline__ void gemm_phase(LAS unsigned char* lds, const Gemm g, const Sched& S, const Epi& E, int wave_id) {
;     ...
;         const bool has_next = S.next(ui + 1, nxt);
;         const char* nA = has_next ? (const char*)g.A + (size_t)nxt.pm * tstepA : cA; const char* nB = has_next ? (const char*)g.Bt + (size_t)nxt.pn * tstepB : cB;
;         for (int t = 0; t < nt; t += 2) {
;             const bool last = (t == nt - 2);
;             const char* a1 = cA + (size_t)(t + 1) * kstep;
;             const char* a2 = last ? nA : cA + (size_t)(t + 2) * kstep; const char* b2 = last ? nB : cB + (size_t)(t + 2) * kstep;
;             const char* a3 = a2 + kstep; const char* b3 = b2 + kstep;
;             PG8_LDB(B0, 0, 0); PG8_LDB(B1, 0, 1); PG8_SCHED; PG8_LDA(At, 0, 0); PG8_STAGE(PG8_SA(1, 1), a1 + hstepA, voffA);
;             PG8_WAIT_V(8); PG8_WAIT_L(0); PG8_BAR; PG8_MMA(0, 0, At, B0); PG8_MMA(0, 1, At, B1); PG8_BAR; PG8_SCHED;
;             PG8_LDA(At, 0, 1); PG8_STAGE(PG8_SB(0, 0), b2, voffB); PG8_STAGE(PG8_SB(0, 1), b2 + hstepB, voffB); PG8_STAGE(PG8_SA(0, 0), a2, voffA);
;             PG8_WAIT_V(8); PG8_WAIT_L(0); PG8_BAR; PG8_MMA(1, 0, At, B0); PG8_MMA(1, 1, At, B1); PG8_BAR; PG8_SCHED;
.LBB0_1381:
	s_ashr_i32 s41, s40, 31
	s_lshl_b64 s[42:43], s[40:41], 19
	s_add_u32 s42, s16, s42
	s_addc_u32 s43, s17, s43
	s_and_b64 s[44:45], s[8:9], exec
	s_cselect_b32 s41, s43, s13
	s_cselect_b32 s50, s42, s12
	s_ashr_i32 s39, s38, 31
	s_lshl_b64 s[44:45], s[38:39], 19
	s_add_u32 s44, s3, s44
	s_addc_u32 s45, s33, s45
	s_and_b64 s[48:49], s[8:9], exec
	s_cselect_b32 s39, s45, s47
	s_cselect_b32 s51, s44, s46
	s_add_u32 s12, s12, 0x40080
	s_addc_u32 s13, s13, 0
	s_add_u32 s65, s46, 0x100
	s_addc_u32 s66, s47, 0
	s_mov_b32 s67, -2
	s_waitcnt vmcnt(0)
	ds_read_b128 v[8:11], v200
	ds_read_b128 v[12:15], v200 offset:1024
	ds_read_b128 v[16:19], v200 offset:2048
	ds_read_b128 v[20:23], v200 offset:3072
	ds_read_b128 v[144:147], v201
	ds_read_b128 v[148:151], v201 offset:1024
	ds_read_b128 v[176:179], v201 offset:2048
	ds_read_b128 v[180:183], v201 offset:3072
	s_add_u32 s46, s12, 0xfffc0080
	s_addc_u32 s47, s13, -1
	s_cmp_eq_u32 s67, 12
	s_cselect_b32 s49, s41, s47
	s_cselect_b32 s48, s50, s46
	s_cselect_b32 s47, s39, s66
	s_cselect_b32 s46, s51, s65
	s_add_u32 s78, s48, 0x80
	s_addc_u32 s79, s49, 0
	s_add_u32 s76, s46, 0x80
	s_addc_u32 s77, s47, 0
	s_add_i32 m0, s37, 0xc000
	ds_read_b128 v[184:187], v202
	ds_read_b128 v[188:191], v202 offset:1024
	ds_read_b128 v[192:195], v202 offset:2048
	ds_read_b128 v[196:199], v202 offset:3072
	ds_read_b128 v[206:209], v202 offset:4096
	ds_read_b128 v[210:213], v202 offset:5120
	ds_read_b128 v[214:217], v202 offset:6144
	ds_read_b128 v[218:221], v202 offset:7168
	global_load_lds_dwordx4 v168, s[12:13]
	s_add_i32 m0, s37, 0xe000
	s_nop 0
	global_load_lds_dwordx4 v170, s[12:13]
	s_waitcnt vmcnt(8)
	s_waitcnt lgkmcnt(0)
	s_barrier
	s_setprio 1
	s_waitcnt lgkmcnt(0)
	v_mfma_f32_16x16x32_bf16 v[140:143], v[8:11], v[184:187], 0
	v_mfma_f32_16x16x32_bf16 v[136:139], v[16:19], v[184:187], 0
	v_mfma_f32_16x16x32_bf16 v[124:127], v[8:11], v[192:195], 0
	v_mfma_f32_16x16x32_bf16 v[120:123], v[16:19], v[192:195], 0
	v_mfma_f32_16x16x32_bf16 v[108:111], v[8:11], v[206:209], 0
	v_mfma_f32_16x16x32_bf16 v[104:107], v[16:19], v[206:209], 0
	v_mfma_f32_16x16x32_bf16 v[92:95], v[8:11], v[214:217], 0
	v_mfma_f32_16x16x32_bf16 v[88:91], v[16:19], v[214:217], 0
	v_mfma_f32_16x16x32_bf16 v[140:143], v[12:15], v[188:191], v[140:143]
	v_mfma_f32_16x16x32_bf16 v[136:139], v[20:23], v[188:191], v[136:139]
	v_mfma_f32_16x16x32_bf16 v[124:127], v[12:15], v[196:199], v[124:127]
	v_mfma_f32_16x16x32_bf16 v[120:123], v[20:23], v[196:199], v[120:123]
	v_mfma_f32_16x16x32_bf16 v[108:111], v[12:15], v[210:213], v[108:111]
	v_mfma_f32_16x16x32_bf16 v[104:107], v[20:23], v[210:213], v[104:107]
	v_mfma_f32_16x16x32_bf16 v[92:95], v[12:15], v[218:221], v[92:95]
	v_mfma_f32_16x16x32_bf16 v[88:91], v[20:23], v[218:221], v[88:91]
	s_setprio 0
	s_setprio 1
	v_mfma_f32_16x16x32_bf16 v[132:135], v[144:147], v[184:187], 0
	v_mfma_f32_16x16x32_bf16 v[128:131], v[176:179], v[184:187], 0
	v_mfma_f32_16x16x32_bf16 v[116:119], v[144:147], v[192:195], 0
	v_mfma_f32_16x16x32_bf16 v[112:115], v[176:179], v[192:195], 0
	v_mfma_f32_16x16x32_bf16 v[100:103], v[144:147], v[206:209], 0
	v_mfma_f32_16x16x32_bf16 v[96:99], v[176:179], v[206:209], 0
	v_mfma_f32_16x16x32_bf16 v[84:87], v[144:147], v[214:217], 0
	v_mfma_f32_16x16x32_bf16 v[80:83], v[176:179], v[214:217], 0
	v_mfma_f32_16x16x32_bf16 v[132:135], v[148:151], v[188:191], v[132:135]
	v_mfma_f32_16x16x32_bf16 v[128:131], v[180:183], v[188:191], v[128:131]
	v_mfma_f32_16x16x32_bf16 v[116:119], v[148:151], v[196:199], v[116:119]
	v_mfma_f32_16x16x32_bf16 v[112:115], v[180:183], v[196:199], v[112:115]
	v_mfma_f32_16x16x32_bf16 v[100:103], v[148:151], v[210:213], v[100:103]
	v_mfma_f32_16x16x32_bf16 v[96:99], v[180:183], v[210:213], v[96:99]
	v_mfma_f32_16x16x32_bf16 v[84:87], v[148:151], v[218:221], v[84:87]
	v_mfma_f32_16x16x32_bf16 v[80:83], v[180:183], v[218:221], v[80:83]
	s_setprio 0
	s_barrier
	s_add_i32 s72, s61, s35
	s_mov_b32 m0, s72
	ds_read_b128 v[184:187], v202 offset:16384
	ds_read_b128 v[188:191], v202 offset:17408
	ds_read_b128 v[192:195], v202 offset:18432
	ds_read_b128 v[196:199], v202 offset:19456
	ds_read_b128 v[206:209], v202 offset:20480
	ds_read_b128 v[210:213], v202 offset:21504
	ds_read_b128 v[214:217], v202 offset:22528
	ds_read_b128 v[218:221], v202 offset:23552
	global_load_lds_dwordx4 v154, s[46:47]
	s_add_i32 m0, s72, 0x2000
	s_add_u32 s72, s46, 0x40000
	s_addc_u32 s73, s47, 0
	s_add_i32 s74, s62, s35
	global_load_lds_dwordx4 v158, s[46:47]
	s_mov_b32 m0, s74
	s_nop 0
	global_load_lds_dwordx4 v154, s[72:73]
	s_add_i32 m0, s74, 0x2000
	s_nop 0
	global_load_lds_dwordx4 v158, s[72:73]
	s_mov_b32 m0, s37
	s_nop 0
	global_load_lds_dwordx4 v152, s[48:49]
	s_mov_b32 m0, s52
	s_nop 0
	global_load_lds_dwordx4 v156, s[48:49]
	s_waitcnt vmcnt(8)
	s_waitcnt lgkmcnt(0)
	s_barrier
; #define PG8_STAGE(bufoff, gbase, voff) do { _Pragma("unroll") for (int _i = 0; _i < 2; ++_i) \
;         __builtin_amdgcn_global_load_lds((const unsigned*)((const char*)(gbase) + (voff)[_i]), (LAS unsigned*)(lds + (bufoff) + ldsw + _i * 8192), 16, 0, 0); } while (0)
; #define PG8_LDA(dst, b, h) do { _Pragma("unroll") for (int m = 0; m < 4; ++m) _Pragma("unroll") for (int k = 0; k < 2; ++k) dst[m][k] = *(const LAS bf16x8*)(lds + PG8_SA(b, h) + aoff + m * 2048 + k * 1024); } while (0)
; #define PG8_LDB(dst, b, h) do { _Pragma("unroll") for (int n = 0; n < 2; ++n) _Pragma("unroll") for (int k = 0; k < 2; ++k) dst[n][k] = *(const LAS bf16x8*)(lds + PG8_SB(b, h) + boff + n * 2048 + k * 1024); } while (0)
; #define PG8_WAIT_V(n) asm volatile("s_waitcnt vmcnt(" #n ")" ::: "memory")
; #define PG8_BAR __builtin_amdgcn_s_barrier()
; template <class Epi, class Sched>
; __device__ __forceinline__ void gemm_phase(LAS unsigned char* lds, const Gemm g, const Sched& S, const Epi& E, int wave_id) {
;     ...
;         for (int t = 0; t < nt; t += 2) {
;             const bool last = (t == nt - 2);
;             const char* a1 = cA + (size_t)(t + 1) * kstep;
;             const char* a2 = last ? nA : cA + (size_t)(t + 2) * kstep; const char* b2 = last ? nB : cB + (size_t)(t + 2) * kstep;
;             const char* a3 = a2 + kstep; const char* b3 = b2 + kstep;
;             PG8_LDB(B0, 0, 0); PG8_LDB(B1, 0, 1); PG8_SCHED; PG8_LDA(At, 0, 0); PG8_STAGE(PG8_SA(1, 1), a1 + hstepA, voffA);
;             PG8_WAIT_V(8); PG8_WAIT_L(0); PG8_BAR; PG8_MMA(0, 0, At, B0); PG8_MMA(0, 1, At, B1); PG8_BAR; PG8_SCHED;
;             PG8_LDA(At, 0, 1); PG8_STAGE(PG8_SB(0, 0), b2, voffB); PG8_STAGE(PG8_SB(0, 1), b2 + hstepB, voffB); PG8_STAGE(PG8_SA(0, 0), a2, voffA);
;             PG8_WAIT_V(8); PG8_WAIT_L(0); PG8_BAR; PG8_MMA(1, 0, At, B0); PG8_MMA(1, 1, At, B1); PG8_BAR; PG8_SCHED;
;             PG8_LDB(B0, 1, 0); PG8_LDB(B1, 1, 1); PG8_SCHED; PG8_LDA(At, 1, 0); PG8_STAGE(PG8_SA(0, 1), a2 + hstepA, voffA);
;             PG8_WAIT_V(8); PG8_WAIT_L(0); PG8_BAR; PG8_MMA(0, 0, At, B0); PG8_MMA(0, 1, At, B1); PG8_BAR; PG8_SCHED;
;             PG8_LDA(At, 1, 1); PG8_STAGE(PG8_SB(1, 0), b3, voffB); PG8_STAGE(PG8_SB(1, 1), b3 + hstepB, voffB); PG8_STAGE(PG8_SA(1, 0), a3, voffA);
;             PG8_WAIT_V(8); PG8_WAIT_L(0); PG8_BAR; PG8_MMA(1, 0, At, B0); PG8_MMA(1, 1, At, B1); PG8_BAR; PG8_SCHED;
	s_setprio 1
	s_waitcnt lgkmcnt(0)
	v_mfma_f32_16x16x32_bf16 v[76:79], v[8:11], v[184:187], 0
	v_mfma_f32_16x16x32_bf16 v[72:75], v[16:19], v[184:187], 0
	v_mfma_f32_16x16x32_bf16 v[60:63], v[8:11], v[192:195], 0
	v_mfma_f32_16x16x32_bf16 v[56:59], v[16:19], v[192:195], 0
	v_mfma_f32_16x16x32_bf16 v[44:47], v[8:11], v[206:209], 0
	v_mfma_f32_16x16x32_bf16 v[40:43], v[16:19], v[206:209], 0
	v_mfma_f32_16x16x32_bf16 v[8:11], v[8:11], v[214:217], 0
	v_mfma_f32_16x16x32_bf16 v[76:79], v[12:15], v[188:191], v[76:79]
	v_mfma_f32_16x16x32_bf16 v[72:75], v[20:23], v[188:191], v[72:75]
	v_mfma_f32_16x16x32_bf16 v[60:63], v[12:15], v[196:199], v[60:63]
	v_mfma_f32_16x16x32_bf16 v[56:59], v[20:23], v[196:199], v[56:59]
	v_mfma_f32_16x16x32_bf16 v[44:47], v[12:15], v[210:213], v[44:47]
	v_mfma_f32_16x16x32_bf16 v[40:43], v[20:23], v[210:213], v[40:43]
	v_mfma_f32_16x16x32_bf16 v[8:11], v[12:15], v[218:221], v[8:11]
	v_mfma_f32_16x16x32_bf16 v[12:15], v[16:19], v[214:217], 0
	v_mfma_f32_16x16x32_bf16 v[12:15], v[20:23], v[218:221], v[12:15]
	s_setprio 0
	s_setprio 1
	v_mfma_f32_16x16x32_bf16 v[24:27], v[144:147], v[192:195], 0
	v_mfma_f32_16x16x32_bf16 v[52:55], v[148:151], v[196:199], v[24:27]
	v_mfma_f32_16x16x32_bf16 v[24:27], v[176:179], v[192:195], 0
	v_mfma_f32_16x16x32_bf16 v[48:51], v[180:183], v[196:199], v[24:27]
	v_mfma_f32_16x16x32_bf16 v[24:27], v[144:147], v[206:209], 0
	v_mfma_f32_16x16x32_bf16 v[36:39], v[148:151], v[210:213], v[24:27]
	v_mfma_f32_16x16x32_bf16 v[24:27], v[176:179], v[206:209], 0
	v_mfma_f32_16x16x32_bf16 v[4:7], v[144:147], v[214:217], 0
	v_mfma_f32_16x16x32_bf16 v[0:3], v[176:179], v[214:217], 0
	v_mfma_f32_16x16x32_bf16 v[16:19], v[144:147], v[184:187], 0
	v_mfma_f32_16x16x32_bf16 v[20:23], v[176:179], v[184:187], 0
	v_mfma_f32_16x16x32_bf16 v[32:35], v[180:183], v[210:213], v[24:27]
	v_mfma_f32_16x16x32_bf16 v[4:7], v[148:151], v[218:221], v[4:7]
	v_mfma_f32_16x16x32_bf16 v[0:3], v[180:183], v[218:221], v[0:3]
	v_mfma_f32_16x16x32_bf16 v[16:19], v[148:151], v[188:191], v[16:19]
	v_mfma_f32_16x16x32_bf16 v[20:23], v[180:183], v[188:191], v[20:23]
	s_setprio 0
	s_barrier
	s_add_i32 s72, 0, 0x18000
	s_add_i32 s73, 0, 0x1c000
	v_add_u32_e32 v68, s72, v165
	v_add_u32_e32 v180, s73, v165
	ds_read_b128 v[24:27], v68
	ds_read_b128 v[28:31], v68 offset:1024
	ds_read_b128 v[64:67], v68 offset:2048
	ds_read_b128 v[68:71], v68 offset:3072
	ds_read_b128 v[144:147], v180
	ds_read_b128 v[148:151], v180 offset:1024
	ds_read_b128 v[176:179], v180 offset:2048
	ds_read_b128 v[180:183], v180 offset:3072
	s_add_u32 s48, s48, 0x40000
	s_addc_u32 s49, s49, 0
	s_mov_b32 m0, s53
	ds_read_b128 v[184:187], v202 offset:32768
	ds_read_b128 v[188:191], v202 offset:33792
	ds_read_b128 v[192:195], v202 offset:34816
	ds_read_b128 v[196:199], v202 offset:35840
	ds_read_b128 v[206:209], v202 offset:36864
	ds_read_b128 v[210:213], v202 offset:37888
	ds_read_b128 v[214:217], v202 offset:38912
	ds_read_b128 v[218:221], v202 offset:39936
	global_load_lds_dwordx4 v152, s[48:49]
	s_mov_b32 m0, s54
	s_nop 0
	global_load_lds_dwordx4 v156, s[48:49]
	s_waitcnt vmcnt(8)
	s_waitcnt lgkmcnt(0)
	s_barrier
	s_setprio 1
	s_waitcnt lgkmcnt(0)
	v_mfma_f32_16x16x32_bf16 v[140:143], v[24:27], v[184:187], v[140:143]
	v_mfma_f32_16x16x32_bf16 v[136:139], v[64:67], v[184:187], v[136:139]
	v_mfma_f32_16x16x32_bf16 v[124:127], v[24:27], v[192:195], v[124:127]
	v_mfma_f32_16x16x32_bf16 v[120:123], v[64:67], v[192:195], v[120:123]
	v_mfma_f32_16x16x32_bf16 v[108:111], v[24:27], v[206:209], v[108:111]
	v_mfma_f32_16x16x32_bf16 v[104:107], v[64:67], v[206:209], v[104:107]
	v_mfma_f32_16x16x32_bf16 v[92:95], v[24:27], v[214:217], v[92:95]
	v_mfma_f32_16x16x32_bf16 v[88:91], v[64:67], v[214:217], v[88:91]
	v_mfma_f32_16x16x32_bf16 v[140:143], v[28:31], v[188:191], v[140:143]
	v_mfma_f32_16x16x32_bf16 v[136:139], v[68:71], v[188:191], v[136:139]
	v_mfma_f32_16x16x32_bf16 v[124:127], v[28:31], v[196:199], v[124:127]
	v_mfma_f32_16x16x32_bf16 v[120:123], v[68:71], v[196:199], v[120:123]
	v_mfma_f32_16x16x32_bf16 v[108:111], v[28:31], v[210:213], v[108:111]
	v_mfma_f32_16x16x32_bf16 v[104:107], v[68:71], v[210:213], v[104:107]
	v_mfma_f32_16x16x32_bf16 v[92:95], v[28:31], v[218:221], v[92:95]
	v_mfma_f32_16x16x32_bf16 v[88:91], v[68:71], v[218:221], v[88:91]
	s_setprio 0
	s_setprio 1
	v_mfma_f32_16x16x32_bf16 v[132:135], v[144:147], v[184:187], v[132:135]
	v_mfma_f32_16x16x32_bf16 v[128:131], v[176:179], v[184:187], v[128:131]
	v_mfma_f32_16x16x32_bf16 v[116:119], v[144:147], v[192:195], v[116:119]
	v_mfma_f32_16x16x32_bf16 v[112:115], v[176:179], v[192:195], v[112:115]
	v_mfma_f32_16x16x32_bf16 v[100:103], v[144:147], v[206:209], v[100:103]
	v_mfma_f32_16x16x32_bf16 v[96:99], v[176:179], v[206:209], v[96:99]
	v_mfma_f32_16x16x32_bf16 v[84:87], v[144:147], v[214:217], v[84:87]
	v_mfma_f32_16x16x32_bf16 v[80:83], v[176:179], v[214:217], v[80:83]
	v_mfma_f32_16x16x32_bf16 v[132:135], v[148:151], v[188:191], v[132:135]
	v_mfma_f32_16x16x32_bf16 v[128:131], v[180:183], v[188:191], v[128:131]
	v_mfma_f32_16x16x32_bf16 v[116:119], v[148:151], v[196:199], v[116:119]
	v_mfma_f32_16x16x32_bf16 v[112:115], v[180:183], v[196:199], v[112:115]
	v_mfma_f32_16x16x32_bf16 v[100:103], v[148:151], v[210:213], v[100:103]
	v_mfma_f32_16x16x32_bf16 v[96:99], v[180:183], v[210:213], v[96:99]
	v_mfma_f32_16x16x32_bf16 v[84:87], v[148:151], v[218:221], v[84:87]
	v_mfma_f32_16x16x32_bf16 v[80:83], v[180:183], v[218:221], v[80:83]
	s_setprio 0
	s_barrier
; #define PG8_STAGE(bufoff, gbase, voff) do { _Pragma("unroll") for (int _i = 0; _i < 2; ++_i) \
;         __builtin_amdgcn_global_load_lds((const unsigned*)((const char*)(gbase) + (voff)[_i]), (LAS unsigned*)(lds + (bufoff) + ldsw + _i * 8192), 16, 0, 0); } while (0)
; #define PG8_LDA(dst, b, h) do { _Pragma("unroll") for (int m = 0; m < 4; ++m) _Pragma("unroll") for (int k = 0; k < 2; ++k) dst[m][k] = *(const LAS bf16x8*)(lds + PG8_SA(b, h) + aoff + m * 2048 + k * 1024); } while (0)
; #define PG8_LDB(dst, b, h) do { _Pragma("unroll") for (int n = 0; n < 2; ++n) _Pragma("unroll") for (int k = 0; k < 2; ++k) dst[n][k] = *(const LAS bf16x8*)(lds + PG8_SB(b, h) + boff + n * 2048 + k * 1024); } while (0)
; #define PG8_WAIT_V(n) asm volatile("s_waitcnt vmcnt(" #n ")" ::: "memory")
; #define PG8_BAR __builtin_amdgcn_s_barrier()
; template <class Epi, class Sched>
; __device__ __forceinline__ void gemm_phase(LAS unsigned char* lds, const Gemm g, const Sched& S, const Epi& E, int wave_id) {
;     ...
;         for (int t = 0; t < nt; t += 2) {
;             const bool last = (t == nt - 2);
;             const char* a1 = cA + (size_t)(t + 1) * kstep;
;             const char* a2 = last ? nA : cA + (size_t)(t + 2) * kstep; const char* b2 = last ? nB : cB + (size_t)(t + 2) * kstep;
;             const char* a3 = a2 + kstep; const char* b3 = b2 + kstep;
;             PG8_LDB(B0, 0, 0); PG8_LDB(B1, 0, 1); PG8_SCHED; PG8_LDA(At, 0, 0); PG8_STAGE(PG8_SA(1, 1), a1 + hstepA, voffA);
;             PG8_WAIT_V(8); PG8_WAIT_L(0); PG8_BAR; PG8_MMA(0, 0, At, B0); PG8_MMA(0, 1, At, B1); PG8_BAR; PG8_SCHED;
;             PG8_LDA(At, 0, 1); PG8_STAGE(PG8_SB(0, 0), b2, voffB); PG8_STAGE(PG8_SB(0, 1), b2 + hstepB, voffB); PG8_STAGE(PG8_SA(0, 0), a2, voffA);
;             PG8_WAIT_V(8); PG8_WAIT_L(0); PG8_BAR; PG8_MMA(1, 0, At, B0); PG8_MMA(1, 1, At, B1); PG8_BAR; PG8_SCHED;
;             PG8_LDB(B0, 1, 0); PG8_LDB(B1, 1, 1); PG8_SCHED; PG8_LDA(At, 1, 0); PG8_STAGE(PG8_SA(0, 1), a2 + hstepA, voffA);
;             PG8_WAIT_V(8); PG8_WAIT_L(0); PG8_BAR; PG8_MMA(0, 0, At, B0); PG8_MMA(0, 1, At, B1); PG8_BAR; PG8_SCHED;
;             PG8_LDA(At, 1, 1); PG8_STAGE(PG8_SB(1, 0), b3, voffB); PG8_STAGE(PG8_SB(1, 1), b3 + hstepB, voffB); PG8_STAGE(PG8_SA(1, 0), a3, voffA);
;             PG8_WAIT_V(8); PG8_WAIT_L(0); PG8_BAR; PG8_MMA(1, 0, At, B0); PG8_MMA(1, 1, At, B1); PG8_BAR; PG8_SCHED;
	s_add_i32 s48, s72, s35
	s_mov_b32 m0, s48
	ds_read_b128 v[184:187], v202 offset:49152
	ds_read_b128 v[188:191], v202 offset:50176
	ds_read_b128 v[192:195], v202 offset:51200
	ds_read_b128 v[196:199], v202 offset:52224
	ds_read_b128 v[206:209], v202 offset:53248
	ds_read_b128 v[210:213], v202 offset:54272
	ds_read_b128 v[214:217], v202 offset:55296
	ds_read_b128 v[218:221], v202 offset:56320
	global_load_lds_dwordx4 v154, s[76:77]
	s_add_i32 m0, s48, 0x2000
	s_add_u32 s46, s46, 0x40080
	s_addc_u32 s47, s47, 0
	s_add_i32 s48, s73, s35
	global_load_lds_dwordx4 v158, s[76:77]
	s_mov_b32 m0, s48
	s_nop 0
	global_load_lds_dwordx4 v154, s[46:47]
	s_add_i32 m0, s48, 0x2000
	s_nop 0
	global_load_lds_dwordx4 v158, s[46:47]
	s_mov_b32 m0, s55
	s_nop 0
	global_load_lds_dwordx4 v152, s[78:79]
	s_mov_b32 m0, s56
	s_nop 0
	global_load_lds_dwordx4 v156, s[78:79]
	s_waitcnt vmcnt(8)
	s_waitcnt lgkmcnt(0)
	s_barrier
	s_setprio 1
	s_waitcnt lgkmcnt(0)
	v_mfma_f32_16x16x32_bf16 v[76:79], v[24:27], v[184:187], v[76:79]
	v_mfma_f32_16x16x32_bf16 v[60:63], v[24:27], v[192:195], v[60:63]
	v_mfma_f32_16x16x32_bf16 v[44:47], v[24:27], v[206:209], v[44:47]
	v_mfma_f32_16x16x32_bf16 v[8:11], v[24:27], v[214:217], v[8:11]
	v_mfma_f32_16x16x32_bf16 v[76:79], v[28:31], v[188:191], v[76:79]
	v_mfma_f32_16x16x32_bf16 v[72:75], v[64:67], v[184:187], v[72:75]
	v_mfma_f32_16x16x32_bf16 v[60:63], v[28:31], v[196:199], v[60:63]
	v_mfma_f32_16x16x32_bf16 v[56:59], v[64:67], v[192:195], v[56:59]
	v_mfma_f32_16x16x32_bf16 v[44:47], v[28:31], v[210:213], v[44:47]
	v_mfma_f32_16x16x32_bf16 v[40:43], v[64:67], v[206:209], v[40:43]
	v_mfma_f32_16x16x32_bf16 v[28:31], v[28:31], v[218:221], v[8:11]
	v_mfma_f32_16x16x32_bf16 v[8:11], v[64:67], v[214:217], v[12:15]
	v_mfma_f32_16x16x32_bf16 v[72:75], v[68:71], v[188:191], v[72:75]
	v_mfma_f32_16x16x32_bf16 v[56:59], v[68:71], v[196:199], v[56:59]
	v_mfma_f32_16x16x32_bf16 v[40:43], v[68:71], v[210:213], v[40:43]
	v_mfma_f32_16x16x32_bf16 v[24:27], v[68:71], v[218:221], v[8:11]
	s_setprio 0
	s_setprio 1
	v_mfma_f32_16x16x32_bf16 v[8:11], v[144:147], v[184:187], v[16:19]
	v_mfma_f32_16x16x32_bf16 v[68:71], v[148:151], v[188:191], v[8:11]
	v_mfma_f32_16x16x32_bf16 v[8:11], v[176:179], v[184:187], v[20:23]
	v_mfma_f32_16x16x32_bf16 v[64:67], v[180:183], v[188:191], v[8:11]
	v_mfma_f32_16x16x32_bf16 v[8:11], v[144:147], v[192:195], v[52:55]
	v_mfma_f32_16x16x32_bf16 v[52:55], v[148:151], v[196:199], v[8:11]
	v_mfma_f32_16x16x32_bf16 v[8:11], v[176:179], v[192:195], v[48:51]
	v_mfma_f32_16x16x32_bf16 v[48:51], v[180:183], v[196:199], v[8:11]
	v_mfma_f32_16x16x32_bf16 v[8:11], v[144:147], v[206:209], v[36:39]
	v_mfma_f32_16x16x32_bf16 v[36:39], v[148:151], v[210:213], v[8:11]
	v_mfma_f32_16x16x32_bf16 v[8:11], v[176:179], v[206:209], v[32:35]
	v_mfma_f32_16x16x32_bf16 v[4:7], v[144:147], v[214:217], v[4:7]
	v_mfma_f32_16x16x32_bf16 v[0:3], v[176:179], v[214:217], v[0:3]
	v_mfma_f32_16x16x32_bf16 v[32:35], v[180:183], v[210:213], v[8:11]
	v_mfma_f32_16x16x32_bf16 v[4:7], v[148:151], v[218:221], v[4:7]
	v_mfma_f32_16x16x32_bf16 v[0:3], v[180:183], v[218:221], v[0:3]
	s_setprio 0
	s_barrier
	s_add_i32 s67, s67, 2
	s_add_u32 s12, s12, 0x100
	s_addc_u32 s13, s13, 0
	s_add_u32 s65, s65, 0x100
	s_addc_u32 s66, s66, 0
	s_cmp_gt_u32 s67, 13
.LBB0_1382:
	ds_read_b128 v[8:11], v200
	ds_read_b128 v[12:15], v200 offset:1024
	ds_read_b128 v[16:19], v200 offset:2048
	ds_read_b128 v[20:23], v200 offset:3072
	ds_read_b128 v[144:147], v201
	ds_read_b128 v[148:151], v201 offset:1024
	ds_read_b128 v[176:179], v201 offset:2048
	ds_read_b128 v[180:183], v201 offset:3072
	s_add_u32 s46, s12, 0xfffc0080
	s_addc_u32 s47, s13, -1
	s_cmp_eq_u32 s67, 12
	s_cselect_b32 s49, s41, s47
	s_cselect_b32 s48, s50, s46
	s_cselect_b32 s47, s39, s66
	s_cselect_b32 s46, s51, s65
	s_add_u32 s78, s48, 0x80
	s_addc_u32 s79, s49, 0
	s_add_u32 s76, s46, 0x80
	s_addc_u32 s77, s47, 0
	s_add_i32 m0, s37, 0xc000
	ds_read_b128 v[184:187], v202
	ds_read_b128 v[188:191], v202 offset:1024
	ds_read_b128 v[192:195], v202 offset:2048
	ds_read_b128 v[196:199], v202 offset:3072
	ds_read_b128 v[206:209], v202 offset:4096
	ds_read_b128 v[210:213], v202 offset:5120
	ds_read_b128 v[214:217], v202 offset:6144
	ds_read_b128 v[218:221], v202 offset:7168
	global_load_lds_dwordx4 v168, s[12:13]
	s_add_i32 m0, s37, 0xe000
	s_nop 0
	global_load_lds_dwordx4 v170, s[12:13]
	s_waitcnt vmcnt(8)
	s_waitcnt lgkmcnt(0)
	s_barrier
	s_setprio 1
	s_waitcnt lgkmcnt(0)
	v_mfma_f32_16x16x32_bf16 v[140:143], v[8:11], v[184:187], v[140:143]
	v_mfma_f32_16x16x32_bf16 v[136:139], v[16:19], v[184:187], v[136:139]
	v_mfma_f32_16x16x32_bf16 v[124:127], v[8:11], v[192:195], v[124:127]
	v_mfma_f32_16x16x32_bf16 v[120:123], v[16:19], v[192:195], v[120:123]
	v_mfma_f32_16x16x32_bf16 v[108:111], v[8:11], v[206:209], v[108:111]
	v_mfma_f32_16x16x32_bf16 v[104:107], v[16:19], v[206:209], v[104:107]
	v_mfma_f32_16x16x32_bf16 v[92:95], v[8:11], v[214:217], v[92:95]
	v_mfma_f32_16x16x32_bf16 v[88:91], v[16:19], v[214:217], v[88:91]
	v_mfma_f32_16x16x32_bf16 v[140:143], v[12:15], v[188:191], v[140:143]
	v_mfma_f32_16x16x32_bf16 v[136:139], v[20:23], v[188:191], v[136:139]
	v_mfma_f32_16x16x32_bf16 v[124:127], v[12:15], v[196:199], v[124:127]
	v_mfma_f32_16x16x32_bf16 v[120:123], v[20:23], v[196:199], v[120:123]
	v_mfma_f32_16x16x32_bf16 v[108:111], v[12:15], v[210:213], v[108:111]
	v_mfma_f32_16x16x32_bf16 v[104:107], v[20:23], v[210:213], v[104:107]
	v_mfma_f32_16x16x32_bf16 v[92:95], v[12:15], v[218:221], v[92:95]
	v_mfma_f32_16x16x32_bf16 v[88:91], v[20:23], v[218:221], v[88:91]
	s_setprio 0
	s_setprio 1
	v_mfma_f32_16x16x32_bf16 v[132:135], v[144:147], v[184:187], v[132:135]
	v_mfma_f32_16x16x32_bf16 v[128:131], v[176:179], v[184:187], v[128:131]
	v_mfma_f32_16x16x32_bf16 v[116:119], v[144:147], v[192:195], v[116:119]
	v_mfma_f32_16x16x32_bf16 v[112:115], v[176:179], v[192:195], v[112:115]
	v_mfma_f32_16x16x32_bf16 v[100:103], v[144:147], v[206:209], v[100:103]
	v_mfma_f32_16x16x32_bf16 v[96:99], v[176:179], v[206:209], v[96:99]
	v_mfma_f32_16x16x32_bf16 v[84:87], v[144:147], v[214:217], v[84:87]
	v_mfma_f32_16x16x32_bf16 v[80:83], v[176:179], v[214:217], v[80:83]
	v_mfma_f32_16x16x32_bf16 v[132:135], v[148:151], v[188:191], v[132:135]
	v_mfma_f32_16x16x32_bf16 v[128:131], v[180:183], v[188:191], v[128:131]
	v_mfma_f32_16x16x32_bf16 v[116:119], v[148:151], v[196:199], v[116:119]
	v_mfma_f32_16x16x32_bf16 v[112:115], v[180:183], v[196:199], v[112:115]
	v_mfma_f32_16x16x32_bf16 v[100:103], v[148:151], v[210:213], v[100:103]
	v_mfma_f32_16x16x32_bf16 v[96:99], v[180:183], v[210:213], v[96:99]
	v_mfma_f32_16x16x32_bf16 v[84:87], v[148:151], v[218:221], v[84:87]
	v_mfma_f32_16x16x32_bf16 v[80:83], v[180:183], v[218:221], v[80:83]
	s_setprio 0
	s_barrier
; #define PG8_STAGE(bufoff, gbase, voff) do { _Pragma("unroll") for (int _i = 0; _i < 2; ++_i) \
;         __builtin_amdgcn_global_load_lds((const unsigned*)((const char*)(gbase) + (voff)[_i]), (LAS unsigned*)(lds + (bufoff) + ldsw + _i * 8192), 16, 0, 0); } while (0)
; #define PG8_LDA(dst, b, h) do { _Pragma("unroll") for (int m = 0; m < 4; ++m) _Pragma("unroll") for (int k = 0; k < 2; ++k) dst[m][k] = *(const LAS bf16x8*)(lds + PG8_SA(b, h) + aoff + m * 2048 + k * 1024); } while (0)
; #define PG8_LDB(dst, b, h) do { _Pragma("unroll") for (int n = 0; n < 2; ++n) _Pragma("unroll") for (int k = 0; k < 2; ++k) dst[n][k] = *(const LAS bf16x8*)(lds + PG8_SB(b, h) + boff + n * 2048 + k * 1024); } while (0)
; #define PG8_MMA(ai, bj, At, Bt) do { __builtin_amdgcn_s_setprio(1); _Pragma("unroll") for (int m = 0; m < 4; ++m) _Pragma("unroll") for (int n = 0; n < 2; ++n) _Pragma("unroll") for (int k = 0; k < 2; ++k) \
;         acc[ai][bj][m][n] = __builtin_amdgcn_mfma_f32_16x16x32_bf16(Bt[n][k], At[m][k], acc[ai][bj][m][n], 0, 0, 0); __builtin_amdgcn_s_setprio(0); } while (0)
; #define PG8_WAIT_V(n) asm volatile("s_waitcnt vmcnt(" #n ")" ::: "memory")
; #define PG8_WAIT_L(n) asm volatile("s_waitcnt lgkmcnt(" #n ")" ::: "memory")
; #define PG8_BAR __builtin_amdgcn_s_barrier()
; #define PG8_SCHED __builtin_amdgcn_sched_barrier(0)
; template <class Epi, class Sched>
; __device__ __forceinline__ void gemm_phase(LAS unsigned char* lds, const Gemm g, const Sched& S, const Epi& E, int wave_id) {
;     ...
;             PG8_LDB(B0, 0, 0); PG8_LDB(B1, 0, 1); PG8_SCHED; PG8_LDA(At, 0, 0); PG8_STAGE(PG8_SA(1, 1), a1 + hstepA, voffA);
;             PG8_WAIT_V(8); PG8_WAIT_L(0); PG8_BAR; PG8_MMA(0, 0, At, B0); PG8_MMA(0, 1, At, B1); PG8_BAR; PG8_SCHED;
;             PG8_LDA(At, 0, 1); PG8_STAGE(PG8_SB(0, 0), b2, voffB); PG8_STAGE(PG8_SB(0, 1), b2 + hstepB, voffB); PG8_STAGE(PG8_SA(0, 0), a2, voffA);
;             PG8_WAIT_V(8); PG8_WAIT_L(0); PG8_BAR; PG8_MMA(1, 0, At, B0); PG8_MMA(1, 1, At, B1); PG8_BAR; PG8_SCHED;
	s_add_i32 s72, s61, s35
	s_mov_b32 m0, s72
	ds_read_b128 v[184:187], v202 offset:16384
	ds_read_b128 v[188:191], v202 offset:17408
	ds_read_b128 v[192:195], v202 offset:18432
	ds_read_b128 v[196:199], v202 offset:19456
	ds_read_b128 v[206:209], v202 offset:20480
	ds_read_b128 v[210:213], v202 offset:21504
	ds_read_b128 v[214:217], v202 offset:22528
	ds_read_b128 v[218:221], v202 offset:23552
	global_load_lds_dwordx4 v154, s[46:47]
	s_add_i32 m0, s72, 0x2000
	s_add_u32 s72, s46, 0x40000
	s_addc_u32 s73, s47, 0
	s_add_i32 s74, s62, s35
	global_load_lds_dwordx4 v158, s[46:47]
	s_mov_b32 m0, s74
	s_nop 0
	global_load_lds_dwordx4 v154, s[72:73]
	s_add_i32 m0, s74, 0x2000
	s_nop 0
	global_load_lds_dwordx4 v158, s[72:73]
	s_mov_b32 m0, s37
	s_nop 0
	global_load_lds_dwordx4 v152, s[48:49]
	s_mov_b32 m0, s52
	s_nop 0
	global_load_lds_dwordx4 v156, s[48:49]
	s_waitcnt vmcnt(8)
	s_waitcnt lgkmcnt(0)
	s_barrier
	s_setprio 1
	s_waitcnt lgkmcnt(0)
	v_mfma_f32_16x16x32_bf16 v[76:79], v[8:11], v[184:187], v[76:79]
	v_mfma_f32_16x16x32_bf16 v[72:75], v[16:19], v[184:187], v[72:75]
	v_mfma_f32_16x16x32_bf16 v[60:63], v[8:11], v[192:195], v[60:63]
	v_mfma_f32_16x16x32_bf16 v[56:59], v[16:19], v[192:195], v[56:59]
	v_mfma_f32_16x16x32_bf16 v[44:47], v[8:11], v[206:209], v[44:47]
	v_mfma_f32_16x16x32_bf16 v[40:43], v[16:19], v[206:209], v[40:43]
	v_mfma_f32_16x16x32_bf16 v[8:11], v[8:11], v[214:217], v[28:31]
	v_mfma_f32_16x16x32_bf16 v[76:79], v[12:15], v[188:191], v[76:79]
	v_mfma_f32_16x16x32_bf16 v[72:75], v[20:23], v[188:191], v[72:75]
	v_mfma_f32_16x16x32_bf16 v[60:63], v[12:15], v[196:199], v[60:63]
	v_mfma_f32_16x16x32_bf16 v[56:59], v[20:23], v[196:199], v[56:59]
	v_mfma_f32_16x16x32_bf16 v[44:47], v[12:15], v[210:213], v[44:47]
	v_mfma_f32_16x16x32_bf16 v[40:43], v[20:23], v[210:213], v[40:43]
	v_mfma_f32_16x16x32_bf16 v[8:11], v[12:15], v[218:221], v[8:11]
	v_mfma_f32_16x16x32_bf16 v[12:15], v[16:19], v[214:217], v[24:27]
	v_mfma_f32_16x16x32_bf16 v[12:15], v[20:23], v[218:221], v[12:15]
	s_setprio 0
	s_setprio 1
	v_mfma_f32_16x16x32_bf16 v[24:27], v[144:147], v[192:195], v[52:55]
	v_mfma_f32_16x16x32_bf16 v[52:55], v[148:151], v[196:199], v[24:27]
	v_mfma_f32_16x16x32_bf16 v[24:27], v[176:179], v[192:195], v[48:51]
	v_mfma_f32_16x16x32_bf16 v[48:51], v[180:183], v[196:199], v[24:27]
	v_mfma_f32_16x16x32_bf16 v[24:27], v[144:147], v[206:209], v[36:39]
	v_mfma_f32_16x16x32_bf16 v[36:39], v[148:151], v[210:213], v[24:27]
	v_mfma_f32_16x16x32_bf16 v[24:27], v[176:179], v[206:209], v[32:35]
	v_mfma_f32_16x16x32_bf16 v[4:7], v[144:147], v[214:217], v[4:7]
	v_mfma_f32_16x16x32_bf16 v[0:3], v[176:179], v[214:217], v[0:3]
	v_mfma_f32_16x16x32_bf16 v[16:19], v[144:147], v[184:187], v[68:71]
	v_mfma_f32_16x16x32_bf16 v[20:23], v[176:179], v[184:187], v[64:67]
	v_mfma_f32_16x16x32_bf16 v[32:35], v[180:183], v[210:213], v[24:27]
	v_mfma_f32_16x16x32_bf16 v[4:7], v[148:151], v[218:221], v[4:7]
	v_mfma_f32_16x16x32_bf16 v[0:3], v[180:183], v[218:221], v[0:3]
	v_mfma_f32_16x16x32_bf16 v[16:19], v[148:151], v[188:191], v[16:19]
	v_mfma_f32_16x16x32_bf16 v[20:23], v[180:183], v[188:191], v[20:23]
	s_setprio 0
	s_barrier
	s_add_i32 s72, 0, 0x18000
	s_add_i32 s73, 0, 0x1c000
	v_add_u32_e32 v68, s72, v165
	v_add_u32_e32 v180, s73, v165
	ds_read_b128 v[24:27], v68
	ds_read_b128 v[28:31], v68 offset:1024
	ds_read_b128 v[64:67], v68 offset:2048
	ds_read_b128 v[68:71], v68 offset:3072
	ds_read_b128 v[144:147], v180
	ds_read_b128 v[148:151], v180 offset:1024
	ds_read_b128 v[176:179], v180 offset:2048
	ds_read_b128 v[180:183], v180 offset:3072
	s_add_u32 s48, s48, 0x40000
	s_addc_u32 s49, s49, 0
	s_mov_b32 m0, s53
	ds_read_b128 v[184:187], v202 offset:32768
	ds_read_b128 v[188:191], v202 offset:33792
	ds_read_b128 v[192:195], v202 offset:34816
	ds_read_b128 v[196:199], v202 offset:35840
	ds_read_b128 v[206:209], v202 offset:36864
	ds_read_b128 v[210:213], v202 offset:37888
	ds_read_b128 v[214:217], v202 offset:38912
	ds_read_b128 v[218:221], v202 offset:39936
	global_load_lds_dwordx4 v152, s[48:49]
	s_mov_b32 m0, s54
	s_nop 0
	global_load_lds_dwordx4 v156, s[48:49]
	s_waitcnt vmcnt(8)
	s_waitcnt lgkmcnt(0)
	s_barrier
; #define PG8_STAGE(bufoff, gbase, voff) do { _Pragma("unroll") for (int _i = 0; _i < 2; ++_i) \
;         __builtin_amdgcn_global_load_lds((const unsigned*)((const char*)(gbase) + (voff)[_i]), (LAS unsigned*)(lds + (bufoff) + ldsw + _i * 8192), 16, 0, 0); } while (0)
; #define PG8_LDA(dst, b, h) do { _Pragma("unroll") for (int m = 0; m < 4; ++m) _Pragma("unroll") for (int k = 0; k < 2; ++k) dst[m][k] = *(const LAS bf16x8*)(lds + PG8_SA(b, h) + aoff + m * 2048 + k * 1024); } while (0)
; #define PG8_LDB(dst, b, h) do { _Pragma("unroll") for (int n = 0; n < 2; ++n) _Pragma("unroll") for (int k = 0; k < 2; ++k) dst[n][k] = *(const LAS bf16x8*)(lds + PG8_SB(b, h) + boff + n * 2048 + k * 1024); } while (0)
; #define PG8_MMA(ai, bj, At, Bt) do { __builtin_amdgcn_s_setprio(1); _Pragma("unroll") for (int m = 0; m < 4; ++m) _Pragma("unroll") for (int n = 0; n < 2; ++n) _Pragma("unroll") for (int k = 0; k < 2; ++k) \
;         acc[ai][bj][m][n] = __builtin_amdgcn_mfma_f32_16x16x32_bf16(Bt[n][k], At[m][k], acc[ai][bj][m][n], 0, 0, 0); __builtin_amdgcn_s_setprio(0); } while (0)
; #define PG8_WAIT_V(n) asm volatile("s_waitcnt vmcnt(" #n ")" ::: "memory")
; #define PG8_WAIT_L(n) asm volatile("s_waitcnt lgkmcnt(" #n ")" ::: "memory")
; #define PG8_BAR __builtin_amdgcn_s_barrier()
; #define PG8_SCHED __builtin_amdgcn_sched_barrier(0)
; template <class Epi, class Sched>
; __device__ __forceinline__ void gemm_phase(LAS unsigned char* lds, const Gemm g, const Sched& S, const Epi& E, int wave_id) {
;     ...
;             PG8_LDB(B0, 1, 0); PG8_LDB(B1, 1, 1); PG8_SCHED; PG8_LDA(At, 1, 0); PG8_STAGE(PG8_SA(0, 1), a2 + hstepA, voffA);
;             PG8_WAIT_V(8); PG8_WAIT_L(0); PG8_BAR; PG8_MMA(0, 0, At, B0); PG8_MMA(0, 1, At, B1); PG8_BAR; PG8_SCHED;
;             PG8_LDA(At, 1, 1); PG8_STAGE(PG8_SB(1, 0), b3, voffB); PG8_STAGE(PG8_SB(1, 1), b3 + hstepB, voffB); PG8_STAGE(PG8_SA(1, 0), a3, voffA);
;             PG8_WAIT_V(8); PG8_WAIT_L(0); PG8_BAR; PG8_MMA(1, 0, At, B0); PG8_MMA(1, 1, At, B1); PG8_BAR; PG8_SCHED;
;         }
;         if (wr == 0) PG8_BAR;
	s_setprio 1
	s_waitcnt lgkmcnt(0)
	v_mfma_f32_16x16x32_bf16 v[140:143], v[24:27], v[184:187], v[140:143]
	v_mfma_f32_16x16x32_bf16 v[136:139], v[64:67], v[184:187], v[136:139]
	v_mfma_f32_16x16x32_bf16 v[124:127], v[24:27], v[192:195], v[124:127]
	v_mfma_f32_16x16x32_bf16 v[120:123], v[64:67], v[192:195], v[120:123]
	v_mfma_f32_16x16x32_bf16 v[108:111], v[24:27], v[206:209], v[108:111]
	v_mfma_f32_16x16x32_bf16 v[104:107], v[64:67], v[206:209], v[104:107]
	v_mfma_f32_16x16x32_bf16 v[92:95], v[24:27], v[214:217], v[92:95]
	v_mfma_f32_16x16x32_bf16 v[88:91], v[64:67], v[214:217], v[88:91]
	v_mfma_f32_16x16x32_bf16 v[140:143], v[28:31], v[188:191], v[140:143]
	v_mfma_f32_16x16x32_bf16 v[136:139], v[68:71], v[188:191], v[136:139]
	v_mfma_f32_16x16x32_bf16 v[124:127], v[28:31], v[196:199], v[124:127]
	v_mfma_f32_16x16x32_bf16 v[120:123], v[68:71], v[196:199], v[120:123]
	v_mfma_f32_16x16x32_bf16 v[108:111], v[28:31], v[210:213], v[108:111]
	v_mfma_f32_16x16x32_bf16 v[104:107], v[68:71], v[210:213], v[104:107]
	v_mfma_f32_16x16x32_bf16 v[92:95], v[28:31], v[218:221], v[92:95]
	v_mfma_f32_16x16x32_bf16 v[88:91], v[68:71], v[218:221], v[88:91]
	s_setprio 0
	s_setprio 1
	v_mfma_f32_16x16x32_bf16 v[132:135], v[144:147], v[184:187], v[132:135]
	v_mfma_f32_16x16x32_bf16 v[128:131], v[176:179], v[184:187], v[128:131]
	v_mfma_f32_16x16x32_bf16 v[116:119], v[144:147], v[192:195], v[116:119]
	v_mfma_f32_16x16x32_bf16 v[112:115], v[176:179], v[192:195], v[112:115]
	v_mfma_f32_16x16x32_bf16 v[100:103], v[144:147], v[206:209], v[100:103]
	v_mfma_f32_16x16x32_bf16 v[96:99], v[176:179], v[206:209], v[96:99]
	v_mfma_f32_16x16x32_bf16 v[84:87], v[144:147], v[214:217], v[84:87]
	v_mfma_f32_16x16x32_bf16 v[80:83], v[176:179], v[214:217], v[80:83]
	v_mfma_f32_16x16x32_bf16 v[132:135], v[148:151], v[188:191], v[132:135]
	v_mfma_f32_16x16x32_bf16 v[128:131], v[180:183], v[188:191], v[128:131]
	v_mfma_f32_16x16x32_bf16 v[116:119], v[148:151], v[196:199], v[116:119]
	v_mfma_f32_16x16x32_bf16 v[112:115], v[180:183], v[196:199], v[112:115]
	v_mfma_f32_16x16x32_bf16 v[100:103], v[148:151], v[210:213], v[100:103]
	v_mfma_f32_16x16x32_bf16 v[96:99], v[180:183], v[210:213], v[96:99]
	v_mfma_f32_16x16x32_bf16 v[84:87], v[148:151], v[218:221], v[84:87]
	v_mfma_f32_16x16x32_bf16 v[80:83], v[180:183], v[218:221], v[80:83]
	s_setprio 0
	s_barrier
	s_add_i32 s48, s72, s35
	s_mov_b32 m0, s48
	ds_read_b128 v[184:187], v202 offset:49152
	ds_read_b128 v[188:191], v202 offset:50176
	ds_read_b128 v[192:195], v202 offset:51200
	ds_read_b128 v[196:199], v202 offset:52224
	ds_read_b128 v[206:209], v202 offset:53248
	ds_read_b128 v[210:213], v202 offset:54272
	ds_read_b128 v[214:217], v202 offset:55296
	ds_read_b128 v[218:221], v202 offset:56320
	global_load_lds_dwordx4 v154, s[76:77]
	s_add_i32 m0, s48, 0x2000
	s_add_u32 s46, s46, 0x40080
	s_addc_u32 s47, s47, 0
	s_add_i32 s48, s73, s35
	global_load_lds_dwordx4 v158, s[76:77]
	s_mov_b32 m0, s48
	s_nop 0
	global_load_lds_dwordx4 v154, s[46:47]
	s_add_i32 m0, s48, 0x2000
	s_nop 0
	global_load_lds_dwordx4 v158, s[46:47]
	s_mov_b32 m0, s55
	s_nop 0
	global_load_lds_dwordx4 v152, s[78:79]
	s_mov_b32 m0, s56
	s_nop 0
	global_load_lds_dwordx4 v156, s[78:79]
	s_waitcnt vmcnt(8)
	s_waitcnt lgkmcnt(0)
	s_barrier
	s_setprio 1
	s_waitcnt lgkmcnt(0)
	v_mfma_f32_16x16x32_bf16 v[76:79], v[24:27], v[184:187], v[76:79]
	v_mfma_f32_16x16x32_bf16 v[60:63], v[24:27], v[192:195], v[60:63]
	v_mfma_f32_16x16x32_bf16 v[44:47], v[24:27], v[206:209], v[44:47]
	v_mfma_f32_16x16x32_bf16 v[8:11], v[24:27], v[214:217], v[8:11]
	v_mfma_f32_16x16x32_bf16 v[76:79], v[28:31], v[188:191], v[76:79]
	v_mfma_f32_16x16x32_bf16 v[72:75], v[64:67], v[184:187], v[72:75]
	v_mfma_f32_16x16x32_bf16 v[60:63], v[28:31], v[196:199], v[60:63]
	v_mfma_f32_16x16x32_bf16 v[56:59], v[64:67], v[192:195], v[56:59]
	v_mfma_f32_16x16x32_bf16 v[44:47], v[28:31], v[210:213], v[44:47]
	v_mfma_f32_16x16x32_bf16 v[40:43], v[64:67], v[206:209], v[40:43]
	v_mfma_f32_16x16x32_bf16 v[28:31], v[28:31], v[218:221], v[8:11]
	v_mfma_f32_16x16x32_bf16 v[8:11], v[64:67], v[214:217], v[12:15]
	v_mfma_f32_16x16x32_bf16 v[72:75], v[68:71], v[188:191], v[72:75]
	v_mfma_f32_16x16x32_bf16 v[56:59], v[68:71], v[196:199], v[56:59]
	v_mfma_f32_16x16x32_bf16 v[40:43], v[68:71], v[210:213], v[40:43]
	v_mfma_f32_16x16x32_bf16 v[24:27], v[68:71], v[218:221], v[8:11]
	s_setprio 0
	s_setprio 1
	v_mfma_f32_16x16x32_bf16 v[8:11], v[144:147], v[184:187], v[16:19]
	v_mfma_f32_16x16x32_bf16 v[68:71], v[148:151], v[188:191], v[8:11]
	v_mfma_f32_16x16x32_bf16 v[8:11], v[176:179], v[184:187], v[20:23]
	v_mfma_f32_16x16x32_bf16 v[64:67], v[180:183], v[188:191], v[8:11]
	v_mfma_f32_16x16x32_bf16 v[8:11], v[144:147], v[192:195], v[52:55]
	v_mfma_f32_16x16x32_bf16 v[52:55], v[148:151], v[196:199], v[8:11]
	v_mfma_f32_16x16x32_bf16 v[8:11], v[176:179], v[192:195], v[48:51]
	v_mfma_f32_16x16x32_bf16 v[48:51], v[180:183], v[196:199], v[8:11]
	v_mfma_f32_16x16x32_bf16 v[8:11], v[144:147], v[206:209], v[36:39]
	v_mfma_f32_16x16x32_bf16 v[36:39], v[148:151], v[210:213], v[8:11]
	v_mfma_f32_16x16x32_bf16 v[8:11], v[176:179], v[206:209], v[32:35]
	v_mfma_f32_16x16x32_bf16 v[4:7], v[144:147], v[214:217], v[4:7]
	v_mfma_f32_16x16x32_bf16 v[0:3], v[176:179], v[214:217], v[0:3]
	v_mfma_f32_16x16x32_bf16 v[32:35], v[180:183], v[210:213], v[8:11]
	v_mfma_f32_16x16x32_bf16 v[4:7], v[148:151], v[218:221], v[4:7]
	v_mfma_f32_16x16x32_bf16 v[0:3], v[180:183], v[218:221], v[0:3]
	s_setprio 0
	s_barrier
	s_add_i32 s67, s67, 2
	s_add_u32 s12, s12, 0x100
	s_addc_u32 s13, s13, 0
	s_add_u32 s65, s65, 0x100
	s_addc_u32 s66, s66, 0
	s_cmp_gt_u32 s67, 13
	s_cbranch_scc0 .LBB0_1382
	s_and_b64 vcc, exec, s[24:25]
	s_cbranch_vccz .LBB0_1385
	s_barrier
